# W_in log-forget epilogue: moves left by the guard removal propagated away (fast copy 3485 -> 3260 instructions)
# speedup vs baseline: 1.0006x; 1.0006x over previous
; __device__ __forceinline__ float silu_f(float x) { return x * __builtin_amdgcn_rcpf(1.f + __expf(-x)); }
; __device__ __forceinline__ v4u pack8(const f32x4 a, const f32x4 b) { v4u w; w.x = cvt_pk_bf16(a[0], a[1]); w.y = cvt_pk_bf16(a[2], a[3]); w.z = cvt_pk_bf16(b[0], b[1]); w.w = cvt_pk_bf16(b[2], b[3]); return w; }
;     __device__ __forceinline__ void operator()(const f32x4 (&acc)[2][2][4][2], const pg8::Unit& u, int wr, int wc, int fr, int fq) const {
;     ...
;         if (grp == 0) { WIN_LOOP( _Pragma("unroll") for (int i = 0; i < 4; ++i) { a[i] = silu_f(a[i]); b[i] = silu_f(b[i]); } *(v4u*)(QO + (size_t)row * DM + c) = pack8(a, b); ) }
;         else if (grp == 3) { WIN_LOOP( _Pragma("unroll") for (int i = 0; i < 4; ++i) { a[i] = silu_f(a[i]); b[i] = silu_f(b[i]); } *(v4u*)(GH + (size_t)row * 512 + c) = pack8(a, b); ) }
;         else if (grp == 1) {
;             f32x4 l0[2], l1[2];
; #pragma unroll
;             for (int bj = 0; bj < 2; ++bj) { l0[bj] = *(const f32x4*)(lb + cb + bj * 128); l1[bj] = *(const f32x4*)(lb + cb + bj * 128 + 4); }
;             WIN_LOOP( _Pragma("unroll") for (int i = 0; i < 4; ++i) { const float s0 = fminf(a[i], 0.f) - __logf(1.f + __expf(-fabsf(a[i]))), s1 = fminf(b[i], 0.f) - __logf(1.f + __expf(-fabsf(b[i]))); const float la = l0[bj][i], lbv = l1[bj][i];
;                     a[i] = la > 0.f ? __logf(la + (1.f - la) * __expf(s0)) : s0; b[i] = lbv > 0.f ? __logf(lbv + (1.f - lbv) * __expf(s1)) : s1; }
;                 *(f32x4*)(LF + (size_t)row * 512 + c) = a; *(f32x4*)(LF + (size_t)row * 512 + c + 4) = b; __builtin_amdgcn_sched_barrier(0); ) }
.LBB0_414:
	s_andn2_b64 vcc, exec, s[8:9]
	s_cbranch_vccnz .LBB0_416
	v_readlane_b32 s8, v255, 35
	v_readlane_b32 s9, v255, 36
	v_lshlrev_b32_e32 v144, 2, v176
	s_nop 4
	global_load_dwordx4 v[128:131], v144, s[8:9]
	global_load_dwordx4 v[132:135], v144, s[8:9] offset:16
	global_load_dwordx4 v[136:139], v144, s[8:9] offset:512
	global_load_dwordx4 v[140:143], v144, s[8:9] offset:528
	s_waitcnt vmcnt(0)
	v_add_u32_e32 v128, -1, v128
	v_add_u32_e32 v129, -1, v129
	v_add_u32_e32 v130, -1, v130
	v_add_u32_e32 v131, -1, v131
	v_add_u32_e32 v132, -1, v132
	v_add_u32_e32 v133, -1, v133
	v_add_u32_e32 v134, -1, v134
	v_add_u32_e32 v135, -1, v135
	v_add_u32_e32 v136, -1, v136
	v_add_u32_e32 v137, -1, v137
	v_add_u32_e32 v138, -1, v138
	v_add_u32_e32 v139, -1, v139
	v_add_u32_e32 v140, -1, v140
	v_add_u32_e32 v141, -1, v141
	v_add_u32_e32 v142, -1, v142
	v_add_u32_e32 v143, -1, v143
	v_min_u32_e32 v128, v128, v129
	v_min_u32_e32 v130, v130, v131
	v_min_u32_e32 v132, v132, v133
	v_min_u32_e32 v134, v134, v135
	v_min_u32_e32 v136, v136, v137
	v_min_u32_e32 v138, v138, v139
	v_min_u32_e32 v140, v140, v141
	v_min_u32_e32 v142, v142, v143
	v_min_u32_e32 v128, v128, v130
	v_min_u32_e32 v132, v132, v134
	v_min_u32_e32 v136, v136, v138
	v_min_u32_e32 v140, v140, v142
	v_min_u32_e32 v128, v128, v132
	v_min_u32_e32 v136, v136, v140
	v_min_u32_e32 v128, v128, v136
	v_mov_b32_e32 v129, 0x7fffff
	v_cmp_lt_u32_e32 vcc, v128, v129
	s_nop 1
	s_cmp_eq_u64 vcc, 0
	s_cbranch_scc1 .Llf_fast
	v_ashrrev_i32_e32 v167, 31, v166
	v_lshlrev_b64 v[128:129], 6, v[166:167]
	v_lshl_add_u64 v[128:129], v[160:161], 0, v[128:129]
	s_nop 0
	v_readlane_b32 s8, v255, 35
	v_lshlrev_b32_e32 v192, 2, v176
	v_readlane_b32 s9, v255, 36
	v_and_b32_e32 v133, 64, v215
	v_xor_b32_e32 v132, 16, v215
	v_lshl_add_u64 v[144:145], s[8:9], 0, v[192:193]
	flat_load_dwordx4 v[140:143], v[144:145]
	flat_load_dwordx4 v[136:139], v[144:145] offset:16
	v_add_u32_e32 v134, 64, v133
	v_cmp_lt_i32_e32 vcc, v132, v134
	v_lshlrev_b64 v[146:147], 11, v[166:167]
	v_readlane_b32 s50, v255, 45
	v_cndmask_b32_e32 v132, v215, v132, vcc
	v_lshlrev_b32_e32 v169, 2, v132
	v_readlane_b32 s51, v255, 46
	s_mov_b32 s95, s28
	s_mov_b32 s91, s29
	v_lshl_add_u64 v[170:171], s[50:51], 0, v[146:147]
	v_lshl_add_u64 v[170:171], v[170:171], 0, v[192:193]
	s_waitcnt vmcnt(0) lgkmcnt(0)
	s_nop 3
	v_xor_b32_e32 v130, 32, v215
	s_nop 1
	v_cmp_lt_i32_e32 vcc, v130, v134
	v_sub_f32_e32 v190, 1.0, v140
	v_sub_f32_e32 v191, 1.0, v136
	v_cndmask_b32_e32 v130, v215, v130, vcc
	v_lshlrev_b32_e32 v202, 2, v130
	s_waitcnt lgkmcnt(0)
	s_nop 1
	flat_load_dwordx4 v[132:135], v[144:145] offset:512
	flat_load_dwordx4 v[128:131], v[144:145] offset:528
	v_sub_f32_e32 v188, 1.0, v141
	v_cmp_lt_f32_e64 s[38:39], 0, v140
	v_cmp_lt_f32_e64 s[36:37], 0, v136
	s_waitcnt lgkmcnt(0)
	s_nop 1
	v_mov_b32_e32 v168, v250
	v_sub_f32_e32 v189, 1.0, v137
	v_cmp_lt_f32_e64 s[34:35], 0, v141
	v_cmp_lt_f32_e64 s[30:31], 0, v137
	v_pk_mul_f32 v[144:145], v[60:61], v[168:169] op_sel_hi:[1,0]
	v_pk_mul_f32 v[148:149], v[56:57], v[168:169] op_sel_hi:[1,0]
	v_min_f32_e32 v167, 0, v144
	v_mul_f32_e64 v144, |v144|, s57
	v_min_f32_e32 v177, 0, v148
	v_mul_f32_e64 v148, |v148|, s57
	v_exp_f32_e32 v144, v144
	v_exp_f32_e32 v148, v148
	v_min_f32_e32 v179, 0, v149
	v_mul_f32_e64 v149, |v149|, s57
	v_add_f32_e32 v144, 1.0, v144
	v_exp_f32_e32 v149, v149
	v_add_f32_e32 v148, 1.0, v148
	v_min_f32_e32 v178, 0, v145
	v_mul_f32_e64 v145, |v145|, s57
	v_exp_f32_e32 v145, v145
	v_log_f32_e32 v144, v144
	v_add_f32_e32 v149, 1.0, v149
	v_log_f32_e32 v148, v148
	v_add_f32_e32 v145, 1.0, v145
	v_mul_f32_e32 v183, 0x3f317217, v144
	v_mul_f32_e32 v184, 0x3f317217, v148
	v_fma_f32 v183, v144, s52, -v183
	v_fma_f32 v184, v148, s52, -v184
	v_fmac_f32_e32 v183, 0x3377d1cf, v144
	v_fmac_f32_e32 v184, 0x3377d1cf, v148
	v_fmac_f32_e32 v183, 0x3f317217, v144
	v_log_f32_e32 v145, v145
	v_fmac_f32_e32 v184, 0x3f317217, v148
	v_log_f32_e32 v149, v149
	v_sub_f32_e32 v144, v167, v183
	v_sub_f32_e32 v167, v177, v184
	v_mul_f32_e32 v148, 0x3fb8aa3b, v144
	v_mul_f32_e32 v185, 0x3f317217, v145
	v_mul_f32_e32 v177, 0x3fb8aa3b, v167
	v_exp_f32_e32 v148, v148
	v_mul_f32_e32 v186, 0x3f317217, v149
	v_fma_f32 v185, v145, s52, -v185
	v_exp_f32_e32 v177, v177
	v_fma_f32 v186, v149, s52, -v186
	v_fmac_f32_e32 v185, 0x3377d1cf, v145
	v_fmac_f32_e32 v186, 0x3377d1cf, v149
	v_fmac_f32_e32 v185, 0x3f317217, v145
	v_fmac_f32_e32 v186, 0x3f317217, v149
	v_fma_f32 v148, v190, v148, v140
	v_fma_f32 v177, v191, v177, v136
	v_cmp_gt_f32_e64 s[10:11], s97, v177
	v_cmp_gt_f32_e64 s[8:9], s97, v148
	s_nop 0
	v_cndmask_b32_e64 v181, 0, 32, s[10:11]
	v_ldexp_f32 v177, v177, v181
	v_cndmask_b32_e64 v180, 0, 32, s[8:9]
	v_ldexp_f32 v148, v148, v180
	v_log_f32_e32 v148, v148
	v_log_f32_e32 v177, v177
	v_sub_f32_e32 v145, v178, v185
	v_mul_f32_e32 v178, 0x3fb8aa3b, v145
	v_mul_f32_e32 v182, 0x3f317217, v148
	v_exp_f32_e32 v178, v178
	v_mul_f32_e32 v183, 0x3f317217, v177
	v_fma_f32 v182, v148, s52, -v182
	v_fma_f32 v183, v177, s52, -v183
	v_fmac_f32_e32 v182, 0x3377d1cf, v148
	v_cndmask_b32_e64 v180, 0, v216, s[8:9]
	v_fmac_f32_e32 v183, 0x3377d1cf, v177
	v_fmac_f32_e32 v182, 0x3f317217, v148
	v_fmac_f32_e32 v183, 0x3f317217, v177
	v_fma_f32 v178, v188, v178, v141
	v_cndmask_b32_e64 v181, 0, v216, s[10:11]
	v_sub_f32_e32 v148, v182, v180
	v_sub_f32_e32 v177, v183, v181
	v_cmp_gt_f32_e64 s[8:9], s97, v178
	v_cndmask_b32_e64 v148, v144, v148, s[38:39]
	v_cndmask_b32_e64 v144, v167, v177, s[36:37]
	v_cndmask_b32_e64 v167, 0, 32, s[8:9]
	v_ldexp_f32 v167, v178, v167
	v_log_f32_e32 v167, v167
	v_sub_f32_e32 v177, v179, v186
; __device__ __forceinline__ float silu_f(float x) { return x * __builtin_amdgcn_rcpf(1.f + __expf(-x)); }
; __device__ __forceinline__ v4u pack8(const f32x4 a, const f32x4 b) { v4u w; w.x = cvt_pk_bf16(a[0], a[1]); w.y = cvt_pk_bf16(a[2], a[3]); w.z = cvt_pk_bf16(b[0], b[1]); w.w = cvt_pk_bf16(b[2], b[3]); return w; }
;     __device__ __forceinline__ void operator()(const f32x4 (&acc)[2][2][4][2], const pg8::Unit& u, int wr, int wc, int fr, int fq) const {
;     ...
;         if (grp == 0) { WIN_LOOP( _Pragma("unroll") for (int i = 0; i < 4; ++i) { a[i] = silu_f(a[i]); b[i] = silu_f(b[i]); } *(v4u*)(QO + (size_t)row * DM + c) = pack8(a, b); ) }
;         else if (grp == 3) { WIN_LOOP( _Pragma("unroll") for (int i = 0; i < 4; ++i) { a[i] = silu_f(a[i]); b[i] = silu_f(b[i]); } *(v4u*)(GH + (size_t)row * 512 + c) = pack8(a, b); ) }
;         else if (grp == 1) {
;             f32x4 l0[2], l1[2];
; #pragma unroll
;             for (int bj = 0; bj < 2; ++bj) { l0[bj] = *(const f32x4*)(lb + cb + bj * 128); l1[bj] = *(const f32x4*)(lb + cb + bj * 128 + 4); }
;             WIN_LOOP( _Pragma("unroll") for (int i = 0; i < 4; ++i) { const float s0 = fminf(a[i], 0.f) - __logf(1.f + __expf(-fabsf(a[i]))), s1 = fminf(b[i], 0.f) - __logf(1.f + __expf(-fabsf(b[i]))); const float la = l0[bj][i], lbv = l1[bj][i];
;                     a[i] = la > 0.f ? __logf(la + (1.f - la) * __expf(s0)) : s0; b[i] = lbv > 0.f ? __logf(lbv + (1.f - lbv) * __expf(s1)) : s1; }
;                 *(f32x4*)(LF + (size_t)row * 512 + c) = a; *(f32x4*)(LF + (size_t)row * 512 + c + 4) = b; __builtin_amdgcn_sched_barrier(0); ) }
	v_mul_f32_e32 v178, 0x3fb8aa3b, v177
	v_exp_f32_e32 v178, v178
	v_mul_f32_e32 v149, 0x3f317217, v167
	v_fma_f32 v149, v167, s52, -v149
	v_fmac_f32_e32 v149, 0x3377d1cf, v167
	v_fmac_f32_e32 v149, 0x3f317217, v167
	v_fma_f32 v178, v189, v178, v137
	v_pk_mul_f32 v[150:151], v[62:63], v[168:169] op_sel_hi:[1,0]
	v_cmp_gt_f32_e32 vcc, s97, v178
	v_cndmask_b32_e64 v167, 0, v216, s[8:9]
	v_sub_f32_e32 v149, v149, v167
	v_cndmask_b32_e64 v179, 0, 32, vcc
	v_ldexp_f32 v178, v178, v179
	v_log_f32_e32 v178, v178
	v_mul_f32_e64 v167, |v150|, s57
	v_exp_f32_e32 v167, v167
	v_cndmask_b32_e64 v149, v145, v149, s[34:35]
	v_mul_f32_e32 v145, 0x3f317217, v178
	v_fma_f32 v145, v178, s52, -v145
	v_fmac_f32_e32 v145, 0x3377d1cf, v178
	v_fmac_f32_e32 v145, 0x3f317217, v178
	v_add_f32_e32 v167, 1.0, v167
	v_pk_mul_f32 v[146:147], v[58:59], v[168:169] op_sel_hi:[1,0]
	v_cndmask_b32_e32 v178, 0, v216, vcc
	v_sub_f32_e32 v145, v145, v178
	v_cndmask_b32_e64 v145, v177, v145, s[30:31]
	v_log_f32_e32 v167, v167
	v_mul_f32_e64 v178, |v146|, s57
	v_exp_f32_e32 v178, v178
	v_min_f32_e32 v150, 0, v150
	v_mul_f32_e32 v177, 0x3f317217, v167
	v_fma_f32 v177, v167, s52, -v177
	v_fmac_f32_e32 v177, 0x3377d1cf, v167
	v_fmac_f32_e32 v177, 0x3f317217, v167
	v_add_f32_e32 v178, 1.0, v178
	v_sub_f32_e32 v187, 1.0, v142
	v_sub_f32_e32 v150, v150, v177
	v_log_f32_e32 v178, v178
	v_mul_f32_e32 v177, 0x3fb8aa3b, v150
	v_exp_f32_e32 v177, v177
	v_min_f32_e32 v146, 0, v146
	v_mul_f32_e32 v167, 0x3f317217, v178
	v_fma_f32 v167, v178, s52, -v167
	v_fmac_f32_e32 v167, 0x3377d1cf, v178
	v_fmac_f32_e32 v167, 0x3f317217, v178
	v_fma_f32 v177, v187, v177, v142
	v_sub_f32_e32 v186, 1.0, v138
	v_mov_b32_e32 v167, v167
	v_cmp_gt_f32_e64 s[8:9], s97, v177
	v_cmp_lt_f32_e64 s[28:29], 0, v142
	v_cmp_lt_f32_e64 s[26:27], 0, v138
	v_cndmask_b32_e64 v178, 0, 32, s[8:9]
	v_ldexp_f32 v177, v177, v178
	v_log_f32_e32 v177, v177
	v_sub_f32_e32 v146, v146, v167
	v_mul_f32_e32 v178, 0x3fb8aa3b, v146
	v_exp_f32_e32 v178, v178
	v_mul_f32_e32 v167, 0x3f317217, v177
	v_fma_f32 v167, v177, s52, -v167
	v_fmac_f32_e32 v167, 0x3377d1cf, v177
	v_fmac_f32_e32 v167, 0x3f317217, v177
	v_fma_f32 v178, v186, v178, v138
	v_sub_f32_e32 v185, 1.0, v143
	v_cmp_gt_f32_e32 vcc, s97, v178
	v_cndmask_b32_e64 v177, 0, v216, s[8:9]
	v_sub_f32_e32 v167, v167, v177
	v_cndmask_b32_e64 v179, 0, 32, vcc
	v_ldexp_f32 v178, v178, v179
	v_log_f32_e32 v178, v178
	v_mul_f32_e64 v177, |v151|, s57
	v_exp_f32_e32 v177, v177
	v_cndmask_b32_e64 v150, v150, v167, s[28:29]
	v_mul_f32_e32 v167, 0x3f317217, v178
	v_fma_f32 v167, v178, s52, -v167
	v_fmac_f32_e32 v167, 0x3377d1cf, v178
	v_fmac_f32_e32 v167, 0x3f317217, v178
	v_add_f32_e32 v177, 1.0, v177
	v_min_f32_e32 v151, 0, v151
	v_cndmask_b32_e32 v178, 0, v216, vcc
	v_sub_f32_e32 v167, v167, v178
	v_cndmask_b32_e64 v146, v146, v167, s[26:27]
	v_log_f32_e32 v177, v177
	v_mul_f32_e64 v178, |v147|, s57
	v_exp_f32_e32 v178, v178
	v_min_f32_e32 v147, 0, v147
	v_mul_f32_e32 v167, 0x3f317217, v177
	v_fma_f32 v167, v177, s52, -v167
	v_fmac_f32_e32 v167, 0x3377d1cf, v177
	v_fmac_f32_e32 v167, 0x3f317217, v177
	v_add_f32_e32 v178, 1.0, v178
	v_sub_f32_e32 v184, 1.0, v139
	v_mov_b32_e32 v167, v167
	v_sub_f32_e32 v151, v151, v167
	v_log_f32_e32 v178, v178
	v_mul_f32_e32 v177, 0x3fb8aa3b, v151
	v_exp_f32_e32 v177, v177
	v_cmp_lt_f32_e64 s[24:25], 0, v143
	v_mul_f32_e32 v167, 0x3f317217, v178
	v_fma_f32 v167, v178, s52, -v167
	v_fmac_f32_e32 v167, 0x3377d1cf, v178
	v_fmac_f32_e32 v167, 0x3f317217, v178
	v_fma_f32 v177, v185, v177, v143
	v_cmp_lt_f32_e64 s[22:23], 0, v139
	v_mov_b32_e32 v167, v167
	v_cmp_gt_f32_e64 s[8:9], s97, v177
	s_nop 1
	v_cndmask_b32_e64 v178, 0, 32, s[8:9]
	v_ldexp_f32 v177, v177, v178
	v_log_f32_e32 v177, v177
	v_sub_f32_e32 v147, v147, v167
	v_mul_f32_e32 v178, 0x3fb8aa3b, v147
	v_exp_f32_e32 v178, v178
	v_mul_f32_e32 v167, 0x3f317217, v177
	v_fma_f32 v167, v177, s52, -v167
	v_fmac_f32_e32 v167, 0x3377d1cf, v177
	v_fmac_f32_e32 v167, 0x3f317217, v177
	v_fma_f32 v178, v184, v178, v139
	s_nop 0
	v_cmp_gt_f32_e32 vcc, s97, v178
	v_cndmask_b32_e64 v177, 0, v216, s[8:9]
	v_sub_f32_e32 v167, v167, v177
	v_cndmask_b32_e64 v179, 0, 32, vcc
	v_ldexp_f32 v178, v178, v179
	v_log_f32_e32 v178, v178
	v_cndmask_b32_e64 v151, v151, v167, s[24:25]
	v_cndmask_b32_e32 v177, 0, v216, vcc
	v_mul_f32_e32 v167, 0x3f317217, v178
	v_fma_f32 v167, v178, s52, -v167
	v_fmac_f32_e32 v167, 0x3377d1cf, v178
	v_fmac_f32_e32 v167, 0x3f317217, v178
	v_sub_f32_e32 v167, v167, v177
	v_cndmask_b32_e64 v147, v147, v167, s[22:23]
	global_store_dwordx4 v[170:171], v[148:151], off
	global_store_dwordx4 v[170:171], v[144:147], off offset:16
	s_nop 1
	v_pk_mul_f32 v[144:145], v[124:125], v[168:169] op_sel_hi:[1,0]
	v_pk_mul_f32 v[150:151], v[126:127], v[168:169] op_sel_hi:[1,0]
	v_mul_f32_e64 v146, |v144|, s57
	v_exp_f32_e32 v148, v146
	v_pk_mul_f32 v[146:147], v[122:123], v[168:169] op_sel_hi:[1,0]
	v_min_f32_e32 v144, 0, v144
	s_waitcnt vmcnt(0)
; __device__ __forceinline__ float silu_f(float x) { return x * __builtin_amdgcn_rcpf(1.f + __expf(-x)); }
; __device__ __forceinline__ v4u pack8(const f32x4 a, const f32x4 b) { v4u w; w.x = cvt_pk_bf16(a[0], a[1]); w.y = cvt_pk_bf16(a[2], a[3]); w.z = cvt_pk_bf16(b[0], b[1]); w.w = cvt_pk_bf16(b[2], b[3]); return w; }
;     __device__ __forceinline__ void operator()(const f32x4 (&acc)[2][2][4][2], const pg8::Unit& u, int wr, int wc, int fr, int fq) const {
;     ...
;         if (grp == 0) { WIN_LOOP( _Pragma("unroll") for (int i = 0; i < 4; ++i) { a[i] = silu_f(a[i]); b[i] = silu_f(b[i]); } *(v4u*)(QO + (size_t)row * DM + c) = pack8(a, b); ) }
;         else if (grp == 3) { WIN_LOOP( _Pragma("unroll") for (int i = 0; i < 4; ++i) { a[i] = silu_f(a[i]); b[i] = silu_f(b[i]); } *(v4u*)(GH + (size_t)row * 512 + c) = pack8(a, b); ) }
;         else if (grp == 1) {
;             f32x4 l0[2], l1[2];
; #pragma unroll
;             for (int bj = 0; bj < 2; ++bj) { l0[bj] = *(const f32x4*)(lb + cb + bj * 128); l1[bj] = *(const f32x4*)(lb + cb + bj * 128 + 4); }
;             WIN_LOOP( _Pragma("unroll") for (int i = 0; i < 4; ++i) { const float s0 = fminf(a[i], 0.f) - __logf(1.f + __expf(-fabsf(a[i]))), s1 = fminf(b[i], 0.f) - __logf(1.f + __expf(-fabsf(b[i]))); const float la = l0[bj][i], lbv = l1[bj][i];
;                     a[i] = la > 0.f ? __logf(la + (1.f - la) * __expf(s0)) : s0; b[i] = lbv > 0.f ? __logf(lbv + (1.f - lbv) * __expf(s1)) : s1; }
;                 *(f32x4*)(LF + (size_t)row * 512 + c) = a; *(f32x4*)(LF + (size_t)row * 512 + c + 4) = b; __builtin_amdgcn_sched_barrier(0); ) }
	v_sub_f32_e32 v183, 1.0, v132
	v_add_f32_e32 v148, 1.0, v148
	v_sub_f32_e32 v182, 1.0, v128
	v_cmp_lt_f32_e64 s[20:21], 0, v132
	v_log_f32_e32 v167, v148
	v_pk_mul_f32 v[148:149], v[120:121], v[168:169] op_sel_hi:[1,0]
	v_cmp_lt_f32_e64 s[18:19], 0, v128
	v_mul_f32_e64 v168, |v148|, s57
	v_exp_f32_e32 v168, v168
	v_mul_f32_e32 v177, 0x3f317217, v167
	v_fma_f32 v177, v167, s52, -v177
	v_fmac_f32_e32 v177, 0x3377d1cf, v167
	v_fmac_f32_e32 v177, 0x3f317217, v167
	v_add_f32_e32 v168, 1.0, v168
	v_min_f32_e32 v148, 0, v148
	v_sub_f32_e32 v144, v144, v177
	v_log_f32_e32 v168, v168
	v_mul_f32_e32 v177, 0x3fb8aa3b, v144
	v_exp_f32_e32 v177, v177
	v_sub_f32_e32 v181, 1.0, v133
	v_mul_f32_e32 v167, 0x3f317217, v168
	v_fma_f32 v167, v168, s52, -v167
	v_fmac_f32_e32 v167, 0x3377d1cf, v168
	v_fmac_f32_e32 v167, 0x3f317217, v168
	v_sub_f32_e32 v180, 1.0, v129
	v_cmp_lt_f32_e64 s[16:17], 0, v133
	v_mov_b32_e32 v167, v167
	v_fma_f32 v168, v183, v177, v132
	v_cmp_gt_f32_e64 s[8:9], s97, v168
	v_cmp_lt_f32_e64 s[14:15], 0, v129
	v_sub_f32_e32 v179, 1.0, v134
	v_cndmask_b32_e64 v177, 0, 32, s[8:9]
	v_ldexp_f32 v168, v168, v177
	v_log_f32_e32 v168, v168
	v_sub_f32_e32 v148, v148, v167
	v_mul_f32_e32 v177, 0x3fb8aa3b, v148
	v_exp_f32_e32 v177, v177
	v_mul_f32_e32 v167, 0x3f317217, v168
	v_fma_f32 v167, v168, s52, -v167
	v_fmac_f32_e32 v167, 0x3377d1cf, v168
	v_fmac_f32_e32 v167, 0x3f317217, v168
	v_fma_f32 v177, v182, v177, v128
	v_cmp_lt_f32_e64 s[12:13], 0, v134
	v_cmp_gt_f32_e32 vcc, s97, v177
	v_cndmask_b32_e64 v168, 0, v216, s[8:9]
	v_sub_f32_e32 v167, v167, v168
	v_cndmask_b32_e64 v178, 0, 32, vcc
	v_ldexp_f32 v177, v177, v178
	v_log_f32_e32 v177, v177
	v_mul_f32_e64 v168, |v145|, s57
	v_exp_f32_e32 v168, v168
	v_cndmask_b32_e64 v144, v144, v167, s[20:21]
	v_mul_f32_e32 v167, 0x3f317217, v177
	v_fma_f32 v167, v177, s52, -v167
	v_fmac_f32_e32 v167, 0x3377d1cf, v177
	v_fmac_f32_e32 v167, 0x3f317217, v177
	v_add_f32_e32 v168, 1.0, v168
	v_min_f32_e32 v145, 0, v145
	v_cndmask_b32_e32 v177, 0, v216, vcc
	v_sub_f32_e32 v167, v167, v177
	v_cndmask_b32_e64 v148, v148, v167, s[18:19]
	v_log_f32_e32 v168, v168
	v_mul_f32_e64 v177, |v149|, s57
	v_exp_f32_e32 v177, v177
	v_min_f32_e32 v149, 0, v149
	v_mul_f32_e32 v167, 0x3f317217, v168
	v_fma_f32 v167, v168, s52, -v167
	v_fmac_f32_e32 v167, 0x3377d1cf, v168
	v_fmac_f32_e32 v167, 0x3f317217, v168
	v_add_f32_e32 v177, 1.0, v177
	v_cmp_lt_f32_e64 s[10:11], 0, v130
	v_mov_b32_e32 v167, v167
	v_sub_f32_e32 v145, v145, v167
	v_log_f32_e32 v177, v177
	v_mul_f32_e32 v168, 0x3fb8aa3b, v145
	v_exp_f32_e32 v168, v168
	s_mov_b32 s2, s40
	v_mul_f32_e32 v167, 0x3f317217, v177
	v_fma_f32 v167, v177, s52, -v167
	v_fmac_f32_e32 v167, 0x3377d1cf, v177
	v_fmac_f32_e32 v167, 0x3f317217, v177
	v_fma_f32 v168, v181, v168, v133
	s_nop 0
	v_mov_b32_e32 v167, v167
	v_cmp_gt_f32_e64 s[8:9], s97, v168
	s_nop 1
	v_cndmask_b32_e64 v177, 0, 32, s[8:9]
	v_ldexp_f32 v168, v168, v177
	v_log_f32_e32 v168, v168
	v_sub_f32_e32 v149, v149, v167
	v_mul_f32_e32 v177, 0x3fb8aa3b, v149
	v_exp_f32_e32 v177, v177
	v_mul_f32_e32 v167, 0x3f317217, v168
	v_fma_f32 v167, v168, s52, -v167
	v_fmac_f32_e32 v167, 0x3377d1cf, v168
	v_fmac_f32_e32 v167, 0x3f317217, v168
	v_fma_f32 v177, v180, v177, v129
	s_nop 0
	v_cmp_gt_f32_e32 vcc, s97, v177
	v_cndmask_b32_e64 v168, 0, v216, s[8:9]
	v_sub_f32_e32 v167, v167, v168
	v_cndmask_b32_e64 v178, 0, 32, vcc
	v_ldexp_f32 v177, v177, v178
	v_log_f32_e32 v177, v177
	v_mul_f32_e64 v168, |v150|, s57
	v_exp_f32_e32 v168, v168
	v_cndmask_b32_e64 v145, v145, v167, s[16:17]
	v_mul_f32_e32 v167, 0x3f317217, v177
	v_fma_f32 v167, v177, s52, -v167
	v_fmac_f32_e32 v167, 0x3377d1cf, v177
	v_fmac_f32_e32 v167, 0x3f317217, v177
	v_add_f32_e32 v168, 1.0, v168
	v_min_f32_e32 v150, 0, v150
	v_cndmask_b32_e32 v177, 0, v216, vcc
	v_sub_f32_e32 v167, v167, v177
	v_cndmask_b32_e64 v149, v149, v167, s[14:15]
	v_log_f32_e32 v168, v168
	v_mul_f32_e64 v177, |v146|, s57
	v_exp_f32_e32 v177, v177
	v_min_f32_e32 v146, 0, v146
	v_mul_f32_e32 v167, 0x3f317217, v168
	v_fma_f32 v167, v168, s52, -v167
	v_fmac_f32_e32 v167, 0x3377d1cf, v168
	v_fmac_f32_e32 v167, 0x3f317217, v168
	v_add_f32_e32 v177, 1.0, v177
	s_nop 0
	v_mov_b32_e32 v167, v167
	v_sub_f32_e32 v150, v150, v167
	v_log_f32_e32 v177, v177
	v_mul_f32_e32 v168, 0x3fb8aa3b, v150
	v_exp_f32_e32 v168, v168
	v_sub_f32_e32 v178, 1.0, v130
	v_mul_f32_e32 v167, 0x3f317217, v177
	v_fma_f32 v167, v177, s52, -v167
	v_fmac_f32_e32 v167, 0x3377d1cf, v177
	v_fmac_f32_e32 v167, 0x3f317217, v177
	v_fma_f32 v168, v179, v168, v134
	s_nop 0
	v_mov_b32_e32 v167, v167
	v_cmp_gt_f32_e64 s[8:9], s97, v168
	s_nop 1
	v_cndmask_b32_e64 v177, 0, 32, s[8:9]
	v_ldexp_f32 v168, v168, v177
	v_log_f32_e32 v168, v168
	v_sub_f32_e32 v167, v146, v167
	v_mul_f32_e32 v177, 0x3fb8aa3b, v167
	v_exp_f32_e32 v177, v177
	v_mul_f32_e32 v146, 0x3f317217, v168
	v_fma_f32 v146, v168, s52, -v146
	v_fmac_f32_e32 v146, 0x3377d1cf, v168
	v_fmac_f32_e32 v146, 0x3f317217, v168
	v_fma_f32 v177, v178, v177, v130
	s_nop 0
	v_cmp_gt_f32_e32 vcc, s97, v177
	v_cndmask_b32_e64 v168, 0, v216, s[8:9]
	v_sub_f32_e32 v146, v146, v168
	v_cndmask_b32_e64 v194, 0, 32, vcc
	v_ldexp_f32 v177, v177, v194
	v_log_f32_e32 v177, v177
	v_mul_f32_e64 v168, |v151|, s57
	v_exp_f32_e32 v168, v168
	v_cndmask_b32_e64 v146, v150, v146, s[12:13]
	v_mul_f32_e32 v150, 0x3f317217, v177
	v_fma_f32 v150, v177, s52, -v150
	v_fmac_f32_e32 v150, 0x3377d1cf, v177
	v_fmac_f32_e32 v150, 0x3f317217, v177
	v_add_f32_e32 v168, 1.0, v168
	v_min_f32_e32 v151, 0, v151
	v_cndmask_b32_e32 v177, 0, v216, vcc
	v_sub_f32_e32 v150, v150, v177
	v_cndmask_b32_e64 v150, v167, v150, s[10:11]
; __device__ __forceinline__ float silu_f(float x) { return x * __builtin_amdgcn_rcpf(1.f + __expf(-x)); }
; __device__ __forceinline__ v4u pack8(const f32x4 a, const f32x4 b) { v4u w; w.x = cvt_pk_bf16(a[0], a[1]); w.y = cvt_pk_bf16(a[2], a[3]); w.z = cvt_pk_bf16(b[0], b[1]); w.w = cvt_pk_bf16(b[2], b[3]); return w; }
;     __device__ __forceinline__ void operator()(const f32x4 (&acc)[2][2][4][2], const pg8::Unit& u, int wr, int wc, int fr, int fq) const {
;     ...
;         if (grp == 0) { WIN_LOOP( _Pragma("unroll") for (int i = 0; i < 4; ++i) { a[i] = silu_f(a[i]); b[i] = silu_f(b[i]); } *(v4u*)(QO + (size_t)row * DM + c) = pack8(a, b); ) }
;         else if (grp == 3) { WIN_LOOP( _Pragma("unroll") for (int i = 0; i < 4; ++i) { a[i] = silu_f(a[i]); b[i] = silu_f(b[i]); } *(v4u*)(GH + (size_t)row * 512 + c) = pack8(a, b); ) }
;         else if (grp == 1) {
;             f32x4 l0[2], l1[2];
; #pragma unroll
;             for (int bj = 0; bj < 2; ++bj) { l0[bj] = *(const f32x4*)(lb + cb + bj * 128); l1[bj] = *(const f32x4*)(lb + cb + bj * 128 + 4); }
;             WIN_LOOP( _Pragma("unroll") for (int i = 0; i < 4; ++i) { const float s0 = fminf(a[i], 0.f) - __logf(1.f + __expf(-fabsf(a[i]))), s1 = fminf(b[i], 0.f) - __logf(1.f + __expf(-fabsf(b[i]))); const float la = l0[bj][i], lbv = l1[bj][i];
;                     a[i] = la > 0.f ? __logf(la + (1.f - la) * __expf(s0)) : s0; b[i] = lbv > 0.f ? __logf(lbv + (1.f - lbv) * __expf(s1)) : s1; }
;                 *(f32x4*)(LF + (size_t)row * 512 + c) = a; *(f32x4*)(LF + (size_t)row * 512 + c + 4) = b; __builtin_amdgcn_sched_barrier(0); ) }
	v_log_f32_e32 v168, v168
	v_mul_f32_e64 v177, |v147|, s57
	v_exp_f32_e32 v177, v177
	v_min_f32_e32 v147, 0, v147
	v_mul_f32_e32 v167, 0x3f317217, v168
	v_fma_f32 v167, v168, s52, -v167
	v_fmac_f32_e32 v167, 0x3377d1cf, v168
	v_fmac_f32_e32 v167, 0x3f317217, v168
	v_add_f32_e32 v177, 1.0, v177
	s_nop 0
	v_mov_b32_e32 v167, v167
	v_sub_f32_e32 v151, v151, v167
	v_log_f32_e32 v177, v177
	v_mul_f32_e32 v168, 0x3fb8aa3b, v151
	v_exp_f32_e32 v168, v168
	v_mul_f32_e32 v167, 0x3f317217, v177
	v_fma_f32 v167, v177, s52, -v167
	v_fmac_f32_e32 v167, 0x3377d1cf, v177
	v_fmac_f32_e32 v167, 0x3f317217, v177
	v_mov_b32_e32 v167, v167
	v_sub_f32_e32 v177, 1.0, v135
	v_fma_f32 v168, v177, v168, v135
	v_cmp_gt_f32_e64 s[8:9], s97, v168
	s_nop 1
	v_cndmask_b32_e64 v194, 0, 32, s[8:9]
	v_ldexp_f32 v168, v168, v194
	v_log_f32_e32 v168, v168
	v_sub_f32_e32 v194, v147, v167
	v_mul_f32_e32 v167, 0x3fb8aa3b, v194
	v_exp_f32_e32 v195, v167
	v_mul_f32_e32 v147, 0x3f317217, v168
	v_fma_f32 v147, v168, s52, -v147
	v_fmac_f32_e32 v147, 0x3377d1cf, v168
	v_sub_f32_e32 v167, 1.0, v131
	v_fmac_f32_e32 v147, 0x3f317217, v168
	v_fma_f32 v195, v167, v195, v131
	s_nop 0
	v_cmp_gt_f32_e32 vcc, s97, v195
	v_cndmask_b32_e64 v168, 0, v216, s[8:9]
	v_sub_f32_e32 v147, v147, v168
	v_cndmask_b32_e64 v204, 0, 32, vcc
	v_ldexp_f32 v195, v195, v204
	v_log_f32_e32 v195, v195
	v_cmp_lt_f32_e64 s[8:9], 0, v135
	v_cndmask_b32_e32 v168, 0, v216, vcc
	v_cmp_lt_f32_e32 vcc, 0, v131
	v_cndmask_b32_e64 v147, v151, v147, s[8:9]
	v_mul_f32_e32 v151, 0x3f317217, v195
	v_fma_f32 v151, v195, s52, -v151
	v_fmac_f32_e32 v151, 0x3377d1cf, v195
	v_fmac_f32_e32 v151, 0x3f317217, v195
	v_sub_f32_e32 v151, v151, v168
	v_cndmask_b32_e32 v151, v194, v151, vcc
	global_store_dwordx4 v[170:171], v[144:147], off offset:512
	global_store_dwordx4 v[170:171], v[148:151], off offset:528
	s_nop 1
	v_or_b32_e32 v148, 16, v166
	v_ashrrev_i32_e32 v149, 31, v148
	v_lshlrev_b64 v[144:145], 6, v[148:149]
	v_lshl_add_u64 v[144:145], v[160:161], 0, v[144:145]
	s_nop 0
	s_waitcnt lgkmcnt(0)
	s_nop 3
	s_nop 0
	s_nop 1
	s_waitcnt lgkmcnt(0)
	s_nop 1
	s_waitcnt lgkmcnt(0)
	s_nop 1
	v_mov_b32_e32 v168, v251
	v_lshlrev_b64 v[144:145], 11, v[148:149]
	v_lshl_add_u64 v[170:171], s[50:51], 0, v[144:145]
	v_lshl_add_u64 v[170:171], v[170:171], 0, v[192:193]
	v_pk_mul_f32 v[148:149], v[52:53], v[168:169] op_sel_hi:[1,0]
	v_pk_mul_f32 v[144:145], v[48:49], v[168:169] op_sel_hi:[1,0]
	v_min_f32_e32 v194, 0, v148
	v_mul_f32_e64 v148, |v148|, s57
	v_exp_f32_e32 v148, v148
	v_pk_mul_f32 v[150:151], v[54:55], v[168:169] op_sel_hi:[1,0]
	v_pk_mul_f32 v[146:147], v[50:51], v[168:169] op_sel_hi:[1,0]
	v_add_f32_e32 v148, 1.0, v148
	v_log_f32_e32 v148, v148
	s_nop 0
	v_mul_f32_e32 v195, 0x3f317217, v148
	v_fma_f32 v195, v148, s52, -v195
	v_fmac_f32_e32 v195, 0x3377d1cf, v148
	v_fmac_f32_e32 v195, 0x3f317217, v148
	v_sub_f32_e32 v148, v194, v195
	v_min_f32_e32 v194, 0, v144
	v_mul_f32_e64 v144, |v144|, s57
	v_exp_f32_e32 v144, v144
	s_nop 0
	v_add_f32_e32 v144, 1.0, v144
	v_log_f32_e32 v144, v144
	s_nop 0
	v_mul_f32_e32 v195, 0x3f317217, v144
	v_fma_f32 v195, v144, s52, -v195
	v_fmac_f32_e32 v195, 0x3377d1cf, v144
	v_fmac_f32_e32 v195, 0x3f317217, v144
	v_sub_f32_e32 v194, v194, v195
	v_mul_f32_e32 v144, 0x3fb8aa3b, v148
	v_exp_f32_e32 v144, v144
	s_nop 0
	v_fma_f32 v144, v190, v144, v140
	v_cmp_gt_f32_e64 s[40:41], s97, v144
	s_nop 1
	v_cndmask_b32_e64 v195, 0, 32, s[40:41]
	v_ldexp_f32 v144, v144, v195
	v_log_f32_e32 v144, v144
	s_nop 0
	v_mul_f32_e32 v195, 0x3f317217, v144
	v_fma_f32 v195, v144, s52, -v195
	v_fmac_f32_e32 v195, 0x3377d1cf, v144
	v_fmac_f32_e32 v195, 0x3f317217, v144
	v_mov_b32_e32 v144, v195
	v_cndmask_b32_e64 v195, 0, v216, s[40:41]
	v_sub_f32_e32 v144, v144, v195
	v_cndmask_b32_e64 v144, v148, v144, s[38:39]
	v_mul_f32_e32 v148, 0x3fb8aa3b, v194
	v_exp_f32_e32 v148, v148
	s_nop 0
	v_fma_f32 v148, v191, v148, v136
	v_cmp_gt_f32_e64 s[40:41], s97, v148
	s_nop 1
	v_cndmask_b32_e64 v195, 0, 32, s[40:41]
	v_ldexp_f32 v148, v148, v195
	v_log_f32_e32 v148, v148
	s_nop 0
	v_mul_f32_e32 v195, 0x3f317217, v148
	v_fma_f32 v195, v148, s52, -v195
	v_fmac_f32_e32 v195, 0x3377d1cf, v148
	v_fmac_f32_e32 v195, 0x3f317217, v148
	v_mov_b32_e32 v148, v195
	v_cndmask_b32_e64 v195, 0, v216, s[40:41]
	v_sub_f32_e32 v148, v148, v195
	v_cndmask_b32_e64 v148, v194, v148, s[36:37]
	v_min_f32_e32 v194, 0, v149
	v_mul_f32_e64 v149, |v149|, s57
	v_exp_f32_e32 v149, v149
	s_nop 0
	v_add_f32_e32 v149, 1.0, v149
	v_log_f32_e32 v149, v149
	s_nop 0
	v_mul_f32_e32 v195, 0x3f317217, v149
	v_fma_f32 v195, v149, s52, -v195
	v_fmac_f32_e32 v195, 0x3377d1cf, v149
	v_fmac_f32_e32 v195, 0x3f317217, v149
	v_sub_f32_e32 v149, v194, v195
	v_min_f32_e32 v194, 0, v145
	v_mul_f32_e64 v145, |v145|, s57
	v_exp_f32_e32 v145, v145
	s_nop 0
	v_add_f32_e32 v145, 1.0, v145
	v_log_f32_e32 v145, v145
	s_nop 0
	v_mul_f32_e32 v195, 0x3f317217, v145
	v_fma_f32 v195, v145, s52, -v195
	v_fmac_f32_e32 v195, 0x3377d1cf, v145
	v_fmac_f32_e32 v195, 0x3f317217, v145
	v_sub_f32_e32 v194, v194, v195
	v_mul_f32_e32 v145, 0x3fb8aa3b, v149
	v_exp_f32_e32 v145, v145
	s_nop 0
	v_fma_f32 v145, v188, v145, v141
	v_cmp_gt_f32_e64 s[40:41], s97, v145
	s_nop 1
	v_cndmask_b32_e64 v195, 0, 32, s[40:41]
	v_ldexp_f32 v145, v145, v195
	v_log_f32_e32 v145, v145
	s_nop 0
	v_mul_f32_e32 v195, 0x3f317217, v145
	v_fma_f32 v195, v145, s52, -v195
	v_fmac_f32_e32 v195, 0x3377d1cf, v145
	v_fmac_f32_e32 v195, 0x3f317217, v145
	v_mov_b32_e32 v145, v195
	v_cndmask_b32_e64 v195, 0, v216, s[40:41]
	v_sub_f32_e32 v145, v145, v195
	v_cndmask_b32_e64 v145, v149, v145, s[34:35]
	v_mul_f32_e32 v149, 0x3fb8aa3b, v194
; __device__ __forceinline__ float silu_f(float x) { return x * __builtin_amdgcn_rcpf(1.f + __expf(-x)); }
; __device__ __forceinline__ v4u pack8(const f32x4 a, const f32x4 b) { v4u w; w.x = cvt_pk_bf16(a[0], a[1]); w.y = cvt_pk_bf16(a[2], a[3]); w.z = cvt_pk_bf16(b[0], b[1]); w.w = cvt_pk_bf16(b[2], b[3]); return w; }
;     __device__ __forceinline__ void operator()(const f32x4 (&acc)[2][2][4][2], const pg8::Unit& u, int wr, int wc, int fr, int fq) const {
;     ...
;         if (grp == 0) { WIN_LOOP( _Pragma("unroll") for (int i = 0; i < 4; ++i) { a[i] = silu_f(a[i]); b[i] = silu_f(b[i]); } *(v4u*)(QO + (size_t)row * DM + c) = pack8(a, b); ) }
;         else if (grp == 3) { WIN_LOOP( _Pragma("unroll") for (int i = 0; i < 4; ++i) { a[i] = silu_f(a[i]); b[i] = silu_f(b[i]); } *(v4u*)(GH + (size_t)row * 512 + c) = pack8(a, b); ) }
;         else if (grp == 1) {
;             f32x4 l0[2], l1[2];
; #pragma unroll
;             for (int bj = 0; bj < 2; ++bj) { l0[bj] = *(const f32x4*)(lb + cb + bj * 128); l1[bj] = *(const f32x4*)(lb + cb + bj * 128 + 4); }
;             WIN_LOOP( _Pragma("unroll") for (int i = 0; i < 4; ++i) { const float s0 = fminf(a[i], 0.f) - __logf(1.f + __expf(-fabsf(a[i]))), s1 = fminf(b[i], 0.f) - __logf(1.f + __expf(-fabsf(b[i]))); const float la = l0[bj][i], lbv = l1[bj][i];
;                     a[i] = la > 0.f ? __logf(la + (1.f - la) * __expf(s0)) : s0; b[i] = lbv > 0.f ? __logf(lbv + (1.f - lbv) * __expf(s1)) : s1; }
;                 *(f32x4*)(LF + (size_t)row * 512 + c) = a; *(f32x4*)(LF + (size_t)row * 512 + c + 4) = b; __builtin_amdgcn_sched_barrier(0); ) }
	v_exp_f32_e32 v149, v149
	s_nop 0
	v_fma_f32 v149, v189, v149, v137
	v_cmp_gt_f32_e64 s[40:41], s97, v149
	s_nop 1
	v_cndmask_b32_e64 v195, 0, 32, s[40:41]
	v_ldexp_f32 v149, v149, v195
	v_log_f32_e32 v149, v149
	s_nop 0
	v_mul_f32_e32 v195, 0x3f317217, v149
	v_fma_f32 v195, v149, s52, -v195
	v_fmac_f32_e32 v195, 0x3377d1cf, v149
	v_fmac_f32_e32 v195, 0x3f317217, v149
	v_mov_b32_e32 v149, v195
	v_cndmask_b32_e64 v195, 0, v216, s[40:41]
	v_sub_f32_e32 v149, v149, v195
	v_cndmask_b32_e64 v149, v194, v149, s[30:31]
	v_min_f32_e32 v194, 0, v150
	v_mul_f32_e64 v150, |v150|, s57
	v_exp_f32_e32 v150, v150
	s_nop 0
	v_add_f32_e32 v150, 1.0, v150
	v_log_f32_e32 v150, v150
	s_nop 0
	v_mul_f32_e32 v195, 0x3f317217, v150
	v_fma_f32 v195, v150, s52, -v195
	v_fmac_f32_e32 v195, 0x3377d1cf, v150
	v_fmac_f32_e32 v195, 0x3f317217, v150
	v_sub_f32_e32 v150, v194, v195
	v_min_f32_e32 v194, 0, v146
	v_mul_f32_e64 v146, |v146|, s57
	v_exp_f32_e32 v146, v146
	s_nop 0
	v_add_f32_e32 v146, 1.0, v146
	v_log_f32_e32 v146, v146
	s_nop 0
	v_mul_f32_e32 v195, 0x3f317217, v146
	v_fma_f32 v195, v146, s52, -v195
	v_fmac_f32_e32 v195, 0x3377d1cf, v146
	v_fmac_f32_e32 v195, 0x3f317217, v146
	v_sub_f32_e32 v194, v194, v195
	v_mul_f32_e32 v146, 0x3fb8aa3b, v150
	v_exp_f32_e32 v146, v146
	s_nop 0
	v_fma_f32 v146, v187, v146, v142
	v_cmp_gt_f32_e64 s[40:41], s97, v146
	s_nop 1
	v_cndmask_b32_e64 v195, 0, 32, s[40:41]
	v_ldexp_f32 v146, v146, v195
	v_log_f32_e32 v146, v146
	s_nop 0
	v_mul_f32_e32 v195, 0x3f317217, v146
	v_fma_f32 v195, v146, s52, -v195
	v_fmac_f32_e32 v195, 0x3377d1cf, v146
	v_fmac_f32_e32 v195, 0x3f317217, v146
	v_mov_b32_e32 v146, v195
	v_cndmask_b32_e64 v195, 0, v216, s[40:41]
	v_sub_f32_e32 v146, v146, v195
	v_cndmask_b32_e64 v146, v150, v146, s[28:29]
	v_mul_f32_e32 v150, 0x3fb8aa3b, v194
	v_exp_f32_e32 v150, v150
	s_nop 0
	v_fma_f32 v150, v186, v150, v138
	v_cmp_gt_f32_e64 s[40:41], s97, v150
	s_nop 1
	v_cndmask_b32_e64 v195, 0, 32, s[40:41]
	v_ldexp_f32 v150, v150, v195
	v_log_f32_e32 v150, v150
	s_nop 0
	v_mul_f32_e32 v195, 0x3f317217, v150
	v_fma_f32 v195, v150, s52, -v195
	v_fmac_f32_e32 v195, 0x3377d1cf, v150
	v_fmac_f32_e32 v195, 0x3f317217, v150
	v_mov_b32_e32 v150, v195
	v_cndmask_b32_e64 v195, 0, v216, s[40:41]
	v_sub_f32_e32 v150, v150, v195
	v_cndmask_b32_e64 v150, v194, v150, s[26:27]
	v_min_f32_e32 v194, 0, v151
	v_mul_f32_e64 v151, |v151|, s57
	v_exp_f32_e32 v151, v151
	s_nop 0
	v_add_f32_e32 v151, 1.0, v151
	v_log_f32_e32 v151, v151
	s_nop 0
	v_mul_f32_e32 v195, 0x3f317217, v151
	v_fma_f32 v195, v151, s52, -v195
	v_fmac_f32_e32 v195, 0x3377d1cf, v151
	v_fmac_f32_e32 v195, 0x3f317217, v151
	v_sub_f32_e32 v151, v194, v195
	v_min_f32_e32 v194, 0, v147
	v_mul_f32_e64 v147, |v147|, s57
	v_exp_f32_e32 v147, v147
	s_nop 0
	v_add_f32_e32 v147, 1.0, v147
	v_log_f32_e32 v147, v147
	s_nop 0
	v_mul_f32_e32 v195, 0x3f317217, v147
	v_fma_f32 v195, v147, s52, -v195
	v_fmac_f32_e32 v195, 0x3377d1cf, v147
	v_fmac_f32_e32 v195, 0x3f317217, v147
	v_sub_f32_e32 v194, v194, v195
	v_mul_f32_e32 v147, 0x3fb8aa3b, v151
	v_exp_f32_e32 v147, v147
	s_nop 0
	v_fma_f32 v147, v185, v147, v143
	v_cmp_gt_f32_e64 s[40:41], s97, v147
	s_nop 1
	v_cndmask_b32_e64 v195, 0, 32, s[40:41]
	v_ldexp_f32 v147, v147, v195
	v_log_f32_e32 v147, v147
	s_nop 0
	v_mul_f32_e32 v195, 0x3f317217, v147
	v_fma_f32 v195, v147, s52, -v195
	v_fmac_f32_e32 v195, 0x3377d1cf, v147
	v_fmac_f32_e32 v195, 0x3f317217, v147
	v_mov_b32_e32 v147, v195
	v_cndmask_b32_e64 v195, 0, v216, s[40:41]
	v_sub_f32_e32 v147, v147, v195
	v_cndmask_b32_e64 v147, v151, v147, s[24:25]
	v_mul_f32_e32 v151, 0x3fb8aa3b, v194
	v_exp_f32_e32 v151, v151
	s_nop 0
	v_fma_f32 v151, v184, v151, v139
	v_cmp_gt_f32_e64 s[40:41], s97, v151
	s_nop 1
	v_cndmask_b32_e64 v195, 0, 32, s[40:41]
	v_ldexp_f32 v151, v151, v195
	v_log_f32_e32 v151, v151
	s_nop 0
	v_mul_f32_e32 v195, 0x3f317217, v151
	v_fma_f32 v195, v151, s52, -v195
	v_fmac_f32_e32 v195, 0x3377d1cf, v151
	v_fmac_f32_e32 v195, 0x3f317217, v151
	v_mov_b32_e32 v151, v195
	v_cndmask_b32_e64 v195, 0, v216, s[40:41]
	v_sub_f32_e32 v151, v151, v195
	v_cndmask_b32_e64 v151, v194, v151, s[22:23]
	global_store_dwordx4 v[170:171], v[144:147], off
	global_store_dwordx4 v[170:171], v[148:151], off offset:16
	s_nop 1
	v_pk_mul_f32 v[148:149], v[116:117], v[168:169] op_sel_hi:[1,0]
	v_pk_mul_f32 v[150:151], v[118:119], v[168:169] op_sel_hi:[1,0]
	v_pk_mul_f32 v[146:147], v[114:115], v[168:169] op_sel_hi:[1,0]
	v_pk_mul_f32 v[144:145], v[112:113], v[168:169] op_sel_hi:[1,0]
	v_min_f32_e32 v168, 0, v148
	v_mul_f32_e64 v148, |v148|, s57
	v_exp_f32_e32 v148, v148
	s_nop 0
	v_add_f32_e32 v148, 1.0, v148
	v_log_f32_e32 v148, v148
	s_nop 0
	v_mul_f32_e32 v194, 0x3f317217, v148
	v_fma_f32 v194, v148, s52, -v194
	v_fmac_f32_e32 v194, 0x3377d1cf, v148
	v_fmac_f32_e32 v194, 0x3f317217, v148
	v_sub_f32_e32 v148, v168, v194
	v_min_f32_e32 v168, 0, v144
	v_mul_f32_e64 v144, |v144|, s57
	v_exp_f32_e32 v144, v144
	s_nop 0
	v_add_f32_e32 v144, 1.0, v144
	v_log_f32_e32 v144, v144
	s_nop 0
	v_mul_f32_e32 v194, 0x3f317217, v144
	v_fma_f32 v194, v144, s52, -v194
	v_fmac_f32_e32 v194, 0x3377d1cf, v144
	v_fmac_f32_e32 v194, 0x3f317217, v144
	v_sub_f32_e32 v168, v168, v194
	v_mul_f32_e32 v144, 0x3fb8aa3b, v148
	v_exp_f32_e32 v144, v144
	s_nop 0
	v_fma_f32 v144, v183, v144, v132
	v_cmp_gt_f32_e64 s[40:41], s97, v144
	s_nop 1
	v_cndmask_b32_e64 v194, 0, 32, s[40:41]
	v_ldexp_f32 v144, v144, v194
	v_log_f32_e32 v144, v144
	s_nop 0
	v_mul_f32_e32 v194, 0x3f317217, v144
	v_fma_f32 v194, v144, s52, -v194
	v_fmac_f32_e32 v194, 0x3377d1cf, v144
	v_fmac_f32_e32 v194, 0x3f317217, v144
	v_mov_b32_e32 v144, v194
; __device__ __forceinline__ float silu_f(float x) { return x * __builtin_amdgcn_rcpf(1.f + __expf(-x)); }
; __device__ __forceinline__ v4u pack8(const f32x4 a, const f32x4 b) { v4u w; w.x = cvt_pk_bf16(a[0], a[1]); w.y = cvt_pk_bf16(a[2], a[3]); w.z = cvt_pk_bf16(b[0], b[1]); w.w = cvt_pk_bf16(b[2], b[3]); return w; }
;     __device__ __forceinline__ void operator()(const f32x4 (&acc)[2][2][4][2], const pg8::Unit& u, int wr, int wc, int fr, int fq) const {
;     ...
;         if (grp == 0) { WIN_LOOP( _Pragma("unroll") for (int i = 0; i < 4; ++i) { a[i] = silu_f(a[i]); b[i] = silu_f(b[i]); } *(v4u*)(QO + (size_t)row * DM + c) = pack8(a, b); ) }
;         else if (grp == 3) { WIN_LOOP( _Pragma("unroll") for (int i = 0; i < 4; ++i) { a[i] = silu_f(a[i]); b[i] = silu_f(b[i]); } *(v4u*)(GH + (size_t)row * 512 + c) = pack8(a, b); ) }
;         else if (grp == 1) {
;             f32x4 l0[2], l1[2];
; #pragma unroll
;             for (int bj = 0; bj < 2; ++bj) { l0[bj] = *(const f32x4*)(lb + cb + bj * 128); l1[bj] = *(const f32x4*)(lb + cb + bj * 128 + 4); }
;             WIN_LOOP( _Pragma("unroll") for (int i = 0; i < 4; ++i) { const float s0 = fminf(a[i], 0.f) - __logf(1.f + __expf(-fabsf(a[i]))), s1 = fminf(b[i], 0.f) - __logf(1.f + __expf(-fabsf(b[i]))); const float la = l0[bj][i], lbv = l1[bj][i];
;                     a[i] = la > 0.f ? __logf(la + (1.f - la) * __expf(s0)) : s0; b[i] = lbv > 0.f ? __logf(lbv + (1.f - lbv) * __expf(s1)) : s1; }
;                 *(f32x4*)(LF + (size_t)row * 512 + c) = a; *(f32x4*)(LF + (size_t)row * 512 + c + 4) = b; __builtin_amdgcn_sched_barrier(0); ) }
	v_cndmask_b32_e64 v194, 0, v216, s[40:41]
	v_sub_f32_e32 v144, v144, v194
	v_cndmask_b32_e64 v144, v148, v144, s[20:21]
	v_mul_f32_e32 v148, 0x3fb8aa3b, v168
	v_exp_f32_e32 v148, v148
	s_nop 0
	v_fma_f32 v148, v182, v148, v128
	v_cmp_gt_f32_e64 s[40:41], s97, v148
	s_nop 1
	v_cndmask_b32_e64 v194, 0, 32, s[40:41]
	v_ldexp_f32 v148, v148, v194
	v_log_f32_e32 v148, v148
	s_nop 0
	v_mul_f32_e32 v194, 0x3f317217, v148
	v_fma_f32 v194, v148, s52, -v194
	v_fmac_f32_e32 v194, 0x3377d1cf, v148
	v_fmac_f32_e32 v194, 0x3f317217, v148
	v_mov_b32_e32 v148, v194
	v_cndmask_b32_e64 v194, 0, v216, s[40:41]
	v_sub_f32_e32 v148, v148, v194
	v_cndmask_b32_e64 v148, v168, v148, s[18:19]
	v_min_f32_e32 v168, 0, v149
	v_mul_f32_e64 v149, |v149|, s57
	v_exp_f32_e32 v149, v149
	s_nop 0
	v_add_f32_e32 v149, 1.0, v149
	v_log_f32_e32 v149, v149
	s_nop 0
	v_mul_f32_e32 v194, 0x3f317217, v149
	v_fma_f32 v194, v149, s52, -v194
	v_fmac_f32_e32 v194, 0x3377d1cf, v149
	v_fmac_f32_e32 v194, 0x3f317217, v149
	v_sub_f32_e32 v149, v168, v194
	v_min_f32_e32 v168, 0, v145
	v_mul_f32_e64 v145, |v145|, s57
	v_exp_f32_e32 v145, v145
	s_nop 0
	v_add_f32_e32 v145, 1.0, v145
	v_log_f32_e32 v145, v145
	s_nop 0
	v_mul_f32_e32 v194, 0x3f317217, v145
	v_fma_f32 v194, v145, s52, -v194
	v_fmac_f32_e32 v194, 0x3377d1cf, v145
	v_fmac_f32_e32 v194, 0x3f317217, v145
	v_sub_f32_e32 v168, v168, v194
	v_mul_f32_e32 v145, 0x3fb8aa3b, v149
	v_exp_f32_e32 v145, v145
	s_nop 0
	v_fma_f32 v145, v181, v145, v133
	v_cmp_gt_f32_e64 s[40:41], s97, v145
	s_nop 1
	v_cndmask_b32_e64 v194, 0, 32, s[40:41]
	v_ldexp_f32 v145, v145, v194
	v_log_f32_e32 v145, v145
	s_nop 0
	v_mul_f32_e32 v194, 0x3f317217, v145
	v_fma_f32 v194, v145, s52, -v194
	v_fmac_f32_e32 v194, 0x3377d1cf, v145
	v_fmac_f32_e32 v194, 0x3f317217, v145
	v_mov_b32_e32 v145, v194
	v_cndmask_b32_e64 v194, 0, v216, s[40:41]
	v_sub_f32_e32 v145, v145, v194
	v_cndmask_b32_e64 v145, v149, v145, s[16:17]
	v_mul_f32_e32 v149, 0x3fb8aa3b, v168
	v_exp_f32_e32 v149, v149
	s_nop 0
	v_fma_f32 v149, v180, v149, v129
	v_cmp_gt_f32_e64 s[40:41], s97, v149
	s_nop 1
	v_cndmask_b32_e64 v194, 0, 32, s[40:41]
	v_ldexp_f32 v149, v149, v194
	v_log_f32_e32 v149, v149
	s_nop 0
	v_mul_f32_e32 v194, 0x3f317217, v149
	v_fma_f32 v194, v149, s52, -v194
	v_fmac_f32_e32 v194, 0x3377d1cf, v149
	v_fmac_f32_e32 v194, 0x3f317217, v149
	v_mov_b32_e32 v149, v194
	v_cndmask_b32_e64 v194, 0, v216, s[40:41]
	v_sub_f32_e32 v149, v149, v194
	v_cndmask_b32_e64 v149, v168, v149, s[14:15]
	v_min_f32_e32 v168, 0, v150
	v_mul_f32_e64 v150, |v150|, s57
	v_exp_f32_e32 v150, v150
	s_nop 0
	v_add_f32_e32 v150, 1.0, v150
	v_log_f32_e32 v150, v150
	s_nop 0
	v_mul_f32_e32 v194, 0x3f317217, v150
	v_fma_f32 v194, v150, s52, -v194
	v_fmac_f32_e32 v194, 0x3377d1cf, v150
	v_fmac_f32_e32 v194, 0x3f317217, v150
	v_sub_f32_e32 v150, v168, v194
	v_min_f32_e32 v168, 0, v146
	v_mul_f32_e64 v146, |v146|, s57
	v_exp_f32_e32 v146, v146
	s_nop 0
	v_add_f32_e32 v146, 1.0, v146
	v_log_f32_e32 v146, v146
	s_nop 0
	v_mul_f32_e32 v194, 0x3f317217, v146
	v_fma_f32 v194, v146, s52, -v194
	v_fmac_f32_e32 v194, 0x3377d1cf, v146
	v_fmac_f32_e32 v194, 0x3f317217, v146
	v_sub_f32_e32 v168, v168, v194
	v_mul_f32_e32 v146, 0x3fb8aa3b, v150
	v_exp_f32_e32 v146, v146
	s_nop 0
	v_fma_f32 v146, v179, v146, v134
	v_cmp_gt_f32_e64 s[40:41], s97, v146
	s_nop 1
	v_cndmask_b32_e64 v194, 0, 32, s[40:41]
	v_ldexp_f32 v146, v146, v194
	v_log_f32_e32 v146, v146
	s_nop 0
	v_mul_f32_e32 v194, 0x3f317217, v146
	v_fma_f32 v194, v146, s52, -v194
	v_fmac_f32_e32 v194, 0x3377d1cf, v146
	v_fmac_f32_e32 v194, 0x3f317217, v146
	v_mov_b32_e32 v146, v194
	v_cndmask_b32_e64 v194, 0, v216, s[40:41]
	v_sub_f32_e32 v146, v146, v194
	v_cndmask_b32_e64 v146, v150, v146, s[12:13]
	v_mul_f32_e32 v150, 0x3fb8aa3b, v168
	v_exp_f32_e32 v150, v150
	s_nop 0
	v_fma_f32 v150, v178, v150, v130
	v_cmp_gt_f32_e64 s[40:41], s97, v150
	s_nop 1
	v_cndmask_b32_e64 v194, 0, 32, s[40:41]
	v_ldexp_f32 v150, v150, v194
	v_log_f32_e32 v150, v150
	s_nop 0
	v_mul_f32_e32 v194, 0x3f317217, v150
	v_fma_f32 v194, v150, s52, -v194
	v_fmac_f32_e32 v194, 0x3377d1cf, v150
	v_fmac_f32_e32 v194, 0x3f317217, v150
	v_mov_b32_e32 v150, v194
	v_cndmask_b32_e64 v194, 0, v216, s[40:41]
	v_sub_f32_e32 v150, v150, v194
	v_cndmask_b32_e64 v150, v168, v150, s[10:11]
	v_min_f32_e32 v168, 0, v151
	v_mul_f32_e64 v151, |v151|, s57
	v_exp_f32_e32 v151, v151
	s_nop 0
	v_add_f32_e32 v151, 1.0, v151
	v_log_f32_e32 v151, v151
	s_nop 0
	v_mul_f32_e32 v194, 0x3f317217, v151
	v_fma_f32 v194, v151, s52, -v194
	v_fmac_f32_e32 v194, 0x3377d1cf, v151
	v_fmac_f32_e32 v194, 0x3f317217, v151
	v_sub_f32_e32 v151, v168, v194
	v_min_f32_e32 v168, 0, v147
	v_mul_f32_e64 v147, |v147|, s57
	v_exp_f32_e32 v147, v147
	s_nop 0
	v_add_f32_e32 v147, 1.0, v147
	v_log_f32_e32 v147, v147
	s_nop 0
	v_mul_f32_e32 v194, 0x3f317217, v147
	v_fma_f32 v194, v147, s52, -v194
	v_fmac_f32_e32 v194, 0x3377d1cf, v147
	v_fmac_f32_e32 v194, 0x3f317217, v147
	v_sub_f32_e32 v168, v168, v194
	v_mul_f32_e32 v147, 0x3fb8aa3b, v151
	v_exp_f32_e32 v147, v147
	s_nop 0
	v_fma_f32 v147, v177, v147, v135
	v_cmp_gt_f32_e64 s[40:41], s97, v147
	s_nop 1
	v_cndmask_b32_e64 v194, 0, 32, s[40:41]
	v_ldexp_f32 v147, v147, v194
	v_log_f32_e32 v147, v147
	s_nop 0
	v_mul_f32_e32 v194, 0x3f317217, v147
	v_fma_f32 v194, v147, s52, -v194
	v_fmac_f32_e32 v194, 0x3377d1cf, v147
	v_fmac_f32_e32 v194, 0x3f317217, v147
	v_mov_b32_e32 v147, v194
	v_cndmask_b32_e64 v194, 0, v216, s[40:41]
	v_sub_f32_e32 v147, v147, v194
	v_cndmask_b32_e64 v147, v151, v147, s[8:9]
	v_mul_f32_e32 v151, 0x3fb8aa3b, v168
	v_exp_f32_e32 v151, v151
	s_nop 0
	v_fma_f32 v151, v167, v151, v131
	v_cmp_gt_f32_e64 s[40:41], s97, v151
	s_nop 1
	v_cndmask_b32_e64 v194, 0, 32, s[40:41]
	v_ldexp_f32 v151, v151, v194
	v_log_f32_e32 v151, v151
	s_nop 0
	v_mul_f32_e32 v194, 0x3f317217, v151
	v_fma_f32 v194, v151, s52, -v194
	v_fmac_f32_e32 v194, 0x3377d1cf, v151
	v_fmac_f32_e32 v194, 0x3f317217, v151
	v_mov_b32_e32 v151, v194
	v_cndmask_b32_e64 v194, 0, v216, s[40:41]
	v_sub_f32_e32 v151, v151, v194
	v_cndmask_b32_e32 v151, v168, v151, vcc
	global_store_dwordx4 v[170:171], v[144:147], off offset:512
	global_store_dwordx4 v[170:171], v[148:151], off offset:528
	s_nop 1
	v_or_b32_e32 v148, 32, v166
	v_ashrrev_i32_e32 v149, 31, v148
	v_lshlrev_b64 v[144:145], 6, v[148:149]
	v_lshl_add_u64 v[144:145], v[160:161], 0, v[144:145]
	s_nop 0
	s_waitcnt lgkmcnt(0)
; __device__ __forceinline__ float silu_f(float x) { return x * __builtin_amdgcn_rcpf(1.f + __expf(-x)); }
; __device__ __forceinline__ v4u pack8(const f32x4 a, const f32x4 b) { v4u w; w.x = cvt_pk_bf16(a[0], a[1]); w.y = cvt_pk_bf16(a[2], a[3]); w.z = cvt_pk_bf16(b[0], b[1]); w.w = cvt_pk_bf16(b[2], b[3]); return w; }
;     __device__ __forceinline__ void operator()(const f32x4 (&acc)[2][2][4][2], const pg8::Unit& u, int wr, int wc, int fr, int fq) const {
;     ...
;         if (grp == 0) { WIN_LOOP( _Pragma("unroll") for (int i = 0; i < 4; ++i) { a[i] = silu_f(a[i]); b[i] = silu_f(b[i]); } *(v4u*)(QO + (size_t)row * DM + c) = pack8(a, b); ) }
;         else if (grp == 3) { WIN_LOOP( _Pragma("unroll") for (int i = 0; i < 4; ++i) { a[i] = silu_f(a[i]); b[i] = silu_f(b[i]); } *(v4u*)(GH + (size_t)row * 512 + c) = pack8(a, b); ) }
;         else if (grp == 1) {
;             f32x4 l0[2], l1[2];
; #pragma unroll
;             for (int bj = 0; bj < 2; ++bj) { l0[bj] = *(const f32x4*)(lb + cb + bj * 128); l1[bj] = *(const f32x4*)(lb + cb + bj * 128 + 4); }
;             WIN_LOOP( _Pragma("unroll") for (int i = 0; i < 4; ++i) { const float s0 = fminf(a[i], 0.f) - __logf(1.f + __expf(-fabsf(a[i]))), s1 = fminf(b[i], 0.f) - __logf(1.f + __expf(-fabsf(b[i]))); const float la = l0[bj][i], lbv = l1[bj][i];
;                     a[i] = la > 0.f ? __logf(la + (1.f - la) * __expf(s0)) : s0; b[i] = lbv > 0.f ? __logf(lbv + (1.f - lbv) * __expf(s1)) : s1; }
;                 *(f32x4*)(LF + (size_t)row * 512 + c) = a; *(f32x4*)(LF + (size_t)row * 512 + c + 4) = b; __builtin_amdgcn_sched_barrier(0); ) }
	s_nop 3
	s_nop 0
	s_nop 1
	s_waitcnt lgkmcnt(0)
	s_nop 1
	s_waitcnt lgkmcnt(0)
	s_nop 1
	v_mov_b32_e32 v168, v252
	v_lshlrev_b64 v[144:145], 11, v[148:149]
	v_lshl_add_u64 v[170:171], s[50:51], 0, v[144:145]
	v_lshl_add_u64 v[170:171], v[170:171], 0, v[192:193]
	v_pk_mul_f32 v[148:149], v[44:45], v[168:169] op_sel_hi:[1,0]
	v_pk_mul_f32 v[144:145], v[40:41], v[168:169] op_sel_hi:[1,0]
	v_min_f32_e32 v194, 0, v148
	v_mul_f32_e64 v148, |v148|, s57
	v_exp_f32_e32 v148, v148
	v_pk_mul_f32 v[150:151], v[46:47], v[168:169] op_sel_hi:[1,0]
	v_pk_mul_f32 v[146:147], v[42:43], v[168:169] op_sel_hi:[1,0]
	v_add_f32_e32 v148, 1.0, v148
	v_log_f32_e32 v148, v148
	s_nop 0
	v_mul_f32_e32 v195, 0x3f317217, v148
	v_fma_f32 v195, v148, s52, -v195
	v_fmac_f32_e32 v195, 0x3377d1cf, v148
	v_fmac_f32_e32 v195, 0x3f317217, v148
	v_sub_f32_e32 v148, v194, v195
	v_min_f32_e32 v194, 0, v144
	v_mul_f32_e64 v144, |v144|, s57
	v_exp_f32_e32 v144, v144
	s_nop 0
	v_add_f32_e32 v144, 1.0, v144
	v_log_f32_e32 v144, v144
	s_nop 0
	v_mul_f32_e32 v195, 0x3f317217, v144
	v_fma_f32 v195, v144, s52, -v195
	v_fmac_f32_e32 v195, 0x3377d1cf, v144
	v_fmac_f32_e32 v195, 0x3f317217, v144
	v_sub_f32_e32 v194, v194, v195
	v_mul_f32_e32 v144, 0x3fb8aa3b, v148
	v_exp_f32_e32 v144, v144
	s_nop 0
	v_fma_f32 v144, v190, v144, v140
	v_cmp_gt_f32_e64 s[40:41], s97, v144
	s_nop 1
	v_cndmask_b32_e64 v195, 0, 32, s[40:41]
	v_ldexp_f32 v144, v144, v195
	v_log_f32_e32 v144, v144
	s_nop 0
	v_mul_f32_e32 v195, 0x3f317217, v144
	v_fma_f32 v195, v144, s52, -v195
	v_fmac_f32_e32 v195, 0x3377d1cf, v144
	v_fmac_f32_e32 v195, 0x3f317217, v144
	v_mov_b32_e32 v144, v195
	v_cndmask_b32_e64 v195, 0, v216, s[40:41]
	v_sub_f32_e32 v144, v144, v195
	v_cndmask_b32_e64 v144, v148, v144, s[38:39]
	v_mul_f32_e32 v148, 0x3fb8aa3b, v194
	v_exp_f32_e32 v148, v148
	s_nop 0
	v_fma_f32 v148, v191, v148, v136
	v_cmp_gt_f32_e64 s[40:41], s97, v148
	s_nop 1
	v_cndmask_b32_e64 v195, 0, 32, s[40:41]
	v_ldexp_f32 v148, v148, v195
	v_log_f32_e32 v148, v148
	s_nop 0
	v_mul_f32_e32 v195, 0x3f317217, v148
	v_fma_f32 v195, v148, s52, -v195
	v_fmac_f32_e32 v195, 0x3377d1cf, v148
	v_fmac_f32_e32 v195, 0x3f317217, v148
	v_mov_b32_e32 v148, v195
	v_cndmask_b32_e64 v195, 0, v216, s[40:41]
	v_sub_f32_e32 v148, v148, v195
	v_cndmask_b32_e64 v148, v194, v148, s[36:37]
	v_min_f32_e32 v194, 0, v149
	v_mul_f32_e64 v149, |v149|, s57
	v_exp_f32_e32 v149, v149
	s_nop 0
	v_add_f32_e32 v149, 1.0, v149
	v_log_f32_e32 v149, v149
	s_nop 0
	v_mul_f32_e32 v195, 0x3f317217, v149
	v_fma_f32 v195, v149, s52, -v195
	v_fmac_f32_e32 v195, 0x3377d1cf, v149
	v_fmac_f32_e32 v195, 0x3f317217, v149
	v_sub_f32_e32 v149, v194, v195
	v_min_f32_e32 v194, 0, v145
	v_mul_f32_e64 v145, |v145|, s57
	v_exp_f32_e32 v145, v145
	s_nop 0
	v_add_f32_e32 v145, 1.0, v145
	v_log_f32_e32 v145, v145
	s_nop 0
	v_mul_f32_e32 v195, 0x3f317217, v145
	v_fma_f32 v195, v145, s52, -v195
	v_fmac_f32_e32 v195, 0x3377d1cf, v145
	v_fmac_f32_e32 v195, 0x3f317217, v145
	v_sub_f32_e32 v194, v194, v195
	v_mul_f32_e32 v145, 0x3fb8aa3b, v149
	v_exp_f32_e32 v145, v145
	s_nop 0
	v_fma_f32 v145, v188, v145, v141
	v_cmp_gt_f32_e64 s[40:41], s97, v145
	s_nop 1
	v_cndmask_b32_e64 v195, 0, 32, s[40:41]
	v_ldexp_f32 v145, v145, v195
	v_log_f32_e32 v145, v145
	s_nop 0
	v_mul_f32_e32 v195, 0x3f317217, v145
	v_fma_f32 v195, v145, s52, -v195
	v_fmac_f32_e32 v195, 0x3377d1cf, v145
	v_fmac_f32_e32 v195, 0x3f317217, v145
	v_mov_b32_e32 v145, v195
	v_cndmask_b32_e64 v195, 0, v216, s[40:41]
	v_sub_f32_e32 v145, v145, v195
	v_cndmask_b32_e64 v145, v149, v145, s[34:35]
	v_mul_f32_e32 v149, 0x3fb8aa3b, v194
	v_exp_f32_e32 v149, v149
	s_nop 0
	v_fma_f32 v149, v189, v149, v137
	v_cmp_gt_f32_e64 s[40:41], s97, v149
	s_nop 1
	v_cndmask_b32_e64 v195, 0, 32, s[40:41]
	v_ldexp_f32 v149, v149, v195
	v_log_f32_e32 v149, v149
	s_nop 0
	v_mul_f32_e32 v195, 0x3f317217, v149
	v_fma_f32 v195, v149, s52, -v195
	v_fmac_f32_e32 v195, 0x3377d1cf, v149
	v_fmac_f32_e32 v195, 0x3f317217, v149
	v_mov_b32_e32 v149, v195
	v_cndmask_b32_e64 v195, 0, v216, s[40:41]
	v_sub_f32_e32 v149, v149, v195
	v_cndmask_b32_e64 v149, v194, v149, s[30:31]
	v_min_f32_e32 v194, 0, v150
	v_mul_f32_e64 v150, |v150|, s57
	v_exp_f32_e32 v150, v150
	s_nop 0
	v_add_f32_e32 v150, 1.0, v150
	v_log_f32_e32 v150, v150
	s_nop 0
	v_mul_f32_e32 v195, 0x3f317217, v150
	v_fma_f32 v195, v150, s52, -v195
	v_fmac_f32_e32 v195, 0x3377d1cf, v150
	v_fmac_f32_e32 v195, 0x3f317217, v150
	v_sub_f32_e32 v150, v194, v195
	v_min_f32_e32 v194, 0, v146
	v_mul_f32_e64 v146, |v146|, s57
	v_exp_f32_e32 v146, v146
	s_nop 0
	v_add_f32_e32 v146, 1.0, v146
	v_log_f32_e32 v146, v146
	s_nop 0
	v_mul_f32_e32 v195, 0x3f317217, v146
	v_fma_f32 v195, v146, s52, -v195
	v_fmac_f32_e32 v195, 0x3377d1cf, v146
	v_fmac_f32_e32 v195, 0x3f317217, v146
	v_sub_f32_e32 v194, v194, v195
	v_mul_f32_e32 v146, 0x3fb8aa3b, v150
	v_exp_f32_e32 v146, v146
	s_nop 0
	v_fma_f32 v146, v187, v146, v142
	v_cmp_gt_f32_e64 s[40:41], s97, v146
	s_nop 1
	v_cndmask_b32_e64 v195, 0, 32, s[40:41]
	v_ldexp_f32 v146, v146, v195
	v_log_f32_e32 v146, v146
	s_nop 0
	v_mul_f32_e32 v195, 0x3f317217, v146
	v_fma_f32 v195, v146, s52, -v195
	v_fmac_f32_e32 v195, 0x3377d1cf, v146
	v_fmac_f32_e32 v195, 0x3f317217, v146
	v_mov_b32_e32 v146, v195
	v_cndmask_b32_e64 v195, 0, v216, s[40:41]
	v_sub_f32_e32 v146, v146, v195
	v_cndmask_b32_e64 v146, v150, v146, s[28:29]
	v_mul_f32_e32 v150, 0x3fb8aa3b, v194
	v_exp_f32_e32 v150, v150
	s_nop 0
	v_fma_f32 v150, v186, v150, v138
	v_cmp_gt_f32_e64 s[40:41], s97, v150
	s_nop 1
	v_cndmask_b32_e64 v195, 0, 32, s[40:41]
	v_ldexp_f32 v150, v150, v195
	v_log_f32_e32 v150, v150
	s_nop 0
; __device__ __forceinline__ float silu_f(float x) { return x * __builtin_amdgcn_rcpf(1.f + __expf(-x)); }
; __device__ __forceinline__ v4u pack8(const f32x4 a, const f32x4 b) { v4u w; w.x = cvt_pk_bf16(a[0], a[1]); w.y = cvt_pk_bf16(a[2], a[3]); w.z = cvt_pk_bf16(b[0], b[1]); w.w = cvt_pk_bf16(b[2], b[3]); return w; }
;     __device__ __forceinline__ void operator()(const f32x4 (&acc)[2][2][4][2], const pg8::Unit& u, int wr, int wc, int fr, int fq) const {
;     ...
;         if (grp == 0) { WIN_LOOP( _Pragma("unroll") for (int i = 0; i < 4; ++i) { a[i] = silu_f(a[i]); b[i] = silu_f(b[i]); } *(v4u*)(QO + (size_t)row * DM + c) = pack8(a, b); ) }
;         else if (grp == 3) { WIN_LOOP( _Pragma("unroll") for (int i = 0; i < 4; ++i) { a[i] = silu_f(a[i]); b[i] = silu_f(b[i]); } *(v4u*)(GH + (size_t)row * 512 + c) = pack8(a, b); ) }
;         else if (grp == 1) {
;             f32x4 l0[2], l1[2];
; #pragma unroll
;             for (int bj = 0; bj < 2; ++bj) { l0[bj] = *(const f32x4*)(lb + cb + bj * 128); l1[bj] = *(const f32x4*)(lb + cb + bj * 128 + 4); }
;             WIN_LOOP( _Pragma("unroll") for (int i = 0; i < 4; ++i) { const float s0 = fminf(a[i], 0.f) - __logf(1.f + __expf(-fabsf(a[i]))), s1 = fminf(b[i], 0.f) - __logf(1.f + __expf(-fabsf(b[i]))); const float la = l0[bj][i], lbv = l1[bj][i];
;                     a[i] = la > 0.f ? __logf(la + (1.f - la) * __expf(s0)) : s0; b[i] = lbv > 0.f ? __logf(lbv + (1.f - lbv) * __expf(s1)) : s1; }
;                 *(f32x4*)(LF + (size_t)row * 512 + c) = a; *(f32x4*)(LF + (size_t)row * 512 + c + 4) = b; __builtin_amdgcn_sched_barrier(0); ) }
	v_mul_f32_e32 v195, 0x3f317217, v150
	v_fma_f32 v195, v150, s52, -v195
	v_fmac_f32_e32 v195, 0x3377d1cf, v150
	v_fmac_f32_e32 v195, 0x3f317217, v150
	v_mov_b32_e32 v150, v195
	v_cndmask_b32_e64 v195, 0, v216, s[40:41]
	v_sub_f32_e32 v150, v150, v195
	v_cndmask_b32_e64 v150, v194, v150, s[26:27]
	v_min_f32_e32 v194, 0, v151
	v_mul_f32_e64 v151, |v151|, s57
	v_exp_f32_e32 v151, v151
	s_nop 0
	v_add_f32_e32 v151, 1.0, v151
	v_log_f32_e32 v151, v151
	s_nop 0
	v_mul_f32_e32 v195, 0x3f317217, v151
	v_fma_f32 v195, v151, s52, -v195
	v_fmac_f32_e32 v195, 0x3377d1cf, v151
	v_fmac_f32_e32 v195, 0x3f317217, v151
	v_sub_f32_e32 v151, v194, v195
	v_min_f32_e32 v194, 0, v147
	v_mul_f32_e64 v147, |v147|, s57
	v_exp_f32_e32 v147, v147
	s_nop 0
	v_add_f32_e32 v147, 1.0, v147
	v_log_f32_e32 v147, v147
	s_nop 0
	v_mul_f32_e32 v195, 0x3f317217, v147
	v_fma_f32 v195, v147, s52, -v195
	v_fmac_f32_e32 v195, 0x3377d1cf, v147
	v_fmac_f32_e32 v195, 0x3f317217, v147
	v_sub_f32_e32 v194, v194, v195
	v_mul_f32_e32 v147, 0x3fb8aa3b, v151
	v_exp_f32_e32 v147, v147
	s_nop 0
	v_fma_f32 v147, v185, v147, v143
	v_cmp_gt_f32_e64 s[40:41], s97, v147
	s_nop 1
	v_cndmask_b32_e64 v195, 0, 32, s[40:41]
	v_ldexp_f32 v147, v147, v195
	v_log_f32_e32 v147, v147
	s_nop 0
	v_mul_f32_e32 v195, 0x3f317217, v147
	v_fma_f32 v195, v147, s52, -v195
	v_fmac_f32_e32 v195, 0x3377d1cf, v147
	v_fmac_f32_e32 v195, 0x3f317217, v147
	v_mov_b32_e32 v147, v195
	v_cndmask_b32_e64 v195, 0, v216, s[40:41]
	v_sub_f32_e32 v147, v147, v195
	v_cndmask_b32_e64 v147, v151, v147, s[24:25]
	v_mul_f32_e32 v151, 0x3fb8aa3b, v194
	v_exp_f32_e32 v151, v151
	s_nop 0
	v_fma_f32 v151, v184, v151, v139
	v_cmp_gt_f32_e64 s[40:41], s97, v151
	s_nop 1
	v_cndmask_b32_e64 v195, 0, 32, s[40:41]
	v_ldexp_f32 v151, v151, v195
	v_log_f32_e32 v151, v151
	s_nop 0
	v_mul_f32_e32 v195, 0x3f317217, v151
	v_fma_f32 v195, v151, s52, -v195
	v_fmac_f32_e32 v195, 0x3377d1cf, v151
	v_fmac_f32_e32 v195, 0x3f317217, v151
	v_mov_b32_e32 v151, v195
	v_cndmask_b32_e64 v195, 0, v216, s[40:41]
	v_sub_f32_e32 v151, v151, v195
	v_cndmask_b32_e64 v151, v194, v151, s[22:23]
	global_store_dwordx4 v[170:171], v[144:147], off
	global_store_dwordx4 v[170:171], v[148:151], off offset:16
	s_nop 1
	v_pk_mul_f32 v[148:149], v[108:109], v[168:169] op_sel_hi:[1,0]
	v_pk_mul_f32 v[150:151], v[110:111], v[168:169] op_sel_hi:[1,0]
	v_pk_mul_f32 v[146:147], v[106:107], v[168:169] op_sel_hi:[1,0]
	v_pk_mul_f32 v[144:145], v[104:105], v[168:169] op_sel_hi:[1,0]
	v_min_f32_e32 v168, 0, v148
	v_mul_f32_e64 v148, |v148|, s57
	v_exp_f32_e32 v148, v148
	s_nop 0
	v_add_f32_e32 v148, 1.0, v148
	v_log_f32_e32 v148, v148
	s_nop 0
	v_mul_f32_e32 v194, 0x3f317217, v148
	v_fma_f32 v194, v148, s52, -v194
	v_fmac_f32_e32 v194, 0x3377d1cf, v148
	v_fmac_f32_e32 v194, 0x3f317217, v148
	v_sub_f32_e32 v148, v168, v194
	v_min_f32_e32 v168, 0, v144
	v_mul_f32_e64 v144, |v144|, s57
	v_exp_f32_e32 v144, v144
	s_nop 0
	v_add_f32_e32 v144, 1.0, v144
	v_log_f32_e32 v144, v144
	s_nop 0
	v_mul_f32_e32 v194, 0x3f317217, v144
	v_fma_f32 v194, v144, s52, -v194
	v_fmac_f32_e32 v194, 0x3377d1cf, v144
	v_fmac_f32_e32 v194, 0x3f317217, v144
	v_sub_f32_e32 v168, v168, v194
	v_mul_f32_e32 v144, 0x3fb8aa3b, v148
	v_exp_f32_e32 v144, v144
	s_nop 0
	v_fma_f32 v144, v183, v144, v132
	v_cmp_gt_f32_e64 s[40:41], s97, v144
	s_nop 1
	v_cndmask_b32_e64 v194, 0, 32, s[40:41]
	v_ldexp_f32 v144, v144, v194
	v_log_f32_e32 v144, v144
	s_nop 0
	v_mul_f32_e32 v194, 0x3f317217, v144
	v_fma_f32 v194, v144, s52, -v194
	v_fmac_f32_e32 v194, 0x3377d1cf, v144
	v_fmac_f32_e32 v194, 0x3f317217, v144
	v_mov_b32_e32 v144, v194
	v_cndmask_b32_e64 v194, 0, v216, s[40:41]
	v_sub_f32_e32 v144, v144, v194
	v_cndmask_b32_e64 v144, v148, v144, s[20:21]
	v_mul_f32_e32 v148, 0x3fb8aa3b, v168
	v_exp_f32_e32 v148, v148
	s_nop 0
	v_fma_f32 v148, v182, v148, v128
	v_cmp_gt_f32_e64 s[40:41], s97, v148
	s_nop 1
	v_cndmask_b32_e64 v194, 0, 32, s[40:41]
	v_ldexp_f32 v148, v148, v194
	v_log_f32_e32 v148, v148
	s_nop 0
	v_mul_f32_e32 v194, 0x3f317217, v148
	v_fma_f32 v194, v148, s52, -v194
	v_fmac_f32_e32 v194, 0x3377d1cf, v148
	v_fmac_f32_e32 v194, 0x3f317217, v148
	v_mov_b32_e32 v148, v194
	v_cndmask_b32_e64 v194, 0, v216, s[40:41]
	v_sub_f32_e32 v148, v148, v194
	v_cndmask_b32_e64 v148, v168, v148, s[18:19]
	v_min_f32_e32 v168, 0, v149
	v_mul_f32_e64 v149, |v149|, s57
	v_exp_f32_e32 v149, v149
	s_nop 0
	v_add_f32_e32 v149, 1.0, v149
	v_log_f32_e32 v149, v149
	s_nop 0
	v_mul_f32_e32 v194, 0x3f317217, v149
	v_fma_f32 v194, v149, s52, -v194
	v_fmac_f32_e32 v194, 0x3377d1cf, v149
	v_fmac_f32_e32 v194, 0x3f317217, v149
	v_sub_f32_e32 v149, v168, v194
	v_min_f32_e32 v168, 0, v145
	v_mul_f32_e64 v145, |v145|, s57
	v_exp_f32_e32 v145, v145
	s_nop 0
	v_add_f32_e32 v145, 1.0, v145
	v_log_f32_e32 v145, v145
	s_nop 0
	v_mul_f32_e32 v194, 0x3f317217, v145
	v_fma_f32 v194, v145, s52, -v194
	v_fmac_f32_e32 v194, 0x3377d1cf, v145
	v_fmac_f32_e32 v194, 0x3f317217, v145
	v_sub_f32_e32 v168, v168, v194
	v_mul_f32_e32 v145, 0x3fb8aa3b, v149
	v_exp_f32_e32 v145, v145
	s_nop 0
	v_fma_f32 v145, v181, v145, v133
	v_cmp_gt_f32_e64 s[40:41], s97, v145
	s_nop 1
	v_cndmask_b32_e64 v194, 0, 32, s[40:41]
	v_ldexp_f32 v145, v145, v194
	v_log_f32_e32 v145, v145
	s_nop 0
	v_mul_f32_e32 v194, 0x3f317217, v145
	v_fma_f32 v194, v145, s52, -v194
	v_fmac_f32_e32 v194, 0x3377d1cf, v145
	v_fmac_f32_e32 v194, 0x3f317217, v145
	v_mov_b32_e32 v145, v194
	v_cndmask_b32_e64 v194, 0, v216, s[40:41]
	v_sub_f32_e32 v145, v145, v194
	v_cndmask_b32_e64 v145, v149, v145, s[16:17]
	v_mul_f32_e32 v149, 0x3fb8aa3b, v168
	v_exp_f32_e32 v149, v149
	s_nop 0
	v_fma_f32 v149, v180, v149, v129
; __device__ __forceinline__ float silu_f(float x) { return x * __builtin_amdgcn_rcpf(1.f + __expf(-x)); }
; __device__ __forceinline__ v4u pack8(const f32x4 a, const f32x4 b) { v4u w; w.x = cvt_pk_bf16(a[0], a[1]); w.y = cvt_pk_bf16(a[2], a[3]); w.z = cvt_pk_bf16(b[0], b[1]); w.w = cvt_pk_bf16(b[2], b[3]); return w; }
;     __device__ __forceinline__ void operator()(const f32x4 (&acc)[2][2][4][2], const pg8::Unit& u, int wr, int wc, int fr, int fq) const {
;     ...
;         if (grp == 0) { WIN_LOOP( _Pragma("unroll") for (int i = 0; i < 4; ++i) { a[i] = silu_f(a[i]); b[i] = silu_f(b[i]); } *(v4u*)(QO + (size_t)row * DM + c) = pack8(a, b); ) }
;         else if (grp == 3) { WIN_LOOP( _Pragma("unroll") for (int i = 0; i < 4; ++i) { a[i] = silu_f(a[i]); b[i] = silu_f(b[i]); } *(v4u*)(GH + (size_t)row * 512 + c) = pack8(a, b); ) }
;         else if (grp == 1) {
;             f32x4 l0[2], l1[2];
; #pragma unroll
;             for (int bj = 0; bj < 2; ++bj) { l0[bj] = *(const f32x4*)(lb + cb + bj * 128); l1[bj] = *(const f32x4*)(lb + cb + bj * 128 + 4); }
;             WIN_LOOP( _Pragma("unroll") for (int i = 0; i < 4; ++i) { const float s0 = fminf(a[i], 0.f) - __logf(1.f + __expf(-fabsf(a[i]))), s1 = fminf(b[i], 0.f) - __logf(1.f + __expf(-fabsf(b[i]))); const float la = l0[bj][i], lbv = l1[bj][i];
;                     a[i] = la > 0.f ? __logf(la + (1.f - la) * __expf(s0)) : s0; b[i] = lbv > 0.f ? __logf(lbv + (1.f - lbv) * __expf(s1)) : s1; }
;                 *(f32x4*)(LF + (size_t)row * 512 + c) = a; *(f32x4*)(LF + (size_t)row * 512 + c + 4) = b; __builtin_amdgcn_sched_barrier(0); ) }
	v_cmp_gt_f32_e64 s[40:41], s97, v149
	s_nop 1
	v_cndmask_b32_e64 v194, 0, 32, s[40:41]
	v_ldexp_f32 v149, v149, v194
	v_log_f32_e32 v149, v149
	s_nop 0
	v_mul_f32_e32 v194, 0x3f317217, v149
	v_fma_f32 v194, v149, s52, -v194
	v_fmac_f32_e32 v194, 0x3377d1cf, v149
	v_fmac_f32_e32 v194, 0x3f317217, v149
	v_mov_b32_e32 v149, v194
	v_cndmask_b32_e64 v194, 0, v216, s[40:41]
	v_sub_f32_e32 v149, v149, v194
	v_cndmask_b32_e64 v149, v168, v149, s[14:15]
	v_min_f32_e32 v168, 0, v150
	v_mul_f32_e64 v150, |v150|, s57
	v_exp_f32_e32 v150, v150
	s_nop 0
	v_add_f32_e32 v150, 1.0, v150
	v_log_f32_e32 v150, v150
	s_nop 0
	v_mul_f32_e32 v194, 0x3f317217, v150
	v_fma_f32 v194, v150, s52, -v194
	v_fmac_f32_e32 v194, 0x3377d1cf, v150
	v_fmac_f32_e32 v194, 0x3f317217, v150
	v_sub_f32_e32 v150, v168, v194
	v_min_f32_e32 v168, 0, v146
	v_mul_f32_e64 v146, |v146|, s57
	v_exp_f32_e32 v146, v146
	s_nop 0
	v_add_f32_e32 v146, 1.0, v146
	v_log_f32_e32 v146, v146
	s_nop 0
	v_mul_f32_e32 v194, 0x3f317217, v146
	v_fma_f32 v194, v146, s52, -v194
	v_fmac_f32_e32 v194, 0x3377d1cf, v146
	v_fmac_f32_e32 v194, 0x3f317217, v146
	v_sub_f32_e32 v168, v168, v194
	v_mul_f32_e32 v146, 0x3fb8aa3b, v150
	v_exp_f32_e32 v146, v146
	s_nop 0
	v_fma_f32 v146, v179, v146, v134
	v_cmp_gt_f32_e64 s[40:41], s97, v146
	s_nop 1
	v_cndmask_b32_e64 v194, 0, 32, s[40:41]
	v_ldexp_f32 v146, v146, v194
	v_log_f32_e32 v146, v146
	s_nop 0
	v_mul_f32_e32 v194, 0x3f317217, v146
	v_fma_f32 v194, v146, s52, -v194
	v_fmac_f32_e32 v194, 0x3377d1cf, v146
	v_fmac_f32_e32 v194, 0x3f317217, v146
	v_mov_b32_e32 v146, v194
	v_cndmask_b32_e64 v194, 0, v216, s[40:41]
	v_sub_f32_e32 v146, v146, v194
	v_cndmask_b32_e64 v146, v150, v146, s[12:13]
	v_mul_f32_e32 v150, 0x3fb8aa3b, v168
	v_exp_f32_e32 v150, v150
	s_nop 0
	v_fma_f32 v150, v178, v150, v130
	v_cmp_gt_f32_e64 s[40:41], s97, v150
	s_nop 1
	v_cndmask_b32_e64 v194, 0, 32, s[40:41]
	v_ldexp_f32 v150, v150, v194
	v_log_f32_e32 v150, v150
	s_nop 0
	v_mul_f32_e32 v194, 0x3f317217, v150
	v_fma_f32 v194, v150, s52, -v194
	v_fmac_f32_e32 v194, 0x3377d1cf, v150
	v_fmac_f32_e32 v194, 0x3f317217, v150
	v_mov_b32_e32 v150, v194
	v_cndmask_b32_e64 v194, 0, v216, s[40:41]
	v_sub_f32_e32 v150, v150, v194
	v_cndmask_b32_e64 v150, v168, v150, s[10:11]
	v_min_f32_e32 v168, 0, v151
	v_mul_f32_e64 v151, |v151|, s57
	v_exp_f32_e32 v151, v151
	s_nop 0
	v_add_f32_e32 v151, 1.0, v151
	v_log_f32_e32 v151, v151
	s_nop 0
	v_mul_f32_e32 v194, 0x3f317217, v151
	v_fma_f32 v194, v151, s52, -v194
	v_fmac_f32_e32 v194, 0x3377d1cf, v151
	v_fmac_f32_e32 v194, 0x3f317217, v151
	v_sub_f32_e32 v151, v168, v194
	v_min_f32_e32 v168, 0, v147
	v_mul_f32_e64 v147, |v147|, s57
	v_exp_f32_e32 v147, v147
	s_nop 0
	v_add_f32_e32 v147, 1.0, v147
	v_log_f32_e32 v147, v147
	s_nop 0
	v_mul_f32_e32 v194, 0x3f317217, v147
	v_fma_f32 v194, v147, s52, -v194
	v_fmac_f32_e32 v194, 0x3377d1cf, v147
	v_fmac_f32_e32 v194, 0x3f317217, v147
	v_sub_f32_e32 v168, v168, v194
	v_mul_f32_e32 v147, 0x3fb8aa3b, v151
	v_exp_f32_e32 v147, v147
	s_nop 0
	v_fma_f32 v147, v177, v147, v135
	v_cmp_gt_f32_e64 s[40:41], s97, v147
	s_nop 1
	v_cndmask_b32_e64 v194, 0, 32, s[40:41]
	v_ldexp_f32 v147, v147, v194
	v_log_f32_e32 v147, v147
	s_nop 0
	v_mul_f32_e32 v194, 0x3f317217, v147
	v_fma_f32 v194, v147, s52, -v194
	v_fmac_f32_e32 v194, 0x3377d1cf, v147
	v_fmac_f32_e32 v194, 0x3f317217, v147
	v_mov_b32_e32 v147, v194
	v_cndmask_b32_e64 v194, 0, v216, s[40:41]
	v_sub_f32_e32 v147, v147, v194
	v_cndmask_b32_e64 v147, v151, v147, s[8:9]
	v_mul_f32_e32 v151, 0x3fb8aa3b, v168
	v_exp_f32_e32 v151, v151
	s_nop 0
	v_fma_f32 v151, v167, v151, v131
	v_cmp_gt_f32_e64 s[40:41], s97, v151
	s_nop 1
	v_cndmask_b32_e64 v194, 0, 32, s[40:41]
	v_ldexp_f32 v151, v151, v194
	v_log_f32_e32 v151, v151
	s_nop 0
	v_mul_f32_e32 v194, 0x3f317217, v151
	v_fma_f32 v194, v151, s52, -v194
	v_fmac_f32_e32 v194, 0x3377d1cf, v151
	v_fmac_f32_e32 v194, 0x3f317217, v151
	v_mov_b32_e32 v151, v194
	v_cndmask_b32_e64 v194, 0, v216, s[40:41]
	v_sub_f32_e32 v151, v151, v194
	v_cndmask_b32_e32 v151, v168, v151, vcc
	global_store_dwordx4 v[170:171], v[144:147], off offset:512
	global_store_dwordx4 v[170:171], v[148:151], off offset:528
	s_nop 1
	v_or_b32_e32 v148, 48, v166
	v_ashrrev_i32_e32 v149, 31, v148
	v_lshlrev_b64 v[144:145], 6, v[148:149]
	v_lshl_add_u64 v[144:145], v[160:161], 0, v[144:145]
	s_nop 0
	s_waitcnt lgkmcnt(0)
	s_nop 3
	s_nop 0
	s_nop 1
	s_waitcnt lgkmcnt(0)
	s_nop 1
	s_waitcnt lgkmcnt(0)
; __device__ __forceinline__ float silu_f(float x) { return x * __builtin_amdgcn_rcpf(1.f + __expf(-x)); }
; __device__ __forceinline__ v4u pack8(const f32x4 a, const f32x4 b) { v4u w; w.x = cvt_pk_bf16(a[0], a[1]); w.y = cvt_pk_bf16(a[2], a[3]); w.z = cvt_pk_bf16(b[0], b[1]); w.w = cvt_pk_bf16(b[2], b[3]); return w; }
;     __device__ __forceinline__ void operator()(const f32x4 (&acc)[2][2][4][2], const pg8::Unit& u, int wr, int wc, int fr, int fq) const {
;     ...
;         if (grp == 0) { WIN_LOOP( _Pragma("unroll") for (int i = 0; i < 4; ++i) { a[i] = silu_f(a[i]); b[i] = silu_f(b[i]); } *(v4u*)(QO + (size_t)row * DM + c) = pack8(a, b); ) }
;         else if (grp == 3) { WIN_LOOP( _Pragma("unroll") for (int i = 0; i < 4; ++i) { a[i] = silu_f(a[i]); b[i] = silu_f(b[i]); } *(v4u*)(GH + (size_t)row * 512 + c) = pack8(a, b); ) }
;         else if (grp == 1) {
;             f32x4 l0[2], l1[2];
; #pragma unroll
;             for (int bj = 0; bj < 2; ++bj) { l0[bj] = *(const f32x4*)(lb + cb + bj * 128); l1[bj] = *(const f32x4*)(lb + cb + bj * 128 + 4); }
;             WIN_LOOP( _Pragma("unroll") for (int i = 0; i < 4; ++i) { const float s0 = fminf(a[i], 0.f) - __logf(1.f + __expf(-fabsf(a[i]))), s1 = fminf(b[i], 0.f) - __logf(1.f + __expf(-fabsf(b[i]))); const float la = l0[bj][i], lbv = l1[bj][i];
;                     a[i] = la > 0.f ? __logf(la + (1.f - la) * __expf(s0)) : s0; b[i] = lbv > 0.f ? __logf(lbv + (1.f - lbv) * __expf(s1)) : s1; }
;                 *(f32x4*)(LF + (size_t)row * 512 + c) = a; *(f32x4*)(LF + (size_t)row * 512 + c + 4) = b; __builtin_amdgcn_sched_barrier(0); ) }
	s_nop 1
	v_mov_b32_e32 v168, v253
	v_lshlrev_b64 v[144:145], 11, v[148:149]
	v_lshl_add_u64 v[170:171], s[50:51], 0, v[144:145]
	v_lshl_add_u64 v[170:171], v[170:171], 0, v[192:193]
	v_pk_mul_f32 v[148:149], v[36:37], v[168:169] op_sel_hi:[1,0]
	v_pk_mul_f32 v[144:145], v[32:33], v[168:169] op_sel_hi:[1,0]
	v_min_f32_e32 v194, 0, v148
	v_mul_f32_e64 v148, |v148|, s57
	v_exp_f32_e32 v148, v148
	v_pk_mul_f32 v[150:151], v[38:39], v[168:169] op_sel_hi:[1,0]
	v_pk_mul_f32 v[146:147], v[34:35], v[168:169] op_sel_hi:[1,0]
	v_add_f32_e32 v148, 1.0, v148
	v_log_f32_e32 v148, v148
	s_nop 0
	v_mul_f32_e32 v195, 0x3f317217, v148
	v_fma_f32 v195, v148, s52, -v195
	v_fmac_f32_e32 v195, 0x3377d1cf, v148
	v_fmac_f32_e32 v195, 0x3f317217, v148
	v_sub_f32_e32 v148, v194, v195
	v_min_f32_e32 v194, 0, v144
	v_mul_f32_e64 v144, |v144|, s57
	v_exp_f32_e32 v144, v144
	s_nop 0
	v_add_f32_e32 v144, 1.0, v144
	v_log_f32_e32 v144, v144
	s_nop 0
	v_mul_f32_e32 v195, 0x3f317217, v144
	v_fma_f32 v195, v144, s52, -v195
	v_fmac_f32_e32 v195, 0x3377d1cf, v144
	v_fmac_f32_e32 v195, 0x3f317217, v144
	v_sub_f32_e32 v194, v194, v195
	v_mul_f32_e32 v144, 0x3fb8aa3b, v148
	v_exp_f32_e32 v144, v144
	s_nop 0
	v_fma_f32 v144, v190, v144, v140
	v_cmp_gt_f32_e64 s[40:41], s97, v144
	s_nop 1
	v_cndmask_b32_e64 v195, 0, 32, s[40:41]
	v_ldexp_f32 v144, v144, v195
	v_log_f32_e32 v144, v144
	s_nop 0
	v_mul_f32_e32 v195, 0x3f317217, v144
	v_fma_f32 v195, v144, s52, -v195
	v_fmac_f32_e32 v195, 0x3377d1cf, v144
	v_fmac_f32_e32 v195, 0x3f317217, v144
	v_mov_b32_e32 v144, v195
	v_cndmask_b32_e64 v195, 0, v216, s[40:41]
	v_sub_f32_e32 v144, v144, v195
	v_cndmask_b32_e64 v144, v148, v144, s[38:39]
	v_mul_f32_e32 v148, 0x3fb8aa3b, v194
	v_exp_f32_e32 v148, v148
	s_nop 0
	v_fma_f32 v148, v191, v148, v136
	v_cmp_gt_f32_e64 s[40:41], s97, v148
	s_nop 1
	v_cndmask_b32_e64 v195, 0, 32, s[40:41]
	v_ldexp_f32 v148, v148, v195
	v_log_f32_e32 v148, v148
	s_nop 0
	v_mul_f32_e32 v195, 0x3f317217, v148
	v_fma_f32 v195, v148, s52, -v195
	v_fmac_f32_e32 v195, 0x3377d1cf, v148
	v_fmac_f32_e32 v195, 0x3f317217, v148
	v_mov_b32_e32 v148, v195
	v_cndmask_b32_e64 v195, 0, v216, s[40:41]
	v_sub_f32_e32 v148, v148, v195
	v_cndmask_b32_e64 v148, v194, v148, s[36:37]
	v_min_f32_e32 v194, 0, v149
	v_mul_f32_e64 v149, |v149|, s57
	v_exp_f32_e32 v149, v149
	s_nop 0
	v_add_f32_e32 v149, 1.0, v149
	v_log_f32_e32 v149, v149
	s_nop 0
	v_mul_f32_e32 v195, 0x3f317217, v149
	v_fma_f32 v195, v149, s52, -v195
	v_fmac_f32_e32 v195, 0x3377d1cf, v149
	v_fmac_f32_e32 v195, 0x3f317217, v149
	v_sub_f32_e32 v149, v194, v195
	v_min_f32_e32 v194, 0, v145
	v_mul_f32_e64 v145, |v145|, s57
	v_exp_f32_e32 v145, v145
	s_nop 0
	v_add_f32_e32 v145, 1.0, v145
	v_log_f32_e32 v145, v145
	s_nop 0
	v_mul_f32_e32 v195, 0x3f317217, v145
	v_fma_f32 v195, v145, s52, -v195
	v_fmac_f32_e32 v195, 0x3377d1cf, v145
	v_fmac_f32_e32 v195, 0x3f317217, v145
	v_sub_f32_e32 v194, v194, v195
	v_mul_f32_e32 v145, 0x3fb8aa3b, v149
	v_exp_f32_e32 v145, v145
	s_nop 0
	v_fma_f32 v145, v188, v145, v141
	v_cmp_gt_f32_e64 s[40:41], s97, v145
	s_nop 1
	v_cndmask_b32_e64 v195, 0, 32, s[40:41]
	v_ldexp_f32 v145, v145, v195
	v_log_f32_e32 v145, v145
	s_nop 0
	v_mul_f32_e32 v195, 0x3f317217, v145
	v_fma_f32 v195, v145, s52, -v195
	v_fmac_f32_e32 v195, 0x3377d1cf, v145
	v_fmac_f32_e32 v195, 0x3f317217, v145
	v_mov_b32_e32 v145, v195
	v_cndmask_b32_e64 v195, 0, v216, s[40:41]
	v_sub_f32_e32 v145, v145, v195
	v_cndmask_b32_e64 v145, v149, v145, s[34:35]
	v_mul_f32_e32 v149, 0x3fb8aa3b, v194
	v_exp_f32_e32 v149, v149
	s_nop 0
	v_fma_f32 v149, v189, v149, v137
	v_cmp_gt_f32_e64 s[40:41], s97, v149
	s_nop 1
	v_cndmask_b32_e64 v195, 0, 32, s[40:41]
	v_ldexp_f32 v149, v149, v195
	v_log_f32_e32 v149, v149
	s_nop 0
	v_mul_f32_e32 v195, 0x3f317217, v149
	v_fma_f32 v195, v149, s52, -v195
	v_fmac_f32_e32 v195, 0x3377d1cf, v149
	v_fmac_f32_e32 v195, 0x3f317217, v149
	v_mov_b32_e32 v149, v195
	v_cndmask_b32_e64 v195, 0, v216, s[40:41]
	v_sub_f32_e32 v149, v149, v195
	v_cndmask_b32_e64 v149, v194, v149, s[30:31]
	v_min_f32_e32 v194, 0, v150
	v_mul_f32_e64 v150, |v150|, s57
	v_exp_f32_e32 v150, v150
	s_nop 0
	v_add_f32_e32 v150, 1.0, v150
	v_log_f32_e32 v150, v150
	s_nop 0
	v_mul_f32_e32 v195, 0x3f317217, v150
	v_fma_f32 v195, v150, s52, -v195
	v_fmac_f32_e32 v195, 0x3377d1cf, v150
	v_fmac_f32_e32 v195, 0x3f317217, v150
	v_sub_f32_e32 v150, v194, v195
	v_min_f32_e32 v194, 0, v146
	v_mul_f32_e64 v146, |v146|, s57
	v_exp_f32_e32 v146, v146
	s_nop 0
	v_add_f32_e32 v146, 1.0, v146
	v_log_f32_e32 v146, v146
	s_nop 0
	v_mul_f32_e32 v195, 0x3f317217, v146
	v_fma_f32 v195, v146, s52, -v195
	v_fmac_f32_e32 v195, 0x3377d1cf, v146
	v_fmac_f32_e32 v195, 0x3f317217, v146
	v_sub_f32_e32 v194, v194, v195
	v_mul_f32_e32 v146, 0x3fb8aa3b, v150
	v_exp_f32_e32 v146, v146
	s_nop 0
	v_fma_f32 v146, v187, v146, v142
	v_cmp_gt_f32_e64 s[40:41], s97, v146
	s_nop 1
	v_cndmask_b32_e64 v195, 0, 32, s[40:41]
	v_ldexp_f32 v146, v146, v195
	v_log_f32_e32 v146, v146
	s_nop 0
	v_mul_f32_e32 v195, 0x3f317217, v146
	v_fma_f32 v195, v146, s52, -v195
	v_fmac_f32_e32 v195, 0x3377d1cf, v146
	v_fmac_f32_e32 v195, 0x3f317217, v146
	v_mov_b32_e32 v146, v195
	v_cndmask_b32_e64 v195, 0, v216, s[40:41]
	v_sub_f32_e32 v146, v146, v195
	v_cndmask_b32_e64 v146, v150, v146, s[28:29]
	v_mul_f32_e32 v150, 0x3fb8aa3b, v194
	v_exp_f32_e32 v150, v150
	s_nop 0
	v_fma_f32 v150, v186, v150, v138
	v_cmp_gt_f32_e64 s[40:41], s97, v150
	s_nop 1
	v_cndmask_b32_e64 v195, 0, 32, s[40:41]
	v_ldexp_f32 v150, v150, v195
	v_log_f32_e32 v150, v150
	s_nop 0
	v_mul_f32_e32 v195, 0x3f317217, v150
	v_fma_f32 v195, v150, s52, -v195
	v_fmac_f32_e32 v195, 0x3377d1cf, v150
; __device__ __forceinline__ float silu_f(float x) { return x * __builtin_amdgcn_rcpf(1.f + __expf(-x)); }
; __device__ __forceinline__ v4u pack8(const f32x4 a, const f32x4 b) { v4u w; w.x = cvt_pk_bf16(a[0], a[1]); w.y = cvt_pk_bf16(a[2], a[3]); w.z = cvt_pk_bf16(b[0], b[1]); w.w = cvt_pk_bf16(b[2], b[3]); return w; }
;     __device__ __forceinline__ void operator()(const f32x4 (&acc)[2][2][4][2], const pg8::Unit& u, int wr, int wc, int fr, int fq) const {
;     ...
;         if (grp == 0) { WIN_LOOP( _Pragma("unroll") for (int i = 0; i < 4; ++i) { a[i] = silu_f(a[i]); b[i] = silu_f(b[i]); } *(v4u*)(QO + (size_t)row * DM + c) = pack8(a, b); ) }
;         else if (grp == 3) { WIN_LOOP( _Pragma("unroll") for (int i = 0; i < 4; ++i) { a[i] = silu_f(a[i]); b[i] = silu_f(b[i]); } *(v4u*)(GH + (size_t)row * 512 + c) = pack8(a, b); ) }
;         else if (grp == 1) {
;             f32x4 l0[2], l1[2];
; #pragma unroll
;             for (int bj = 0; bj < 2; ++bj) { l0[bj] = *(const f32x4*)(lb + cb + bj * 128); l1[bj] = *(const f32x4*)(lb + cb + bj * 128 + 4); }
;             WIN_LOOP( _Pragma("unroll") for (int i = 0; i < 4; ++i) { const float s0 = fminf(a[i], 0.f) - __logf(1.f + __expf(-fabsf(a[i]))), s1 = fminf(b[i], 0.f) - __logf(1.f + __expf(-fabsf(b[i]))); const float la = l0[bj][i], lbv = l1[bj][i];
;                     a[i] = la > 0.f ? __logf(la + (1.f - la) * __expf(s0)) : s0; b[i] = lbv > 0.f ? __logf(lbv + (1.f - lbv) * __expf(s1)) : s1; }
;                 *(f32x4*)(LF + (size_t)row * 512 + c) = a; *(f32x4*)(LF + (size_t)row * 512 + c + 4) = b; __builtin_amdgcn_sched_barrier(0); ) }
	v_fmac_f32_e32 v195, 0x3f317217, v150
	v_mov_b32_e32 v150, v195
	v_cndmask_b32_e64 v195, 0, v216, s[40:41]
	v_sub_f32_e32 v150, v150, v195
	v_cndmask_b32_e64 v150, v194, v150, s[26:27]
	v_min_f32_e32 v194, 0, v151
	v_mul_f32_e64 v151, |v151|, s57
	v_exp_f32_e32 v151, v151
	s_nop 0
	v_add_f32_e32 v151, 1.0, v151
	v_log_f32_e32 v151, v151
	s_nop 0
	v_mul_f32_e32 v195, 0x3f317217, v151
	v_fma_f32 v195, v151, s52, -v195
	v_fmac_f32_e32 v195, 0x3377d1cf, v151
	v_fmac_f32_e32 v195, 0x3f317217, v151
	v_sub_f32_e32 v151, v194, v195
	v_min_f32_e32 v194, 0, v147
	v_mul_f32_e64 v147, |v147|, s57
	v_exp_f32_e32 v147, v147
	s_nop 0
	v_add_f32_e32 v147, 1.0, v147
	v_log_f32_e32 v147, v147
	s_nop 0
	v_mul_f32_e32 v195, 0x3f317217, v147
	v_fma_f32 v195, v147, s52, -v195
	v_fmac_f32_e32 v195, 0x3377d1cf, v147
	v_fmac_f32_e32 v195, 0x3f317217, v147
	v_sub_f32_e32 v194, v194, v195
	v_mul_f32_e32 v147, 0x3fb8aa3b, v151
	v_exp_f32_e32 v147, v147
	s_nop 0
	v_fma_f32 v147, v185, v147, v143
	v_cmp_gt_f32_e64 s[40:41], s97, v147
	s_nop 1
	v_cndmask_b32_e64 v195, 0, 32, s[40:41]
	v_ldexp_f32 v147, v147, v195
	v_log_f32_e32 v147, v147
	s_nop 0
	v_mul_f32_e32 v195, 0x3f317217, v147
	v_fma_f32 v195, v147, s52, -v195
	v_fmac_f32_e32 v195, 0x3377d1cf, v147
	v_fmac_f32_e32 v195, 0x3f317217, v147
	v_mov_b32_e32 v147, v195
	v_cndmask_b32_e64 v195, 0, v216, s[40:41]
	v_sub_f32_e32 v147, v147, v195
	v_cndmask_b32_e64 v147, v151, v147, s[24:25]
	v_mul_f32_e32 v151, 0x3fb8aa3b, v194
	v_exp_f32_e32 v151, v151
	s_nop 0
	v_fma_f32 v151, v184, v151, v139
	v_cmp_gt_f32_e64 s[40:41], s97, v151
	s_nop 1
	v_cndmask_b32_e64 v195, 0, 32, s[40:41]
	v_ldexp_f32 v151, v151, v195
	v_log_f32_e32 v151, v151
	s_nop 0
	v_mul_f32_e32 v195, 0x3f317217, v151
	v_fma_f32 v195, v151, s52, -v195
	v_fmac_f32_e32 v195, 0x3377d1cf, v151
	v_fmac_f32_e32 v195, 0x3f317217, v151
	v_mov_b32_e32 v151, v195
	v_cndmask_b32_e64 v195, 0, v216, s[40:41]
	v_sub_f32_e32 v151, v151, v195
	v_cndmask_b32_e64 v151, v194, v151, s[22:23]
	global_store_dwordx4 v[170:171], v[144:147], off
	global_store_dwordx4 v[170:171], v[148:151], off offset:16
	s_nop 1
	v_pk_mul_f32 v[148:149], v[100:101], v[168:169] op_sel_hi:[1,0]
	v_pk_mul_f32 v[150:151], v[102:103], v[168:169] op_sel_hi:[1,0]
	v_pk_mul_f32 v[146:147], v[98:99], v[168:169] op_sel_hi:[1,0]
	v_pk_mul_f32 v[144:145], v[96:97], v[168:169] op_sel_hi:[1,0]
	v_min_f32_e32 v168, 0, v148
	v_mul_f32_e64 v148, |v148|, s57
	v_exp_f32_e32 v148, v148
	s_nop 0
	v_add_f32_e32 v148, 1.0, v148
	v_log_f32_e32 v148, v148
	s_nop 0
	v_mul_f32_e32 v194, 0x3f317217, v148
	v_fma_f32 v194, v148, s52, -v194
	v_fmac_f32_e32 v194, 0x3377d1cf, v148
	v_fmac_f32_e32 v194, 0x3f317217, v148
	v_sub_f32_e32 v148, v168, v194
	v_min_f32_e32 v168, 0, v144
	v_mul_f32_e64 v144, |v144|, s57
	v_exp_f32_e32 v144, v144
	s_nop 0
	v_add_f32_e32 v144, 1.0, v144
	v_log_f32_e32 v144, v144
	s_nop 0
	v_mul_f32_e32 v194, 0x3f317217, v144
	v_fma_f32 v194, v144, s52, -v194
	v_fmac_f32_e32 v194, 0x3377d1cf, v144
	v_fmac_f32_e32 v194, 0x3f317217, v144
	v_sub_f32_e32 v168, v168, v194
	v_mul_f32_e32 v144, 0x3fb8aa3b, v148
	v_exp_f32_e32 v144, v144
	s_nop 0
	v_fma_f32 v144, v183, v144, v132
	v_cmp_gt_f32_e64 s[40:41], s97, v144
	s_nop 1
	v_cndmask_b32_e64 v194, 0, 32, s[40:41]
	v_ldexp_f32 v144, v144, v194
	v_log_f32_e32 v144, v144
	s_nop 0
	v_mul_f32_e32 v194, 0x3f317217, v144
	v_fma_f32 v194, v144, s52, -v194
	v_fmac_f32_e32 v194, 0x3377d1cf, v144
	v_fmac_f32_e32 v194, 0x3f317217, v144
	v_mov_b32_e32 v144, v194
	v_cndmask_b32_e64 v194, 0, v216, s[40:41]
	v_sub_f32_e32 v144, v144, v194
	v_cndmask_b32_e64 v144, v148, v144, s[20:21]
	v_mul_f32_e32 v148, 0x3fb8aa3b, v168
	v_exp_f32_e32 v148, v148
	s_nop 0
	v_fma_f32 v148, v182, v148, v128
	v_cmp_gt_f32_e64 s[40:41], s97, v148
	s_nop 1
	v_cndmask_b32_e64 v194, 0, 32, s[40:41]
	v_ldexp_f32 v148, v148, v194
	v_log_f32_e32 v148, v148
	s_nop 0
	v_mul_f32_e32 v194, 0x3f317217, v148
	v_fma_f32 v194, v148, s52, -v194
	v_fmac_f32_e32 v194, 0x3377d1cf, v148
	v_fmac_f32_e32 v194, 0x3f317217, v148
	v_mov_b32_e32 v148, v194
	v_cndmask_b32_e64 v194, 0, v216, s[40:41]
	v_sub_f32_e32 v148, v148, v194
	v_cndmask_b32_e64 v148, v168, v148, s[18:19]
	v_min_f32_e32 v168, 0, v149
	v_mul_f32_e64 v149, |v149|, s57
	v_exp_f32_e32 v149, v149
	s_nop 0
	v_add_f32_e32 v149, 1.0, v149
	v_log_f32_e32 v149, v149
	s_nop 0
	v_mul_f32_e32 v194, 0x3f317217, v149
	v_fma_f32 v194, v149, s52, -v194
	v_fmac_f32_e32 v194, 0x3377d1cf, v149
	v_fmac_f32_e32 v194, 0x3f317217, v149
	v_sub_f32_e32 v149, v168, v194
	v_min_f32_e32 v168, 0, v145
	v_mul_f32_e64 v145, |v145|, s57
	v_exp_f32_e32 v145, v145
	s_nop 0
	v_add_f32_e32 v145, 1.0, v145
	v_log_f32_e32 v145, v145
	s_nop 0
	v_mul_f32_e32 v194, 0x3f317217, v145
	v_fma_f32 v194, v145, s52, -v194
	v_fmac_f32_e32 v194, 0x3377d1cf, v145
	v_fmac_f32_e32 v194, 0x3f317217, v145
	v_sub_f32_e32 v168, v168, v194
	v_mul_f32_e32 v145, 0x3fb8aa3b, v149
	v_exp_f32_e32 v145, v145
	s_nop 0
	v_fma_f32 v145, v181, v145, v133
	v_cmp_gt_f32_e64 s[40:41], s97, v145
	s_nop 1
	v_cndmask_b32_e64 v194, 0, 32, s[40:41]
	v_ldexp_f32 v145, v145, v194
	v_log_f32_e32 v145, v145
	s_nop 0
	v_mul_f32_e32 v194, 0x3f317217, v145
	v_fma_f32 v194, v145, s52, -v194
	v_fmac_f32_e32 v194, 0x3377d1cf, v145
	v_fmac_f32_e32 v194, 0x3f317217, v145
	v_mov_b32_e32 v145, v194
	v_cndmask_b32_e64 v194, 0, v216, s[40:41]
	v_sub_f32_e32 v145, v145, v194
	v_cndmask_b32_e64 v145, v149, v145, s[16:17]
	v_mul_f32_e32 v149, 0x3fb8aa3b, v168
	v_exp_f32_e32 v149, v149
	s_nop 0
	v_fma_f32 v149, v180, v149, v129
	v_cmp_gt_f32_e64 s[40:41], s97, v149
	s_nop 1
	v_cndmask_b32_e64 v194, 0, 32, s[40:41]
	v_ldexp_f32 v149, v149, v194
; __device__ __forceinline__ float silu_f(float x) { return x * __builtin_amdgcn_rcpf(1.f + __expf(-x)); }
; __device__ __forceinline__ v4u pack8(const f32x4 a, const f32x4 b) { v4u w; w.x = cvt_pk_bf16(a[0], a[1]); w.y = cvt_pk_bf16(a[2], a[3]); w.z = cvt_pk_bf16(b[0], b[1]); w.w = cvt_pk_bf16(b[2], b[3]); return w; }
;     __device__ __forceinline__ void operator()(const f32x4 (&acc)[2][2][4][2], const pg8::Unit& u, int wr, int wc, int fr, int fq) const {
;     ...
;         if (grp == 0) { WIN_LOOP( _Pragma("unroll") for (int i = 0; i < 4; ++i) { a[i] = silu_f(a[i]); b[i] = silu_f(b[i]); } *(v4u*)(QO + (size_t)row * DM + c) = pack8(a, b); ) }
;         else if (grp == 3) { WIN_LOOP( _Pragma("unroll") for (int i = 0; i < 4; ++i) { a[i] = silu_f(a[i]); b[i] = silu_f(b[i]); } *(v4u*)(GH + (size_t)row * 512 + c) = pack8(a, b); ) }
;         else if (grp == 1) {
;             f32x4 l0[2], l1[2];
; #pragma unroll
;             for (int bj = 0; bj < 2; ++bj) { l0[bj] = *(const f32x4*)(lb + cb + bj * 128); l1[bj] = *(const f32x4*)(lb + cb + bj * 128 + 4); }
;             WIN_LOOP( _Pragma("unroll") for (int i = 0; i < 4; ++i) { const float s0 = fminf(a[i], 0.f) - __logf(1.f + __expf(-fabsf(a[i]))), s1 = fminf(b[i], 0.f) - __logf(1.f + __expf(-fabsf(b[i]))); const float la = l0[bj][i], lbv = l1[bj][i];
;                     a[i] = la > 0.f ? __logf(la + (1.f - la) * __expf(s0)) : s0; b[i] = lbv > 0.f ? __logf(lbv + (1.f - lbv) * __expf(s1)) : s1; }
;                 *(f32x4*)(LF + (size_t)row * 512 + c) = a; *(f32x4*)(LF + (size_t)row * 512 + c + 4) = b; __builtin_amdgcn_sched_barrier(0); ) }
	v_log_f32_e32 v149, v149
	s_nop 0
	v_mul_f32_e32 v194, 0x3f317217, v149
	v_fma_f32 v194, v149, s52, -v194
	v_fmac_f32_e32 v194, 0x3377d1cf, v149
	v_fmac_f32_e32 v194, 0x3f317217, v149
	v_mov_b32_e32 v149, v194
	v_cndmask_b32_e64 v194, 0, v216, s[40:41]
	v_sub_f32_e32 v149, v149, v194
	v_cndmask_b32_e64 v149, v168, v149, s[14:15]
	v_min_f32_e32 v168, 0, v150
	v_mul_f32_e64 v150, |v150|, s57
	v_exp_f32_e32 v150, v150
	s_nop 0
	v_add_f32_e32 v150, 1.0, v150
	v_log_f32_e32 v150, v150
	s_nop 0
	v_mul_f32_e32 v194, 0x3f317217, v150
	v_fma_f32 v194, v150, s52, -v194
	v_fmac_f32_e32 v194, 0x3377d1cf, v150
	v_fmac_f32_e32 v194, 0x3f317217, v150
	v_sub_f32_e32 v150, v168, v194
	v_min_f32_e32 v168, 0, v146
	v_mul_f32_e64 v146, |v146|, s57
	v_exp_f32_e32 v146, v146
	s_nop 0
	v_add_f32_e32 v146, 1.0, v146
	v_log_f32_e32 v146, v146
	s_nop 0
	v_mul_f32_e32 v194, 0x3f317217, v146
	v_fma_f32 v194, v146, s52, -v194
	v_fmac_f32_e32 v194, 0x3377d1cf, v146
	v_fmac_f32_e32 v194, 0x3f317217, v146
	v_sub_f32_e32 v168, v168, v194
	v_mul_f32_e32 v146, 0x3fb8aa3b, v150
	v_exp_f32_e32 v146, v146
	s_nop 0
	v_fma_f32 v146, v179, v146, v134
	v_cmp_gt_f32_e64 s[40:41], s97, v146
	s_nop 1
	v_cndmask_b32_e64 v194, 0, 32, s[40:41]
	v_ldexp_f32 v146, v146, v194
	v_log_f32_e32 v146, v146
	s_nop 0
	v_mul_f32_e32 v194, 0x3f317217, v146
	v_fma_f32 v194, v146, s52, -v194
	v_fmac_f32_e32 v194, 0x3377d1cf, v146
	v_fmac_f32_e32 v194, 0x3f317217, v146
	v_mov_b32_e32 v146, v194
	v_cndmask_b32_e64 v194, 0, v216, s[40:41]
	v_sub_f32_e32 v146, v146, v194
	v_cndmask_b32_e64 v146, v150, v146, s[12:13]
	v_mul_f32_e32 v150, 0x3fb8aa3b, v168
	v_exp_f32_e32 v150, v150
	s_nop 0
	v_fma_f32 v150, v178, v150, v130
	v_cmp_gt_f32_e64 s[40:41], s97, v150
	s_nop 1
	v_cndmask_b32_e64 v194, 0, 32, s[40:41]
	v_ldexp_f32 v150, v150, v194
	v_log_f32_e32 v150, v150
	s_nop 0
	v_mul_f32_e32 v194, 0x3f317217, v150
	v_fma_f32 v194, v150, s52, -v194
	v_fmac_f32_e32 v194, 0x3377d1cf, v150
	v_fmac_f32_e32 v194, 0x3f317217, v150
	v_mov_b32_e32 v150, v194
	v_cndmask_b32_e64 v194, 0, v216, s[40:41]
	v_sub_f32_e32 v150, v150, v194
	v_cndmask_b32_e64 v150, v168, v150, s[10:11]
	v_min_f32_e32 v168, 0, v151
	v_mul_f32_e64 v151, |v151|, s57
	v_exp_f32_e32 v151, v151
	s_nop 0
	v_add_f32_e32 v151, 1.0, v151
	v_log_f32_e32 v151, v151
	s_nop 0
	v_mul_f32_e32 v194, 0x3f317217, v151
	v_fma_f32 v194, v151, s52, -v194
	v_fmac_f32_e32 v194, 0x3377d1cf, v151
	v_fmac_f32_e32 v194, 0x3f317217, v151
	v_sub_f32_e32 v151, v168, v194
	v_min_f32_e32 v168, 0, v147
	v_mul_f32_e64 v147, |v147|, s57
	v_exp_f32_e32 v147, v147
	s_nop 0
	v_add_f32_e32 v147, 1.0, v147
	v_log_f32_e32 v147, v147
	s_nop 0
	v_mul_f32_e32 v194, 0x3f317217, v147
	v_fma_f32 v194, v147, s52, -v194
	v_fmac_f32_e32 v194, 0x3377d1cf, v147
	v_fmac_f32_e32 v194, 0x3f317217, v147
	v_sub_f32_e32 v168, v168, v194
	v_mul_f32_e32 v147, 0x3fb8aa3b, v151
	v_exp_f32_e32 v147, v147
	s_nop 0
	v_fma_f32 v147, v177, v147, v135
	v_cmp_gt_f32_e64 s[40:41], s97, v147
	s_nop 1
	v_cndmask_b32_e64 v194, 0, 32, s[40:41]
	v_ldexp_f32 v147, v147, v194
	v_log_f32_e32 v147, v147
	s_nop 0
	v_mul_f32_e32 v194, 0x3f317217, v147
	v_fma_f32 v194, v147, s52, -v194
	v_fmac_f32_e32 v194, 0x3377d1cf, v147
	v_fmac_f32_e32 v194, 0x3f317217, v147
	v_mov_b32_e32 v147, v194
	v_cndmask_b32_e64 v194, 0, v216, s[40:41]
	v_sub_f32_e32 v147, v147, v194
	v_cndmask_b32_e64 v147, v151, v147, s[8:9]
	v_mul_f32_e32 v151, 0x3fb8aa3b, v168
	v_exp_f32_e32 v151, v151
	s_nop 0
	v_fma_f32 v151, v167, v151, v131
	v_cmp_gt_f32_e64 s[40:41], s97, v151
	s_nop 1
	v_cndmask_b32_e64 v194, 0, 32, s[40:41]
	v_ldexp_f32 v151, v151, v194
	v_log_f32_e32 v151, v151
	s_nop 0
	v_mul_f32_e32 v194, 0x3f317217, v151
	v_fma_f32 v194, v151, s52, -v194
	v_fmac_f32_e32 v194, 0x3377d1cf, v151
	v_fmac_f32_e32 v194, 0x3f317217, v151
	v_mov_b32_e32 v151, v194
	v_cndmask_b32_e64 v194, 0, v216, s[40:41]
	v_sub_f32_e32 v151, v151, v194
	v_cndmask_b32_e32 v151, v168, v151, vcc
	global_store_dwordx4 v[170:171], v[144:147], off offset:512
	global_store_dwordx4 v[170:171], v[148:151], off offset:528
	s_nop 1
	v_add_u32_e32 v148, 0x80, v166
	v_ashrrev_i32_e32 v149, 31, v148
	v_lshlrev_b64 v[144:145], 6, v[148:149]
	v_lshl_add_u64 v[144:145], v[160:161], 0, v[144:145]
	s_nop 0
	s_waitcnt lgkmcnt(0)
	s_nop 3
	s_nop 0
	s_nop 1
	s_waitcnt lgkmcnt(0)
	s_nop 1
	s_waitcnt lgkmcnt(0)
; __device__ __forceinline__ float silu_f(float x) { return x * __builtin_amdgcn_rcpf(1.f + __expf(-x)); }
; __device__ __forceinline__ v4u pack8(const f32x4 a, const f32x4 b) { v4u w; w.x = cvt_pk_bf16(a[0], a[1]); w.y = cvt_pk_bf16(a[2], a[3]); w.z = cvt_pk_bf16(b[0], b[1]); w.w = cvt_pk_bf16(b[2], b[3]); return w; }
;     __device__ __forceinline__ void operator()(const f32x4 (&acc)[2][2][4][2], const pg8::Unit& u, int wr, int wc, int fr, int fq) const {
;     ...
;         if (grp == 0) { WIN_LOOP( _Pragma("unroll") for (int i = 0; i < 4; ++i) { a[i] = silu_f(a[i]); b[i] = silu_f(b[i]); } *(v4u*)(QO + (size_t)row * DM + c) = pack8(a, b); ) }
;         else if (grp == 3) { WIN_LOOP( _Pragma("unroll") for (int i = 0; i < 4; ++i) { a[i] = silu_f(a[i]); b[i] = silu_f(b[i]); } *(v4u*)(GH + (size_t)row * 512 + c) = pack8(a, b); ) }
;         else if (grp == 1) {
;             f32x4 l0[2], l1[2];
; #pragma unroll
;             for (int bj = 0; bj < 2; ++bj) { l0[bj] = *(const f32x4*)(lb + cb + bj * 128); l1[bj] = *(const f32x4*)(lb + cb + bj * 128 + 4); }
;             WIN_LOOP( _Pragma("unroll") for (int i = 0; i < 4; ++i) { const float s0 = fminf(a[i], 0.f) - __logf(1.f + __expf(-fabsf(a[i]))), s1 = fminf(b[i], 0.f) - __logf(1.f + __expf(-fabsf(b[i]))); const float la = l0[bj][i], lbv = l1[bj][i];
;                     a[i] = la > 0.f ? __logf(la + (1.f - la) * __expf(s0)) : s0; b[i] = lbv > 0.f ? __logf(lbv + (1.f - lbv) * __expf(s1)) : s1; }
;                 *(f32x4*)(LF + (size_t)row * 512 + c) = a; *(f32x4*)(LF + (size_t)row * 512 + c + 4) = b; __builtin_amdgcn_sched_barrier(0); ) }
	s_nop 1
	v_mov_b32_e32 v168, v254
	v_lshlrev_b64 v[144:145], 11, v[148:149]
	v_lshl_add_u64 v[170:171], s[50:51], 0, v[144:145]
	v_lshl_add_u64 v[170:171], v[170:171], 0, v[192:193]
	v_pk_mul_f32 v[148:149], v[28:29], v[168:169] op_sel_hi:[1,0]
	v_pk_mul_f32 v[144:145], v[24:25], v[168:169] op_sel_hi:[1,0]
	v_min_f32_e32 v194, 0, v148
	v_mul_f32_e64 v148, |v148|, s57
	v_exp_f32_e32 v148, v148
	v_pk_mul_f32 v[150:151], v[30:31], v[168:169] op_sel_hi:[1,0]
	v_pk_mul_f32 v[146:147], v[26:27], v[168:169] op_sel_hi:[1,0]
	v_add_f32_e32 v148, 1.0, v148
	v_log_f32_e32 v148, v148
	s_nop 0
	v_mul_f32_e32 v195, 0x3f317217, v148
	v_fma_f32 v195, v148, s52, -v195
	v_fmac_f32_e32 v195, 0x3377d1cf, v148
	v_fmac_f32_e32 v195, 0x3f317217, v148
	v_sub_f32_e32 v148, v194, v195
	v_min_f32_e32 v194, 0, v144
	v_mul_f32_e64 v144, |v144|, s57
	v_exp_f32_e32 v144, v144
	s_nop 0
	v_add_f32_e32 v144, 1.0, v144
	v_log_f32_e32 v144, v144
	s_nop 0
	v_mul_f32_e32 v195, 0x3f317217, v144
	v_fma_f32 v195, v144, s52, -v195
	v_fmac_f32_e32 v195, 0x3377d1cf, v144
	v_fmac_f32_e32 v195, 0x3f317217, v144
	v_sub_f32_e32 v194, v194, v195
	v_mul_f32_e32 v144, 0x3fb8aa3b, v148
	v_exp_f32_e32 v144, v144
	s_nop 0
	v_fma_f32 v144, v190, v144, v140
	v_cmp_gt_f32_e64 s[40:41], s97, v144
	s_nop 1
	v_cndmask_b32_e64 v195, 0, 32, s[40:41]
	v_ldexp_f32 v144, v144, v195
	v_log_f32_e32 v144, v144
	s_nop 0
	v_mul_f32_e32 v195, 0x3f317217, v144
	v_fma_f32 v195, v144, s52, -v195
	v_fmac_f32_e32 v195, 0x3377d1cf, v144
	v_fmac_f32_e32 v195, 0x3f317217, v144
	v_mov_b32_e32 v144, v195
	v_cndmask_b32_e64 v195, 0, v216, s[40:41]
	v_sub_f32_e32 v144, v144, v195
	v_cndmask_b32_e64 v144, v148, v144, s[38:39]
	v_mul_f32_e32 v148, 0x3fb8aa3b, v194
	v_exp_f32_e32 v148, v148
	s_nop 0
	v_fma_f32 v148, v191, v148, v136
	v_cmp_gt_f32_e64 s[40:41], s97, v148
	s_nop 1
	v_cndmask_b32_e64 v195, 0, 32, s[40:41]
	v_ldexp_f32 v148, v148, v195
	v_log_f32_e32 v148, v148
	s_nop 0
	v_mul_f32_e32 v195, 0x3f317217, v148
	v_fma_f32 v195, v148, s52, -v195
	v_fmac_f32_e32 v195, 0x3377d1cf, v148
	v_fmac_f32_e32 v195, 0x3f317217, v148
	v_mov_b32_e32 v148, v195
	v_cndmask_b32_e64 v195, 0, v216, s[40:41]
	v_sub_f32_e32 v148, v148, v195
	v_cndmask_b32_e64 v148, v194, v148, s[36:37]
	v_min_f32_e32 v194, 0, v149
	v_mul_f32_e64 v149, |v149|, s57
	v_exp_f32_e32 v149, v149
	s_nop 0
	v_add_f32_e32 v149, 1.0, v149
	v_log_f32_e32 v149, v149
	s_nop 0
	v_mul_f32_e32 v195, 0x3f317217, v149
	v_fma_f32 v195, v149, s52, -v195
	v_fmac_f32_e32 v195, 0x3377d1cf, v149
	v_fmac_f32_e32 v195, 0x3f317217, v149
	v_sub_f32_e32 v149, v194, v195
	v_min_f32_e32 v194, 0, v145
	v_mul_f32_e64 v145, |v145|, s57
	v_exp_f32_e32 v145, v145
	s_nop 0
	v_add_f32_e32 v145, 1.0, v145
	v_log_f32_e32 v145, v145
	s_nop 0
	v_mul_f32_e32 v195, 0x3f317217, v145
	v_fma_f32 v195, v145, s52, -v195
	v_fmac_f32_e32 v195, 0x3377d1cf, v145
	v_fmac_f32_e32 v195, 0x3f317217, v145
	v_sub_f32_e32 v194, v194, v195
	v_mul_f32_e32 v145, 0x3fb8aa3b, v149
	v_exp_f32_e32 v145, v145
	s_nop 0
	v_fma_f32 v145, v188, v145, v141
	v_cmp_gt_f32_e64 s[40:41], s97, v145
	s_nop 1
	v_cndmask_b32_e64 v195, 0, 32, s[40:41]
	v_ldexp_f32 v145, v145, v195
	v_log_f32_e32 v145, v145
	s_nop 0
	v_mul_f32_e32 v195, 0x3f317217, v145
	v_fma_f32 v195, v145, s52, -v195
	v_fmac_f32_e32 v195, 0x3377d1cf, v145
	v_fmac_f32_e32 v195, 0x3f317217, v145
	v_mov_b32_e32 v145, v195
	v_cndmask_b32_e64 v195, 0, v216, s[40:41]
	v_sub_f32_e32 v145, v145, v195
	v_cndmask_b32_e64 v145, v149, v145, s[34:35]
	v_mul_f32_e32 v149, 0x3fb8aa3b, v194
	v_exp_f32_e32 v149, v149
	s_nop 0
	v_fma_f32 v149, v189, v149, v137
	v_cmp_gt_f32_e64 s[40:41], s97, v149
	s_nop 1
	v_cndmask_b32_e64 v195, 0, 32, s[40:41]
	v_ldexp_f32 v149, v149, v195
	v_log_f32_e32 v149, v149
	s_nop 0
	v_mul_f32_e32 v195, 0x3f317217, v149
	v_fma_f32 v195, v149, s52, -v195
	v_fmac_f32_e32 v195, 0x3377d1cf, v149
	v_fmac_f32_e32 v195, 0x3f317217, v149
	v_mov_b32_e32 v149, v195
	v_cndmask_b32_e64 v195, 0, v216, s[40:41]
	v_sub_f32_e32 v149, v149, v195
	v_cndmask_b32_e64 v149, v194, v149, s[30:31]
	v_min_f32_e32 v194, 0, v150
	v_mul_f32_e64 v150, |v150|, s57
	v_exp_f32_e32 v150, v150
	s_nop 0
	v_add_f32_e32 v150, 1.0, v150
	v_log_f32_e32 v150, v150
	s_nop 0
	v_mul_f32_e32 v195, 0x3f317217, v150
	v_fma_f32 v195, v150, s52, -v195
	v_fmac_f32_e32 v195, 0x3377d1cf, v150
	v_fmac_f32_e32 v195, 0x3f317217, v150
	v_sub_f32_e32 v150, v194, v195
	v_min_f32_e32 v194, 0, v146
	v_mul_f32_e64 v146, |v146|, s57
	v_exp_f32_e32 v146, v146
	s_nop 0
	v_add_f32_e32 v146, 1.0, v146
	v_log_f32_e32 v146, v146
	s_nop 0
	v_mul_f32_e32 v195, 0x3f317217, v146
	v_fma_f32 v195, v146, s52, -v195
	v_fmac_f32_e32 v195, 0x3377d1cf, v146
	v_fmac_f32_e32 v195, 0x3f317217, v146
	v_sub_f32_e32 v194, v194, v195
	v_mul_f32_e32 v146, 0x3fb8aa3b, v150
	v_exp_f32_e32 v146, v146
	s_nop 0
	v_fma_f32 v146, v187, v146, v142
	v_cmp_gt_f32_e64 s[40:41], s97, v146
	s_nop 1
	v_cndmask_b32_e64 v195, 0, 32, s[40:41]
	v_ldexp_f32 v146, v146, v195
	v_log_f32_e32 v146, v146
	s_nop 0
	v_mul_f32_e32 v195, 0x3f317217, v146
	v_fma_f32 v195, v146, s52, -v195
	v_fmac_f32_e32 v195, 0x3377d1cf, v146
	v_fmac_f32_e32 v195, 0x3f317217, v146
	v_mov_b32_e32 v146, v195
	v_cndmask_b32_e64 v195, 0, v216, s[40:41]
	v_sub_f32_e32 v146, v146, v195
	v_cndmask_b32_e64 v146, v150, v146, s[28:29]
	v_mul_f32_e32 v150, 0x3fb8aa3b, v194
	v_exp_f32_e32 v150, v150
	s_nop 0
	v_fma_f32 v150, v186, v150, v138
	v_cmp_gt_f32_e64 s[40:41], s97, v150
	s_nop 1
	v_cndmask_b32_e64 v195, 0, 32, s[40:41]
	v_ldexp_f32 v150, v150, v195
	v_log_f32_e32 v150, v150
	s_nop 0
	v_mul_f32_e32 v195, 0x3f317217, v150
	v_fma_f32 v195, v150, s52, -v195
	v_fmac_f32_e32 v195, 0x3377d1cf, v150
; __device__ __forceinline__ float silu_f(float x) { return x * __builtin_amdgcn_rcpf(1.f + __expf(-x)); }
; __device__ __forceinline__ v4u pack8(const f32x4 a, const f32x4 b) { v4u w; w.x = cvt_pk_bf16(a[0], a[1]); w.y = cvt_pk_bf16(a[2], a[3]); w.z = cvt_pk_bf16(b[0], b[1]); w.w = cvt_pk_bf16(b[2], b[3]); return w; }
;     __device__ __forceinline__ void operator()(const f32x4 (&acc)[2][2][4][2], const pg8::Unit& u, int wr, int wc, int fr, int fq) const {
;     ...
;         if (grp == 0) { WIN_LOOP( _Pragma("unroll") for (int i = 0; i < 4; ++i) { a[i] = silu_f(a[i]); b[i] = silu_f(b[i]); } *(v4u*)(QO + (size_t)row * DM + c) = pack8(a, b); ) }
;         else if (grp == 3) { WIN_LOOP( _Pragma("unroll") for (int i = 0; i < 4; ++i) { a[i] = silu_f(a[i]); b[i] = silu_f(b[i]); } *(v4u*)(GH + (size_t)row * 512 + c) = pack8(a, b); ) }
;         else if (grp == 1) {
;             f32x4 l0[2], l1[2];
; #pragma unroll
;             for (int bj = 0; bj < 2; ++bj) { l0[bj] = *(const f32x4*)(lb + cb + bj * 128); l1[bj] = *(const f32x4*)(lb + cb + bj * 128 + 4); }
;             WIN_LOOP( _Pragma("unroll") for (int i = 0; i < 4; ++i) { const float s0 = fminf(a[i], 0.f) - __logf(1.f + __expf(-fabsf(a[i]))), s1 = fminf(b[i], 0.f) - __logf(1.f + __expf(-fabsf(b[i]))); const float la = l0[bj][i], lbv = l1[bj][i];
;                     a[i] = la > 0.f ? __logf(la + (1.f - la) * __expf(s0)) : s0; b[i] = lbv > 0.f ? __logf(lbv + (1.f - lbv) * __expf(s1)) : s1; }
;                 *(f32x4*)(LF + (size_t)row * 512 + c) = a; *(f32x4*)(LF + (size_t)row * 512 + c + 4) = b; __builtin_amdgcn_sched_barrier(0); ) }
	v_fmac_f32_e32 v195, 0x3f317217, v150
	v_mov_b32_e32 v150, v195
	v_cndmask_b32_e64 v195, 0, v216, s[40:41]
	v_sub_f32_e32 v150, v150, v195
	v_cndmask_b32_e64 v150, v194, v150, s[26:27]
	v_min_f32_e32 v194, 0, v151
	v_mul_f32_e64 v151, |v151|, s57
	v_exp_f32_e32 v151, v151
	s_nop 0
	v_add_f32_e32 v151, 1.0, v151
	v_log_f32_e32 v151, v151
	s_nop 0
	v_mul_f32_e32 v195, 0x3f317217, v151
	v_fma_f32 v195, v151, s52, -v195
	v_fmac_f32_e32 v195, 0x3377d1cf, v151
	v_fmac_f32_e32 v195, 0x3f317217, v151
	v_sub_f32_e32 v151, v194, v195
	v_min_f32_e32 v194, 0, v147
	v_mul_f32_e64 v147, |v147|, s57
	v_exp_f32_e32 v147, v147
	s_nop 0
	v_add_f32_e32 v147, 1.0, v147
	v_log_f32_e32 v147, v147
	s_nop 0
	v_mul_f32_e32 v195, 0x3f317217, v147
	v_fma_f32 v195, v147, s52, -v195
	v_fmac_f32_e32 v195, 0x3377d1cf, v147
	v_fmac_f32_e32 v195, 0x3f317217, v147
	v_sub_f32_e32 v194, v194, v195
	v_mul_f32_e32 v147, 0x3fb8aa3b, v151
	v_exp_f32_e32 v147, v147
	s_nop 0
	v_fma_f32 v147, v185, v147, v143
	v_cmp_gt_f32_e64 s[40:41], s97, v147
	s_nop 1
	v_cndmask_b32_e64 v195, 0, 32, s[40:41]
	v_ldexp_f32 v147, v147, v195
	v_log_f32_e32 v147, v147
	s_nop 0
	v_mul_f32_e32 v195, 0x3f317217, v147
	v_fma_f32 v195, v147, s52, -v195
	v_fmac_f32_e32 v195, 0x3377d1cf, v147
	v_fmac_f32_e32 v195, 0x3f317217, v147
	v_mov_b32_e32 v147, v195
	v_cndmask_b32_e64 v195, 0, v216, s[40:41]
	v_sub_f32_e32 v147, v147, v195
	v_cndmask_b32_e64 v147, v151, v147, s[24:25]
	v_mul_f32_e32 v151, 0x3fb8aa3b, v194
	v_exp_f32_e32 v151, v151
	s_nop 0
	v_fma_f32 v151, v184, v151, v139
	v_cmp_gt_f32_e64 s[40:41], s97, v151
	s_nop 1
	v_cndmask_b32_e64 v195, 0, 32, s[40:41]
	v_ldexp_f32 v151, v151, v195
	v_log_f32_e32 v151, v151
	s_nop 0
	v_mul_f32_e32 v195, 0x3f317217, v151
	v_fma_f32 v195, v151, s52, -v195
	v_fmac_f32_e32 v195, 0x3377d1cf, v151
	v_fmac_f32_e32 v195, 0x3f317217, v151
	v_mov_b32_e32 v151, v195
	v_cndmask_b32_e64 v195, 0, v216, s[40:41]
	v_sub_f32_e32 v151, v151, v195
	v_cndmask_b32_e64 v151, v194, v151, s[22:23]
	global_store_dwordx4 v[170:171], v[144:147], off
	global_store_dwordx4 v[170:171], v[148:151], off offset:16
	s_nop 1
	v_pk_mul_f32 v[148:149], v[92:93], v[168:169] op_sel_hi:[1,0]
	v_pk_mul_f32 v[150:151], v[94:95], v[168:169] op_sel_hi:[1,0]
	v_pk_mul_f32 v[146:147], v[90:91], v[168:169] op_sel_hi:[1,0]
	v_pk_mul_f32 v[144:145], v[88:89], v[168:169] op_sel_hi:[1,0]
	v_min_f32_e32 v168, 0, v148
	v_mul_f32_e64 v148, |v148|, s57
	v_exp_f32_e32 v148, v148
	s_nop 0
	v_add_f32_e32 v148, 1.0, v148
	v_log_f32_e32 v148, v148
	s_nop 0
	v_mul_f32_e32 v194, 0x3f317217, v148
	v_fma_f32 v194, v148, s52, -v194
	v_fmac_f32_e32 v194, 0x3377d1cf, v148
	v_fmac_f32_e32 v194, 0x3f317217, v148
	v_sub_f32_e32 v148, v168, v194
	v_min_f32_e32 v168, 0, v144
	v_mul_f32_e64 v144, |v144|, s57
	v_exp_f32_e32 v144, v144
	s_nop 0
	v_add_f32_e32 v144, 1.0, v144
	v_log_f32_e32 v144, v144
	s_nop 0
	v_mul_f32_e32 v194, 0x3f317217, v144
	v_fma_f32 v194, v144, s52, -v194
	v_fmac_f32_e32 v194, 0x3377d1cf, v144
	v_fmac_f32_e32 v194, 0x3f317217, v144
	v_sub_f32_e32 v168, v168, v194
	v_mul_f32_e32 v144, 0x3fb8aa3b, v148
	v_exp_f32_e32 v144, v144
	s_nop 0
	v_fma_f32 v144, v183, v144, v132
	v_cmp_gt_f32_e64 s[40:41], s97, v144
	s_nop 1
	v_cndmask_b32_e64 v194, 0, 32, s[40:41]
	v_ldexp_f32 v144, v144, v194
	v_log_f32_e32 v144, v144
	s_nop 0
	v_mul_f32_e32 v194, 0x3f317217, v144
	v_fma_f32 v194, v144, s52, -v194
	v_fmac_f32_e32 v194, 0x3377d1cf, v144
	v_fmac_f32_e32 v194, 0x3f317217, v144
	v_mov_b32_e32 v144, v194
	v_cndmask_b32_e64 v194, 0, v216, s[40:41]
	v_sub_f32_e32 v144, v144, v194
	v_cndmask_b32_e64 v144, v148, v144, s[20:21]
	v_mul_f32_e32 v148, 0x3fb8aa3b, v168
	v_exp_f32_e32 v148, v148
	s_nop 0
	v_fma_f32 v148, v182, v148, v128
	v_cmp_gt_f32_e64 s[40:41], s97, v148
	s_nop 1
	v_cndmask_b32_e64 v194, 0, 32, s[40:41]
	v_ldexp_f32 v148, v148, v194
	v_log_f32_e32 v148, v148
	s_nop 0
	v_mul_f32_e32 v194, 0x3f317217, v148
	v_fma_f32 v194, v148, s52, -v194
	v_fmac_f32_e32 v194, 0x3377d1cf, v148
	v_fmac_f32_e32 v194, 0x3f317217, v148
	v_mov_b32_e32 v148, v194
	v_cndmask_b32_e64 v194, 0, v216, s[40:41]
	v_sub_f32_e32 v148, v148, v194
	v_cndmask_b32_e64 v148, v168, v148, s[18:19]
	v_min_f32_e32 v168, 0, v149
	v_mul_f32_e64 v149, |v149|, s57
	v_exp_f32_e32 v149, v149
	s_nop 0
	v_add_f32_e32 v149, 1.0, v149
	v_log_f32_e32 v149, v149
	s_nop 0
	v_mul_f32_e32 v194, 0x3f317217, v149
	v_fma_f32 v194, v149, s52, -v194
	v_fmac_f32_e32 v194, 0x3377d1cf, v149
	v_fmac_f32_e32 v194, 0x3f317217, v149
	v_sub_f32_e32 v149, v168, v194
	v_min_f32_e32 v168, 0, v145
	v_mul_f32_e64 v145, |v145|, s57
	v_exp_f32_e32 v145, v145
	s_nop 0
	v_add_f32_e32 v145, 1.0, v145
	v_log_f32_e32 v145, v145
	s_nop 0
	v_mul_f32_e32 v194, 0x3f317217, v145
	v_fma_f32 v194, v145, s52, -v194
	v_fmac_f32_e32 v194, 0x3377d1cf, v145
	v_fmac_f32_e32 v194, 0x3f317217, v145
	v_sub_f32_e32 v168, v168, v194
	v_mul_f32_e32 v145, 0x3fb8aa3b, v149
	v_exp_f32_e32 v145, v145
	s_nop 0
	v_fma_f32 v145, v181, v145, v133
	v_cmp_gt_f32_e64 s[40:41], s97, v145
	s_nop 1
	v_cndmask_b32_e64 v194, 0, 32, s[40:41]
	v_ldexp_f32 v145, v145, v194
	v_log_f32_e32 v145, v145
	s_nop 0
	v_mul_f32_e32 v194, 0x3f317217, v145
	v_fma_f32 v194, v145, s52, -v194
	v_fmac_f32_e32 v194, 0x3377d1cf, v145
	v_fmac_f32_e32 v194, 0x3f317217, v145
	v_mov_b32_e32 v145, v194
	v_cndmask_b32_e64 v194, 0, v216, s[40:41]
	v_sub_f32_e32 v145, v145, v194
	v_cndmask_b32_e64 v145, v149, v145, s[16:17]
	v_mul_f32_e32 v149, 0x3fb8aa3b, v168
	v_exp_f32_e32 v149, v149
	s_nop 0
	v_fma_f32 v149, v180, v149, v129
	v_cmp_gt_f32_e64 s[40:41], s97, v149
	s_nop 1
	v_cndmask_b32_e64 v194, 0, 32, s[40:41]
	v_ldexp_f32 v149, v149, v194
; __device__ __forceinline__ float silu_f(float x) { return x * __builtin_amdgcn_rcpf(1.f + __expf(-x)); }
; __device__ __forceinline__ v4u pack8(const f32x4 a, const f32x4 b) { v4u w; w.x = cvt_pk_bf16(a[0], a[1]); w.y = cvt_pk_bf16(a[2], a[3]); w.z = cvt_pk_bf16(b[0], b[1]); w.w = cvt_pk_bf16(b[2], b[3]); return w; }
;     __device__ __forceinline__ void operator()(const f32x4 (&acc)[2][2][4][2], const pg8::Unit& u, int wr, int wc, int fr, int fq) const {
;     ...
;         if (grp == 0) { WIN_LOOP( _Pragma("unroll") for (int i = 0; i < 4; ++i) { a[i] = silu_f(a[i]); b[i] = silu_f(b[i]); } *(v4u*)(QO + (size_t)row * DM + c) = pack8(a, b); ) }
;         else if (grp == 3) { WIN_LOOP( _Pragma("unroll") for (int i = 0; i < 4; ++i) { a[i] = silu_f(a[i]); b[i] = silu_f(b[i]); } *(v4u*)(GH + (size_t)row * 512 + c) = pack8(a, b); ) }
;         else if (grp == 1) {
;             f32x4 l0[2], l1[2];
; #pragma unroll
;             for (int bj = 0; bj < 2; ++bj) { l0[bj] = *(const f32x4*)(lb + cb + bj * 128); l1[bj] = *(const f32x4*)(lb + cb + bj * 128 + 4); }
;             WIN_LOOP( _Pragma("unroll") for (int i = 0; i < 4; ++i) { const float s0 = fminf(a[i], 0.f) - __logf(1.f + __expf(-fabsf(a[i]))), s1 = fminf(b[i], 0.f) - __logf(1.f + __expf(-fabsf(b[i]))); const float la = l0[bj][i], lbv = l1[bj][i];
;                     a[i] = la > 0.f ? __logf(la + (1.f - la) * __expf(s0)) : s0; b[i] = lbv > 0.f ? __logf(lbv + (1.f - lbv) * __expf(s1)) : s1; }
;                 *(f32x4*)(LF + (size_t)row * 512 + c) = a; *(f32x4*)(LF + (size_t)row * 512 + c + 4) = b; __builtin_amdgcn_sched_barrier(0); ) }
	v_log_f32_e32 v149, v149
	s_nop 0
	v_mul_f32_e32 v194, 0x3f317217, v149
	v_fma_f32 v194, v149, s52, -v194
	v_fmac_f32_e32 v194, 0x3377d1cf, v149
	v_fmac_f32_e32 v194, 0x3f317217, v149
	v_mov_b32_e32 v149, v194
	v_cndmask_b32_e64 v194, 0, v216, s[40:41]
	v_sub_f32_e32 v149, v149, v194
	v_cndmask_b32_e64 v149, v168, v149, s[14:15]
	v_min_f32_e32 v168, 0, v150
	v_mul_f32_e64 v150, |v150|, s57
	v_exp_f32_e32 v150, v150
	s_nop 0
	v_add_f32_e32 v150, 1.0, v150
	v_log_f32_e32 v150, v150
	s_nop 0
	v_mul_f32_e32 v194, 0x3f317217, v150
	v_fma_f32 v194, v150, s52, -v194
	v_fmac_f32_e32 v194, 0x3377d1cf, v150
	v_fmac_f32_e32 v194, 0x3f317217, v150
	v_sub_f32_e32 v150, v168, v194
	v_min_f32_e32 v168, 0, v146
	v_mul_f32_e64 v146, |v146|, s57
	v_exp_f32_e32 v146, v146
	s_nop 0
	v_add_f32_e32 v146, 1.0, v146
	v_log_f32_e32 v146, v146
	s_nop 0
	v_mul_f32_e32 v194, 0x3f317217, v146
	v_fma_f32 v194, v146, s52, -v194
	v_fmac_f32_e32 v194, 0x3377d1cf, v146
	v_fmac_f32_e32 v194, 0x3f317217, v146
	v_sub_f32_e32 v168, v168, v194
	v_mul_f32_e32 v146, 0x3fb8aa3b, v150
	v_exp_f32_e32 v146, v146
	s_nop 0
	v_fma_f32 v146, v179, v146, v134
	v_cmp_gt_f32_e64 s[40:41], s97, v146
	s_nop 1
	v_cndmask_b32_e64 v194, 0, 32, s[40:41]
	v_ldexp_f32 v146, v146, v194
	v_log_f32_e32 v146, v146
	s_nop 0
	v_mul_f32_e32 v194, 0x3f317217, v146
	v_fma_f32 v194, v146, s52, -v194
	v_fmac_f32_e32 v194, 0x3377d1cf, v146
	v_fmac_f32_e32 v194, 0x3f317217, v146
	v_mov_b32_e32 v146, v194
	v_cndmask_b32_e64 v194, 0, v216, s[40:41]
	v_sub_f32_e32 v146, v146, v194
	v_cndmask_b32_e64 v146, v150, v146, s[12:13]
	v_mul_f32_e32 v150, 0x3fb8aa3b, v168
	v_exp_f32_e32 v150, v150
	s_nop 0
	v_fma_f32 v150, v178, v150, v130
	v_cmp_gt_f32_e64 s[40:41], s97, v150
	s_nop 1
	v_cndmask_b32_e64 v194, 0, 32, s[40:41]
	v_ldexp_f32 v150, v150, v194
	v_log_f32_e32 v150, v150
	s_nop 0
	v_mul_f32_e32 v194, 0x3f317217, v150
	v_fma_f32 v194, v150, s52, -v194
	v_fmac_f32_e32 v194, 0x3377d1cf, v150
	v_fmac_f32_e32 v194, 0x3f317217, v150
	v_mov_b32_e32 v150, v194
	v_cndmask_b32_e64 v194, 0, v216, s[40:41]
	v_sub_f32_e32 v150, v150, v194
	v_cndmask_b32_e64 v150, v168, v150, s[10:11]
	v_min_f32_e32 v168, 0, v151
	v_mul_f32_e64 v151, |v151|, s57
	v_exp_f32_e32 v151, v151
	s_nop 0
	v_add_f32_e32 v151, 1.0, v151
	v_log_f32_e32 v151, v151
	s_nop 0
	v_mul_f32_e32 v194, 0x3f317217, v151
	v_fma_f32 v194, v151, s52, -v194
	v_fmac_f32_e32 v194, 0x3377d1cf, v151
	v_fmac_f32_e32 v194, 0x3f317217, v151
	v_sub_f32_e32 v151, v168, v194
	v_min_f32_e32 v168, 0, v147
	v_mul_f32_e64 v147, |v147|, s57
	v_exp_f32_e32 v147, v147
	s_nop 0
	v_add_f32_e32 v147, 1.0, v147
	v_log_f32_e32 v147, v147
	s_nop 0
	v_mul_f32_e32 v194, 0x3f317217, v147
	v_fma_f32 v194, v147, s52, -v194
	v_fmac_f32_e32 v194, 0x3377d1cf, v147
	v_fmac_f32_e32 v194, 0x3f317217, v147
	v_sub_f32_e32 v168, v168, v194
	v_mul_f32_e32 v147, 0x3fb8aa3b, v151
	v_exp_f32_e32 v147, v147
	s_nop 0
	v_fma_f32 v147, v177, v147, v135
	v_cmp_gt_f32_e64 s[40:41], s97, v147
	s_nop 1
	v_cndmask_b32_e64 v194, 0, 32, s[40:41]
	v_ldexp_f32 v147, v147, v194
	v_log_f32_e32 v147, v147
	s_nop 0
	v_mul_f32_e32 v194, 0x3f317217, v147
	v_fma_f32 v194, v147, s52, -v194
	v_fmac_f32_e32 v194, 0x3377d1cf, v147
	v_fmac_f32_e32 v194, 0x3f317217, v147
	v_mov_b32_e32 v147, v194
	v_cndmask_b32_e64 v194, 0, v216, s[40:41]
	v_sub_f32_e32 v147, v147, v194
	v_cndmask_b32_e64 v147, v151, v147, s[8:9]
	v_mul_f32_e32 v151, 0x3fb8aa3b, v168
	v_exp_f32_e32 v151, v151
	s_nop 0
	v_fma_f32 v151, v167, v151, v131
	v_cmp_gt_f32_e64 s[40:41], s97, v151
	s_nop 1
	v_cndmask_b32_e64 v194, 0, 32, s[40:41]
	v_ldexp_f32 v151, v151, v194
	v_log_f32_e32 v151, v151
	s_nop 0
	v_mul_f32_e32 v194, 0x3f317217, v151
	v_fma_f32 v194, v151, s52, -v194
	v_fmac_f32_e32 v194, 0x3377d1cf, v151
	v_fmac_f32_e32 v194, 0x3f317217, v151
	v_mov_b32_e32 v151, v194
	v_cndmask_b32_e64 v194, 0, v216, s[40:41]
	v_sub_f32_e32 v151, v151, v194
	v_cndmask_b32_e32 v151, v168, v151, vcc
	global_store_dwordx4 v[170:171], v[144:147], off offset:512
	global_store_dwordx4 v[170:171], v[148:151], off offset:528
	s_nop 1
	v_add_u32_e32 v148, 0x90, v166
	v_ashrrev_i32_e32 v149, 31, v148
	v_lshlrev_b64 v[144:145], 6, v[148:149]
	v_lshl_add_u64 v[144:145], v[160:161], 0, v[144:145]
	s_nop 0
	s_waitcnt lgkmcnt(0)
	s_nop 3
	s_nop 0
	s_nop 1
	s_waitcnt lgkmcnt(0)
	s_nop 1
	s_waitcnt lgkmcnt(0)
; __device__ __forceinline__ float silu_f(float x) { return x * __builtin_amdgcn_rcpf(1.f + __expf(-x)); }
; __device__ __forceinline__ v4u pack8(const f32x4 a, const f32x4 b) { v4u w; w.x = cvt_pk_bf16(a[0], a[1]); w.y = cvt_pk_bf16(a[2], a[3]); w.z = cvt_pk_bf16(b[0], b[1]); w.w = cvt_pk_bf16(b[2], b[3]); return w; }
;     __device__ __forceinline__ void operator()(const f32x4 (&acc)[2][2][4][2], const pg8::Unit& u, int wr, int wc, int fr, int fq) const {
;     ...
;         if (grp == 0) { WIN_LOOP( _Pragma("unroll") for (int i = 0; i < 4; ++i) { a[i] = silu_f(a[i]); b[i] = silu_f(b[i]); } *(v4u*)(QO + (size_t)row * DM + c) = pack8(a, b); ) }
;         else if (grp == 3) { WIN_LOOP( _Pragma("unroll") for (int i = 0; i < 4; ++i) { a[i] = silu_f(a[i]); b[i] = silu_f(b[i]); } *(v4u*)(GH + (size_t)row * 512 + c) = pack8(a, b); ) }
;         else if (grp == 1) {
;             f32x4 l0[2], l1[2];
; #pragma unroll
;             for (int bj = 0; bj < 2; ++bj) { l0[bj] = *(const f32x4*)(lb + cb + bj * 128); l1[bj] = *(const f32x4*)(lb + cb + bj * 128 + 4); }
;             WIN_LOOP( _Pragma("unroll") for (int i = 0; i < 4; ++i) { const float s0 = fminf(a[i], 0.f) - __logf(1.f + __expf(-fabsf(a[i]))), s1 = fminf(b[i], 0.f) - __logf(1.f + __expf(-fabsf(b[i]))); const float la = l0[bj][i], lbv = l1[bj][i];
;                     a[i] = la > 0.f ? __logf(la + (1.f - la) * __expf(s0)) : s0; b[i] = lbv > 0.f ? __logf(lbv + (1.f - lbv) * __expf(s1)) : s1; }
;                 *(f32x4*)(LF + (size_t)row * 512 + c) = a; *(f32x4*)(LF + (size_t)row * 512 + c + 4) = b; __builtin_amdgcn_sched_barrier(0); ) }
	s_nop 1
	v_mov_b32_e32 v168, v240
	v_lshlrev_b64 v[144:145], 11, v[148:149]
	v_lshl_add_u64 v[170:171], s[50:51], 0, v[144:145]
	v_lshl_add_u64 v[170:171], v[170:171], 0, v[192:193]
	v_pk_mul_f32 v[148:149], v[20:21], v[168:169] op_sel_hi:[1,0]
	v_pk_mul_f32 v[144:145], v[16:17], v[168:169] op_sel_hi:[1,0]
	v_min_f32_e32 v194, 0, v148
	v_mul_f32_e64 v148, |v148|, s57
	v_exp_f32_e32 v148, v148
	v_pk_mul_f32 v[150:151], v[22:23], v[168:169] op_sel_hi:[1,0]
	v_pk_mul_f32 v[146:147], v[18:19], v[168:169] op_sel_hi:[1,0]
	v_add_f32_e32 v148, 1.0, v148
	v_log_f32_e32 v148, v148
	s_nop 0
	v_mul_f32_e32 v195, 0x3f317217, v148
	v_fma_f32 v195, v148, s52, -v195
	v_fmac_f32_e32 v195, 0x3377d1cf, v148
	v_fmac_f32_e32 v195, 0x3f317217, v148
	v_sub_f32_e32 v148, v194, v195
	v_min_f32_e32 v194, 0, v144
	v_mul_f32_e64 v144, |v144|, s57
	v_exp_f32_e32 v144, v144
	s_nop 0
	v_add_f32_e32 v144, 1.0, v144
	v_log_f32_e32 v144, v144
	s_nop 0
	v_mul_f32_e32 v195, 0x3f317217, v144
	v_fma_f32 v195, v144, s52, -v195
	v_fmac_f32_e32 v195, 0x3377d1cf, v144
	v_fmac_f32_e32 v195, 0x3f317217, v144
	v_sub_f32_e32 v194, v194, v195
	v_mul_f32_e32 v144, 0x3fb8aa3b, v148
	v_exp_f32_e32 v144, v144
	s_nop 0
	v_fma_f32 v144, v190, v144, v140
	v_cmp_gt_f32_e64 s[40:41], s97, v144
	s_nop 1
	v_cndmask_b32_e64 v195, 0, 32, s[40:41]
	v_ldexp_f32 v144, v144, v195
	v_log_f32_e32 v144, v144
	s_nop 0
	v_mul_f32_e32 v195, 0x3f317217, v144
	v_fma_f32 v195, v144, s52, -v195
	v_fmac_f32_e32 v195, 0x3377d1cf, v144
	v_fmac_f32_e32 v195, 0x3f317217, v144
	v_mov_b32_e32 v144, v195
	v_cndmask_b32_e64 v195, 0, v216, s[40:41]
	v_sub_f32_e32 v144, v144, v195
	v_cndmask_b32_e64 v144, v148, v144, s[38:39]
	v_mul_f32_e32 v148, 0x3fb8aa3b, v194
	v_exp_f32_e32 v148, v148
	s_nop 0
	v_fma_f32 v148, v191, v148, v136
	v_cmp_gt_f32_e64 s[40:41], s97, v148
	s_nop 1
	v_cndmask_b32_e64 v195, 0, 32, s[40:41]
	v_ldexp_f32 v148, v148, v195
	v_log_f32_e32 v148, v148
	s_nop 0
	v_mul_f32_e32 v195, 0x3f317217, v148
	v_fma_f32 v195, v148, s52, -v195
	v_fmac_f32_e32 v195, 0x3377d1cf, v148
	v_fmac_f32_e32 v195, 0x3f317217, v148
	v_mov_b32_e32 v148, v195
	v_cndmask_b32_e64 v195, 0, v216, s[40:41]
	v_sub_f32_e32 v148, v148, v195
	v_cndmask_b32_e64 v148, v194, v148, s[36:37]
	v_min_f32_e32 v194, 0, v149
	v_mul_f32_e64 v149, |v149|, s57
	v_exp_f32_e32 v149, v149
	s_nop 0
	v_add_f32_e32 v149, 1.0, v149
	v_log_f32_e32 v149, v149
	s_nop 0
	v_mul_f32_e32 v195, 0x3f317217, v149
	v_fma_f32 v195, v149, s52, -v195
	v_fmac_f32_e32 v195, 0x3377d1cf, v149
	v_fmac_f32_e32 v195, 0x3f317217, v149
	v_sub_f32_e32 v149, v194, v195
	v_min_f32_e32 v194, 0, v145
	v_mul_f32_e64 v145, |v145|, s57
	v_exp_f32_e32 v145, v145
	s_nop 0
	v_add_f32_e32 v145, 1.0, v145
	v_log_f32_e32 v145, v145
	s_nop 0
	v_mul_f32_e32 v195, 0x3f317217, v145
	v_fma_f32 v195, v145, s52, -v195
	v_fmac_f32_e32 v195, 0x3377d1cf, v145
	v_fmac_f32_e32 v195, 0x3f317217, v145
	v_sub_f32_e32 v194, v194, v195
	v_mul_f32_e32 v145, 0x3fb8aa3b, v149
	v_exp_f32_e32 v145, v145
	s_nop 0
	v_fma_f32 v145, v188, v145, v141
	v_cmp_gt_f32_e64 s[40:41], s97, v145
	s_nop 1
	v_cndmask_b32_e64 v195, 0, 32, s[40:41]
	v_ldexp_f32 v145, v145, v195
	v_log_f32_e32 v145, v145
	s_nop 0
	v_mul_f32_e32 v195, 0x3f317217, v145
	v_fma_f32 v195, v145, s52, -v195
	v_fmac_f32_e32 v195, 0x3377d1cf, v145
	v_fmac_f32_e32 v195, 0x3f317217, v145
	v_mov_b32_e32 v145, v195
	v_cndmask_b32_e64 v195, 0, v216, s[40:41]
	v_sub_f32_e32 v145, v145, v195
	v_cndmask_b32_e64 v145, v149, v145, s[34:35]
	v_mul_f32_e32 v149, 0x3fb8aa3b, v194
	v_exp_f32_e32 v149, v149
	s_nop 0
	v_fma_f32 v149, v189, v149, v137
	v_cmp_gt_f32_e64 s[40:41], s97, v149
	s_nop 1
	v_cndmask_b32_e64 v195, 0, 32, s[40:41]
	v_ldexp_f32 v149, v149, v195
	v_log_f32_e32 v149, v149
	s_nop 0
	v_mul_f32_e32 v195, 0x3f317217, v149
	v_fma_f32 v195, v149, s52, -v195
	v_fmac_f32_e32 v195, 0x3377d1cf, v149
	v_fmac_f32_e32 v195, 0x3f317217, v149
	v_mov_b32_e32 v149, v195
	v_cndmask_b32_e64 v195, 0, v216, s[40:41]
	v_sub_f32_e32 v149, v149, v195
	v_cndmask_b32_e64 v149, v194, v149, s[30:31]
	v_min_f32_e32 v194, 0, v150
	v_mul_f32_e64 v150, |v150|, s57
	v_exp_f32_e32 v150, v150
	s_nop 0
	v_add_f32_e32 v150, 1.0, v150
	v_log_f32_e32 v150, v150
	s_nop 0
	v_mul_f32_e32 v195, 0x3f317217, v150
	v_fma_f32 v195, v150, s52, -v195
	v_fmac_f32_e32 v195, 0x3377d1cf, v150
	v_fmac_f32_e32 v195, 0x3f317217, v150
	v_sub_f32_e32 v150, v194, v195
	v_min_f32_e32 v194, 0, v146
	v_mul_f32_e64 v146, |v146|, s57
	v_exp_f32_e32 v146, v146
	s_nop 0
	v_add_f32_e32 v146, 1.0, v146
	v_log_f32_e32 v146, v146
	s_nop 0
	v_mul_f32_e32 v195, 0x3f317217, v146
	v_fma_f32 v195, v146, s52, -v195
	v_fmac_f32_e32 v195, 0x3377d1cf, v146
	v_fmac_f32_e32 v195, 0x3f317217, v146
	v_sub_f32_e32 v194, v194, v195
	v_mul_f32_e32 v146, 0x3fb8aa3b, v150
	v_exp_f32_e32 v146, v146
	s_nop 0
	v_fma_f32 v146, v187, v146, v142
	v_cmp_gt_f32_e64 s[40:41], s97, v146
	s_nop 1
	v_cndmask_b32_e64 v195, 0, 32, s[40:41]
	v_ldexp_f32 v146, v146, v195
	v_log_f32_e32 v146, v146
	s_nop 0
	v_mul_f32_e32 v195, 0x3f317217, v146
	v_fma_f32 v195, v146, s52, -v195
	v_fmac_f32_e32 v195, 0x3377d1cf, v146
	v_fmac_f32_e32 v195, 0x3f317217, v146
	v_mov_b32_e32 v146, v195
	v_cndmask_b32_e64 v195, 0, v216, s[40:41]
	v_sub_f32_e32 v146, v146, v195
	v_cndmask_b32_e64 v146, v150, v146, s[28:29]
	v_mul_f32_e32 v150, 0x3fb8aa3b, v194
	v_exp_f32_e32 v150, v150
	s_nop 0
	v_fma_f32 v150, v186, v150, v138
	v_cmp_gt_f32_e64 s[40:41], s97, v150
	s_nop 1
	v_cndmask_b32_e64 v195, 0, 32, s[40:41]
	v_ldexp_f32 v150, v150, v195
	v_log_f32_e32 v150, v150
	s_nop 0
	v_mul_f32_e32 v195, 0x3f317217, v150
	v_fma_f32 v195, v150, s52, -v195
	v_fmac_f32_e32 v195, 0x3377d1cf, v150
; __device__ __forceinline__ float silu_f(float x) { return x * __builtin_amdgcn_rcpf(1.f + __expf(-x)); }
; __device__ __forceinline__ v4u pack8(const f32x4 a, const f32x4 b) { v4u w; w.x = cvt_pk_bf16(a[0], a[1]); w.y = cvt_pk_bf16(a[2], a[3]); w.z = cvt_pk_bf16(b[0], b[1]); w.w = cvt_pk_bf16(b[2], b[3]); return w; }
;     __device__ __forceinline__ void operator()(const f32x4 (&acc)[2][2][4][2], const pg8::Unit& u, int wr, int wc, int fr, int fq) const {
;     ...
;         if (grp == 0) { WIN_LOOP( _Pragma("unroll") for (int i = 0; i < 4; ++i) { a[i] = silu_f(a[i]); b[i] = silu_f(b[i]); } *(v4u*)(QO + (size_t)row * DM + c) = pack8(a, b); ) }
;         else if (grp == 3) { WIN_LOOP( _Pragma("unroll") for (int i = 0; i < 4; ++i) { a[i] = silu_f(a[i]); b[i] = silu_f(b[i]); } *(v4u*)(GH + (size_t)row * 512 + c) = pack8(a, b); ) }
;         else if (grp == 1) {
;             f32x4 l0[2], l1[2];
; #pragma unroll
;             for (int bj = 0; bj < 2; ++bj) { l0[bj] = *(const f32x4*)(lb + cb + bj * 128); l1[bj] = *(const f32x4*)(lb + cb + bj * 128 + 4); }
;             WIN_LOOP( _Pragma("unroll") for (int i = 0; i < 4; ++i) { const float s0 = fminf(a[i], 0.f) - __logf(1.f + __expf(-fabsf(a[i]))), s1 = fminf(b[i], 0.f) - __logf(1.f + __expf(-fabsf(b[i]))); const float la = l0[bj][i], lbv = l1[bj][i];
;                     a[i] = la > 0.f ? __logf(la + (1.f - la) * __expf(s0)) : s0; b[i] = lbv > 0.f ? __logf(lbv + (1.f - lbv) * __expf(s1)) : s1; }
;                 *(f32x4*)(LF + (size_t)row * 512 + c) = a; *(f32x4*)(LF + (size_t)row * 512 + c + 4) = b; __builtin_amdgcn_sched_barrier(0); ) }
	v_fmac_f32_e32 v195, 0x3f317217, v150
	v_mov_b32_e32 v150, v195
	v_cndmask_b32_e64 v195, 0, v216, s[40:41]
	v_sub_f32_e32 v150, v150, v195
	v_cndmask_b32_e64 v150, v194, v150, s[26:27]
	v_min_f32_e32 v194, 0, v151
	v_mul_f32_e64 v151, |v151|, s57
	v_exp_f32_e32 v151, v151
	s_nop 0
	v_add_f32_e32 v151, 1.0, v151
	v_log_f32_e32 v151, v151
	s_nop 0
	v_mul_f32_e32 v195, 0x3f317217, v151
	v_fma_f32 v195, v151, s52, -v195
	v_fmac_f32_e32 v195, 0x3377d1cf, v151
	v_fmac_f32_e32 v195, 0x3f317217, v151
	v_sub_f32_e32 v151, v194, v195
	v_min_f32_e32 v194, 0, v147
	v_mul_f32_e64 v147, |v147|, s57
	v_exp_f32_e32 v147, v147
	s_nop 0
	v_add_f32_e32 v147, 1.0, v147
	v_log_f32_e32 v147, v147
	s_nop 0
	v_mul_f32_e32 v195, 0x3f317217, v147
	v_fma_f32 v195, v147, s52, -v195
	v_fmac_f32_e32 v195, 0x3377d1cf, v147
	v_fmac_f32_e32 v195, 0x3f317217, v147
	v_sub_f32_e32 v194, v194, v195
	v_mul_f32_e32 v147, 0x3fb8aa3b, v151
	v_exp_f32_e32 v147, v147
	s_nop 0
	v_fma_f32 v147, v185, v147, v143
	v_cmp_gt_f32_e64 s[40:41], s97, v147
	s_nop 1
	v_cndmask_b32_e64 v195, 0, 32, s[40:41]
	v_ldexp_f32 v147, v147, v195
	v_log_f32_e32 v147, v147
	s_nop 0
	v_mul_f32_e32 v195, 0x3f317217, v147
	v_fma_f32 v195, v147, s52, -v195
	v_fmac_f32_e32 v195, 0x3377d1cf, v147
	v_fmac_f32_e32 v195, 0x3f317217, v147
	v_mov_b32_e32 v147, v195
	v_cndmask_b32_e64 v195, 0, v216, s[40:41]
	v_sub_f32_e32 v147, v147, v195
	v_cndmask_b32_e64 v147, v151, v147, s[24:25]
	v_mul_f32_e32 v151, 0x3fb8aa3b, v194
	v_exp_f32_e32 v151, v151
	s_nop 0
	v_fma_f32 v151, v184, v151, v139
	v_cmp_gt_f32_e64 s[40:41], s97, v151
	s_nop 1
	v_cndmask_b32_e64 v195, 0, 32, s[40:41]
	v_ldexp_f32 v151, v151, v195
	v_log_f32_e32 v151, v151
	s_nop 0
	v_mul_f32_e32 v195, 0x3f317217, v151
	v_fma_f32 v195, v151, s52, -v195
	v_fmac_f32_e32 v195, 0x3377d1cf, v151
	v_fmac_f32_e32 v195, 0x3f317217, v151
	v_mov_b32_e32 v151, v195
	v_cndmask_b32_e64 v195, 0, v216, s[40:41]
	v_sub_f32_e32 v151, v151, v195
	v_cndmask_b32_e64 v151, v194, v151, s[22:23]
	global_store_dwordx4 v[170:171], v[144:147], off
	global_store_dwordx4 v[170:171], v[148:151], off offset:16
	s_nop 1
	v_pk_mul_f32 v[148:149], v[84:85], v[168:169] op_sel_hi:[1,0]
	v_pk_mul_f32 v[150:151], v[86:87], v[168:169] op_sel_hi:[1,0]
	v_pk_mul_f32 v[146:147], v[82:83], v[168:169] op_sel_hi:[1,0]
	v_pk_mul_f32 v[144:145], v[80:81], v[168:169] op_sel_hi:[1,0]
	v_min_f32_e32 v168, 0, v148
	v_mul_f32_e64 v148, |v148|, s57
	v_exp_f32_e32 v148, v148
	s_nop 0
	v_add_f32_e32 v148, 1.0, v148
	v_log_f32_e32 v148, v148
	s_nop 0
	v_mul_f32_e32 v194, 0x3f317217, v148
	v_fma_f32 v194, v148, s52, -v194
	v_fmac_f32_e32 v194, 0x3377d1cf, v148
	v_fmac_f32_e32 v194, 0x3f317217, v148
	v_sub_f32_e32 v148, v168, v194
	v_min_f32_e32 v168, 0, v144
	v_mul_f32_e64 v144, |v144|, s57
	v_exp_f32_e32 v144, v144
	s_nop 0
	v_add_f32_e32 v144, 1.0, v144
	v_log_f32_e32 v144, v144
	s_nop 0
	v_mul_f32_e32 v194, 0x3f317217, v144
	v_fma_f32 v194, v144, s52, -v194
	v_fmac_f32_e32 v194, 0x3377d1cf, v144
	v_fmac_f32_e32 v194, 0x3f317217, v144
	v_sub_f32_e32 v168, v168, v194
	v_mul_f32_e32 v144, 0x3fb8aa3b, v148
	v_exp_f32_e32 v144, v144
	s_nop 0
	v_fma_f32 v144, v183, v144, v132
	v_cmp_gt_f32_e64 s[40:41], s97, v144
	s_nop 1
	v_cndmask_b32_e64 v194, 0, 32, s[40:41]
	v_ldexp_f32 v144, v144, v194
	v_log_f32_e32 v144, v144
	s_nop 0
	v_mul_f32_e32 v194, 0x3f317217, v144
	v_fma_f32 v194, v144, s52, -v194
	v_fmac_f32_e32 v194, 0x3377d1cf, v144
	v_fmac_f32_e32 v194, 0x3f317217, v144
	v_mov_b32_e32 v144, v194
	v_cndmask_b32_e64 v194, 0, v216, s[40:41]
	v_sub_f32_e32 v144, v144, v194
	v_cndmask_b32_e64 v144, v148, v144, s[20:21]
	v_mul_f32_e32 v148, 0x3fb8aa3b, v168
	v_exp_f32_e32 v148, v148
	s_nop 0
	v_fma_f32 v148, v182, v148, v128
	v_cmp_gt_f32_e64 s[40:41], s97, v148
	s_nop 1
	v_cndmask_b32_e64 v194, 0, 32, s[40:41]
	v_ldexp_f32 v148, v148, v194
	v_log_f32_e32 v148, v148
	s_nop 0
	v_mul_f32_e32 v194, 0x3f317217, v148
	v_fma_f32 v194, v148, s52, -v194
	v_fmac_f32_e32 v194, 0x3377d1cf, v148
	v_fmac_f32_e32 v194, 0x3f317217, v148
	v_mov_b32_e32 v148, v194
	v_cndmask_b32_e64 v194, 0, v216, s[40:41]
	v_sub_f32_e32 v148, v148, v194
	v_cndmask_b32_e64 v148, v168, v148, s[18:19]
	v_min_f32_e32 v168, 0, v149
	v_mul_f32_e64 v149, |v149|, s57
	v_exp_f32_e32 v149, v149
	s_nop 0
	v_add_f32_e32 v149, 1.0, v149
	v_log_f32_e32 v149, v149
	s_nop 0
	v_mul_f32_e32 v194, 0x3f317217, v149
	v_fma_f32 v194, v149, s52, -v194
	v_fmac_f32_e32 v194, 0x3377d1cf, v149
	v_fmac_f32_e32 v194, 0x3f317217, v149
	v_sub_f32_e32 v149, v168, v194
	v_min_f32_e32 v168, 0, v145
	v_mul_f32_e64 v145, |v145|, s57
	v_exp_f32_e32 v145, v145
	s_nop 0
	v_add_f32_e32 v145, 1.0, v145
	v_log_f32_e32 v145, v145
	s_nop 0
	v_mul_f32_e32 v194, 0x3f317217, v145
	v_fma_f32 v194, v145, s52, -v194
	v_fmac_f32_e32 v194, 0x3377d1cf, v145
	v_fmac_f32_e32 v194, 0x3f317217, v145
	v_sub_f32_e32 v168, v168, v194
	v_mul_f32_e32 v145, 0x3fb8aa3b, v149
	v_exp_f32_e32 v145, v145
	s_nop 0
	v_fma_f32 v145, v181, v145, v133
	v_cmp_gt_f32_e64 s[40:41], s97, v145
	s_nop 1
	v_cndmask_b32_e64 v194, 0, 32, s[40:41]
	v_ldexp_f32 v145, v145, v194
	v_log_f32_e32 v145, v145
	s_nop 0
	v_mul_f32_e32 v194, 0x3f317217, v145
	v_fma_f32 v194, v145, s52, -v194
	v_fmac_f32_e32 v194, 0x3377d1cf, v145
	v_fmac_f32_e32 v194, 0x3f317217, v145
	v_mov_b32_e32 v145, v194
	v_cndmask_b32_e64 v194, 0, v216, s[40:41]
	v_sub_f32_e32 v145, v145, v194
	v_cndmask_b32_e64 v145, v149, v145, s[16:17]
	v_mul_f32_e32 v149, 0x3fb8aa3b, v168
	v_exp_f32_e32 v149, v149
	s_nop 0
	v_fma_f32 v149, v180, v149, v129
	v_cmp_gt_f32_e64 s[40:41], s97, v149
	s_nop 1
	v_cndmask_b32_e64 v194, 0, 32, s[40:41]
	v_ldexp_f32 v149, v149, v194
; __device__ __forceinline__ float silu_f(float x) { return x * __builtin_amdgcn_rcpf(1.f + __expf(-x)); }
; __device__ __forceinline__ v4u pack8(const f32x4 a, const f32x4 b) { v4u w; w.x = cvt_pk_bf16(a[0], a[1]); w.y = cvt_pk_bf16(a[2], a[3]); w.z = cvt_pk_bf16(b[0], b[1]); w.w = cvt_pk_bf16(b[2], b[3]); return w; }
;     __device__ __forceinline__ void operator()(const f32x4 (&acc)[2][2][4][2], const pg8::Unit& u, int wr, int wc, int fr, int fq) const {
;     ...
;         if (grp == 0) { WIN_LOOP( _Pragma("unroll") for (int i = 0; i < 4; ++i) { a[i] = silu_f(a[i]); b[i] = silu_f(b[i]); } *(v4u*)(QO + (size_t)row * DM + c) = pack8(a, b); ) }
;         else if (grp == 3) { WIN_LOOP( _Pragma("unroll") for (int i = 0; i < 4; ++i) { a[i] = silu_f(a[i]); b[i] = silu_f(b[i]); } *(v4u*)(GH + (size_t)row * 512 + c) = pack8(a, b); ) }
;         else if (grp == 1) {
;             f32x4 l0[2], l1[2];
; #pragma unroll
;             for (int bj = 0; bj < 2; ++bj) { l0[bj] = *(const f32x4*)(lb + cb + bj * 128); l1[bj] = *(const f32x4*)(lb + cb + bj * 128 + 4); }
;             WIN_LOOP( _Pragma("unroll") for (int i = 0; i < 4; ++i) { const float s0 = fminf(a[i], 0.f) - __logf(1.f + __expf(-fabsf(a[i]))), s1 = fminf(b[i], 0.f) - __logf(1.f + __expf(-fabsf(b[i]))); const float la = l0[bj][i], lbv = l1[bj][i];
;                     a[i] = la > 0.f ? __logf(la + (1.f - la) * __expf(s0)) : s0; b[i] = lbv > 0.f ? __logf(lbv + (1.f - lbv) * __expf(s1)) : s1; }
;                 *(f32x4*)(LF + (size_t)row * 512 + c) = a; *(f32x4*)(LF + (size_t)row * 512 + c + 4) = b; __builtin_amdgcn_sched_barrier(0); ) }
	v_log_f32_e32 v149, v149
	s_nop 0
	v_mul_f32_e32 v194, 0x3f317217, v149
	v_fma_f32 v194, v149, s52, -v194
	v_fmac_f32_e32 v194, 0x3377d1cf, v149
	v_fmac_f32_e32 v194, 0x3f317217, v149
	v_mov_b32_e32 v149, v194
	v_cndmask_b32_e64 v194, 0, v216, s[40:41]
	v_sub_f32_e32 v149, v149, v194
	v_cndmask_b32_e64 v149, v168, v149, s[14:15]
	v_min_f32_e32 v168, 0, v150
	v_mul_f32_e64 v150, |v150|, s57
	v_exp_f32_e32 v150, v150
	s_nop 0
	v_add_f32_e32 v150, 1.0, v150
	v_log_f32_e32 v150, v150
	s_nop 0
	v_mul_f32_e32 v194, 0x3f317217, v150
	v_fma_f32 v194, v150, s52, -v194
	v_fmac_f32_e32 v194, 0x3377d1cf, v150
	v_fmac_f32_e32 v194, 0x3f317217, v150
	v_sub_f32_e32 v150, v168, v194
	v_min_f32_e32 v168, 0, v146
	v_mul_f32_e64 v146, |v146|, s57
	v_exp_f32_e32 v146, v146
	s_nop 0
	v_add_f32_e32 v146, 1.0, v146
	v_log_f32_e32 v146, v146
	s_nop 0
	v_mul_f32_e32 v194, 0x3f317217, v146
	v_fma_f32 v194, v146, s52, -v194
	v_fmac_f32_e32 v194, 0x3377d1cf, v146
	v_fmac_f32_e32 v194, 0x3f317217, v146
	v_sub_f32_e32 v168, v168, v194
	v_mul_f32_e32 v146, 0x3fb8aa3b, v150
	v_exp_f32_e32 v146, v146
	s_nop 0
	v_fma_f32 v146, v179, v146, v134
	v_cmp_gt_f32_e64 s[40:41], s97, v146
	s_nop 1
	v_cndmask_b32_e64 v194, 0, 32, s[40:41]
	v_ldexp_f32 v146, v146, v194
	v_log_f32_e32 v146, v146
	s_nop 0
	v_mul_f32_e32 v194, 0x3f317217, v146
	v_fma_f32 v194, v146, s52, -v194
	v_fmac_f32_e32 v194, 0x3377d1cf, v146
	v_fmac_f32_e32 v194, 0x3f317217, v146
	v_mov_b32_e32 v146, v194
	v_cndmask_b32_e64 v194, 0, v216, s[40:41]
	v_sub_f32_e32 v146, v146, v194
	v_cndmask_b32_e64 v146, v150, v146, s[12:13]
	v_mul_f32_e32 v150, 0x3fb8aa3b, v168
	v_exp_f32_e32 v150, v150
	s_nop 0
	v_fma_f32 v150, v178, v150, v130
	v_cmp_gt_f32_e64 s[40:41], s97, v150
	s_nop 1
	v_cndmask_b32_e64 v194, 0, 32, s[40:41]
	v_ldexp_f32 v150, v150, v194
	v_log_f32_e32 v150, v150
	s_nop 0
	v_mul_f32_e32 v194, 0x3f317217, v150
	v_fma_f32 v194, v150, s52, -v194
	v_fmac_f32_e32 v194, 0x3377d1cf, v150
	v_fmac_f32_e32 v194, 0x3f317217, v150
	v_mov_b32_e32 v150, v194
	v_cndmask_b32_e64 v194, 0, v216, s[40:41]
	v_sub_f32_e32 v150, v150, v194
	v_cndmask_b32_e64 v150, v168, v150, s[10:11]
	v_min_f32_e32 v168, 0, v151
	v_mul_f32_e64 v151, |v151|, s57
	v_exp_f32_e32 v151, v151
	s_nop 0
	v_add_f32_e32 v151, 1.0, v151
	v_log_f32_e32 v151, v151
	s_nop 0
	v_mul_f32_e32 v194, 0x3f317217, v151
	v_fma_f32 v194, v151, s52, -v194
	v_fmac_f32_e32 v194, 0x3377d1cf, v151
	v_fmac_f32_e32 v194, 0x3f317217, v151
	v_sub_f32_e32 v151, v168, v194
	v_min_f32_e32 v168, 0, v147
	v_mul_f32_e64 v147, |v147|, s57
	v_exp_f32_e32 v147, v147
	s_nop 0
	v_add_f32_e32 v147, 1.0, v147
	v_log_f32_e32 v147, v147
	s_nop 0
	v_mul_f32_e32 v194, 0x3f317217, v147
	v_fma_f32 v194, v147, s52, -v194
	v_fmac_f32_e32 v194, 0x3377d1cf, v147
	v_fmac_f32_e32 v194, 0x3f317217, v147
	v_sub_f32_e32 v168, v168, v194
	v_mul_f32_e32 v147, 0x3fb8aa3b, v151
	v_exp_f32_e32 v147, v147
	s_nop 0
	v_fma_f32 v147, v177, v147, v135
	v_cmp_gt_f32_e64 s[40:41], s97, v147
	s_nop 1
	v_cndmask_b32_e64 v194, 0, 32, s[40:41]
	v_ldexp_f32 v147, v147, v194
	v_log_f32_e32 v147, v147
	s_nop 0
	v_mul_f32_e32 v194, 0x3f317217, v147
	v_fma_f32 v194, v147, s52, -v194
	v_fmac_f32_e32 v194, 0x3377d1cf, v147
	v_fmac_f32_e32 v194, 0x3f317217, v147
	v_mov_b32_e32 v147, v194
	v_cndmask_b32_e64 v194, 0, v216, s[40:41]
	v_sub_f32_e32 v147, v147, v194
	v_cndmask_b32_e64 v147, v151, v147, s[8:9]
	v_mul_f32_e32 v151, 0x3fb8aa3b, v168
	v_exp_f32_e32 v151, v151
	s_nop 0
	v_fma_f32 v151, v167, v151, v131
	v_cmp_gt_f32_e64 s[40:41], s97, v151
	s_nop 1
	v_cndmask_b32_e64 v194, 0, 32, s[40:41]
	v_ldexp_f32 v151, v151, v194
	v_log_f32_e32 v151, v151
	s_nop 0
	v_mul_f32_e32 v194, 0x3f317217, v151
	v_fma_f32 v194, v151, s52, -v194
	v_fmac_f32_e32 v194, 0x3377d1cf, v151
	v_fmac_f32_e32 v194, 0x3f317217, v151
	v_mov_b32_e32 v151, v194
	v_cndmask_b32_e64 v194, 0, v216, s[40:41]
	v_sub_f32_e32 v151, v151, v194
	v_cndmask_b32_e32 v151, v168, v151, vcc
	global_store_dwordx4 v[170:171], v[144:147], off offset:512
	global_store_dwordx4 v[170:171], v[148:151], off offset:528
	s_nop 1
	v_add_u32_e32 v148, 0xa0, v166
	v_ashrrev_i32_e32 v149, 31, v148
	v_lshlrev_b64 v[144:145], 6, v[148:149]
	v_lshl_add_u64 v[144:145], v[160:161], 0, v[144:145]
	s_nop 0
	s_waitcnt lgkmcnt(0)
	s_nop 3
	s_nop 0
	s_nop 1
	s_waitcnt lgkmcnt(0)
	s_nop 1
	s_waitcnt lgkmcnt(0)
; __device__ __forceinline__ float silu_f(float x) { return x * __builtin_amdgcn_rcpf(1.f + __expf(-x)); }
; __device__ __forceinline__ v4u pack8(const f32x4 a, const f32x4 b) { v4u w; w.x = cvt_pk_bf16(a[0], a[1]); w.y = cvt_pk_bf16(a[2], a[3]); w.z = cvt_pk_bf16(b[0], b[1]); w.w = cvt_pk_bf16(b[2], b[3]); return w; }
;     __device__ __forceinline__ void operator()(const f32x4 (&acc)[2][2][4][2], const pg8::Unit& u, int wr, int wc, int fr, int fq) const {
;     ...
;         if (grp == 0) { WIN_LOOP( _Pragma("unroll") for (int i = 0; i < 4; ++i) { a[i] = silu_f(a[i]); b[i] = silu_f(b[i]); } *(v4u*)(QO + (size_t)row * DM + c) = pack8(a, b); ) }
;         else if (grp == 3) { WIN_LOOP( _Pragma("unroll") for (int i = 0; i < 4; ++i) { a[i] = silu_f(a[i]); b[i] = silu_f(b[i]); } *(v4u*)(GH + (size_t)row * 512 + c) = pack8(a, b); ) }
;         else if (grp == 1) {
;             f32x4 l0[2], l1[2];
; #pragma unroll
;             for (int bj = 0; bj < 2; ++bj) { l0[bj] = *(const f32x4*)(lb + cb + bj * 128); l1[bj] = *(const f32x4*)(lb + cb + bj * 128 + 4); }
;             WIN_LOOP( _Pragma("unroll") for (int i = 0; i < 4; ++i) { const float s0 = fminf(a[i], 0.f) - __logf(1.f + __expf(-fabsf(a[i]))), s1 = fminf(b[i], 0.f) - __logf(1.f + __expf(-fabsf(b[i]))); const float la = l0[bj][i], lbv = l1[bj][i];
;                     a[i] = la > 0.f ? __logf(la + (1.f - la) * __expf(s0)) : s0; b[i] = lbv > 0.f ? __logf(lbv + (1.f - lbv) * __expf(s1)) : s1; }
;                 *(f32x4*)(LF + (size_t)row * 512 + c) = a; *(f32x4*)(LF + (size_t)row * 512 + c + 4) = b; __builtin_amdgcn_sched_barrier(0); ) }
	s_nop 1
	v_mov_b32_e32 v168, v241
	v_lshlrev_b64 v[144:145], 11, v[148:149]
	v_lshl_add_u64 v[170:171], s[50:51], 0, v[144:145]
	v_lshl_add_u64 v[170:171], v[170:171], 0, v[192:193]
	v_pk_mul_f32 v[148:149], v[12:13], v[168:169] op_sel_hi:[1,0]
	v_pk_mul_f32 v[144:145], v[8:9], v[168:169] op_sel_hi:[1,0]
	v_min_f32_e32 v194, 0, v148
	v_mul_f32_e64 v148, |v148|, s57
	v_exp_f32_e32 v148, v148
	v_pk_mul_f32 v[150:151], v[14:15], v[168:169] op_sel_hi:[1,0]
	v_pk_mul_f32 v[146:147], v[10:11], v[168:169] op_sel_hi:[1,0]
	v_add_f32_e32 v148, 1.0, v148
	v_log_f32_e32 v148, v148
	s_nop 0
	v_mul_f32_e32 v195, 0x3f317217, v148
	v_fma_f32 v195, v148, s52, -v195
	v_fmac_f32_e32 v195, 0x3377d1cf, v148
	v_fmac_f32_e32 v195, 0x3f317217, v148
	v_sub_f32_e32 v148, v194, v195
	v_min_f32_e32 v194, 0, v144
	v_mul_f32_e64 v144, |v144|, s57
	v_exp_f32_e32 v144, v144
	s_nop 0
	v_add_f32_e32 v144, 1.0, v144
	v_log_f32_e32 v144, v144
	s_nop 0
	v_mul_f32_e32 v195, 0x3f317217, v144
	v_fma_f32 v195, v144, s52, -v195
	v_fmac_f32_e32 v195, 0x3377d1cf, v144
	v_fmac_f32_e32 v195, 0x3f317217, v144
	v_sub_f32_e32 v194, v194, v195
	v_mul_f32_e32 v144, 0x3fb8aa3b, v148
	v_exp_f32_e32 v144, v144
	s_nop 0
	v_fma_f32 v144, v190, v144, v140
	v_cmp_gt_f32_e64 s[40:41], s97, v144
	s_nop 1
	v_cndmask_b32_e64 v195, 0, 32, s[40:41]
	v_ldexp_f32 v144, v144, v195
	v_log_f32_e32 v144, v144
	s_nop 0
	v_mul_f32_e32 v195, 0x3f317217, v144
	v_fma_f32 v195, v144, s52, -v195
	v_fmac_f32_e32 v195, 0x3377d1cf, v144
	v_fmac_f32_e32 v195, 0x3f317217, v144
	v_mov_b32_e32 v144, v195
	v_cndmask_b32_e64 v195, 0, v216, s[40:41]
	v_sub_f32_e32 v144, v144, v195
	v_cndmask_b32_e64 v144, v148, v144, s[38:39]
	v_mul_f32_e32 v148, 0x3fb8aa3b, v194
	v_exp_f32_e32 v148, v148
	s_nop 0
	v_fma_f32 v148, v191, v148, v136
	v_cmp_gt_f32_e64 s[40:41], s97, v148
	s_nop 1
	v_cndmask_b32_e64 v195, 0, 32, s[40:41]
	v_ldexp_f32 v148, v148, v195
	v_log_f32_e32 v148, v148
	s_nop 0
	v_mul_f32_e32 v195, 0x3f317217, v148
	v_fma_f32 v195, v148, s52, -v195
	v_fmac_f32_e32 v195, 0x3377d1cf, v148
	v_fmac_f32_e32 v195, 0x3f317217, v148
	v_mov_b32_e32 v148, v195
	v_cndmask_b32_e64 v195, 0, v216, s[40:41]
	v_sub_f32_e32 v148, v148, v195
	v_cndmask_b32_e64 v148, v194, v148, s[36:37]
	v_min_f32_e32 v194, 0, v149
	v_mul_f32_e64 v149, |v149|, s57
	v_exp_f32_e32 v149, v149
	s_nop 0
	v_add_f32_e32 v149, 1.0, v149
	v_log_f32_e32 v149, v149
	s_nop 0
	v_mul_f32_e32 v195, 0x3f317217, v149
	v_fma_f32 v195, v149, s52, -v195
	v_fmac_f32_e32 v195, 0x3377d1cf, v149
	v_fmac_f32_e32 v195, 0x3f317217, v149
	v_sub_f32_e32 v149, v194, v195
	v_min_f32_e32 v194, 0, v145
	v_mul_f32_e64 v145, |v145|, s57
	v_exp_f32_e32 v145, v145
	s_nop 0
	v_add_f32_e32 v145, 1.0, v145
	v_log_f32_e32 v145, v145
	s_nop 0
	v_mul_f32_e32 v195, 0x3f317217, v145
	v_fma_f32 v195, v145, s52, -v195
	v_fmac_f32_e32 v195, 0x3377d1cf, v145
	v_fmac_f32_e32 v195, 0x3f317217, v145
	v_sub_f32_e32 v194, v194, v195
	v_mul_f32_e32 v145, 0x3fb8aa3b, v149
	v_exp_f32_e32 v145, v145
	s_nop 0
	v_fma_f32 v145, v188, v145, v141
	v_cmp_gt_f32_e64 s[40:41], s97, v145
	s_nop 1
	v_cndmask_b32_e64 v195, 0, 32, s[40:41]
	v_ldexp_f32 v145, v145, v195
	v_log_f32_e32 v145, v145
	s_nop 0
	v_mul_f32_e32 v195, 0x3f317217, v145
	v_fma_f32 v195, v145, s52, -v195
	v_fmac_f32_e32 v195, 0x3377d1cf, v145
	v_fmac_f32_e32 v195, 0x3f317217, v145
	v_mov_b32_e32 v145, v195
	v_cndmask_b32_e64 v195, 0, v216, s[40:41]
	v_sub_f32_e32 v145, v145, v195
	v_cndmask_b32_e64 v145, v149, v145, s[34:35]
	v_mul_f32_e32 v149, 0x3fb8aa3b, v194
	v_exp_f32_e32 v149, v149
	s_nop 0
	v_fma_f32 v149, v189, v149, v137
	v_cmp_gt_f32_e64 s[40:41], s97, v149
	s_nop 1
	v_cndmask_b32_e64 v195, 0, 32, s[40:41]
	v_ldexp_f32 v149, v149, v195
	v_log_f32_e32 v149, v149
	s_nop 0
	v_mul_f32_e32 v195, 0x3f317217, v149
	v_fma_f32 v195, v149, s52, -v195
	v_fmac_f32_e32 v195, 0x3377d1cf, v149
	v_fmac_f32_e32 v195, 0x3f317217, v149
	v_mov_b32_e32 v149, v195
	v_cndmask_b32_e64 v195, 0, v216, s[40:41]
	v_sub_f32_e32 v149, v149, v195
	v_cndmask_b32_e64 v149, v194, v149, s[30:31]
	v_min_f32_e32 v194, 0, v150
	v_mul_f32_e64 v150, |v150|, s57
	v_exp_f32_e32 v150, v150
	s_nop 0
	v_add_f32_e32 v150, 1.0, v150
	v_log_f32_e32 v150, v150
	s_nop 0
	v_mul_f32_e32 v195, 0x3f317217, v150
	v_fma_f32 v195, v150, s52, -v195
	v_fmac_f32_e32 v195, 0x3377d1cf, v150
	v_fmac_f32_e32 v195, 0x3f317217, v150
	v_sub_f32_e32 v150, v194, v195
	v_min_f32_e32 v194, 0, v146
	v_mul_f32_e64 v146, |v146|, s57
	v_exp_f32_e32 v146, v146
	s_nop 0
	v_add_f32_e32 v146, 1.0, v146
	v_log_f32_e32 v146, v146
	s_nop 0
	v_mul_f32_e32 v195, 0x3f317217, v146
	v_fma_f32 v195, v146, s52, -v195
	v_fmac_f32_e32 v195, 0x3377d1cf, v146
	v_fmac_f32_e32 v195, 0x3f317217, v146
	v_sub_f32_e32 v194, v194, v195
	v_mul_f32_e32 v146, 0x3fb8aa3b, v150
	v_exp_f32_e32 v146, v146
	s_nop 0
	v_fma_f32 v146, v187, v146, v142
	v_cmp_gt_f32_e64 s[40:41], s97, v146
	s_nop 1
	v_cndmask_b32_e64 v195, 0, 32, s[40:41]
	v_ldexp_f32 v146, v146, v195
	v_log_f32_e32 v146, v146
	s_nop 0
	v_mul_f32_e32 v195, 0x3f317217, v146
	v_fma_f32 v195, v146, s52, -v195
	v_fmac_f32_e32 v195, 0x3377d1cf, v146
	v_fmac_f32_e32 v195, 0x3f317217, v146
	v_mov_b32_e32 v146, v195
	v_cndmask_b32_e64 v195, 0, v216, s[40:41]
	v_sub_f32_e32 v146, v146, v195
	v_cndmask_b32_e64 v146, v150, v146, s[28:29]
	v_mul_f32_e32 v150, 0x3fb8aa3b, v194
	v_exp_f32_e32 v150, v150
	s_nop 0
	v_fma_f32 v150, v186, v150, v138
	v_cmp_gt_f32_e64 s[40:41], s97, v150
	s_nop 1
	v_cndmask_b32_e64 v195, 0, 32, s[40:41]
	v_ldexp_f32 v150, v150, v195
	v_log_f32_e32 v150, v150
	s_nop 0
	v_mul_f32_e32 v195, 0x3f317217, v150
	v_fma_f32 v195, v150, s52, -v195
	v_fmac_f32_e32 v195, 0x3377d1cf, v150
; __device__ __forceinline__ float silu_f(float x) { return x * __builtin_amdgcn_rcpf(1.f + __expf(-x)); }
; __device__ __forceinline__ v4u pack8(const f32x4 a, const f32x4 b) { v4u w; w.x = cvt_pk_bf16(a[0], a[1]); w.y = cvt_pk_bf16(a[2], a[3]); w.z = cvt_pk_bf16(b[0], b[1]); w.w = cvt_pk_bf16(b[2], b[3]); return w; }
;     __device__ __forceinline__ void operator()(const f32x4 (&acc)[2][2][4][2], const pg8::Unit& u, int wr, int wc, int fr, int fq) const {
;     ...
;         if (grp == 0) { WIN_LOOP( _Pragma("unroll") for (int i = 0; i < 4; ++i) { a[i] = silu_f(a[i]); b[i] = silu_f(b[i]); } *(v4u*)(QO + (size_t)row * DM + c) = pack8(a, b); ) }
;         else if (grp == 3) { WIN_LOOP( _Pragma("unroll") for (int i = 0; i < 4; ++i) { a[i] = silu_f(a[i]); b[i] = silu_f(b[i]); } *(v4u*)(GH + (size_t)row * 512 + c) = pack8(a, b); ) }
;         else if (grp == 1) {
;             f32x4 l0[2], l1[2];
; #pragma unroll
;             for (int bj = 0; bj < 2; ++bj) { l0[bj] = *(const f32x4*)(lb + cb + bj * 128); l1[bj] = *(const f32x4*)(lb + cb + bj * 128 + 4); }
;             WIN_LOOP( _Pragma("unroll") for (int i = 0; i < 4; ++i) { const float s0 = fminf(a[i], 0.f) - __logf(1.f + __expf(-fabsf(a[i]))), s1 = fminf(b[i], 0.f) - __logf(1.f + __expf(-fabsf(b[i]))); const float la = l0[bj][i], lbv = l1[bj][i];
;                     a[i] = la > 0.f ? __logf(la + (1.f - la) * __expf(s0)) : s0; b[i] = lbv > 0.f ? __logf(lbv + (1.f - lbv) * __expf(s1)) : s1; }
;                 *(f32x4*)(LF + (size_t)row * 512 + c) = a; *(f32x4*)(LF + (size_t)row * 512 + c + 4) = b; __builtin_amdgcn_sched_barrier(0); ) }
	v_fmac_f32_e32 v195, 0x3f317217, v150
	v_mov_b32_e32 v150, v195
	v_cndmask_b32_e64 v195, 0, v216, s[40:41]
	v_sub_f32_e32 v150, v150, v195
	v_cndmask_b32_e64 v150, v194, v150, s[26:27]
	v_min_f32_e32 v194, 0, v151
	v_mul_f32_e64 v151, |v151|, s57
	v_exp_f32_e32 v151, v151
	s_nop 0
	v_add_f32_e32 v151, 1.0, v151
	v_log_f32_e32 v151, v151
	s_nop 0
	v_mul_f32_e32 v195, 0x3f317217, v151
	v_fma_f32 v195, v151, s52, -v195
	v_fmac_f32_e32 v195, 0x3377d1cf, v151
	v_fmac_f32_e32 v195, 0x3f317217, v151
	v_sub_f32_e32 v151, v194, v195
	v_min_f32_e32 v194, 0, v147
	v_mul_f32_e64 v147, |v147|, s57
	v_exp_f32_e32 v147, v147
	s_nop 0
	v_add_f32_e32 v147, 1.0, v147
	v_log_f32_e32 v147, v147
	s_nop 0
	v_mul_f32_e32 v195, 0x3f317217, v147
	v_fma_f32 v195, v147, s52, -v195
	v_fmac_f32_e32 v195, 0x3377d1cf, v147
	v_fmac_f32_e32 v195, 0x3f317217, v147
	v_sub_f32_e32 v194, v194, v195
	v_mul_f32_e32 v147, 0x3fb8aa3b, v151
	v_exp_f32_e32 v147, v147
	s_nop 0
	v_fma_f32 v147, v185, v147, v143
	v_cmp_gt_f32_e64 s[40:41], s97, v147
	s_nop 1
	v_cndmask_b32_e64 v195, 0, 32, s[40:41]
	v_ldexp_f32 v147, v147, v195
	v_log_f32_e32 v147, v147
	s_nop 0
	v_mul_f32_e32 v195, 0x3f317217, v147
	v_fma_f32 v195, v147, s52, -v195
	v_fmac_f32_e32 v195, 0x3377d1cf, v147
	v_fmac_f32_e32 v195, 0x3f317217, v147
	v_mov_b32_e32 v147, v195
	v_cndmask_b32_e64 v195, 0, v216, s[40:41]
	v_sub_f32_e32 v147, v147, v195
	v_cndmask_b32_e64 v147, v151, v147, s[24:25]
	v_mul_f32_e32 v151, 0x3fb8aa3b, v194
	v_exp_f32_e32 v151, v151
	s_nop 0
	v_fma_f32 v151, v184, v151, v139
	v_cmp_gt_f32_e64 s[40:41], s97, v151
	s_nop 1
	v_cndmask_b32_e64 v195, 0, 32, s[40:41]
	v_ldexp_f32 v151, v151, v195
	v_log_f32_e32 v151, v151
	s_nop 0
	v_mul_f32_e32 v195, 0x3f317217, v151
	v_fma_f32 v195, v151, s52, -v195
	v_fmac_f32_e32 v195, 0x3377d1cf, v151
	v_fmac_f32_e32 v195, 0x3f317217, v151
	v_mov_b32_e32 v151, v195
	v_cndmask_b32_e64 v195, 0, v216, s[40:41]
	v_sub_f32_e32 v151, v151, v195
	v_cndmask_b32_e64 v151, v194, v151, s[22:23]
	global_store_dwordx4 v[170:171], v[144:147], off
	global_store_dwordx4 v[170:171], v[148:151], off offset:16
	s_nop 1
	v_pk_mul_f32 v[148:149], v[76:77], v[168:169] op_sel_hi:[1,0]
	v_pk_mul_f32 v[150:151], v[78:79], v[168:169] op_sel_hi:[1,0]
	v_pk_mul_f32 v[146:147], v[74:75], v[168:169] op_sel_hi:[1,0]
	v_pk_mul_f32 v[144:145], v[72:73], v[168:169] op_sel_hi:[1,0]
	v_min_f32_e32 v168, 0, v148
	v_mul_f32_e64 v148, |v148|, s57
	v_exp_f32_e32 v148, v148
	s_nop 0
	v_add_f32_e32 v148, 1.0, v148
	v_log_f32_e32 v148, v148
	s_nop 0
	v_mul_f32_e32 v194, 0x3f317217, v148
	v_fma_f32 v194, v148, s52, -v194
	v_fmac_f32_e32 v194, 0x3377d1cf, v148
	v_fmac_f32_e32 v194, 0x3f317217, v148
	v_sub_f32_e32 v148, v168, v194
	v_min_f32_e32 v168, 0, v144
	v_mul_f32_e64 v144, |v144|, s57
	v_exp_f32_e32 v144, v144
	s_nop 0
	v_add_f32_e32 v144, 1.0, v144
	v_log_f32_e32 v144, v144
	s_nop 0
	v_mul_f32_e32 v194, 0x3f317217, v144
	v_fma_f32 v194, v144, s52, -v194
	v_fmac_f32_e32 v194, 0x3377d1cf, v144
	v_fmac_f32_e32 v194, 0x3f317217, v144
	v_sub_f32_e32 v168, v168, v194
	v_mul_f32_e32 v144, 0x3fb8aa3b, v148
	v_exp_f32_e32 v144, v144
	s_nop 0
	v_fma_f32 v144, v183, v144, v132
	v_cmp_gt_f32_e64 s[40:41], s97, v144
	s_nop 1
	v_cndmask_b32_e64 v194, 0, 32, s[40:41]
	v_ldexp_f32 v144, v144, v194
	v_log_f32_e32 v144, v144
	s_nop 0
	v_mul_f32_e32 v194, 0x3f317217, v144
	v_fma_f32 v194, v144, s52, -v194
	v_fmac_f32_e32 v194, 0x3377d1cf, v144
	v_fmac_f32_e32 v194, 0x3f317217, v144
	v_mov_b32_e32 v144, v194
	v_cndmask_b32_e64 v194, 0, v216, s[40:41]
	v_sub_f32_e32 v144, v144, v194
	v_cndmask_b32_e64 v144, v148, v144, s[20:21]
	v_mul_f32_e32 v148, 0x3fb8aa3b, v168
	v_exp_f32_e32 v148, v148
	s_nop 0
	v_fma_f32 v148, v182, v148, v128
	v_cmp_gt_f32_e64 s[40:41], s97, v148
	s_nop 1
	v_cndmask_b32_e64 v194, 0, 32, s[40:41]
	v_ldexp_f32 v148, v148, v194
	v_log_f32_e32 v148, v148
	s_nop 0
	v_mul_f32_e32 v194, 0x3f317217, v148
	v_fma_f32 v194, v148, s52, -v194
	v_fmac_f32_e32 v194, 0x3377d1cf, v148
	v_fmac_f32_e32 v194, 0x3f317217, v148
	v_mov_b32_e32 v148, v194
	v_cndmask_b32_e64 v194, 0, v216, s[40:41]
	v_sub_f32_e32 v148, v148, v194
	v_cndmask_b32_e64 v148, v168, v148, s[18:19]
	v_min_f32_e32 v168, 0, v149
	v_mul_f32_e64 v149, |v149|, s57
	v_exp_f32_e32 v149, v149
	s_nop 0
	v_add_f32_e32 v149, 1.0, v149
	v_log_f32_e32 v149, v149
	s_nop 0
	v_mul_f32_e32 v194, 0x3f317217, v149
	v_fma_f32 v194, v149, s52, -v194
	v_fmac_f32_e32 v194, 0x3377d1cf, v149
	v_fmac_f32_e32 v194, 0x3f317217, v149
	v_sub_f32_e32 v149, v168, v194
	v_min_f32_e32 v168, 0, v145
	v_mul_f32_e64 v145, |v145|, s57
	v_exp_f32_e32 v145, v145
	s_nop 0
	v_add_f32_e32 v145, 1.0, v145
	v_log_f32_e32 v145, v145
	s_nop 0
	v_mul_f32_e32 v194, 0x3f317217, v145
	v_fma_f32 v194, v145, s52, -v194
	v_fmac_f32_e32 v194, 0x3377d1cf, v145
	v_fmac_f32_e32 v194, 0x3f317217, v145
	v_sub_f32_e32 v168, v168, v194
	v_mul_f32_e32 v145, 0x3fb8aa3b, v149
	v_exp_f32_e32 v145, v145
	s_nop 0
	v_fma_f32 v145, v181, v145, v133
	v_cmp_gt_f32_e64 s[40:41], s97, v145
	s_nop 1
	v_cndmask_b32_e64 v194, 0, 32, s[40:41]
	v_ldexp_f32 v145, v145, v194
	v_log_f32_e32 v145, v145
	s_nop 0
	v_mul_f32_e32 v194, 0x3f317217, v145
	v_fma_f32 v194, v145, s52, -v194
	v_fmac_f32_e32 v194, 0x3377d1cf, v145
	v_fmac_f32_e32 v194, 0x3f317217, v145
	v_mov_b32_e32 v145, v194
	v_cndmask_b32_e64 v194, 0, v216, s[40:41]
	v_sub_f32_e32 v145, v145, v194
	v_cndmask_b32_e64 v145, v149, v145, s[16:17]
	v_mul_f32_e32 v149, 0x3fb8aa3b, v168
	v_exp_f32_e32 v149, v149
	s_nop 0
	v_fma_f32 v149, v180, v149, v129
	v_cmp_gt_f32_e64 s[40:41], s97, v149
	s_nop 1
	v_cndmask_b32_e64 v194, 0, 32, s[40:41]
	v_ldexp_f32 v149, v149, v194
; __device__ __forceinline__ float silu_f(float x) { return x * __builtin_amdgcn_rcpf(1.f + __expf(-x)); }
; __device__ __forceinline__ v4u pack8(const f32x4 a, const f32x4 b) { v4u w; w.x = cvt_pk_bf16(a[0], a[1]); w.y = cvt_pk_bf16(a[2], a[3]); w.z = cvt_pk_bf16(b[0], b[1]); w.w = cvt_pk_bf16(b[2], b[3]); return w; }
;     __device__ __forceinline__ void operator()(const f32x4 (&acc)[2][2][4][2], const pg8::Unit& u, int wr, int wc, int fr, int fq) const {
;     ...
;         if (grp == 0) { WIN_LOOP( _Pragma("unroll") for (int i = 0; i < 4; ++i) { a[i] = silu_f(a[i]); b[i] = silu_f(b[i]); } *(v4u*)(QO + (size_t)row * DM + c) = pack8(a, b); ) }
;         else if (grp == 3) { WIN_LOOP( _Pragma("unroll") for (int i = 0; i < 4; ++i) { a[i] = silu_f(a[i]); b[i] = silu_f(b[i]); } *(v4u*)(GH + (size_t)row * 512 + c) = pack8(a, b); ) }
;         else if (grp == 1) {
;             f32x4 l0[2], l1[2];
; #pragma unroll
;             for (int bj = 0; bj < 2; ++bj) { l0[bj] = *(const f32x4*)(lb + cb + bj * 128); l1[bj] = *(const f32x4*)(lb + cb + bj * 128 + 4); }
;             WIN_LOOP( _Pragma("unroll") for (int i = 0; i < 4; ++i) { const float s0 = fminf(a[i], 0.f) - __logf(1.f + __expf(-fabsf(a[i]))), s1 = fminf(b[i], 0.f) - __logf(1.f + __expf(-fabsf(b[i]))); const float la = l0[bj][i], lbv = l1[bj][i];
;                     a[i] = la > 0.f ? __logf(la + (1.f - la) * __expf(s0)) : s0; b[i] = lbv > 0.f ? __logf(lbv + (1.f - lbv) * __expf(s1)) : s1; }
;                 *(f32x4*)(LF + (size_t)row * 512 + c) = a; *(f32x4*)(LF + (size_t)row * 512 + c + 4) = b; __builtin_amdgcn_sched_barrier(0); ) }
	v_log_f32_e32 v149, v149
	s_nop 0
	v_mul_f32_e32 v194, 0x3f317217, v149
	v_fma_f32 v194, v149, s52, -v194
	v_fmac_f32_e32 v194, 0x3377d1cf, v149
	v_fmac_f32_e32 v194, 0x3f317217, v149
	v_mov_b32_e32 v149, v194
	v_cndmask_b32_e64 v194, 0, v216, s[40:41]
	v_sub_f32_e32 v149, v149, v194
	v_cndmask_b32_e64 v149, v168, v149, s[14:15]
	v_min_f32_e32 v168, 0, v150
	v_mul_f32_e64 v150, |v150|, s57
	v_exp_f32_e32 v150, v150
	s_nop 0
	v_add_f32_e32 v150, 1.0, v150
	v_log_f32_e32 v150, v150
	s_nop 0
	v_mul_f32_e32 v194, 0x3f317217, v150
	v_fma_f32 v194, v150, s52, -v194
	v_fmac_f32_e32 v194, 0x3377d1cf, v150
	v_fmac_f32_e32 v194, 0x3f317217, v150
	v_sub_f32_e32 v150, v168, v194
	v_min_f32_e32 v168, 0, v146
	v_mul_f32_e64 v146, |v146|, s57
	v_exp_f32_e32 v146, v146
	s_nop 0
	v_add_f32_e32 v146, 1.0, v146
	v_log_f32_e32 v146, v146
	s_nop 0
	v_mul_f32_e32 v194, 0x3f317217, v146
	v_fma_f32 v194, v146, s52, -v194
	v_fmac_f32_e32 v194, 0x3377d1cf, v146
	v_fmac_f32_e32 v194, 0x3f317217, v146
	v_sub_f32_e32 v168, v168, v194
	v_mul_f32_e32 v146, 0x3fb8aa3b, v150
	v_exp_f32_e32 v146, v146
	s_nop 0
	v_fma_f32 v146, v179, v146, v134
	v_cmp_gt_f32_e64 s[40:41], s97, v146
	s_nop 1
	v_cndmask_b32_e64 v194, 0, 32, s[40:41]
	v_ldexp_f32 v146, v146, v194
	v_log_f32_e32 v146, v146
	s_nop 0
	v_mul_f32_e32 v194, 0x3f317217, v146
	v_fma_f32 v194, v146, s52, -v194
	v_fmac_f32_e32 v194, 0x3377d1cf, v146
	v_fmac_f32_e32 v194, 0x3f317217, v146
	v_mov_b32_e32 v146, v194
	v_cndmask_b32_e64 v194, 0, v216, s[40:41]
	v_sub_f32_e32 v146, v146, v194
	v_cndmask_b32_e64 v146, v150, v146, s[12:13]
	v_mul_f32_e32 v150, 0x3fb8aa3b, v168
	v_exp_f32_e32 v150, v150
	s_nop 0
	v_fma_f32 v150, v178, v150, v130
	v_cmp_gt_f32_e64 s[40:41], s97, v150
	s_nop 1
	v_cndmask_b32_e64 v194, 0, 32, s[40:41]
	v_ldexp_f32 v150, v150, v194
	v_log_f32_e32 v150, v150
	s_nop 0
	v_mul_f32_e32 v194, 0x3f317217, v150
	v_fma_f32 v194, v150, s52, -v194
	v_fmac_f32_e32 v194, 0x3377d1cf, v150
	v_fmac_f32_e32 v194, 0x3f317217, v150
	v_mov_b32_e32 v150, v194
	v_cndmask_b32_e64 v194, 0, v216, s[40:41]
	v_sub_f32_e32 v150, v150, v194
	v_cndmask_b32_e64 v150, v168, v150, s[10:11]
	v_min_f32_e32 v168, 0, v151
	v_mul_f32_e64 v151, |v151|, s57
	v_exp_f32_e32 v151, v151
	s_nop 0
	v_add_f32_e32 v151, 1.0, v151
	v_log_f32_e32 v151, v151
	s_nop 0
	v_mul_f32_e32 v194, 0x3f317217, v151
	v_fma_f32 v194, v151, s52, -v194
	v_fmac_f32_e32 v194, 0x3377d1cf, v151
	v_fmac_f32_e32 v194, 0x3f317217, v151
	v_sub_f32_e32 v151, v168, v194
	v_min_f32_e32 v168, 0, v147
	v_mul_f32_e64 v147, |v147|, s57
	v_exp_f32_e32 v147, v147
	s_nop 0
	v_add_f32_e32 v147, 1.0, v147
	v_log_f32_e32 v147, v147
	s_nop 0
	v_mul_f32_e32 v194, 0x3f317217, v147
	v_fma_f32 v194, v147, s52, -v194
	v_fmac_f32_e32 v194, 0x3377d1cf, v147
	v_fmac_f32_e32 v194, 0x3f317217, v147
	v_sub_f32_e32 v168, v168, v194
	v_mul_f32_e32 v147, 0x3fb8aa3b, v151
	v_exp_f32_e32 v147, v147
	s_nop 0
	v_fma_f32 v147, v177, v147, v135
	v_cmp_gt_f32_e64 s[40:41], s97, v147
	s_nop 1
	v_cndmask_b32_e64 v194, 0, 32, s[40:41]
	v_ldexp_f32 v147, v147, v194
	v_log_f32_e32 v147, v147
	s_nop 0
	v_mul_f32_e32 v194, 0x3f317217, v147
	v_fma_f32 v194, v147, s52, -v194
	v_fmac_f32_e32 v194, 0x3377d1cf, v147
	v_fmac_f32_e32 v194, 0x3f317217, v147
	v_mov_b32_e32 v147, v194
	v_cndmask_b32_e64 v194, 0, v216, s[40:41]
	v_sub_f32_e32 v147, v147, v194
	v_cndmask_b32_e64 v147, v151, v147, s[8:9]
	v_mul_f32_e32 v151, 0x3fb8aa3b, v168
	v_exp_f32_e32 v151, v151
	s_nop 0
	v_fma_f32 v151, v167, v151, v131
	v_cmp_gt_f32_e64 s[40:41], s97, v151
	s_nop 1
	v_cndmask_b32_e64 v194, 0, 32, s[40:41]
	v_ldexp_f32 v151, v151, v194
	v_log_f32_e32 v151, v151
	s_nop 0
	v_mul_f32_e32 v194, 0x3f317217, v151
	v_fma_f32 v194, v151, s52, -v194
	v_fmac_f32_e32 v194, 0x3377d1cf, v151
	v_fmac_f32_e32 v194, 0x3f317217, v151
	v_mov_b32_e32 v151, v194
	v_cndmask_b32_e64 v194, 0, v216, s[40:41]
	v_sub_f32_e32 v151, v151, v194
	v_cndmask_b32_e32 v151, v168, v151, vcc
	global_store_dwordx4 v[170:171], v[144:147], off offset:512
	global_store_dwordx4 v[170:171], v[148:151], off offset:528
	s_nop 1
	v_add_u32_e32 v148, 0xb0, v166
	v_ashrrev_i32_e32 v149, 31, v148
	v_lshlrev_b64 v[144:145], 6, v[148:149]
	v_lshl_add_u64 v[144:145], v[160:161], 0, v[144:145]
	s_nop 0
	s_waitcnt lgkmcnt(0)
	s_nop 3
	v_lshlrev_b64 v[146:147], 11, v[148:149]
	s_nop 1
	v_lshl_add_u64 v[146:147], s[50:51], 0, v[146:147]
	v_lshl_add_u64 v[146:147], v[146:147], 0, v[192:193]
	s_waitcnt lgkmcnt(0)
	s_nop 1
	s_waitcnt lgkmcnt(0)
; __device__ __forceinline__ float silu_f(float x) { return x * __builtin_amdgcn_rcpf(1.f + __expf(-x)); }
; __device__ __forceinline__ v4u pack8(const f32x4 a, const f32x4 b) { v4u w; w.x = cvt_pk_bf16(a[0], a[1]); w.y = cvt_pk_bf16(a[2], a[3]); w.z = cvt_pk_bf16(b[0], b[1]); w.w = cvt_pk_bf16(b[2], b[3]); return w; }
;     __device__ __forceinline__ void operator()(const f32x4 (&acc)[2][2][4][2], const pg8::Unit& u, int wr, int wc, int fr, int fq) const {
;     ...
;         if (grp == 0) { WIN_LOOP( _Pragma("unroll") for (int i = 0; i < 4; ++i) { a[i] = silu_f(a[i]); b[i] = silu_f(b[i]); } *(v4u*)(QO + (size_t)row * DM + c) = pack8(a, b); ) }
;         else if (grp == 3) { WIN_LOOP( _Pragma("unroll") for (int i = 0; i < 4; ++i) { a[i] = silu_f(a[i]); b[i] = silu_f(b[i]); } *(v4u*)(GH + (size_t)row * 512 + c) = pack8(a, b); ) }
;         else if (grp == 1) {
;             f32x4 l0[2], l1[2];
; #pragma unroll
;             for (int bj = 0; bj < 2; ++bj) { l0[bj] = *(const f32x4*)(lb + cb + bj * 128); l1[bj] = *(const f32x4*)(lb + cb + bj * 128 + 4); }
;             WIN_LOOP( _Pragma("unroll") for (int i = 0; i < 4; ++i) { const float s0 = fminf(a[i], 0.f) - __logf(1.f + __expf(-fabsf(a[i]))), s1 = fminf(b[i], 0.f) - __logf(1.f + __expf(-fabsf(b[i]))); const float la = l0[bj][i], lbv = l1[bj][i];
;                     a[i] = la > 0.f ? __logf(la + (1.f - la) * __expf(s0)) : s0; b[i] = lbv > 0.f ? __logf(lbv + (1.f - lbv) * __expf(s1)) : s1; }
;                 *(f32x4*)(LF + (size_t)row * 512 + c) = a; *(f32x4*)(LF + (size_t)row * 512 + c + 4) = b; __builtin_amdgcn_sched_barrier(0); ) }
	s_nop 1
	v_mov_b32_e32 v144, v245
	s_nop 0
	v_pk_mul_f32 v[170:171], v[4:5], v[144:145] op_sel_hi:[1,0]
	v_pk_mul_f32 v[150:151], v[6:7], v[144:145] op_sel_hi:[1,0]
	v_pk_mul_f32 v[148:149], v[2:3], v[144:145] op_sel_hi:[1,0]
	v_pk_mul_f32 v[168:169], v[0:1], v[144:145] op_sel_hi:[1,0]
	v_min_f32_e32 v145, 0, v170
	v_mul_f32_e64 v170, |v170|, s57
	v_exp_f32_e32 v170, v170
	s_nop 0
	v_add_f32_e32 v170, 1.0, v170
	v_log_f32_e32 v170, v170
	s_nop 0
	v_mul_f32_e32 v194, 0x3f317217, v170
	v_fma_f32 v194, v170, s52, -v194
	v_fmac_f32_e32 v194, 0x3377d1cf, v170
	v_fmac_f32_e32 v194, 0x3f317217, v170
	v_sub_f32_e32 v145, v145, v194
	v_min_f32_e32 v170, 0, v168
	v_mul_f32_e64 v168, |v168|, s57
	v_exp_f32_e32 v168, v168
	s_nop 0
	v_add_f32_e32 v168, 1.0, v168
	v_log_f32_e32 v168, v168
	s_nop 0
	v_mul_f32_e32 v194, 0x3f317217, v168
	v_fma_f32 v194, v168, s52, -v194
	v_fmac_f32_e32 v194, 0x3377d1cf, v168
	v_fmac_f32_e32 v194, 0x3f317217, v168
	v_sub_f32_e32 v168, v170, v194
	v_mul_f32_e32 v170, 0x3fb8aa3b, v145
	v_exp_f32_e32 v170, v170
	s_nop 0
	v_fma_f32 v140, v190, v170, v140
	v_cmp_gt_f32_e64 s[40:41], s97, v140
	s_nop 1
	v_cndmask_b32_e64 v170, 0, 32, s[40:41]
	v_ldexp_f32 v140, v140, v170
	v_log_f32_e32 v140, v140
	s_nop 0
	v_mul_f32_e32 v170, 0x3f317217, v140
	v_fma_f32 v170, v140, s52, -v170
	v_fmac_f32_e32 v170, 0x3377d1cf, v140
	v_fmac_f32_e32 v170, 0x3f317217, v140
	v_mov_b32_e32 v140, v170
	v_cndmask_b32_e64 v170, 0, v216, s[40:41]
	v_sub_f32_e32 v140, v140, v170
	v_cndmask_b32_e64 v140, v145, v140, s[38:39]
	v_mul_f32_e32 v145, 0x3fb8aa3b, v168
	v_exp_f32_e32 v145, v145
	v_readlane_b32 s42, v255, 57
	v_readlane_b32 s43, v255, 58
	v_fma_f32 v136, v191, v145, v136
	v_cmp_gt_f32_e64 s[38:39], s97, v136
	s_nop 1
	v_cndmask_b32_e64 v145, 0, 32, s[38:39]
	v_ldexp_f32 v136, v136, v145
	v_log_f32_e32 v136, v136
	s_nop 0
	v_mul_f32_e32 v145, 0x3f317217, v136
	v_fma_f32 v145, v136, s52, -v145
	v_fmac_f32_e32 v145, 0x3377d1cf, v136
	v_fmac_f32_e32 v145, 0x3f317217, v136
	v_mov_b32_e32 v136, v145
	v_cndmask_b32_e64 v145, 0, v216, s[38:39]
	v_sub_f32_e32 v136, v136, v145
	v_cndmask_b32_e64 v136, v168, v136, s[36:37]
	v_mul_f32_e64 v168, |v171|, s57
	v_exp_f32_e32 v168, v168
	v_min_f32_e32 v145, 0, v171
	s_mov_b32 s40, s2
	v_add_f32_e32 v168, 1.0, v168
	v_log_f32_e32 v168, v168
	s_nop 0
	v_mul_f32_e32 v170, 0x3f317217, v168
	v_fma_f32 v170, v168, s52, -v170
	v_fmac_f32_e32 v170, 0x3377d1cf, v168
	v_fmac_f32_e32 v170, 0x3f317217, v168
	v_sub_f32_e32 v145, v145, v170
	v_min_f32_e32 v168, 0, v169
	v_mul_f32_e64 v169, |v169|, s57
	v_exp_f32_e32 v169, v169
	s_nop 0
	v_add_f32_e32 v169, 1.0, v169
	v_log_f32_e32 v169, v169
	s_nop 0
	v_mul_f32_e32 v170, 0x3f317217, v169
	v_fma_f32 v170, v169, s52, -v170
	v_fmac_f32_e32 v170, 0x3377d1cf, v169
	v_fmac_f32_e32 v170, 0x3f317217, v169
	v_sub_f32_e32 v168, v168, v170
	v_mul_f32_e32 v169, 0x3fb8aa3b, v145
	v_exp_f32_e32 v169, v169
	s_nop 0
	v_fma_f32 v141, v188, v169, v141
	v_cmp_gt_f32_e64 s[36:37], s97, v141
	s_nop 1
	v_cndmask_b32_e64 v169, 0, 32, s[36:37]
	v_ldexp_f32 v141, v141, v169
	v_log_f32_e32 v141, v141
	s_nop 0
	v_mul_f32_e32 v169, 0x3f317217, v141
	v_fma_f32 v169, v141, s52, -v169
	v_fmac_f32_e32 v169, 0x3377d1cf, v141
	v_fmac_f32_e32 v169, 0x3f317217, v141
	v_mov_b32_e32 v141, v169
	v_cndmask_b32_e64 v169, 0, v216, s[36:37]
	v_sub_f32_e32 v141, v141, v169
	v_cndmask_b32_e64 v141, v145, v141, s[34:35]
	v_mul_f32_e32 v145, 0x3fb8aa3b, v168
	v_exp_f32_e32 v145, v145
	v_readlane_b32 s38, v255, 53
	v_readlane_b32 s39, v255, 54
	v_fma_f32 v137, v189, v145, v137
	v_cmp_gt_f32_e64 s[34:35], s97, v137
	s_nop 1
	v_cndmask_b32_e64 v145, 0, 32, s[34:35]
	v_ldexp_f32 v137, v137, v145
	v_log_f32_e32 v137, v137
	s_nop 0
	v_mul_f32_e32 v145, 0x3f317217, v137
	v_fma_f32 v145, v137, s52, -v145
	v_fmac_f32_e32 v145, 0x3377d1cf, v137
	v_fmac_f32_e32 v145, 0x3f317217, v137
	v_mov_b32_e32 v137, v145
	v_cndmask_b32_e64 v145, 0, v216, s[34:35]
	v_sub_f32_e32 v137, v137, v145
	v_min_f32_e32 v145, 0, v150
	v_mul_f32_e64 v150, |v150|, s57
	v_exp_f32_e32 v150, v150
	v_cndmask_b32_e64 v137, v168, v137, s[30:31]
	v_readlane_b32 s36, v255, 51
	v_readlane_b32 s37, v255, 52
	v_add_f32_e32 v150, 1.0, v150
	v_log_f32_e32 v150, v150
	s_nop 0
	v_mul_f32_e32 v168, 0x3f317217, v150
	v_fma_f32 v168, v150, s52, -v168
	v_fmac_f32_e32 v168, 0x3377d1cf, v150
	v_fmac_f32_e32 v168, 0x3f317217, v150
	v_sub_f32_e32 v145, v145, v168
	v_min_f32_e32 v150, 0, v148
	v_mul_f32_e64 v148, |v148|, s57
	v_exp_f32_e32 v148, v148
	s_nop 0
	v_add_f32_e32 v148, 1.0, v148
	v_log_f32_e32 v148, v148
	s_nop 0
	v_mul_f32_e32 v168, 0x3f317217, v148
	v_fma_f32 v168, v148, s52, -v168
	v_fmac_f32_e32 v168, 0x3377d1cf, v148
	v_fmac_f32_e32 v168, 0x3f317217, v148
	v_sub_f32_e32 v148, v150, v168
	v_mul_f32_e32 v150, 0x3fb8aa3b, v145
	v_exp_f32_e32 v150, v150
	s_nop 0
	v_fma_f32 v142, v187, v150, v142
	v_cmp_gt_f32_e64 s[30:31], s97, v142
	s_nop 1
	v_cndmask_b32_e64 v150, 0, 32, s[30:31]
	v_ldexp_f32 v142, v142, v150
	v_log_f32_e32 v142, v142
	s_nop 0
	v_mul_f32_e32 v150, 0x3f317217, v142
	v_fma_f32 v150, v142, s52, -v150
	v_fmac_f32_e32 v150, 0x3377d1cf, v142
	v_fmac_f32_e32 v150, 0x3f317217, v142
	v_mov_b32_e32 v142, v150
	v_cndmask_b32_e64 v150, 0, v216, s[30:31]
	v_sub_f32_e32 v142, v142, v150
	v_cndmask_b32_e64 v142, v145, v142, s[28:29]
	v_mul_f32_e32 v145, 0x3fb8aa3b, v148
	v_exp_f32_e32 v145, v145
	v_readlane_b32 s34, v255, 49
	v_readlane_b32 s35, v255, 50
	v_fma_f32 v138, v186, v145, v138
	v_cmp_gt_f32_e64 s[28:29], s97, v138
	s_nop 1
	v_cndmask_b32_e64 v145, 0, 32, s[28:29]
	v_ldexp_f32 v138, v138, v145
	v_log_f32_e32 v138, v138
	s_nop 0
	v_mul_f32_e32 v145, 0x3f317217, v138
; __device__ __forceinline__ float silu_f(float x) { return x * __builtin_amdgcn_rcpf(1.f + __expf(-x)); }
; __device__ __forceinline__ v4u pack8(const f32x4 a, const f32x4 b) { v4u w; w.x = cvt_pk_bf16(a[0], a[1]); w.y = cvt_pk_bf16(a[2], a[3]); w.z = cvt_pk_bf16(b[0], b[1]); w.w = cvt_pk_bf16(b[2], b[3]); return w; }
;     __device__ __forceinline__ void operator()(const f32x4 (&acc)[2][2][4][2], const pg8::Unit& u, int wr, int wc, int fr, int fq) const {
;     ...
;         if (grp == 0) { WIN_LOOP( _Pragma("unroll") for (int i = 0; i < 4; ++i) { a[i] = silu_f(a[i]); b[i] = silu_f(b[i]); } *(v4u*)(QO + (size_t)row * DM + c) = pack8(a, b); ) }
;         else if (grp == 3) { WIN_LOOP( _Pragma("unroll") for (int i = 0; i < 4; ++i) { a[i] = silu_f(a[i]); b[i] = silu_f(b[i]); } *(v4u*)(GH + (size_t)row * 512 + c) = pack8(a, b); ) }
;         else if (grp == 1) {
;             f32x4 l0[2], l1[2];
; #pragma unroll
;             for (int bj = 0; bj < 2; ++bj) { l0[bj] = *(const f32x4*)(lb + cb + bj * 128); l1[bj] = *(const f32x4*)(lb + cb + bj * 128 + 4); }
;             WIN_LOOP( _Pragma("unroll") for (int i = 0; i < 4; ++i) { const float s0 = fminf(a[i], 0.f) - __logf(1.f + __expf(-fabsf(a[i]))), s1 = fminf(b[i], 0.f) - __logf(1.f + __expf(-fabsf(b[i]))); const float la = l0[bj][i], lbv = l1[bj][i];
;                     a[i] = la > 0.f ? __logf(la + (1.f - la) * __expf(s0)) : s0; b[i] = lbv > 0.f ? __logf(lbv + (1.f - lbv) * __expf(s1)) : s1; }
;                 *(f32x4*)(LF + (size_t)row * 512 + c) = a; *(f32x4*)(LF + (size_t)row * 512 + c + 4) = b; __builtin_amdgcn_sched_barrier(0); ) }
	v_fma_f32 v145, v138, s52, -v145
	v_fmac_f32_e32 v145, 0x3377d1cf, v138
	v_fmac_f32_e32 v145, 0x3f317217, v138
	v_mov_b32_e32 v138, v145
	v_cndmask_b32_e64 v145, 0, v216, s[28:29]
	v_sub_f32_e32 v138, v138, v145
	v_cndmask_b32_e64 v138, v148, v138, s[26:27]
	v_mul_f32_e64 v148, |v151|, s57
	v_exp_f32_e32 v148, v148
	v_min_f32_e32 v145, 0, v151
	v_readlane_b32 s30, v255, 47
	v_readlane_b32 s31, v255, 48
	v_add_f32_e32 v148, 1.0, v148
	v_log_f32_e32 v148, v148
	s_nop 0
	v_mul_f32_e32 v150, 0x3f317217, v148
	v_fma_f32 v150, v148, s52, -v150
	v_fmac_f32_e32 v150, 0x3377d1cf, v148
	v_fmac_f32_e32 v150, 0x3f317217, v148
	v_sub_f32_e32 v145, v145, v150
	v_min_f32_e32 v148, 0, v149
	v_mul_f32_e64 v149, |v149|, s57
	v_exp_f32_e32 v149, v149
	s_nop 0
	v_add_f32_e32 v149, 1.0, v149
	v_log_f32_e32 v149, v149
	s_nop 0
	v_mul_f32_e32 v150, 0x3f317217, v149
	v_fma_f32 v150, v149, s52, -v150
	v_fmac_f32_e32 v150, 0x3377d1cf, v149
	v_fmac_f32_e32 v150, 0x3f317217, v149
	v_sub_f32_e32 v148, v148, v150
	v_mul_f32_e32 v149, 0x3fb8aa3b, v145
	v_exp_f32_e32 v149, v149
	s_nop 0
	v_fmac_f32_e32 v143, v185, v149
	v_cmp_gt_f32_e64 s[26:27], s97, v143
	s_nop 1
	v_cndmask_b32_e64 v149, 0, 32, s[26:27]
	v_ldexp_f32 v143, v143, v149
	v_log_f32_e32 v143, v143
	s_nop 0
	v_mul_f32_e32 v149, 0x3f317217, v143
	v_fma_f32 v149, v143, s52, -v149
	v_fmac_f32_e32 v149, 0x3377d1cf, v143
	v_fmac_f32_e32 v149, 0x3f317217, v143
	v_cmp_lt_f32_e64 s[28:29], |v143|, s53
	s_nop 1
	v_cndmask_b32_e64 v143, v143, v149, s[28:29]
	v_cndmask_b32_e64 v149, 0, v216, s[26:27]
	v_sub_f32_e32 v143, v143, v149
	v_cndmask_b32_e64 v143, v145, v143, s[24:25]
	v_mul_f32_e32 v145, 0x3fb8aa3b, v148
	v_exp_f32_e32 v145, v145
	s_mov_b32 s29, s91
	s_mov_b32 s28, s95
	v_fmac_f32_e32 v139, v184, v145
	v_cmp_gt_f32_e64 s[24:25], s97, v139
	s_nop 1
	v_cndmask_b32_e64 v145, 0, 32, s[24:25]
	v_ldexp_f32 v139, v139, v145
	v_log_f32_e32 v139, v139
	s_nop 0
	v_mul_f32_e32 v145, 0x3f317217, v139
	v_fma_f32 v145, v139, s52, -v145
	v_fmac_f32_e32 v145, 0x3377d1cf, v139
	v_fmac_f32_e32 v145, 0x3f317217, v139
	v_cmp_lt_f32_e64 s[26:27], |v139|, s53
	s_nop 1
	v_cndmask_b32_e64 v139, v139, v145, s[26:27]
	v_cndmask_b32_e64 v145, 0, v216, s[24:25]
	v_readlane_b32 s27, v255, 56
	v_readlane_b32 s26, v255, 31
	v_sub_f32_e32 v139, v139, v145
	v_cndmask_b32_e64 v139, v148, v139, s[22:23]
	global_store_dwordx4 v[146:147], v[140:143], off
	global_store_dwordx4 v[146:147], v[136:139], off offset:16
	s_nop 0
	v_pk_mul_f32 v[142:143], v[68:69], v[144:145] op_sel_hi:[1,0]
	v_pk_mul_f32 v[138:139], v[70:71], v[144:145] op_sel_hi:[1,0]
	v_pk_mul_f32 v[136:137], v[66:67], v[144:145] op_sel_hi:[1,0]
	v_pk_mul_f32 v[140:141], v[64:65], v[144:145] op_sel_hi:[1,0]
	v_min_f32_e32 v144, 0, v142
	v_mul_f32_e64 v142, |v142|, s57
	v_exp_f32_e32 v142, v142
	s_nop 0
	v_add_f32_e32 v142, 1.0, v142
	v_log_f32_e32 v142, v142
	s_nop 0
	v_mul_f32_e32 v145, 0x3f317217, v142
	v_fma_f32 v145, v142, s52, -v145
	v_fmac_f32_e32 v145, 0x3377d1cf, v142
	v_fmac_f32_e32 v145, 0x3f317217, v142
	v_sub_f32_e32 v142, v144, v145
	v_min_f32_e32 v144, 0, v140
	v_mul_f32_e64 v140, |v140|, s57
	v_exp_f32_e32 v140, v140
	s_nop 0
	v_add_f32_e32 v140, 1.0, v140
	v_log_f32_e32 v140, v140
	s_nop 0
	v_mul_f32_e32 v145, 0x3f317217, v140
	v_fma_f32 v145, v140, s52, -v145
	v_fmac_f32_e32 v145, 0x3377d1cf, v140
	v_fmac_f32_e32 v145, 0x3f317217, v140
	v_sub_f32_e32 v140, v144, v145
	v_mul_f32_e32 v144, 0x3fb8aa3b, v142
	v_exp_f32_e32 v144, v144
	s_nop 0
	v_fma_f32 v132, v183, v144, v132
	v_cmp_gt_f32_e64 s[22:23], s97, v132
	s_nop 1
	v_cndmask_b32_e64 v144, 0, 32, s[22:23]
	v_ldexp_f32 v132, v132, v144
	v_log_f32_e32 v132, v132
	s_nop 0
	v_mul_f32_e32 v144, 0x3f317217, v132
	v_fma_f32 v144, v132, s52, -v144
	v_fmac_f32_e32 v144, 0x3377d1cf, v132
	v_fmac_f32_e32 v144, 0x3f317217, v132
	v_mov_b32_e32 v132, v144
	v_cndmask_b32_e64 v144, 0, v216, s[22:23]
	v_sub_f32_e32 v132, v132, v144
	v_cndmask_b32_e64 v132, v142, v132, s[20:21]
	v_mul_f32_e32 v142, 0x3fb8aa3b, v140
	v_exp_f32_e32 v142, v142
	s_nop 0
	v_fma_f32 v128, v182, v142, v128
	v_cmp_gt_f32_e64 s[20:21], s97, v128
	s_nop 1
	v_cndmask_b32_e64 v142, 0, 32, s[20:21]
	v_ldexp_f32 v128, v128, v142
	v_log_f32_e32 v128, v128
	s_nop 0
	v_mul_f32_e32 v142, 0x3f317217, v128
	v_fma_f32 v142, v128, s52, -v142
	v_fmac_f32_e32 v142, 0x3377d1cf, v128
	v_fmac_f32_e32 v142, 0x3f317217, v128
	v_mov_b32_e32 v128, v142
	v_cndmask_b32_e64 v142, 0, v216, s[20:21]
	v_sub_f32_e32 v128, v128, v142
	v_mul_f32_e64 v142, |v143|, s57
	v_exp_f32_e32 v142, v142
	v_cndmask_b32_e64 v128, v140, v128, s[18:19]
	v_min_f32_e32 v140, 0, v143
	v_readlane_b32 s23, v255, 55
	v_add_f32_e32 v142, 1.0, v142
	v_log_f32_e32 v142, v142
	s_nop 0
	v_mul_f32_e32 v143, 0x3f317217, v142
	v_fma_f32 v143, v142, s52, -v143
	v_fmac_f32_e32 v143, 0x3377d1cf, v142
	v_fmac_f32_e32 v143, 0x3f317217, v142
	v_sub_f32_e32 v140, v140, v143
	v_min_f32_e32 v142, 0, v141
	v_mul_f32_e64 v141, |v141|, s57
	v_exp_f32_e32 v141, v141
	s_nop 0
	v_add_f32_e32 v141, 1.0, v141
	v_log_f32_e32 v141, v141
	s_nop 0
	v_mul_f32_e32 v143, 0x3f317217, v141
	v_fma_f32 v143, v141, s52, -v143
	v_fmac_f32_e32 v143, 0x3377d1cf, v141
	v_fmac_f32_e32 v143, 0x3f317217, v141
	v_sub_f32_e32 v141, v142, v143
	v_mul_f32_e32 v142, 0x3fb8aa3b, v140
	v_exp_f32_e32 v142, v142
	s_nop 0
	v_fma_f32 v133, v181, v142, v133
	v_cmp_gt_f32_e64 s[18:19], s97, v133
	s_nop 1
	v_cndmask_b32_e64 v142, 0, 32, s[18:19]
	v_ldexp_f32 v133, v133, v142
	v_log_f32_e32 v133, v133
	s_nop 0
	v_mul_f32_e32 v142, 0x3f317217, v133
	v_fma_f32 v142, v133, s52, -v142
	v_fmac_f32_e32 v142, 0x3377d1cf, v133
	v_fmac_f32_e32 v142, 0x3f317217, v133
; __device__ __forceinline__ float silu_f(float x) { return x * __builtin_amdgcn_rcpf(1.f + __expf(-x)); }
; __device__ __forceinline__ v4u pack8(const f32x4 a, const f32x4 b) { v4u w; w.x = cvt_pk_bf16(a[0], a[1]); w.y = cvt_pk_bf16(a[2], a[3]); w.z = cvt_pk_bf16(b[0], b[1]); w.w = cvt_pk_bf16(b[2], b[3]); return w; }
;     __device__ __forceinline__ void operator()(const f32x4 (&acc)[2][2][4][2], const pg8::Unit& u, int wr, int wc, int fr, int fq) const {
;     ...
;         if (grp == 0) { WIN_LOOP( _Pragma("unroll") for (int i = 0; i < 4; ++i) { a[i] = silu_f(a[i]); b[i] = silu_f(b[i]); } *(v4u*)(QO + (size_t)row * DM + c) = pack8(a, b); ) }
;         else if (grp == 3) { WIN_LOOP( _Pragma("unroll") for (int i = 0; i < 4; ++i) { a[i] = silu_f(a[i]); b[i] = silu_f(b[i]); } *(v4u*)(GH + (size_t)row * 512 + c) = pack8(a, b); ) }
;         else if (grp == 1) {
;             f32x4 l0[2], l1[2];
; #pragma unroll
;             for (int bj = 0; bj < 2; ++bj) { l0[bj] = *(const f32x4*)(lb + cb + bj * 128); l1[bj] = *(const f32x4*)(lb + cb + bj * 128 + 4); }
;             WIN_LOOP( _Pragma("unroll") for (int i = 0; i < 4; ++i) { const float s0 = fminf(a[i], 0.f) - __logf(1.f + __expf(-fabsf(a[i]))), s1 = fminf(b[i], 0.f) - __logf(1.f + __expf(-fabsf(b[i]))); const float la = l0[bj][i], lbv = l1[bj][i];
;                     a[i] = la > 0.f ? __logf(la + (1.f - la) * __expf(s0)) : s0; b[i] = lbv > 0.f ? __logf(lbv + (1.f - lbv) * __expf(s1)) : s1; }
;                 *(f32x4*)(LF + (size_t)row * 512 + c) = a; *(f32x4*)(LF + (size_t)row * 512 + c + 4) = b; __builtin_amdgcn_sched_barrier(0); ) }
	v_mov_b32_e32 v133, v142
	v_cndmask_b32_e64 v142, 0, v216, s[18:19]
	v_sub_f32_e32 v133, v133, v142
	v_cndmask_b32_e64 v133, v140, v133, s[16:17]
	v_mul_f32_e32 v140, 0x3fb8aa3b, v141
	v_exp_f32_e32 v140, v140
	s_nop 0
	v_fma_f32 v129, v180, v140, v129
	v_cmp_gt_f32_e64 s[16:17], s97, v129
	s_nop 1
	v_cndmask_b32_e64 v140, 0, 32, s[16:17]
	v_ldexp_f32 v129, v129, v140
	v_log_f32_e32 v129, v129
	s_nop 0
	v_mul_f32_e32 v140, 0x3f317217, v129
	v_fma_f32 v140, v129, s52, -v140
	v_fmac_f32_e32 v140, 0x3377d1cf, v129
	v_fmac_f32_e32 v140, 0x3f317217, v129
	v_mov_b32_e32 v129, v140
	v_cndmask_b32_e64 v140, 0, v216, s[16:17]
	v_sub_f32_e32 v129, v129, v140
	v_min_f32_e32 v140, 0, v138
	v_mul_f32_e64 v138, |v138|, s57
	v_exp_f32_e32 v138, v138
	v_cndmask_b32_e64 v129, v141, v129, s[14:15]
	v_add_f32_e32 v138, 1.0, v138
	v_log_f32_e32 v138, v138
	s_nop 0
	v_mul_f32_e32 v141, 0x3f317217, v138
	v_fma_f32 v141, v138, s52, -v141
	v_fmac_f32_e32 v141, 0x3377d1cf, v138
	v_fmac_f32_e32 v141, 0x3f317217, v138
	v_sub_f32_e32 v138, v140, v141
	v_min_f32_e32 v140, 0, v136
	v_mul_f32_e64 v136, |v136|, s57
	v_exp_f32_e32 v136, v136
	s_nop 0
	v_add_f32_e32 v136, 1.0, v136
	v_log_f32_e32 v136, v136
	s_nop 0
	v_mul_f32_e32 v141, 0x3f317217, v136
	v_fma_f32 v141, v136, s52, -v141
	v_fmac_f32_e32 v141, 0x3377d1cf, v136
	v_fmac_f32_e32 v141, 0x3f317217, v136
	v_sub_f32_e32 v136, v140, v141
	v_mul_f32_e32 v140, 0x3fb8aa3b, v138
	v_exp_f32_e32 v140, v140
	s_nop 0
	v_fma_f32 v134, v179, v140, v134
	v_cmp_gt_f32_e64 s[14:15], s97, v134
	s_nop 1
	v_cndmask_b32_e64 v140, 0, 32, s[14:15]
	v_ldexp_f32 v134, v134, v140
	v_log_f32_e32 v134, v134
	s_nop 0
	v_mul_f32_e32 v140, 0x3f317217, v134
	v_fma_f32 v140, v134, s52, -v140
	v_fmac_f32_e32 v140, 0x3377d1cf, v134
	v_fmac_f32_e32 v140, 0x3f317217, v134
	v_mov_b32_e32 v134, v140
	v_cndmask_b32_e64 v140, 0, v216, s[14:15]
	v_sub_f32_e32 v134, v134, v140
	v_cndmask_b32_e64 v134, v138, v134, s[12:13]
	v_mul_f32_e32 v138, 0x3fb8aa3b, v136
	v_exp_f32_e32 v138, v138
	s_nop 0
	v_fma_f32 v130, v178, v138, v130
	v_cmp_gt_f32_e64 s[12:13], s97, v130
	s_nop 1
	v_cndmask_b32_e64 v138, 0, 32, s[12:13]
	v_ldexp_f32 v130, v130, v138
	v_log_f32_e32 v130, v130
	s_nop 0
	v_mul_f32_e32 v138, 0x3f317217, v130
	v_fma_f32 v138, v130, s52, -v138
	v_fmac_f32_e32 v138, 0x3377d1cf, v130
	v_fmac_f32_e32 v138, 0x3f317217, v130
	v_mov_b32_e32 v130, v138
	v_cndmask_b32_e64 v138, 0, v216, s[12:13]
	v_sub_f32_e32 v130, v130, v138
	v_mul_f32_e64 v138, |v139|, s57
	v_exp_f32_e32 v138, v138
	v_cndmask_b32_e64 v130, v136, v130, s[10:11]
	v_min_f32_e32 v136, 0, v139
	v_add_f32_e32 v138, 1.0, v138
	v_log_f32_e32 v138, v138
	s_nop 0
	v_mul_f32_e32 v139, 0x3f317217, v138
	v_fma_f32 v139, v138, s52, -v139
	v_fmac_f32_e32 v139, 0x3377d1cf, v138
	v_fmac_f32_e32 v139, 0x3f317217, v138
	v_sub_f32_e32 v136, v136, v139
	v_min_f32_e32 v138, 0, v137
	v_mul_f32_e64 v137, |v137|, s57
	v_exp_f32_e32 v137, v137
	s_nop 0
	v_add_f32_e32 v137, 1.0, v137
	v_log_f32_e32 v137, v137
	s_nop 0
	v_mul_f32_e32 v139, 0x3f317217, v137
	v_fma_f32 v139, v137, s52, -v139
	v_fmac_f32_e32 v139, 0x3377d1cf, v137
	v_fmac_f32_e32 v139, 0x3f317217, v137
	v_sub_f32_e32 v137, v138, v139
	v_mul_f32_e32 v138, 0x3fb8aa3b, v136
	v_exp_f32_e32 v138, v138
	s_nop 0
	v_fmac_f32_e32 v135, v177, v138
	v_cmp_gt_f32_e64 s[10:11], s97, v135
	s_nop 1
	v_cndmask_b32_e64 v138, 0, 32, s[10:11]
	v_ldexp_f32 v135, v135, v138
	v_log_f32_e32 v135, v135
	s_nop 0
	v_mul_f32_e32 v138, 0x3f317217, v135
	v_fma_f32 v138, v135, s52, -v138
	v_fmac_f32_e32 v138, 0x3377d1cf, v135
	v_fmac_f32_e32 v138, 0x3f317217, v135
	v_cmp_lt_f32_e64 s[12:13], |v135|, s53
	s_nop 1
	v_cndmask_b32_e64 v135, v135, v138, s[12:13]
	v_cndmask_b32_e64 v138, 0, v216, s[10:11]
	v_sub_f32_e32 v135, v135, v138
	v_cndmask_b32_e64 v135, v136, v135, s[8:9]
	v_mul_f32_e32 v136, 0x3fb8aa3b, v137
	v_exp_f32_e32 v136, v136
	s_nop 0
	v_fmac_f32_e32 v131, v167, v136
	v_cmp_gt_f32_e64 s[8:9], s97, v131
	s_nop 1
	v_cndmask_b32_e64 v136, 0, 32, s[8:9]
	v_ldexp_f32 v131, v131, v136
	v_log_f32_e32 v131, v131
	s_nop 0
	v_mul_f32_e32 v136, 0x3f317217, v131
	v_fma_f32 v136, v131, s52, -v136
	v_fmac_f32_e32 v136, 0x3377d1cf, v131
	v_fmac_f32_e32 v136, 0x3f317217, v131
	v_cmp_lt_f32_e64 s[10:11], |v131|, s53
	s_nop 1
	v_cndmask_b32_e64 v131, v131, v136, s[10:11]
	v_cndmask_b32_e64 v136, 0, v216, s[8:9]
	v_sub_f32_e32 v131, v131, v136
	v_cndmask_b32_e32 v131, v137, v131, vcc
	global_store_dwordx4 v[146:147], v[132:135], off offset:512
	global_store_dwordx4 v[146:147], v[128:131], off offset:528
	s_branch .LBB0_416
; __device__ __forceinline__ float silu_f(float x) { return x * __builtin_amdgcn_rcpf(1.f + __expf(-x)); }
; __device__ __forceinline__ v4u pack8(const f32x4 a, const f32x4 b) { v4u w; w.x = cvt_pk_bf16(a[0], a[1]); w.y = cvt_pk_bf16(a[2], a[3]); w.z = cvt_pk_bf16(b[0], b[1]); w.w = cvt_pk_bf16(b[2], b[3]); return w; }
;     __device__ __forceinline__ void operator()(const f32x4 (&acc)[2][2][4][2], const pg8::Unit& u, int wr, int wc, int fr, int fq) const {
;     ...
;         if (grp == 0) { WIN_LOOP( _Pragma("unroll") for (int i = 0; i < 4; ++i) { a[i] = silu_f(a[i]); b[i] = silu_f(b[i]); } *(v4u*)(QO + (size_t)row * DM + c) = pack8(a, b); ) }
;         else if (grp == 3) { WIN_LOOP( _Pragma("unroll") for (int i = 0; i < 4; ++i) { a[i] = silu_f(a[i]); b[i] = silu_f(b[i]); } *(v4u*)(GH + (size_t)row * 512 + c) = pack8(a, b); ) }
;         else if (grp == 1) {
;             f32x4 l0[2], l1[2];
; #pragma unroll
;             for (int bj = 0; bj < 2; ++bj) { l0[bj] = *(const f32x4*)(lb + cb + bj * 128); l1[bj] = *(const f32x4*)(lb + cb + bj * 128 + 4); }
;             WIN_LOOP( _Pragma("unroll") for (int i = 0; i < 4; ++i) { const float s0 = fminf(a[i], 0.f) - __logf(1.f + __expf(-fabsf(a[i]))), s1 = fminf(b[i], 0.f) - __logf(1.f + __expf(-fabsf(b[i]))); const float la = l0[bj][i], lbv = l1[bj][i];
;                     a[i] = la > 0.f ? __logf(la + (1.f - la) * __expf(s0)) : s0; b[i] = lbv > 0.f ? __logf(lbv + (1.f - lbv) * __expf(s1)) : s1; }
;                 *(f32x4*)(LF + (size_t)row * 512 + c) = a; *(f32x4*)(LF + (size_t)row * 512 + c + 4) = b; __builtin_amdgcn_sched_barrier(0); ) }
.Llf_fast:
	v_ashrrev_i32_e32 v167, 31, v166
	v_lshlrev_b64 v[128:129], 6, v[166:167]
	v_lshl_add_u64 v[128:129], v[160:161], 0, v[128:129]
	s_nop 0
	v_readlane_b32 s8, v255, 35
	v_lshlrev_b32_e32 v192, 2, v176
	v_readlane_b32 s9, v255, 36
	v_and_b32_e32 v133, 64, v215
	v_xor_b32_e32 v132, 16, v215
	v_lshl_add_u64 v[144:145], s[8:9], 0, v[192:193]
	flat_load_dwordx4 v[140:143], v[144:145]
	flat_load_dwordx4 v[136:139], v[144:145] offset:16
	v_add_u32_e32 v134, 64, v133
	v_cmp_lt_i32_e32 vcc, v132, v134
	v_lshlrev_b64 v[146:147], 11, v[166:167]
	v_readlane_b32 s50, v255, 45
	v_cndmask_b32_e32 v132, v215, v132, vcc
	v_lshlrev_b32_e32 v169, 2, v132
	v_readlane_b32 s51, v255, 46
	s_mov_b32 s95, s28
	s_mov_b32 s91, s29
	v_lshl_add_u64 v[170:171], s[50:51], 0, v[146:147]
	v_lshl_add_u64 v[170:171], v[170:171], 0, v[192:193]
	s_waitcnt vmcnt(0) lgkmcnt(0)
	s_nop 3
	v_xor_b32_e32 v130, 32, v215
	s_nop 1
	v_cmp_lt_i32_e32 vcc, v130, v134
	v_sub_f32_e32 v190, 1.0, v140
	v_sub_f32_e32 v191, 1.0, v136
	v_cndmask_b32_e32 v130, v215, v130, vcc
	v_lshlrev_b32_e32 v202, 2, v130
	s_waitcnt lgkmcnt(0)
	s_nop 1
	flat_load_dwordx4 v[132:135], v[144:145] offset:512
	flat_load_dwordx4 v[128:131], v[144:145] offset:528
	v_sub_f32_e32 v188, 1.0, v141
	v_cmp_lt_f32_e64 s[38:39], 0, v140
	v_cmp_lt_f32_e64 s[36:37], 0, v136
	s_waitcnt lgkmcnt(0)
	s_nop 1
	v_mov_b32_e32 v168, v250
	v_sub_f32_e32 v189, 1.0, v137
	v_cmp_lt_f32_e64 s[34:35], 0, v141
	v_cmp_lt_f32_e64 s[30:31], 0, v137
	v_pk_mul_f32 v[144:145], v[60:61], v[168:169] op_sel_hi:[1,0]
	v_pk_mul_f32 v[148:149], v[56:57], v[168:169] op_sel_hi:[1,0]
	v_min_f32_e32 v167, 0, v144
	v_mul_f32_e64 v144, |v144|, s57
	v_min_f32_e32 v177, 0, v148
	v_mul_f32_e64 v148, |v148|, s57
	v_exp_f32_e32 v144, v144
	v_exp_f32_e32 v148, v148
	v_min_f32_e32 v179, 0, v149
	v_mul_f32_e64 v149, |v149|, s57
	v_add_f32_e32 v144, 1.0, v144
	v_exp_f32_e32 v149, v149
	v_add_f32_e32 v148, 1.0, v148
	v_min_f32_e32 v178, 0, v145
	v_mul_f32_e64 v145, |v145|, s57
	v_exp_f32_e32 v145, v145
	v_log_f32_e32 v144, v144
	v_add_f32_e32 v149, 1.0, v149
	v_log_f32_e32 v148, v148
	v_add_f32_e32 v145, 1.0, v145
	v_mul_f32_e32 v183, 0x3f317217, v144
	v_mul_f32_e32 v184, 0x3f317217, v148
	v_fma_f32 v183, v144, s52, -v183
	v_fma_f32 v184, v148, s52, -v184
	v_fmac_f32_e32 v183, 0x3377d1cf, v144
	v_fmac_f32_e32 v184, 0x3377d1cf, v148
	v_fmac_f32_e32 v183, 0x3f317217, v144
	v_log_f32_e32 v145, v145
	v_fmac_f32_e32 v184, 0x3f317217, v148
	v_log_f32_e32 v149, v149
	v_sub_f32_e32 v144, v167, v183
	v_sub_f32_e32 v167, v177, v184
	v_mul_f32_e32 v148, 0x3fb8aa3b, v144
	v_mul_f32_e32 v185, 0x3f317217, v145
	v_mul_f32_e32 v177, 0x3fb8aa3b, v167
	v_exp_f32_e32 v148, v148
	v_mul_f32_e32 v186, 0x3f317217, v149
	v_fma_f32 v185, v145, s52, -v185
	v_exp_f32_e32 v177, v177
	v_fma_f32 v186, v149, s52, -v186
	v_fmac_f32_e32 v185, 0x3377d1cf, v145
	v_fmac_f32_e32 v186, 0x3377d1cf, v149
	v_fmac_f32_e32 v185, 0x3f317217, v145
	v_fmac_f32_e32 v186, 0x3f317217, v149
	v_fma_f32 v148, v190, v148, v140
	v_fma_f32 v177, v191, v177, v136
	v_log_f32_e32 v148, v148
	v_log_f32_e32 v177, v177
	v_sub_f32_e32 v145, v178, v185
	v_mul_f32_e32 v178, 0x3fb8aa3b, v145
	v_mul_f32_e32 v182, 0x3f317217, v148
	v_exp_f32_e32 v178, v178
	v_mul_f32_e32 v183, 0x3f317217, v177
	v_fma_f32 v182, v148, s52, -v182
	v_fma_f32 v183, v177, s52, -v183
	v_fmac_f32_e32 v182, 0x3377d1cf, v148
	v_fmac_f32_e32 v183, 0x3377d1cf, v177
	v_fmac_f32_e32 v182, 0x3f317217, v148
	v_fmac_f32_e32 v183, 0x3f317217, v177
	v_fma_f32 v178, v188, v178, v141
	v_cndmask_b32_e64 v148, v144, v182, s[38:39]
	v_cndmask_b32_e64 v144, v167, v183, s[36:37]
	v_log_f32_e32 v167, v178
	v_sub_f32_e32 v177, v179, v186
	v_mul_f32_e32 v178, 0x3fb8aa3b, v177
	v_exp_f32_e32 v178, v178
	v_mul_f32_e32 v149, 0x3f317217, v167
	v_fma_f32 v149, v167, s52, -v149
	v_fmac_f32_e32 v149, 0x3377d1cf, v167
	v_fmac_f32_e32 v149, 0x3f317217, v167
	v_fma_f32 v178, v189, v178, v137
	v_pk_mul_f32 v[150:151], v[62:63], v[168:169] op_sel_hi:[1,0]
	v_log_f32_e32 v178, v178
	v_mul_f32_e64 v167, |v150|, s57
	v_exp_f32_e32 v167, v167
	v_cndmask_b32_e64 v149, v145, v149, s[34:35]
	v_mul_f32_e32 v145, 0x3f317217, v178
	v_fma_f32 v145, v178, s52, -v145
	v_fmac_f32_e32 v145, 0x3377d1cf, v178
	v_fmac_f32_e32 v145, 0x3f317217, v178
	v_add_f32_e32 v167, 1.0, v167
	v_pk_mul_f32 v[146:147], v[58:59], v[168:169] op_sel_hi:[1,0]
	v_cndmask_b32_e64 v145, v177, v145, s[30:31]
	v_log_f32_e32 v167, v167
	v_mul_f32_e64 v178, |v146|, s57
	v_exp_f32_e32 v178, v178
	v_min_f32_e32 v150, 0, v150
	v_mul_f32_e32 v177, 0x3f317217, v167
	v_fma_f32 v177, v167, s52, -v177
	v_fmac_f32_e32 v177, 0x3377d1cf, v167
	v_fmac_f32_e32 v177, 0x3f317217, v167
	v_add_f32_e32 v178, 1.0, v178
	v_sub_f32_e32 v187, 1.0, v142
	v_sub_f32_e32 v150, v150, v177
	v_log_f32_e32 v178, v178
	v_mul_f32_e32 v177, 0x3fb8aa3b, v150
	v_exp_f32_e32 v177, v177
	v_min_f32_e32 v146, 0, v146
	v_mul_f32_e32 v167, 0x3f317217, v178
	v_fma_f32 v167, v178, s52, -v167
	v_fmac_f32_e32 v167, 0x3377d1cf, v178
	v_fmac_f32_e32 v167, 0x3f317217, v178
	v_fma_f32 v177, v187, v177, v142
	v_sub_f32_e32 v186, 1.0, v138
	v_mov_b32_e32 v167, v167
	v_cmp_lt_f32_e64 s[28:29], 0, v142
	v_cmp_lt_f32_e64 s[26:27], 0, v138
	v_log_f32_e32 v177, v177
	v_sub_f32_e32 v146, v146, v167
	v_mul_f32_e32 v178, 0x3fb8aa3b, v146
	v_exp_f32_e32 v178, v178
	v_mul_f32_e32 v167, 0x3f317217, v177
	v_fma_f32 v167, v177, s52, -v167
	v_fmac_f32_e32 v167, 0x3377d1cf, v177
	v_fmac_f32_e32 v167, 0x3f317217, v177
	v_fma_f32 v178, v186, v178, v138
	v_sub_f32_e32 v185, 1.0, v143
	v_log_f32_e32 v178, v178
	v_mul_f32_e64 v177, |v151|, s57
	v_exp_f32_e32 v177, v177
; __device__ __forceinline__ float silu_f(float x) { return x * __builtin_amdgcn_rcpf(1.f + __expf(-x)); }
; __device__ __forceinline__ v4u pack8(const f32x4 a, const f32x4 b) { v4u w; w.x = cvt_pk_bf16(a[0], a[1]); w.y = cvt_pk_bf16(a[2], a[3]); w.z = cvt_pk_bf16(b[0], b[1]); w.w = cvt_pk_bf16(b[2], b[3]); return w; }
;     __device__ __forceinline__ void operator()(const f32x4 (&acc)[2][2][4][2], const pg8::Unit& u, int wr, int wc, int fr, int fq) const {
;     ...
;         if (grp == 0) { WIN_LOOP( _Pragma("unroll") for (int i = 0; i < 4; ++i) { a[i] = silu_f(a[i]); b[i] = silu_f(b[i]); } *(v4u*)(QO + (size_t)row * DM + c) = pack8(a, b); ) }
;         else if (grp == 3) { WIN_LOOP( _Pragma("unroll") for (int i = 0; i < 4; ++i) { a[i] = silu_f(a[i]); b[i] = silu_f(b[i]); } *(v4u*)(GH + (size_t)row * 512 + c) = pack8(a, b); ) }
;         else if (grp == 1) {
;             f32x4 l0[2], l1[2];
; #pragma unroll
;             for (int bj = 0; bj < 2; ++bj) { l0[bj] = *(const f32x4*)(lb + cb + bj * 128); l1[bj] = *(const f32x4*)(lb + cb + bj * 128 + 4); }
;             WIN_LOOP( _Pragma("unroll") for (int i = 0; i < 4; ++i) { const float s0 = fminf(a[i], 0.f) - __logf(1.f + __expf(-fabsf(a[i]))), s1 = fminf(b[i], 0.f) - __logf(1.f + __expf(-fabsf(b[i]))); const float la = l0[bj][i], lbv = l1[bj][i];
;                     a[i] = la > 0.f ? __logf(la + (1.f - la) * __expf(s0)) : s0; b[i] = lbv > 0.f ? __logf(lbv + (1.f - lbv) * __expf(s1)) : s1; }
;                 *(f32x4*)(LF + (size_t)row * 512 + c) = a; *(f32x4*)(LF + (size_t)row * 512 + c + 4) = b; __builtin_amdgcn_sched_barrier(0); ) }
	v_cndmask_b32_e64 v150, v150, v167, s[28:29]
	v_mul_f32_e32 v167, 0x3f317217, v178
	v_fma_f32 v167, v178, s52, -v167
	v_fmac_f32_e32 v167, 0x3377d1cf, v178
	v_fmac_f32_e32 v167, 0x3f317217, v178
	v_add_f32_e32 v177, 1.0, v177
	v_min_f32_e32 v151, 0, v151
	v_cndmask_b32_e64 v146, v146, v167, s[26:27]
	v_log_f32_e32 v177, v177
	v_mul_f32_e64 v178, |v147|, s57
	v_exp_f32_e32 v178, v178
	v_min_f32_e32 v147, 0, v147
	v_mul_f32_e32 v167, 0x3f317217, v177
	v_fma_f32 v167, v177, s52, -v167
	v_fmac_f32_e32 v167, 0x3377d1cf, v177
	v_fmac_f32_e32 v167, 0x3f317217, v177
	v_add_f32_e32 v178, 1.0, v178
	v_sub_f32_e32 v184, 1.0, v139
	v_mov_b32_e32 v167, v167
	v_sub_f32_e32 v151, v151, v167
	v_log_f32_e32 v178, v178
	v_mul_f32_e32 v177, 0x3fb8aa3b, v151
	v_exp_f32_e32 v177, v177
	v_cmp_lt_f32_e64 s[24:25], 0, v143
	v_mul_f32_e32 v167, 0x3f317217, v178
	v_fma_f32 v167, v178, s52, -v167
	v_fmac_f32_e32 v167, 0x3377d1cf, v178
	v_fmac_f32_e32 v167, 0x3f317217, v178
	v_fma_f32 v177, v185, v177, v143
	v_cmp_lt_f32_e64 s[22:23], 0, v139
	v_mov_b32_e32 v167, v167
	v_log_f32_e32 v177, v177
	v_sub_f32_e32 v147, v147, v167
	v_mul_f32_e32 v178, 0x3fb8aa3b, v147
	v_exp_f32_e32 v178, v178
	v_mul_f32_e32 v167, 0x3f317217, v177
	v_fma_f32 v167, v177, s52, -v167
	v_fmac_f32_e32 v167, 0x3377d1cf, v177
	v_fmac_f32_e32 v167, 0x3f317217, v177
	v_fma_f32 v178, v184, v178, v139
	s_nop 0
	v_log_f32_e32 v178, v178
	v_cndmask_b32_e64 v151, v151, v167, s[24:25]
	v_mul_f32_e32 v167, 0x3f317217, v178
	v_fma_f32 v167, v178, s52, -v167
	v_fmac_f32_e32 v167, 0x3377d1cf, v178
	v_fmac_f32_e32 v167, 0x3f317217, v178
	v_cndmask_b32_e64 v147, v147, v167, s[22:23]
	global_store_dwordx4 v[170:171], v[148:151], off
	global_store_dwordx4 v[170:171], v[144:147], off offset:16
	s_nop 1
	v_pk_mul_f32 v[144:145], v[124:125], v[168:169] op_sel_hi:[1,0]
	v_pk_mul_f32 v[150:151], v[126:127], v[168:169] op_sel_hi:[1,0]
	v_mul_f32_e64 v146, |v144|, s57
	v_exp_f32_e32 v148, v146
	v_pk_mul_f32 v[146:147], v[122:123], v[168:169] op_sel_hi:[1,0]
	v_min_f32_e32 v144, 0, v144
	s_waitcnt vmcnt(0)
	v_sub_f32_e32 v183, 1.0, v132
	v_add_f32_e32 v148, 1.0, v148
	v_sub_f32_e32 v182, 1.0, v128
	v_cmp_lt_f32_e64 s[20:21], 0, v132
	v_log_f32_e32 v167, v148
	v_pk_mul_f32 v[148:149], v[120:121], v[168:169] op_sel_hi:[1,0]
	v_cmp_lt_f32_e64 s[18:19], 0, v128
	v_mul_f32_e64 v168, |v148|, s57
	v_exp_f32_e32 v168, v168
	v_mul_f32_e32 v177, 0x3f317217, v167
	v_fma_f32 v177, v167, s52, -v177
	v_fmac_f32_e32 v177, 0x3377d1cf, v167
	v_fmac_f32_e32 v177, 0x3f317217, v167
	v_add_f32_e32 v168, 1.0, v168
	v_min_f32_e32 v148, 0, v148
	v_sub_f32_e32 v144, v144, v177
	v_log_f32_e32 v168, v168
	v_mul_f32_e32 v177, 0x3fb8aa3b, v144
	v_exp_f32_e32 v177, v177
	v_sub_f32_e32 v181, 1.0, v133
	v_mul_f32_e32 v167, 0x3f317217, v168
	v_fma_f32 v167, v168, s52, -v167
	v_fmac_f32_e32 v167, 0x3377d1cf, v168
	v_fmac_f32_e32 v167, 0x3f317217, v168
	v_sub_f32_e32 v180, 1.0, v129
	v_cmp_lt_f32_e64 s[16:17], 0, v133
	v_mov_b32_e32 v167, v167
	v_fma_f32 v168, v183, v177, v132
	v_cmp_lt_f32_e64 s[14:15], 0, v129
	v_sub_f32_e32 v179, 1.0, v134
	v_log_f32_e32 v168, v168
	v_sub_f32_e32 v148, v148, v167
	v_mul_f32_e32 v177, 0x3fb8aa3b, v148
	v_exp_f32_e32 v177, v177
	v_mul_f32_e32 v167, 0x3f317217, v168
	v_fma_f32 v167, v168, s52, -v167
	v_fmac_f32_e32 v167, 0x3377d1cf, v168
	v_fmac_f32_e32 v167, 0x3f317217, v168
	v_fma_f32 v177, v182, v177, v128
	v_cmp_lt_f32_e64 s[12:13], 0, v134
	v_log_f32_e32 v177, v177
	v_mul_f32_e64 v168, |v145|, s57
	v_exp_f32_e32 v168, v168
	v_cndmask_b32_e64 v144, v144, v167, s[20:21]
	v_mul_f32_e32 v167, 0x3f317217, v177
	v_fma_f32 v167, v177, s52, -v167
	v_fmac_f32_e32 v167, 0x3377d1cf, v177
	v_fmac_f32_e32 v167, 0x3f317217, v177
	v_add_f32_e32 v168, 1.0, v168
	v_min_f32_e32 v145, 0, v145
	v_cndmask_b32_e64 v148, v148, v167, s[18:19]
	v_log_f32_e32 v168, v168
	v_mul_f32_e64 v177, |v149|, s57
	v_exp_f32_e32 v177, v177
	v_min_f32_e32 v149, 0, v149
	v_mul_f32_e32 v167, 0x3f317217, v168
	v_fma_f32 v167, v168, s52, -v167
	v_fmac_f32_e32 v167, 0x3377d1cf, v168
	v_fmac_f32_e32 v167, 0x3f317217, v168
	v_add_f32_e32 v177, 1.0, v177
	v_cmp_lt_f32_e64 s[10:11], 0, v130
	v_mov_b32_e32 v167, v167
	v_sub_f32_e32 v145, v145, v167
	v_log_f32_e32 v177, v177
	v_mul_f32_e32 v168, 0x3fb8aa3b, v145
	v_exp_f32_e32 v168, v168
	s_mov_b32 s2, s40
	v_mul_f32_e32 v167, 0x3f317217, v177
	v_fma_f32 v167, v177, s52, -v167
	v_fmac_f32_e32 v167, 0x3377d1cf, v177
	v_fmac_f32_e32 v167, 0x3f317217, v177
	v_fma_f32 v168, v181, v168, v133
	s_nop 0
	v_mov_b32_e32 v167, v167
	v_log_f32_e32 v168, v168
	v_sub_f32_e32 v149, v149, v167
	v_mul_f32_e32 v177, 0x3fb8aa3b, v149
	v_exp_f32_e32 v177, v177
	v_mul_f32_e32 v167, 0x3f317217, v168
	v_fma_f32 v167, v168, s52, -v167
	v_fmac_f32_e32 v167, 0x3377d1cf, v168
	v_fmac_f32_e32 v167, 0x3f317217, v168
	v_fma_f32 v177, v180, v177, v129
	s_nop 0
	v_log_f32_e32 v177, v177
	v_mul_f32_e64 v168, |v150|, s57
	v_exp_f32_e32 v168, v168
	v_cndmask_b32_e64 v145, v145, v167, s[16:17]
	v_mul_f32_e32 v167, 0x3f317217, v177
	v_fma_f32 v167, v177, s52, -v167
	v_fmac_f32_e32 v167, 0x3377d1cf, v177
	v_fmac_f32_e32 v167, 0x3f317217, v177
	v_add_f32_e32 v168, 1.0, v168
	v_min_f32_e32 v150, 0, v150
	v_cndmask_b32_e64 v149, v149, v167, s[14:15]
	v_log_f32_e32 v168, v168
	v_mul_f32_e64 v177, |v146|, s57
	v_exp_f32_e32 v177, v177
	v_min_f32_e32 v146, 0, v146
	v_mul_f32_e32 v167, 0x3f317217, v168
	v_fma_f32 v167, v168, s52, -v167
	v_fmac_f32_e32 v167, 0x3377d1cf, v168
	v_fmac_f32_e32 v167, 0x3f317217, v168
	v_add_f32_e32 v177, 1.0, v177
	s_nop 0
	v_mov_b32_e32 v167, v167
	v_sub_f32_e32 v150, v150, v167
	v_log_f32_e32 v177, v177
; __device__ __forceinline__ float silu_f(float x) { return x * __builtin_amdgcn_rcpf(1.f + __expf(-x)); }
; __device__ __forceinline__ v4u pack8(const f32x4 a, const f32x4 b) { v4u w; w.x = cvt_pk_bf16(a[0], a[1]); w.y = cvt_pk_bf16(a[2], a[3]); w.z = cvt_pk_bf16(b[0], b[1]); w.w = cvt_pk_bf16(b[2], b[3]); return w; }
;     __device__ __forceinline__ void operator()(const f32x4 (&acc)[2][2][4][2], const pg8::Unit& u, int wr, int wc, int fr, int fq) const {
;     ...
;         if (grp == 0) { WIN_LOOP( _Pragma("unroll") for (int i = 0; i < 4; ++i) { a[i] = silu_f(a[i]); b[i] = silu_f(b[i]); } *(v4u*)(QO + (size_t)row * DM + c) = pack8(a, b); ) }
;         else if (grp == 3) { WIN_LOOP( _Pragma("unroll") for (int i = 0; i < 4; ++i) { a[i] = silu_f(a[i]); b[i] = silu_f(b[i]); } *(v4u*)(GH + (size_t)row * 512 + c) = pack8(a, b); ) }
;         else if (grp == 1) {
;             f32x4 l0[2], l1[2];
; #pragma unroll
;             for (int bj = 0; bj < 2; ++bj) { l0[bj] = *(const f32x4*)(lb + cb + bj * 128); l1[bj] = *(const f32x4*)(lb + cb + bj * 128 + 4); }
;             WIN_LOOP( _Pragma("unroll") for (int i = 0; i < 4; ++i) { const float s0 = fminf(a[i], 0.f) - __logf(1.f + __expf(-fabsf(a[i]))), s1 = fminf(b[i], 0.f) - __logf(1.f + __expf(-fabsf(b[i]))); const float la = l0[bj][i], lbv = l1[bj][i];
;                     a[i] = la > 0.f ? __logf(la + (1.f - la) * __expf(s0)) : s0; b[i] = lbv > 0.f ? __logf(lbv + (1.f - lbv) * __expf(s1)) : s1; }
;                 *(f32x4*)(LF + (size_t)row * 512 + c) = a; *(f32x4*)(LF + (size_t)row * 512 + c + 4) = b; __builtin_amdgcn_sched_barrier(0); ) }
	v_mul_f32_e32 v168, 0x3fb8aa3b, v150
	v_exp_f32_e32 v168, v168
	v_sub_f32_e32 v178, 1.0, v130
	v_mul_f32_e32 v167, 0x3f317217, v177
	v_fma_f32 v167, v177, s52, -v167
	v_fmac_f32_e32 v167, 0x3377d1cf, v177
	v_fmac_f32_e32 v167, 0x3f317217, v177
	v_fma_f32 v168, v179, v168, v134
	s_nop 0
	v_mov_b32_e32 v167, v167
	v_log_f32_e32 v168, v168
	v_sub_f32_e32 v167, v146, v167
	v_mul_f32_e32 v177, 0x3fb8aa3b, v167
	v_exp_f32_e32 v177, v177
	v_mul_f32_e32 v146, 0x3f317217, v168
	v_fma_f32 v146, v168, s52, -v146
	v_fmac_f32_e32 v146, 0x3377d1cf, v168
	v_fmac_f32_e32 v146, 0x3f317217, v168
	v_fma_f32 v177, v178, v177, v130
	s_nop 0
	v_log_f32_e32 v177, v177
	v_mul_f32_e64 v168, |v151|, s57
	v_exp_f32_e32 v168, v168
	v_cndmask_b32_e64 v146, v150, v146, s[12:13]
	v_mul_f32_e32 v150, 0x3f317217, v177
	v_fma_f32 v150, v177, s52, -v150
	v_fmac_f32_e32 v150, 0x3377d1cf, v177
	v_fmac_f32_e32 v150, 0x3f317217, v177
	v_add_f32_e32 v168, 1.0, v168
	v_min_f32_e32 v151, 0, v151
	v_cndmask_b32_e64 v150, v167, v150, s[10:11]
	v_log_f32_e32 v168, v168
	v_mul_f32_e64 v177, |v147|, s57
	v_exp_f32_e32 v177, v177
	v_min_f32_e32 v147, 0, v147
	v_mul_f32_e32 v167, 0x3f317217, v168
	v_fma_f32 v167, v168, s52, -v167
	v_fmac_f32_e32 v167, 0x3377d1cf, v168
	v_fmac_f32_e32 v167, 0x3f317217, v168
	v_add_f32_e32 v177, 1.0, v177
	s_nop 0
	v_mov_b32_e32 v167, v167
	v_sub_f32_e32 v151, v151, v167
	v_log_f32_e32 v177, v177
	v_mul_f32_e32 v168, 0x3fb8aa3b, v151
	v_exp_f32_e32 v168, v168
	v_mul_f32_e32 v167, 0x3f317217, v177
	v_fma_f32 v167, v177, s52, -v167
	v_fmac_f32_e32 v167, 0x3377d1cf, v177
	v_fmac_f32_e32 v167, 0x3f317217, v177
	v_mov_b32_e32 v167, v167
	v_sub_f32_e32 v177, 1.0, v135
	v_fma_f32 v168, v177, v168, v135
	v_log_f32_e32 v168, v168
	v_sub_f32_e32 v194, v147, v167
	v_mul_f32_e32 v167, 0x3fb8aa3b, v194
	v_exp_f32_e32 v195, v167
	v_mul_f32_e32 v147, 0x3f317217, v168
	v_fma_f32 v147, v168, s52, -v147
	v_fmac_f32_e32 v147, 0x3377d1cf, v168
	v_sub_f32_e32 v167, 1.0, v131
	v_fmac_f32_e32 v147, 0x3f317217, v168
	v_fma_f32 v195, v167, v195, v131
	s_nop 0
	v_log_f32_e32 v195, v195
	v_cmp_lt_f32_e64 s[8:9], 0, v135
	v_cmp_lt_f32_e32 vcc, 0, v131
	s_nop 0
	v_cndmask_b32_e64 v147, v151, v147, s[8:9]
	v_mul_f32_e32 v151, 0x3f317217, v195
	v_fma_f32 v151, v195, s52, -v151
	v_fmac_f32_e32 v151, 0x3377d1cf, v195
	v_fmac_f32_e32 v151, 0x3f317217, v195
	v_cndmask_b32_e32 v151, v194, v151, vcc
	global_store_dwordx4 v[170:171], v[144:147], off offset:512
	global_store_dwordx4 v[170:171], v[148:151], off offset:528
	s_nop 1
	v_or_b32_e32 v148, 16, v166
	v_ashrrev_i32_e32 v149, 31, v148
	v_lshlrev_b64 v[144:145], 6, v[148:149]
	v_lshl_add_u64 v[144:145], v[160:161], 0, v[144:145]
	s_nop 0
	s_waitcnt lgkmcnt(0)
	s_nop 3
	s_nop 0
	s_nop 1
	s_waitcnt lgkmcnt(0)
	s_nop 1
	s_waitcnt lgkmcnt(0)
	s_nop 1
	v_mov_b32_e32 v168, v251
	v_lshlrev_b64 v[144:145], 11, v[148:149]
	v_lshl_add_u64 v[170:171], s[50:51], 0, v[144:145]
	v_lshl_add_u64 v[170:171], v[170:171], 0, v[192:193]
	v_pk_mul_f32 v[148:149], v[52:53], v[168:169] op_sel_hi:[1,0]
	v_pk_mul_f32 v[144:145], v[48:49], v[168:169] op_sel_hi:[1,0]
	v_min_f32_e32 v194, 0, v148
	v_mul_f32_e64 v148, |v148|, s57
	v_exp_f32_e32 v148, v148
	v_pk_mul_f32 v[150:151], v[54:55], v[168:169] op_sel_hi:[1,0]
	v_pk_mul_f32 v[146:147], v[50:51], v[168:169] op_sel_hi:[1,0]
	v_add_f32_e32 v148, 1.0, v148
	v_log_f32_e32 v148, v148
	s_nop 0
	v_mul_f32_e32 v195, 0x3f317217, v148
	v_fma_f32 v195, v148, s52, -v195
	v_fmac_f32_e32 v195, 0x3377d1cf, v148
	v_fmac_f32_e32 v195, 0x3f317217, v148
	v_sub_f32_e32 v148, v194, v195
	v_min_f32_e32 v194, 0, v144
	v_mul_f32_e64 v144, |v144|, s57
	v_exp_f32_e32 v144, v144
	s_nop 0
	v_add_f32_e32 v144, 1.0, v144
	v_log_f32_e32 v144, v144
	s_nop 0
	v_mul_f32_e32 v195, 0x3f317217, v144
	v_fma_f32 v195, v144, s52, -v195
	v_fmac_f32_e32 v195, 0x3377d1cf, v144
	v_fmac_f32_e32 v195, 0x3f317217, v144
	v_sub_f32_e32 v194, v194, v195
	v_mul_f32_e32 v144, 0x3fb8aa3b, v148
	v_exp_f32_e32 v144, v144
	s_nop 0
	v_fma_f32 v144, v190, v144, v140
	v_log_f32_e32 v144, v144
	s_nop 0
	v_mul_f32_e32 v195, 0x3f317217, v144
	v_fma_f32 v195, v144, s52, -v195
	v_fmac_f32_e32 v195, 0x3377d1cf, v144
	v_fmac_f32_e32 v195, 0x3f317217, v144
	v_cndmask_b32_e64 v144, v148, v195, s[38:39]
	v_mul_f32_e32 v148, 0x3fb8aa3b, v194
	v_exp_f32_e32 v148, v148
	s_nop 0
	v_fma_f32 v148, v191, v148, v136
	v_log_f32_e32 v148, v148
	s_nop 0
	v_mul_f32_e32 v195, 0x3f317217, v148
	v_fma_f32 v195, v148, s52, -v195
	v_fmac_f32_e32 v195, 0x3377d1cf, v148
	v_fmac_f32_e32 v195, 0x3f317217, v148
	v_cndmask_b32_e64 v148, v194, v195, s[36:37]
	v_min_f32_e32 v194, 0, v149
	v_mul_f32_e64 v149, |v149|, s57
	v_exp_f32_e32 v149, v149
	s_nop 0
	v_add_f32_e32 v149, 1.0, v149
	v_log_f32_e32 v149, v149
	s_nop 0
	v_mul_f32_e32 v195, 0x3f317217, v149
	v_fma_f32 v195, v149, s52, -v195
	v_fmac_f32_e32 v195, 0x3377d1cf, v149
	v_fmac_f32_e32 v195, 0x3f317217, v149
	v_sub_f32_e32 v149, v194, v195
	v_min_f32_e32 v194, 0, v145
	v_mul_f32_e64 v145, |v145|, s57
	v_exp_f32_e32 v145, v145
	s_nop 0
	v_add_f32_e32 v145, 1.0, v145
	v_log_f32_e32 v145, v145
	s_nop 0
	v_mul_f32_e32 v195, 0x3f317217, v145
	v_fma_f32 v195, v145, s52, -v195
	v_fmac_f32_e32 v195, 0x3377d1cf, v145
	v_fmac_f32_e32 v195, 0x3f317217, v145
	v_sub_f32_e32 v194, v194, v195
	v_mul_f32_e32 v145, 0x3fb8aa3b, v149
	v_exp_f32_e32 v145, v145
	s_nop 0
	v_fma_f32 v145, v188, v145, v141
	v_log_f32_e32 v145, v145
	s_nop 0
	v_mul_f32_e32 v195, 0x3f317217, v145
	v_fma_f32 v195, v145, s52, -v195
	v_fmac_f32_e32 v195, 0x3377d1cf, v145
	v_fmac_f32_e32 v195, 0x3f317217, v145
	v_cndmask_b32_e64 v145, v149, v195, s[34:35]
	v_mul_f32_e32 v149, 0x3fb8aa3b, v194
; __device__ __forceinline__ float silu_f(float x) { return x * __builtin_amdgcn_rcpf(1.f + __expf(-x)); }
; __device__ __forceinline__ v4u pack8(const f32x4 a, const f32x4 b) { v4u w; w.x = cvt_pk_bf16(a[0], a[1]); w.y = cvt_pk_bf16(a[2], a[3]); w.z = cvt_pk_bf16(b[0], b[1]); w.w = cvt_pk_bf16(b[2], b[3]); return w; }
;     __device__ __forceinline__ void operator()(const f32x4 (&acc)[2][2][4][2], const pg8::Unit& u, int wr, int wc, int fr, int fq) const {
;     ...
;         if (grp == 0) { WIN_LOOP( _Pragma("unroll") for (int i = 0; i < 4; ++i) { a[i] = silu_f(a[i]); b[i] = silu_f(b[i]); } *(v4u*)(QO + (size_t)row * DM + c) = pack8(a, b); ) }
;         else if (grp == 3) { WIN_LOOP( _Pragma("unroll") for (int i = 0; i < 4; ++i) { a[i] = silu_f(a[i]); b[i] = silu_f(b[i]); } *(v4u*)(GH + (size_t)row * 512 + c) = pack8(a, b); ) }
;         else if (grp == 1) {
;             f32x4 l0[2], l1[2];
; #pragma unroll
;             for (int bj = 0; bj < 2; ++bj) { l0[bj] = *(const f32x4*)(lb + cb + bj * 128); l1[bj] = *(const f32x4*)(lb + cb + bj * 128 + 4); }
;             WIN_LOOP( _Pragma("unroll") for (int i = 0; i < 4; ++i) { const float s0 = fminf(a[i], 0.f) - __logf(1.f + __expf(-fabsf(a[i]))), s1 = fminf(b[i], 0.f) - __logf(1.f + __expf(-fabsf(b[i]))); const float la = l0[bj][i], lbv = l1[bj][i];
;                     a[i] = la > 0.f ? __logf(la + (1.f - la) * __expf(s0)) : s0; b[i] = lbv > 0.f ? __logf(lbv + (1.f - lbv) * __expf(s1)) : s1; }
;                 *(f32x4*)(LF + (size_t)row * 512 + c) = a; *(f32x4*)(LF + (size_t)row * 512 + c + 4) = b; __builtin_amdgcn_sched_barrier(0); ) }
	v_exp_f32_e32 v149, v149
	s_nop 0
	v_fma_f32 v149, v189, v149, v137
	v_log_f32_e32 v149, v149
	s_nop 0
	v_mul_f32_e32 v195, 0x3f317217, v149
	v_fma_f32 v195, v149, s52, -v195
	v_fmac_f32_e32 v195, 0x3377d1cf, v149
	v_fmac_f32_e32 v195, 0x3f317217, v149
	v_cndmask_b32_e64 v149, v194, v195, s[30:31]
	v_min_f32_e32 v194, 0, v150
	v_mul_f32_e64 v150, |v150|, s57
	v_exp_f32_e32 v150, v150
	s_nop 0
	v_add_f32_e32 v150, 1.0, v150
	v_log_f32_e32 v150, v150
	s_nop 0
	v_mul_f32_e32 v195, 0x3f317217, v150
	v_fma_f32 v195, v150, s52, -v195
	v_fmac_f32_e32 v195, 0x3377d1cf, v150
	v_fmac_f32_e32 v195, 0x3f317217, v150
	v_sub_f32_e32 v150, v194, v195
	v_min_f32_e32 v194, 0, v146
	v_mul_f32_e64 v146, |v146|, s57
	v_exp_f32_e32 v146, v146
	s_nop 0
	v_add_f32_e32 v146, 1.0, v146
	v_log_f32_e32 v146, v146
	s_nop 0
	v_mul_f32_e32 v195, 0x3f317217, v146
	v_fma_f32 v195, v146, s52, -v195
	v_fmac_f32_e32 v195, 0x3377d1cf, v146
	v_fmac_f32_e32 v195, 0x3f317217, v146
	v_sub_f32_e32 v194, v194, v195
	v_mul_f32_e32 v146, 0x3fb8aa3b, v150
	v_exp_f32_e32 v146, v146
	s_nop 0
	v_fma_f32 v146, v187, v146, v142
	v_log_f32_e32 v146, v146
	s_nop 0
	v_mul_f32_e32 v195, 0x3f317217, v146
	v_fma_f32 v195, v146, s52, -v195
	v_fmac_f32_e32 v195, 0x3377d1cf, v146
	v_fmac_f32_e32 v195, 0x3f317217, v146
	v_cndmask_b32_e64 v146, v150, v195, s[28:29]
	v_mul_f32_e32 v150, 0x3fb8aa3b, v194
	v_exp_f32_e32 v150, v150
	s_nop 0
	v_fma_f32 v150, v186, v150, v138
	v_log_f32_e32 v150, v150
	s_nop 0
	v_mul_f32_e32 v195, 0x3f317217, v150
	v_fma_f32 v195, v150, s52, -v195
	v_fmac_f32_e32 v195, 0x3377d1cf, v150
	v_fmac_f32_e32 v195, 0x3f317217, v150
	v_cndmask_b32_e64 v150, v194, v195, s[26:27]
	v_min_f32_e32 v194, 0, v151
	v_mul_f32_e64 v151, |v151|, s57
	v_exp_f32_e32 v151, v151
	s_nop 0
	v_add_f32_e32 v151, 1.0, v151
	v_log_f32_e32 v151, v151
	s_nop 0
	v_mul_f32_e32 v195, 0x3f317217, v151
	v_fma_f32 v195, v151, s52, -v195
	v_fmac_f32_e32 v195, 0x3377d1cf, v151
	v_fmac_f32_e32 v195, 0x3f317217, v151
	v_sub_f32_e32 v151, v194, v195
	v_min_f32_e32 v194, 0, v147
	v_mul_f32_e64 v147, |v147|, s57
	v_exp_f32_e32 v147, v147
	s_nop 0
	v_add_f32_e32 v147, 1.0, v147
	v_log_f32_e32 v147, v147
	s_nop 0
	v_mul_f32_e32 v195, 0x3f317217, v147
	v_fma_f32 v195, v147, s52, -v195
	v_fmac_f32_e32 v195, 0x3377d1cf, v147
	v_fmac_f32_e32 v195, 0x3f317217, v147
	v_sub_f32_e32 v194, v194, v195
	v_mul_f32_e32 v147, 0x3fb8aa3b, v151
	v_exp_f32_e32 v147, v147
	s_nop 0
	v_fma_f32 v147, v185, v147, v143
	v_log_f32_e32 v147, v147
	s_nop 0
	v_mul_f32_e32 v195, 0x3f317217, v147
	v_fma_f32 v195, v147, s52, -v195
	v_fmac_f32_e32 v195, 0x3377d1cf, v147
	v_fmac_f32_e32 v195, 0x3f317217, v147
	v_cndmask_b32_e64 v147, v151, v195, s[24:25]
	v_mul_f32_e32 v151, 0x3fb8aa3b, v194
	v_exp_f32_e32 v151, v151
	s_nop 0
	v_fma_f32 v151, v184, v151, v139
	v_log_f32_e32 v151, v151
	s_nop 0
	v_mul_f32_e32 v195, 0x3f317217, v151
	v_fma_f32 v195, v151, s52, -v195
	v_fmac_f32_e32 v195, 0x3377d1cf, v151
	v_fmac_f32_e32 v195, 0x3f317217, v151
	v_cndmask_b32_e64 v151, v194, v195, s[22:23]
	global_store_dwordx4 v[170:171], v[144:147], off
	global_store_dwordx4 v[170:171], v[148:151], off offset:16
	s_nop 1
	v_pk_mul_f32 v[148:149], v[116:117], v[168:169] op_sel_hi:[1,0]
	v_pk_mul_f32 v[150:151], v[118:119], v[168:169] op_sel_hi:[1,0]
	v_pk_mul_f32 v[146:147], v[114:115], v[168:169] op_sel_hi:[1,0]
	v_pk_mul_f32 v[144:145], v[112:113], v[168:169] op_sel_hi:[1,0]
	v_min_f32_e32 v168, 0, v148
	v_mul_f32_e64 v148, |v148|, s57
	v_exp_f32_e32 v148, v148
	s_nop 0
	v_add_f32_e32 v148, 1.0, v148
	v_log_f32_e32 v148, v148
	s_nop 0
	v_mul_f32_e32 v194, 0x3f317217, v148
	v_fma_f32 v194, v148, s52, -v194
	v_fmac_f32_e32 v194, 0x3377d1cf, v148
	v_fmac_f32_e32 v194, 0x3f317217, v148
	v_sub_f32_e32 v148, v168, v194
	v_min_f32_e32 v168, 0, v144
	v_mul_f32_e64 v144, |v144|, s57
	v_exp_f32_e32 v144, v144
	s_nop 0
	v_add_f32_e32 v144, 1.0, v144
	v_log_f32_e32 v144, v144
	s_nop 0
	v_mul_f32_e32 v194, 0x3f317217, v144
	v_fma_f32 v194, v144, s52, -v194
	v_fmac_f32_e32 v194, 0x3377d1cf, v144
	v_fmac_f32_e32 v194, 0x3f317217, v144
	v_sub_f32_e32 v168, v168, v194
	v_mul_f32_e32 v144, 0x3fb8aa3b, v148
	v_exp_f32_e32 v144, v144
	s_nop 0
	v_fma_f32 v144, v183, v144, v132
	v_log_f32_e32 v144, v144
	s_nop 0
	v_mul_f32_e32 v194, 0x3f317217, v144
	v_fma_f32 v194, v144, s52, -v194
	v_fmac_f32_e32 v194, 0x3377d1cf, v144
	v_fmac_f32_e32 v194, 0x3f317217, v144
	v_cndmask_b32_e64 v144, v148, v194, s[20:21]
	v_mul_f32_e32 v148, 0x3fb8aa3b, v168
	v_exp_f32_e32 v148, v148
	s_nop 0
	v_fma_f32 v148, v182, v148, v128
	v_log_f32_e32 v148, v148
	s_nop 0
	v_mul_f32_e32 v194, 0x3f317217, v148
	v_fma_f32 v194, v148, s52, -v194
	v_fmac_f32_e32 v194, 0x3377d1cf, v148
	v_fmac_f32_e32 v194, 0x3f317217, v148
	v_cndmask_b32_e64 v148, v168, v194, s[18:19]
	v_min_f32_e32 v168, 0, v149
	v_mul_f32_e64 v149, |v149|, s57
	v_exp_f32_e32 v149, v149
	s_nop 0
	v_add_f32_e32 v149, 1.0, v149
	v_log_f32_e32 v149, v149
	s_nop 0
	v_mul_f32_e32 v194, 0x3f317217, v149
	v_fma_f32 v194, v149, s52, -v194
	v_fmac_f32_e32 v194, 0x3377d1cf, v149
	v_fmac_f32_e32 v194, 0x3f317217, v149
	v_sub_f32_e32 v149, v168, v194
	v_min_f32_e32 v168, 0, v145
	v_mul_f32_e64 v145, |v145|, s57
	v_exp_f32_e32 v145, v145
	s_nop 0
	v_add_f32_e32 v145, 1.0, v145
	v_log_f32_e32 v145, v145
	s_nop 0
	v_mul_f32_e32 v194, 0x3f317217, v145
	v_fma_f32 v194, v145, s52, -v194
	v_fmac_f32_e32 v194, 0x3377d1cf, v145
	v_fmac_f32_e32 v194, 0x3f317217, v145
	v_sub_f32_e32 v168, v168, v194
	v_mul_f32_e32 v145, 0x3fb8aa3b, v149
	v_exp_f32_e32 v145, v145
	s_nop 0
	v_fma_f32 v145, v181, v145, v133
	v_log_f32_e32 v145, v145
	s_nop 0
	v_mul_f32_e32 v194, 0x3f317217, v145
; __device__ __forceinline__ float silu_f(float x) { return x * __builtin_amdgcn_rcpf(1.f + __expf(-x)); }
; __device__ __forceinline__ v4u pack8(const f32x4 a, const f32x4 b) { v4u w; w.x = cvt_pk_bf16(a[0], a[1]); w.y = cvt_pk_bf16(a[2], a[3]); w.z = cvt_pk_bf16(b[0], b[1]); w.w = cvt_pk_bf16(b[2], b[3]); return w; }
;     __device__ __forceinline__ void operator()(const f32x4 (&acc)[2][2][4][2], const pg8::Unit& u, int wr, int wc, int fr, int fq) const {
;     ...
;         if (grp == 0) { WIN_LOOP( _Pragma("unroll") for (int i = 0; i < 4; ++i) { a[i] = silu_f(a[i]); b[i] = silu_f(b[i]); } *(v4u*)(QO + (size_t)row * DM + c) = pack8(a, b); ) }
;         else if (grp == 3) { WIN_LOOP( _Pragma("unroll") for (int i = 0; i < 4; ++i) { a[i] = silu_f(a[i]); b[i] = silu_f(b[i]); } *(v4u*)(GH + (size_t)row * 512 + c) = pack8(a, b); ) }
;         else if (grp == 1) {
;             f32x4 l0[2], l1[2];
; #pragma unroll
;             for (int bj = 0; bj < 2; ++bj) { l0[bj] = *(const f32x4*)(lb + cb + bj * 128); l1[bj] = *(const f32x4*)(lb + cb + bj * 128 + 4); }
;             WIN_LOOP( _Pragma("unroll") for (int i = 0; i < 4; ++i) { const float s0 = fminf(a[i], 0.f) - __logf(1.f + __expf(-fabsf(a[i]))), s1 = fminf(b[i], 0.f) - __logf(1.f + __expf(-fabsf(b[i]))); const float la = l0[bj][i], lbv = l1[bj][i];
;                     a[i] = la > 0.f ? __logf(la + (1.f - la) * __expf(s0)) : s0; b[i] = lbv > 0.f ? __logf(lbv + (1.f - lbv) * __expf(s1)) : s1; }
;                 *(f32x4*)(LF + (size_t)row * 512 + c) = a; *(f32x4*)(LF + (size_t)row * 512 + c + 4) = b; __builtin_amdgcn_sched_barrier(0); ) }
	v_fma_f32 v194, v145, s52, -v194
	v_fmac_f32_e32 v194, 0x3377d1cf, v145
	v_fmac_f32_e32 v194, 0x3f317217, v145
	v_cndmask_b32_e64 v145, v149, v194, s[16:17]
	v_mul_f32_e32 v149, 0x3fb8aa3b, v168
	v_exp_f32_e32 v149, v149
	s_nop 0
	v_fma_f32 v149, v180, v149, v129
	v_log_f32_e32 v149, v149
	s_nop 0
	v_mul_f32_e32 v194, 0x3f317217, v149
	v_fma_f32 v194, v149, s52, -v194
	v_fmac_f32_e32 v194, 0x3377d1cf, v149
	v_fmac_f32_e32 v194, 0x3f317217, v149
	v_cndmask_b32_e64 v149, v168, v194, s[14:15]
	v_min_f32_e32 v168, 0, v150
	v_mul_f32_e64 v150, |v150|, s57
	v_exp_f32_e32 v150, v150
	s_nop 0
	v_add_f32_e32 v150, 1.0, v150
	v_log_f32_e32 v150, v150
	s_nop 0
	v_mul_f32_e32 v194, 0x3f317217, v150
	v_fma_f32 v194, v150, s52, -v194
	v_fmac_f32_e32 v194, 0x3377d1cf, v150
	v_fmac_f32_e32 v194, 0x3f317217, v150
	v_sub_f32_e32 v150, v168, v194
	v_min_f32_e32 v168, 0, v146
	v_mul_f32_e64 v146, |v146|, s57
	v_exp_f32_e32 v146, v146
	s_nop 0
	v_add_f32_e32 v146, 1.0, v146
	v_log_f32_e32 v146, v146
	s_nop 0
	v_mul_f32_e32 v194, 0x3f317217, v146
	v_fma_f32 v194, v146, s52, -v194
	v_fmac_f32_e32 v194, 0x3377d1cf, v146
	v_fmac_f32_e32 v194, 0x3f317217, v146
	v_sub_f32_e32 v168, v168, v194
	v_mul_f32_e32 v146, 0x3fb8aa3b, v150
	v_exp_f32_e32 v146, v146
	s_nop 0
	v_fma_f32 v146, v179, v146, v134
	v_log_f32_e32 v146, v146
	s_nop 0
	v_mul_f32_e32 v194, 0x3f317217, v146
	v_fma_f32 v194, v146, s52, -v194
	v_fmac_f32_e32 v194, 0x3377d1cf, v146
	v_fmac_f32_e32 v194, 0x3f317217, v146
	v_cndmask_b32_e64 v146, v150, v194, s[12:13]
	v_mul_f32_e32 v150, 0x3fb8aa3b, v168
	v_exp_f32_e32 v150, v150
	s_nop 0
	v_fma_f32 v150, v178, v150, v130
	v_log_f32_e32 v150, v150
	s_nop 0
	v_mul_f32_e32 v194, 0x3f317217, v150
	v_fma_f32 v194, v150, s52, -v194
	v_fmac_f32_e32 v194, 0x3377d1cf, v150
	v_fmac_f32_e32 v194, 0x3f317217, v150
	v_cndmask_b32_e64 v150, v168, v194, s[10:11]
	v_min_f32_e32 v168, 0, v151
	v_mul_f32_e64 v151, |v151|, s57
	v_exp_f32_e32 v151, v151
	s_nop 0
	v_add_f32_e32 v151, 1.0, v151
	v_log_f32_e32 v151, v151
	s_nop 0
	v_mul_f32_e32 v194, 0x3f317217, v151
	v_fma_f32 v194, v151, s52, -v194
	v_fmac_f32_e32 v194, 0x3377d1cf, v151
	v_fmac_f32_e32 v194, 0x3f317217, v151
	v_sub_f32_e32 v151, v168, v194
	v_min_f32_e32 v168, 0, v147
	v_mul_f32_e64 v147, |v147|, s57
	v_exp_f32_e32 v147, v147
	s_nop 0
	v_add_f32_e32 v147, 1.0, v147
	v_log_f32_e32 v147, v147
	s_nop 0
	v_mul_f32_e32 v194, 0x3f317217, v147
	v_fma_f32 v194, v147, s52, -v194
	v_fmac_f32_e32 v194, 0x3377d1cf, v147
	v_fmac_f32_e32 v194, 0x3f317217, v147
	v_sub_f32_e32 v168, v168, v194
	v_mul_f32_e32 v147, 0x3fb8aa3b, v151
	v_exp_f32_e32 v147, v147
	s_nop 0
	v_fma_f32 v147, v177, v147, v135
	v_log_f32_e32 v147, v147
	s_nop 0
	v_mul_f32_e32 v194, 0x3f317217, v147
	v_fma_f32 v194, v147, s52, -v194
	v_fmac_f32_e32 v194, 0x3377d1cf, v147
	v_fmac_f32_e32 v194, 0x3f317217, v147
	v_cndmask_b32_e64 v147, v151, v194, s[8:9]
	v_mul_f32_e32 v151, 0x3fb8aa3b, v168
	v_exp_f32_e32 v151, v151
	s_nop 0
	v_fma_f32 v151, v167, v151, v131
	v_log_f32_e32 v151, v151
	s_nop 0
	v_mul_f32_e32 v194, 0x3f317217, v151
	v_fma_f32 v194, v151, s52, -v194
	v_fmac_f32_e32 v194, 0x3377d1cf, v151
	v_fmac_f32_e32 v194, 0x3f317217, v151
	v_cndmask_b32_e32 v151, v168, v194, vcc
	global_store_dwordx4 v[170:171], v[144:147], off offset:512
	global_store_dwordx4 v[170:171], v[148:151], off offset:528
	s_nop 1
	v_or_b32_e32 v148, 32, v166
	v_ashrrev_i32_e32 v149, 31, v148
	v_lshlrev_b64 v[144:145], 6, v[148:149]
	v_lshl_add_u64 v[144:145], v[160:161], 0, v[144:145]
	s_nop 0
	s_waitcnt lgkmcnt(0)
	s_nop 3
	s_nop 0
	s_nop 1
	s_waitcnt lgkmcnt(0)
	s_nop 1
	s_waitcnt lgkmcnt(0)
	s_nop 1
	v_mov_b32_e32 v168, v252
	v_lshlrev_b64 v[144:145], 11, v[148:149]
	v_lshl_add_u64 v[170:171], s[50:51], 0, v[144:145]
	v_lshl_add_u64 v[170:171], v[170:171], 0, v[192:193]
	v_pk_mul_f32 v[148:149], v[44:45], v[168:169] op_sel_hi:[1,0]
	v_pk_mul_f32 v[144:145], v[40:41], v[168:169] op_sel_hi:[1,0]
	v_min_f32_e32 v194, 0, v148
	v_mul_f32_e64 v148, |v148|, s57
	v_exp_f32_e32 v148, v148
	v_pk_mul_f32 v[150:151], v[46:47], v[168:169] op_sel_hi:[1,0]
	v_pk_mul_f32 v[146:147], v[42:43], v[168:169] op_sel_hi:[1,0]
	v_add_f32_e32 v148, 1.0, v148
	v_log_f32_e32 v148, v148
	s_nop 0
	v_mul_f32_e32 v195, 0x3f317217, v148
	v_fma_f32 v195, v148, s52, -v195
	v_fmac_f32_e32 v195, 0x3377d1cf, v148
	v_fmac_f32_e32 v195, 0x3f317217, v148
	v_sub_f32_e32 v148, v194, v195
	v_min_f32_e32 v194, 0, v144
	v_mul_f32_e64 v144, |v144|, s57
	v_exp_f32_e32 v144, v144
	s_nop 0
	v_add_f32_e32 v144, 1.0, v144
	v_log_f32_e32 v144, v144
	s_nop 0
	v_mul_f32_e32 v195, 0x3f317217, v144
	v_fma_f32 v195, v144, s52, -v195
	v_fmac_f32_e32 v195, 0x3377d1cf, v144
	v_fmac_f32_e32 v195, 0x3f317217, v144
	v_sub_f32_e32 v194, v194, v195
	v_mul_f32_e32 v144, 0x3fb8aa3b, v148
	v_exp_f32_e32 v144, v144
	s_nop 0
	v_fma_f32 v144, v190, v144, v140
	v_log_f32_e32 v144, v144
	s_nop 0
	v_mul_f32_e32 v195, 0x3f317217, v144
	v_fma_f32 v195, v144, s52, -v195
	v_fmac_f32_e32 v195, 0x3377d1cf, v144
	v_fmac_f32_e32 v195, 0x3f317217, v144
	v_cndmask_b32_e64 v144, v148, v195, s[38:39]
	v_mul_f32_e32 v148, 0x3fb8aa3b, v194
	v_exp_f32_e32 v148, v148
	s_nop 0
	v_fma_f32 v148, v191, v148, v136
	v_log_f32_e32 v148, v148
	s_nop 0
	v_mul_f32_e32 v195, 0x3f317217, v148
	v_fma_f32 v195, v148, s52, -v195
	v_fmac_f32_e32 v195, 0x3377d1cf, v148
	v_fmac_f32_e32 v195, 0x3f317217, v148
	v_cndmask_b32_e64 v148, v194, v195, s[36:37]
	v_min_f32_e32 v194, 0, v149
	v_mul_f32_e64 v149, |v149|, s57
	v_exp_f32_e32 v149, v149
	s_nop 0
	v_add_f32_e32 v149, 1.0, v149
	v_log_f32_e32 v149, v149
	s_nop 0
	v_mul_f32_e32 v195, 0x3f317217, v149
	v_fma_f32 v195, v149, s52, -v195
; __device__ __forceinline__ float silu_f(float x) { return x * __builtin_amdgcn_rcpf(1.f + __expf(-x)); }
; __device__ __forceinline__ v4u pack8(const f32x4 a, const f32x4 b) { v4u w; w.x = cvt_pk_bf16(a[0], a[1]); w.y = cvt_pk_bf16(a[2], a[3]); w.z = cvt_pk_bf16(b[0], b[1]); w.w = cvt_pk_bf16(b[2], b[3]); return w; }
;     __device__ __forceinline__ void operator()(const f32x4 (&acc)[2][2][4][2], const pg8::Unit& u, int wr, int wc, int fr, int fq) const {
;     ...
;         if (grp == 0) { WIN_LOOP( _Pragma("unroll") for (int i = 0; i < 4; ++i) { a[i] = silu_f(a[i]); b[i] = silu_f(b[i]); } *(v4u*)(QO + (size_t)row * DM + c) = pack8(a, b); ) }
;         else if (grp == 3) { WIN_LOOP( _Pragma("unroll") for (int i = 0; i < 4; ++i) { a[i] = silu_f(a[i]); b[i] = silu_f(b[i]); } *(v4u*)(GH + (size_t)row * 512 + c) = pack8(a, b); ) }
;         else if (grp == 1) {
;             f32x4 l0[2], l1[2];
; #pragma unroll
;             for (int bj = 0; bj < 2; ++bj) { l0[bj] = *(const f32x4*)(lb + cb + bj * 128); l1[bj] = *(const f32x4*)(lb + cb + bj * 128 + 4); }
;             WIN_LOOP( _Pragma("unroll") for (int i = 0; i < 4; ++i) { const float s0 = fminf(a[i], 0.f) - __logf(1.f + __expf(-fabsf(a[i]))), s1 = fminf(b[i], 0.f) - __logf(1.f + __expf(-fabsf(b[i]))); const float la = l0[bj][i], lbv = l1[bj][i];
;                     a[i] = la > 0.f ? __logf(la + (1.f - la) * __expf(s0)) : s0; b[i] = lbv > 0.f ? __logf(lbv + (1.f - lbv) * __expf(s1)) : s1; }
;                 *(f32x4*)(LF + (size_t)row * 512 + c) = a; *(f32x4*)(LF + (size_t)row * 512 + c + 4) = b; __builtin_amdgcn_sched_barrier(0); ) }
	v_fmac_f32_e32 v195, 0x3377d1cf, v149
	v_fmac_f32_e32 v195, 0x3f317217, v149
	v_sub_f32_e32 v149, v194, v195
	v_min_f32_e32 v194, 0, v145
	v_mul_f32_e64 v145, |v145|, s57
	v_exp_f32_e32 v145, v145
	s_nop 0
	v_add_f32_e32 v145, 1.0, v145
	v_log_f32_e32 v145, v145
	s_nop 0
	v_mul_f32_e32 v195, 0x3f317217, v145
	v_fma_f32 v195, v145, s52, -v195
	v_fmac_f32_e32 v195, 0x3377d1cf, v145
	v_fmac_f32_e32 v195, 0x3f317217, v145
	v_sub_f32_e32 v194, v194, v195
	v_mul_f32_e32 v145, 0x3fb8aa3b, v149
	v_exp_f32_e32 v145, v145
	s_nop 0
	v_fma_f32 v145, v188, v145, v141
	v_log_f32_e32 v145, v145
	s_nop 0
	v_mul_f32_e32 v195, 0x3f317217, v145
	v_fma_f32 v195, v145, s52, -v195
	v_fmac_f32_e32 v195, 0x3377d1cf, v145
	v_fmac_f32_e32 v195, 0x3f317217, v145
	v_cndmask_b32_e64 v145, v149, v195, s[34:35]
	v_mul_f32_e32 v149, 0x3fb8aa3b, v194
	v_exp_f32_e32 v149, v149
	s_nop 0
	v_fma_f32 v149, v189, v149, v137
	v_log_f32_e32 v149, v149
	s_nop 0
	v_mul_f32_e32 v195, 0x3f317217, v149
	v_fma_f32 v195, v149, s52, -v195
	v_fmac_f32_e32 v195, 0x3377d1cf, v149
	v_fmac_f32_e32 v195, 0x3f317217, v149
	v_cndmask_b32_e64 v149, v194, v195, s[30:31]
	v_min_f32_e32 v194, 0, v150
	v_mul_f32_e64 v150, |v150|, s57
	v_exp_f32_e32 v150, v150
	s_nop 0
	v_add_f32_e32 v150, 1.0, v150
	v_log_f32_e32 v150, v150
	s_nop 0
	v_mul_f32_e32 v195, 0x3f317217, v150
	v_fma_f32 v195, v150, s52, -v195
	v_fmac_f32_e32 v195, 0x3377d1cf, v150
	v_fmac_f32_e32 v195, 0x3f317217, v150
	v_sub_f32_e32 v150, v194, v195
	v_min_f32_e32 v194, 0, v146
	v_mul_f32_e64 v146, |v146|, s57
	v_exp_f32_e32 v146, v146
	s_nop 0
	v_add_f32_e32 v146, 1.0, v146
	v_log_f32_e32 v146, v146
	s_nop 0
	v_mul_f32_e32 v195, 0x3f317217, v146
	v_fma_f32 v195, v146, s52, -v195
	v_fmac_f32_e32 v195, 0x3377d1cf, v146
	v_fmac_f32_e32 v195, 0x3f317217, v146
	v_sub_f32_e32 v194, v194, v195
	v_mul_f32_e32 v146, 0x3fb8aa3b, v150
	v_exp_f32_e32 v146, v146
	s_nop 0
	v_fma_f32 v146, v187, v146, v142
	v_log_f32_e32 v146, v146
	s_nop 0
	v_mul_f32_e32 v195, 0x3f317217, v146
	v_fma_f32 v195, v146, s52, -v195
	v_fmac_f32_e32 v195, 0x3377d1cf, v146
	v_fmac_f32_e32 v195, 0x3f317217, v146
	v_cndmask_b32_e64 v146, v150, v195, s[28:29]
	v_mul_f32_e32 v150, 0x3fb8aa3b, v194
	v_exp_f32_e32 v150, v150
	s_nop 0
	v_fma_f32 v150, v186, v150, v138
	v_log_f32_e32 v150, v150
	s_nop 0
	v_mul_f32_e32 v195, 0x3f317217, v150
	v_fma_f32 v195, v150, s52, -v195
	v_fmac_f32_e32 v195, 0x3377d1cf, v150
	v_fmac_f32_e32 v195, 0x3f317217, v150
	v_cndmask_b32_e64 v150, v194, v195, s[26:27]
	v_min_f32_e32 v194, 0, v151
	v_mul_f32_e64 v151, |v151|, s57
	v_exp_f32_e32 v151, v151
	s_nop 0
	v_add_f32_e32 v151, 1.0, v151
	v_log_f32_e32 v151, v151
	s_nop 0
	v_mul_f32_e32 v195, 0x3f317217, v151
	v_fma_f32 v195, v151, s52, -v195
	v_fmac_f32_e32 v195, 0x3377d1cf, v151
	v_fmac_f32_e32 v195, 0x3f317217, v151
	v_sub_f32_e32 v151, v194, v195
	v_min_f32_e32 v194, 0, v147
	v_mul_f32_e64 v147, |v147|, s57
	v_exp_f32_e32 v147, v147
	s_nop 0
	v_add_f32_e32 v147, 1.0, v147
	v_log_f32_e32 v147, v147
	s_nop 0
	v_mul_f32_e32 v195, 0x3f317217, v147
	v_fma_f32 v195, v147, s52, -v195
	v_fmac_f32_e32 v195, 0x3377d1cf, v147
	v_fmac_f32_e32 v195, 0x3f317217, v147
	v_sub_f32_e32 v194, v194, v195
	v_mul_f32_e32 v147, 0x3fb8aa3b, v151
	v_exp_f32_e32 v147, v147
	s_nop 0
	v_fma_f32 v147, v185, v147, v143
	v_log_f32_e32 v147, v147
	s_nop 0
	v_mul_f32_e32 v195, 0x3f317217, v147
	v_fma_f32 v195, v147, s52, -v195
	v_fmac_f32_e32 v195, 0x3377d1cf, v147
	v_fmac_f32_e32 v195, 0x3f317217, v147
	v_cndmask_b32_e64 v147, v151, v195, s[24:25]
	v_mul_f32_e32 v151, 0x3fb8aa3b, v194
	v_exp_f32_e32 v151, v151
	s_nop 0
	v_fma_f32 v151, v184, v151, v139
	v_log_f32_e32 v151, v151
	s_nop 0
	v_mul_f32_e32 v195, 0x3f317217, v151
	v_fma_f32 v195, v151, s52, -v195
	v_fmac_f32_e32 v195, 0x3377d1cf, v151
	v_fmac_f32_e32 v195, 0x3f317217, v151
	v_cndmask_b32_e64 v151, v194, v195, s[22:23]
	global_store_dwordx4 v[170:171], v[144:147], off
	global_store_dwordx4 v[170:171], v[148:151], off offset:16
	s_nop 1
	v_pk_mul_f32 v[148:149], v[108:109], v[168:169] op_sel_hi:[1,0]
	v_pk_mul_f32 v[150:151], v[110:111], v[168:169] op_sel_hi:[1,0]
	v_pk_mul_f32 v[146:147], v[106:107], v[168:169] op_sel_hi:[1,0]
	v_pk_mul_f32 v[144:145], v[104:105], v[168:169] op_sel_hi:[1,0]
	v_min_f32_e32 v168, 0, v148
	v_mul_f32_e64 v148, |v148|, s57
	v_exp_f32_e32 v148, v148
	s_nop 0
	v_add_f32_e32 v148, 1.0, v148
	v_log_f32_e32 v148, v148
	s_nop 0
	v_mul_f32_e32 v194, 0x3f317217, v148
	v_fma_f32 v194, v148, s52, -v194
	v_fmac_f32_e32 v194, 0x3377d1cf, v148
	v_fmac_f32_e32 v194, 0x3f317217, v148
	v_sub_f32_e32 v148, v168, v194
	v_min_f32_e32 v168, 0, v144
	v_mul_f32_e64 v144, |v144|, s57
	v_exp_f32_e32 v144, v144
	s_nop 0
	v_add_f32_e32 v144, 1.0, v144
	v_log_f32_e32 v144, v144
	s_nop 0
	v_mul_f32_e32 v194, 0x3f317217, v144
	v_fma_f32 v194, v144, s52, -v194
	v_fmac_f32_e32 v194, 0x3377d1cf, v144
	v_fmac_f32_e32 v194, 0x3f317217, v144
	v_sub_f32_e32 v168, v168, v194
	v_mul_f32_e32 v144, 0x3fb8aa3b, v148
	v_exp_f32_e32 v144, v144
	s_nop 0
	v_fma_f32 v144, v183, v144, v132
	v_log_f32_e32 v144, v144
	s_nop 0
	v_mul_f32_e32 v194, 0x3f317217, v144
	v_fma_f32 v194, v144, s52, -v194
	v_fmac_f32_e32 v194, 0x3377d1cf, v144
	v_fmac_f32_e32 v194, 0x3f317217, v144
	v_cndmask_b32_e64 v144, v148, v194, s[20:21]
	v_mul_f32_e32 v148, 0x3fb8aa3b, v168
	v_exp_f32_e32 v148, v148
	s_nop 0
	v_fma_f32 v148, v182, v148, v128
	v_log_f32_e32 v148, v148
	s_nop 0
	v_mul_f32_e32 v194, 0x3f317217, v148
	v_fma_f32 v194, v148, s52, -v194
	v_fmac_f32_e32 v194, 0x3377d1cf, v148
	v_fmac_f32_e32 v194, 0x3f317217, v148
	v_cndmask_b32_e64 v148, v168, v194, s[18:19]
	v_min_f32_e32 v168, 0, v149
; __device__ __forceinline__ float silu_f(float x) { return x * __builtin_amdgcn_rcpf(1.f + __expf(-x)); }
; __device__ __forceinline__ v4u pack8(const f32x4 a, const f32x4 b) { v4u w; w.x = cvt_pk_bf16(a[0], a[1]); w.y = cvt_pk_bf16(a[2], a[3]); w.z = cvt_pk_bf16(b[0], b[1]); w.w = cvt_pk_bf16(b[2], b[3]); return w; }
;     __device__ __forceinline__ void operator()(const f32x4 (&acc)[2][2][4][2], const pg8::Unit& u, int wr, int wc, int fr, int fq) const {
;     ...
;         if (grp == 0) { WIN_LOOP( _Pragma("unroll") for (int i = 0; i < 4; ++i) { a[i] = silu_f(a[i]); b[i] = silu_f(b[i]); } *(v4u*)(QO + (size_t)row * DM + c) = pack8(a, b); ) }
;         else if (grp == 3) { WIN_LOOP( _Pragma("unroll") for (int i = 0; i < 4; ++i) { a[i] = silu_f(a[i]); b[i] = silu_f(b[i]); } *(v4u*)(GH + (size_t)row * 512 + c) = pack8(a, b); ) }
;         else if (grp == 1) {
;             f32x4 l0[2], l1[2];
; #pragma unroll
;             for (int bj = 0; bj < 2; ++bj) { l0[bj] = *(const f32x4*)(lb + cb + bj * 128); l1[bj] = *(const f32x4*)(lb + cb + bj * 128 + 4); }
;             WIN_LOOP( _Pragma("unroll") for (int i = 0; i < 4; ++i) { const float s0 = fminf(a[i], 0.f) - __logf(1.f + __expf(-fabsf(a[i]))), s1 = fminf(b[i], 0.f) - __logf(1.f + __expf(-fabsf(b[i]))); const float la = l0[bj][i], lbv = l1[bj][i];
;                     a[i] = la > 0.f ? __logf(la + (1.f - la) * __expf(s0)) : s0; b[i] = lbv > 0.f ? __logf(lbv + (1.f - lbv) * __expf(s1)) : s1; }
;                 *(f32x4*)(LF + (size_t)row * 512 + c) = a; *(f32x4*)(LF + (size_t)row * 512 + c + 4) = b; __builtin_amdgcn_sched_barrier(0); ) }
	v_mul_f32_e64 v149, |v149|, s57
	v_exp_f32_e32 v149, v149
	s_nop 0
	v_add_f32_e32 v149, 1.0, v149
	v_log_f32_e32 v149, v149
	s_nop 0
	v_mul_f32_e32 v194, 0x3f317217, v149
	v_fma_f32 v194, v149, s52, -v194
	v_fmac_f32_e32 v194, 0x3377d1cf, v149
	v_fmac_f32_e32 v194, 0x3f317217, v149
	v_sub_f32_e32 v149, v168, v194
	v_min_f32_e32 v168, 0, v145
	v_mul_f32_e64 v145, |v145|, s57
	v_exp_f32_e32 v145, v145
	s_nop 0
	v_add_f32_e32 v145, 1.0, v145
	v_log_f32_e32 v145, v145
	s_nop 0
	v_mul_f32_e32 v194, 0x3f317217, v145
	v_fma_f32 v194, v145, s52, -v194
	v_fmac_f32_e32 v194, 0x3377d1cf, v145
	v_fmac_f32_e32 v194, 0x3f317217, v145
	v_sub_f32_e32 v168, v168, v194
	v_mul_f32_e32 v145, 0x3fb8aa3b, v149
	v_exp_f32_e32 v145, v145
	s_nop 0
	v_fma_f32 v145, v181, v145, v133
	v_log_f32_e32 v145, v145
	s_nop 0
	v_mul_f32_e32 v194, 0x3f317217, v145
	v_fma_f32 v194, v145, s52, -v194
	v_fmac_f32_e32 v194, 0x3377d1cf, v145
	v_fmac_f32_e32 v194, 0x3f317217, v145
	v_cndmask_b32_e64 v145, v149, v194, s[16:17]
	v_mul_f32_e32 v149, 0x3fb8aa3b, v168
	v_exp_f32_e32 v149, v149
	s_nop 0
	v_fma_f32 v149, v180, v149, v129
	v_log_f32_e32 v149, v149
	s_nop 0
	v_mul_f32_e32 v194, 0x3f317217, v149
	v_fma_f32 v194, v149, s52, -v194
	v_fmac_f32_e32 v194, 0x3377d1cf, v149
	v_fmac_f32_e32 v194, 0x3f317217, v149
	v_cndmask_b32_e64 v149, v168, v194, s[14:15]
	v_min_f32_e32 v168, 0, v150
	v_mul_f32_e64 v150, |v150|, s57
	v_exp_f32_e32 v150, v150
	s_nop 0
	v_add_f32_e32 v150, 1.0, v150
	v_log_f32_e32 v150, v150
	s_nop 0
	v_mul_f32_e32 v194, 0x3f317217, v150
	v_fma_f32 v194, v150, s52, -v194
	v_fmac_f32_e32 v194, 0x3377d1cf, v150
	v_fmac_f32_e32 v194, 0x3f317217, v150
	v_sub_f32_e32 v150, v168, v194
	v_min_f32_e32 v168, 0, v146
	v_mul_f32_e64 v146, |v146|, s57
	v_exp_f32_e32 v146, v146
	s_nop 0
	v_add_f32_e32 v146, 1.0, v146
	v_log_f32_e32 v146, v146
	s_nop 0
	v_mul_f32_e32 v194, 0x3f317217, v146
	v_fma_f32 v194, v146, s52, -v194
	v_fmac_f32_e32 v194, 0x3377d1cf, v146
	v_fmac_f32_e32 v194, 0x3f317217, v146
	v_sub_f32_e32 v168, v168, v194
	v_mul_f32_e32 v146, 0x3fb8aa3b, v150
	v_exp_f32_e32 v146, v146
	s_nop 0
	v_fma_f32 v146, v179, v146, v134
	v_log_f32_e32 v146, v146
	s_nop 0
	v_mul_f32_e32 v194, 0x3f317217, v146
	v_fma_f32 v194, v146, s52, -v194
	v_fmac_f32_e32 v194, 0x3377d1cf, v146
	v_fmac_f32_e32 v194, 0x3f317217, v146
	v_cndmask_b32_e64 v146, v150, v194, s[12:13]
	v_mul_f32_e32 v150, 0x3fb8aa3b, v168
	v_exp_f32_e32 v150, v150
	s_nop 0
	v_fma_f32 v150, v178, v150, v130
	v_log_f32_e32 v150, v150
	s_nop 0
	v_mul_f32_e32 v194, 0x3f317217, v150
	v_fma_f32 v194, v150, s52, -v194
	v_fmac_f32_e32 v194, 0x3377d1cf, v150
	v_fmac_f32_e32 v194, 0x3f317217, v150
	v_cndmask_b32_e64 v150, v168, v194, s[10:11]
	v_min_f32_e32 v168, 0, v151
	v_mul_f32_e64 v151, |v151|, s57
	v_exp_f32_e32 v151, v151
	s_nop 0
	v_add_f32_e32 v151, 1.0, v151
	v_log_f32_e32 v151, v151
	s_nop 0
	v_mul_f32_e32 v194, 0x3f317217, v151
	v_fma_f32 v194, v151, s52, -v194
	v_fmac_f32_e32 v194, 0x3377d1cf, v151
	v_fmac_f32_e32 v194, 0x3f317217, v151
	v_sub_f32_e32 v151, v168, v194
	v_min_f32_e32 v168, 0, v147
	v_mul_f32_e64 v147, |v147|, s57
	v_exp_f32_e32 v147, v147
	s_nop 0
	v_add_f32_e32 v147, 1.0, v147
	v_log_f32_e32 v147, v147
	s_nop 0
	v_mul_f32_e32 v194, 0x3f317217, v147
	v_fma_f32 v194, v147, s52, -v194
	v_fmac_f32_e32 v194, 0x3377d1cf, v147
	v_fmac_f32_e32 v194, 0x3f317217, v147
	v_sub_f32_e32 v168, v168, v194
	v_mul_f32_e32 v147, 0x3fb8aa3b, v151
	v_exp_f32_e32 v147, v147
	s_nop 0
	v_fma_f32 v147, v177, v147, v135
	v_log_f32_e32 v147, v147
	s_nop 0
	v_mul_f32_e32 v194, 0x3f317217, v147
	v_fma_f32 v194, v147, s52, -v194
	v_fmac_f32_e32 v194, 0x3377d1cf, v147
	v_fmac_f32_e32 v194, 0x3f317217, v147
	v_cndmask_b32_e64 v147, v151, v194, s[8:9]
	v_mul_f32_e32 v151, 0x3fb8aa3b, v168
	v_exp_f32_e32 v151, v151
	s_nop 0
	v_fma_f32 v151, v167, v151, v131
	v_log_f32_e32 v151, v151
	s_nop 0
	v_mul_f32_e32 v194, 0x3f317217, v151
	v_fma_f32 v194, v151, s52, -v194
	v_fmac_f32_e32 v194, 0x3377d1cf, v151
	v_fmac_f32_e32 v194, 0x3f317217, v151
	v_cndmask_b32_e32 v151, v168, v194, vcc
	global_store_dwordx4 v[170:171], v[144:147], off offset:512
	global_store_dwordx4 v[170:171], v[148:151], off offset:528
	s_nop 1
	v_or_b32_e32 v148, 48, v166
	v_ashrrev_i32_e32 v149, 31, v148
	v_lshlrev_b64 v[144:145], 6, v[148:149]
	v_lshl_add_u64 v[144:145], v[160:161], 0, v[144:145]
	s_nop 0
	s_waitcnt lgkmcnt(0)
	s_nop 3
	s_nop 0
	s_nop 1
	s_waitcnt lgkmcnt(0)
	s_nop 1
	s_waitcnt lgkmcnt(0)
; __device__ __forceinline__ float silu_f(float x) { return x * __builtin_amdgcn_rcpf(1.f + __expf(-x)); }
; __device__ __forceinline__ v4u pack8(const f32x4 a, const f32x4 b) { v4u w; w.x = cvt_pk_bf16(a[0], a[1]); w.y = cvt_pk_bf16(a[2], a[3]); w.z = cvt_pk_bf16(b[0], b[1]); w.w = cvt_pk_bf16(b[2], b[3]); return w; }
;     __device__ __forceinline__ void operator()(const f32x4 (&acc)[2][2][4][2], const pg8::Unit& u, int wr, int wc, int fr, int fq) const {
;     ...
;         if (grp == 0) { WIN_LOOP( _Pragma("unroll") for (int i = 0; i < 4; ++i) { a[i] = silu_f(a[i]); b[i] = silu_f(b[i]); } *(v4u*)(QO + (size_t)row * DM + c) = pack8(a, b); ) }
;         else if (grp == 3) { WIN_LOOP( _Pragma("unroll") for (int i = 0; i < 4; ++i) { a[i] = silu_f(a[i]); b[i] = silu_f(b[i]); } *(v4u*)(GH + (size_t)row * 512 + c) = pack8(a, b); ) }
;         else if (grp == 1) {
;             f32x4 l0[2], l1[2];
; #pragma unroll
;             for (int bj = 0; bj < 2; ++bj) { l0[bj] = *(const f32x4*)(lb + cb + bj * 128); l1[bj] = *(const f32x4*)(lb + cb + bj * 128 + 4); }
;             WIN_LOOP( _Pragma("unroll") for (int i = 0; i < 4; ++i) { const float s0 = fminf(a[i], 0.f) - __logf(1.f + __expf(-fabsf(a[i]))), s1 = fminf(b[i], 0.f) - __logf(1.f + __expf(-fabsf(b[i]))); const float la = l0[bj][i], lbv = l1[bj][i];
;                     a[i] = la > 0.f ? __logf(la + (1.f - la) * __expf(s0)) : s0; b[i] = lbv > 0.f ? __logf(lbv + (1.f - lbv) * __expf(s1)) : s1; }
;                 *(f32x4*)(LF + (size_t)row * 512 + c) = a; *(f32x4*)(LF + (size_t)row * 512 + c + 4) = b; __builtin_amdgcn_sched_barrier(0); ) }
	s_nop 1
	v_mov_b32_e32 v168, v253
	v_lshlrev_b64 v[144:145], 11, v[148:149]
	v_lshl_add_u64 v[170:171], s[50:51], 0, v[144:145]
	v_lshl_add_u64 v[170:171], v[170:171], 0, v[192:193]
	v_pk_mul_f32 v[148:149], v[36:37], v[168:169] op_sel_hi:[1,0]
	v_pk_mul_f32 v[144:145], v[32:33], v[168:169] op_sel_hi:[1,0]
	v_min_f32_e32 v194, 0, v148
	v_mul_f32_e64 v148, |v148|, s57
	v_exp_f32_e32 v148, v148
	v_pk_mul_f32 v[150:151], v[38:39], v[168:169] op_sel_hi:[1,0]
	v_pk_mul_f32 v[146:147], v[34:35], v[168:169] op_sel_hi:[1,0]
	v_add_f32_e32 v148, 1.0, v148
	v_log_f32_e32 v148, v148
	s_nop 0
	v_mul_f32_e32 v195, 0x3f317217, v148
	v_fma_f32 v195, v148, s52, -v195
	v_fmac_f32_e32 v195, 0x3377d1cf, v148
	v_fmac_f32_e32 v195, 0x3f317217, v148
	v_sub_f32_e32 v148, v194, v195
	v_min_f32_e32 v194, 0, v144
	v_mul_f32_e64 v144, |v144|, s57
	v_exp_f32_e32 v144, v144
	s_nop 0
	v_add_f32_e32 v144, 1.0, v144
	v_log_f32_e32 v144, v144
	s_nop 0
	v_mul_f32_e32 v195, 0x3f317217, v144
	v_fma_f32 v195, v144, s52, -v195
	v_fmac_f32_e32 v195, 0x3377d1cf, v144
	v_fmac_f32_e32 v195, 0x3f317217, v144
	v_sub_f32_e32 v194, v194, v195
	v_mul_f32_e32 v144, 0x3fb8aa3b, v148
	v_exp_f32_e32 v144, v144
	s_nop 0
	v_fma_f32 v144, v190, v144, v140
	v_log_f32_e32 v144, v144
	s_nop 0
	v_mul_f32_e32 v195, 0x3f317217, v144
	v_fma_f32 v195, v144, s52, -v195
	v_fmac_f32_e32 v195, 0x3377d1cf, v144
	v_fmac_f32_e32 v195, 0x3f317217, v144
	v_cndmask_b32_e64 v144, v148, v195, s[38:39]
	v_mul_f32_e32 v148, 0x3fb8aa3b, v194
	v_exp_f32_e32 v148, v148
	s_nop 0
	v_fma_f32 v148, v191, v148, v136
	v_log_f32_e32 v148, v148
	s_nop 0
	v_mul_f32_e32 v195, 0x3f317217, v148
	v_fma_f32 v195, v148, s52, -v195
	v_fmac_f32_e32 v195, 0x3377d1cf, v148
	v_fmac_f32_e32 v195, 0x3f317217, v148
	v_cndmask_b32_e64 v148, v194, v195, s[36:37]
	v_min_f32_e32 v194, 0, v149
	v_mul_f32_e64 v149, |v149|, s57
	v_exp_f32_e32 v149, v149
	s_nop 0
	v_add_f32_e32 v149, 1.0, v149
	v_log_f32_e32 v149, v149
	s_nop 0
	v_mul_f32_e32 v195, 0x3f317217, v149
	v_fma_f32 v195, v149, s52, -v195
	v_fmac_f32_e32 v195, 0x3377d1cf, v149
	v_fmac_f32_e32 v195, 0x3f317217, v149
	v_sub_f32_e32 v149, v194, v195
	v_min_f32_e32 v194, 0, v145
	v_mul_f32_e64 v145, |v145|, s57
	v_exp_f32_e32 v145, v145
	s_nop 0
	v_add_f32_e32 v145, 1.0, v145
	v_log_f32_e32 v145, v145
	s_nop 0
	v_mul_f32_e32 v195, 0x3f317217, v145
	v_fma_f32 v195, v145, s52, -v195
	v_fmac_f32_e32 v195, 0x3377d1cf, v145
	v_fmac_f32_e32 v195, 0x3f317217, v145
	v_sub_f32_e32 v194, v194, v195
	v_mul_f32_e32 v145, 0x3fb8aa3b, v149
	v_exp_f32_e32 v145, v145
	s_nop 0
	v_fma_f32 v145, v188, v145, v141
	v_log_f32_e32 v145, v145
	s_nop 0
	v_mul_f32_e32 v195, 0x3f317217, v145
	v_fma_f32 v195, v145, s52, -v195
	v_fmac_f32_e32 v195, 0x3377d1cf, v145
	v_fmac_f32_e32 v195, 0x3f317217, v145
	v_cndmask_b32_e64 v145, v149, v195, s[34:35]
	v_mul_f32_e32 v149, 0x3fb8aa3b, v194
	v_exp_f32_e32 v149, v149
	s_nop 0
	v_fma_f32 v149, v189, v149, v137
	v_log_f32_e32 v149, v149
	s_nop 0
	v_mul_f32_e32 v195, 0x3f317217, v149
	v_fma_f32 v195, v149, s52, -v195
	v_fmac_f32_e32 v195, 0x3377d1cf, v149
	v_fmac_f32_e32 v195, 0x3f317217, v149
	v_cndmask_b32_e64 v149, v194, v195, s[30:31]
	v_min_f32_e32 v194, 0, v150
	v_mul_f32_e64 v150, |v150|, s57
	v_exp_f32_e32 v150, v150
	s_nop 0
	v_add_f32_e32 v150, 1.0, v150
	v_log_f32_e32 v150, v150
	s_nop 0
	v_mul_f32_e32 v195, 0x3f317217, v150
	v_fma_f32 v195, v150, s52, -v195
	v_fmac_f32_e32 v195, 0x3377d1cf, v150
	v_fmac_f32_e32 v195, 0x3f317217, v150
	v_sub_f32_e32 v150, v194, v195
	v_min_f32_e32 v194, 0, v146
	v_mul_f32_e64 v146, |v146|, s57
	v_exp_f32_e32 v146, v146
	s_nop 0
	v_add_f32_e32 v146, 1.0, v146
	v_log_f32_e32 v146, v146
	s_nop 0
	v_mul_f32_e32 v195, 0x3f317217, v146
	v_fma_f32 v195, v146, s52, -v195
	v_fmac_f32_e32 v195, 0x3377d1cf, v146
	v_fmac_f32_e32 v195, 0x3f317217, v146
	v_sub_f32_e32 v194, v194, v195
	v_mul_f32_e32 v146, 0x3fb8aa3b, v150
	v_exp_f32_e32 v146, v146
	s_nop 0
	v_fma_f32 v146, v187, v146, v142
	v_log_f32_e32 v146, v146
	s_nop 0
	v_mul_f32_e32 v195, 0x3f317217, v146
	v_fma_f32 v195, v146, s52, -v195
	v_fmac_f32_e32 v195, 0x3377d1cf, v146
	v_fmac_f32_e32 v195, 0x3f317217, v146
	v_cndmask_b32_e64 v146, v150, v195, s[28:29]
	v_mul_f32_e32 v150, 0x3fb8aa3b, v194
	v_exp_f32_e32 v150, v150
	s_nop 0
	v_fma_f32 v150, v186, v150, v138
	v_log_f32_e32 v150, v150
	s_nop 0
	v_mul_f32_e32 v195, 0x3f317217, v150
	v_fma_f32 v195, v150, s52, -v195
	v_fmac_f32_e32 v195, 0x3377d1cf, v150
	v_fmac_f32_e32 v195, 0x3f317217, v150
	v_cndmask_b32_e64 v150, v194, v195, s[26:27]
	v_min_f32_e32 v194, 0, v151
	v_mul_f32_e64 v151, |v151|, s57
	v_exp_f32_e32 v151, v151
	s_nop 0
	v_add_f32_e32 v151, 1.0, v151
	v_log_f32_e32 v151, v151
	s_nop 0
	v_mul_f32_e32 v195, 0x3f317217, v151
	v_fma_f32 v195, v151, s52, -v195
	v_fmac_f32_e32 v195, 0x3377d1cf, v151
	v_fmac_f32_e32 v195, 0x3f317217, v151
	v_sub_f32_e32 v151, v194, v195
	v_min_f32_e32 v194, 0, v147
	v_mul_f32_e64 v147, |v147|, s57
	v_exp_f32_e32 v147, v147
	s_nop 0
	v_add_f32_e32 v147, 1.0, v147
	v_log_f32_e32 v147, v147
	s_nop 0
	v_mul_f32_e32 v195, 0x3f317217, v147
	v_fma_f32 v195, v147, s52, -v195
	v_fmac_f32_e32 v195, 0x3377d1cf, v147
	v_fmac_f32_e32 v195, 0x3f317217, v147
	v_sub_f32_e32 v194, v194, v195
	v_mul_f32_e32 v147, 0x3fb8aa3b, v151
	v_exp_f32_e32 v147, v147
	s_nop 0
	v_fma_f32 v147, v185, v147, v143
	v_log_f32_e32 v147, v147
	s_nop 0
	v_mul_f32_e32 v195, 0x3f317217, v147
	v_fma_f32 v195, v147, s52, -v195
	v_fmac_f32_e32 v195, 0x3377d1cf, v147
	v_fmac_f32_e32 v195, 0x3f317217, v147
	v_cndmask_b32_e64 v147, v151, v195, s[24:25]
	v_mul_f32_e32 v151, 0x3fb8aa3b, v194
	v_exp_f32_e32 v151, v151
	s_nop 0
; __device__ __forceinline__ float silu_f(float x) { return x * __builtin_amdgcn_rcpf(1.f + __expf(-x)); }
; __device__ __forceinline__ v4u pack8(const f32x4 a, const f32x4 b) { v4u w; w.x = cvt_pk_bf16(a[0], a[1]); w.y = cvt_pk_bf16(a[2], a[3]); w.z = cvt_pk_bf16(b[0], b[1]); w.w = cvt_pk_bf16(b[2], b[3]); return w; }
;     __device__ __forceinline__ void operator()(const f32x4 (&acc)[2][2][4][2], const pg8::Unit& u, int wr, int wc, int fr, int fq) const {
;     ...
;         if (grp == 0) { WIN_LOOP( _Pragma("unroll") for (int i = 0; i < 4; ++i) { a[i] = silu_f(a[i]); b[i] = silu_f(b[i]); } *(v4u*)(QO + (size_t)row * DM + c) = pack8(a, b); ) }
;         else if (grp == 3) { WIN_LOOP( _Pragma("unroll") for (int i = 0; i < 4; ++i) { a[i] = silu_f(a[i]); b[i] = silu_f(b[i]); } *(v4u*)(GH + (size_t)row * 512 + c) = pack8(a, b); ) }
;         else if (grp == 1) {
;             f32x4 l0[2], l1[2];
; #pragma unroll
;             for (int bj = 0; bj < 2; ++bj) { l0[bj] = *(const f32x4*)(lb + cb + bj * 128); l1[bj] = *(const f32x4*)(lb + cb + bj * 128 + 4); }
;             WIN_LOOP( _Pragma("unroll") for (int i = 0; i < 4; ++i) { const float s0 = fminf(a[i], 0.f) - __logf(1.f + __expf(-fabsf(a[i]))), s1 = fminf(b[i], 0.f) - __logf(1.f + __expf(-fabsf(b[i]))); const float la = l0[bj][i], lbv = l1[bj][i];
;                     a[i] = la > 0.f ? __logf(la + (1.f - la) * __expf(s0)) : s0; b[i] = lbv > 0.f ? __logf(lbv + (1.f - lbv) * __expf(s1)) : s1; }
;                 *(f32x4*)(LF + (size_t)row * 512 + c) = a; *(f32x4*)(LF + (size_t)row * 512 + c + 4) = b; __builtin_amdgcn_sched_barrier(0); ) }
	v_fma_f32 v151, v184, v151, v139
	v_log_f32_e32 v151, v151
	s_nop 0
	v_mul_f32_e32 v195, 0x3f317217, v151
	v_fma_f32 v195, v151, s52, -v195
	v_fmac_f32_e32 v195, 0x3377d1cf, v151
	v_fmac_f32_e32 v195, 0x3f317217, v151
	v_cndmask_b32_e64 v151, v194, v195, s[22:23]
	global_store_dwordx4 v[170:171], v[144:147], off
	global_store_dwordx4 v[170:171], v[148:151], off offset:16
	s_nop 1
	v_pk_mul_f32 v[148:149], v[100:101], v[168:169] op_sel_hi:[1,0]
	v_pk_mul_f32 v[150:151], v[102:103], v[168:169] op_sel_hi:[1,0]
	v_pk_mul_f32 v[146:147], v[98:99], v[168:169] op_sel_hi:[1,0]
	v_pk_mul_f32 v[144:145], v[96:97], v[168:169] op_sel_hi:[1,0]
	v_min_f32_e32 v168, 0, v148
	v_mul_f32_e64 v148, |v148|, s57
	v_exp_f32_e32 v148, v148
	s_nop 0
	v_add_f32_e32 v148, 1.0, v148
	v_log_f32_e32 v148, v148
	s_nop 0
	v_mul_f32_e32 v194, 0x3f317217, v148
	v_fma_f32 v194, v148, s52, -v194
	v_fmac_f32_e32 v194, 0x3377d1cf, v148
	v_fmac_f32_e32 v194, 0x3f317217, v148
	v_sub_f32_e32 v148, v168, v194
	v_min_f32_e32 v168, 0, v144
	v_mul_f32_e64 v144, |v144|, s57
	v_exp_f32_e32 v144, v144
	s_nop 0
	v_add_f32_e32 v144, 1.0, v144
	v_log_f32_e32 v144, v144
	s_nop 0
	v_mul_f32_e32 v194, 0x3f317217, v144
	v_fma_f32 v194, v144, s52, -v194
	v_fmac_f32_e32 v194, 0x3377d1cf, v144
	v_fmac_f32_e32 v194, 0x3f317217, v144
	v_sub_f32_e32 v168, v168, v194
	v_mul_f32_e32 v144, 0x3fb8aa3b, v148
	v_exp_f32_e32 v144, v144
	s_nop 0
	v_fma_f32 v144, v183, v144, v132
	v_log_f32_e32 v144, v144
	s_nop 0
	v_mul_f32_e32 v194, 0x3f317217, v144
	v_fma_f32 v194, v144, s52, -v194
	v_fmac_f32_e32 v194, 0x3377d1cf, v144
	v_fmac_f32_e32 v194, 0x3f317217, v144
	v_cndmask_b32_e64 v144, v148, v194, s[20:21]
	v_mul_f32_e32 v148, 0x3fb8aa3b, v168
	v_exp_f32_e32 v148, v148
	s_nop 0
	v_fma_f32 v148, v182, v148, v128
	v_log_f32_e32 v148, v148
	s_nop 0
	v_mul_f32_e32 v194, 0x3f317217, v148
	v_fma_f32 v194, v148, s52, -v194
	v_fmac_f32_e32 v194, 0x3377d1cf, v148
	v_fmac_f32_e32 v194, 0x3f317217, v148
	v_cndmask_b32_e64 v148, v168, v194, s[18:19]
	v_min_f32_e32 v168, 0, v149
	v_mul_f32_e64 v149, |v149|, s57
	v_exp_f32_e32 v149, v149
	s_nop 0
	v_add_f32_e32 v149, 1.0, v149
	v_log_f32_e32 v149, v149
	s_nop 0
	v_mul_f32_e32 v194, 0x3f317217, v149
	v_fma_f32 v194, v149, s52, -v194
	v_fmac_f32_e32 v194, 0x3377d1cf, v149
	v_fmac_f32_e32 v194, 0x3f317217, v149
	v_sub_f32_e32 v149, v168, v194
	v_min_f32_e32 v168, 0, v145
	v_mul_f32_e64 v145, |v145|, s57
	v_exp_f32_e32 v145, v145
	s_nop 0
	v_add_f32_e32 v145, 1.0, v145
	v_log_f32_e32 v145, v145
	s_nop 0
	v_mul_f32_e32 v194, 0x3f317217, v145
	v_fma_f32 v194, v145, s52, -v194
	v_fmac_f32_e32 v194, 0x3377d1cf, v145
	v_fmac_f32_e32 v194, 0x3f317217, v145
	v_sub_f32_e32 v168, v168, v194
	v_mul_f32_e32 v145, 0x3fb8aa3b, v149
	v_exp_f32_e32 v145, v145
	s_nop 0
	v_fma_f32 v145, v181, v145, v133
	v_log_f32_e32 v145, v145
	s_nop 0
	v_mul_f32_e32 v194, 0x3f317217, v145
	v_fma_f32 v194, v145, s52, -v194
	v_fmac_f32_e32 v194, 0x3377d1cf, v145
	v_fmac_f32_e32 v194, 0x3f317217, v145
	v_cndmask_b32_e64 v145, v149, v194, s[16:17]
	v_mul_f32_e32 v149, 0x3fb8aa3b, v168
	v_exp_f32_e32 v149, v149
	s_nop 0
	v_fma_f32 v149, v180, v149, v129
	v_log_f32_e32 v149, v149
	s_nop 0
	v_mul_f32_e32 v194, 0x3f317217, v149
	v_fma_f32 v194, v149, s52, -v194
	v_fmac_f32_e32 v194, 0x3377d1cf, v149
	v_fmac_f32_e32 v194, 0x3f317217, v149
	v_cndmask_b32_e64 v149, v168, v194, s[14:15]
	v_min_f32_e32 v168, 0, v150
	v_mul_f32_e64 v150, |v150|, s57
	v_exp_f32_e32 v150, v150
	s_nop 0
	v_add_f32_e32 v150, 1.0, v150
	v_log_f32_e32 v150, v150
	s_nop 0
	v_mul_f32_e32 v194, 0x3f317217, v150
	v_fma_f32 v194, v150, s52, -v194
	v_fmac_f32_e32 v194, 0x3377d1cf, v150
	v_fmac_f32_e32 v194, 0x3f317217, v150
	v_sub_f32_e32 v150, v168, v194
	v_min_f32_e32 v168, 0, v146
	v_mul_f32_e64 v146, |v146|, s57
	v_exp_f32_e32 v146, v146
	s_nop 0
	v_add_f32_e32 v146, 1.0, v146
	v_log_f32_e32 v146, v146
	s_nop 0
	v_mul_f32_e32 v194, 0x3f317217, v146
	v_fma_f32 v194, v146, s52, -v194
	v_fmac_f32_e32 v194, 0x3377d1cf, v146
	v_fmac_f32_e32 v194, 0x3f317217, v146
	v_sub_f32_e32 v168, v168, v194
	v_mul_f32_e32 v146, 0x3fb8aa3b, v150
	v_exp_f32_e32 v146, v146
	s_nop 0
	v_fma_f32 v146, v179, v146, v134
	v_log_f32_e32 v146, v146
	s_nop 0
	v_mul_f32_e32 v194, 0x3f317217, v146
	v_fma_f32 v194, v146, s52, -v194
	v_fmac_f32_e32 v194, 0x3377d1cf, v146
	v_fmac_f32_e32 v194, 0x3f317217, v146
	v_cndmask_b32_e64 v146, v150, v194, s[12:13]
	v_mul_f32_e32 v150, 0x3fb8aa3b, v168
	v_exp_f32_e32 v150, v150
	s_nop 0
	v_fma_f32 v150, v178, v150, v130
	v_log_f32_e32 v150, v150
	s_nop 0
	v_mul_f32_e32 v194, 0x3f317217, v150
	v_fma_f32 v194, v150, s52, -v194
	v_fmac_f32_e32 v194, 0x3377d1cf, v150
	v_fmac_f32_e32 v194, 0x3f317217, v150
	v_cndmask_b32_e64 v150, v168, v194, s[10:11]
	v_min_f32_e32 v168, 0, v151
	v_mul_f32_e64 v151, |v151|, s57
	v_exp_f32_e32 v151, v151
	s_nop 0
	v_add_f32_e32 v151, 1.0, v151
	v_log_f32_e32 v151, v151
	s_nop 0
	v_mul_f32_e32 v194, 0x3f317217, v151
	v_fma_f32 v194, v151, s52, -v194
	v_fmac_f32_e32 v194, 0x3377d1cf, v151
	v_fmac_f32_e32 v194, 0x3f317217, v151
	v_sub_f32_e32 v151, v168, v194
	v_min_f32_e32 v168, 0, v147
	v_mul_f32_e64 v147, |v147|, s57
	v_exp_f32_e32 v147, v147
	s_nop 0
	v_add_f32_e32 v147, 1.0, v147
	v_log_f32_e32 v147, v147
	s_nop 0
	v_mul_f32_e32 v194, 0x3f317217, v147
	v_fma_f32 v194, v147, s52, -v194
	v_fmac_f32_e32 v194, 0x3377d1cf, v147
	v_fmac_f32_e32 v194, 0x3f317217, v147
	v_sub_f32_e32 v168, v168, v194
	v_mul_f32_e32 v147, 0x3fb8aa3b, v151
	v_exp_f32_e32 v147, v147
	s_nop 0
	v_fma_f32 v147, v177, v147, v135
	v_log_f32_e32 v147, v147
	s_nop 0
	v_mul_f32_e32 v194, 0x3f317217, v147
	v_fma_f32 v194, v147, s52, -v194
	v_fmac_f32_e32 v194, 0x3377d1cf, v147
	v_fmac_f32_e32 v194, 0x3f317217, v147
	v_cndmask_b32_e64 v147, v151, v194, s[8:9]
	v_mul_f32_e32 v151, 0x3fb8aa3b, v168
	v_exp_f32_e32 v151, v151
	s_nop 0
	v_fma_f32 v151, v167, v151, v131
	v_log_f32_e32 v151, v151
	s_nop 0
	v_mul_f32_e32 v194, 0x3f317217, v151
	v_fma_f32 v194, v151, s52, -v194
	v_fmac_f32_e32 v194, 0x3377d1cf, v151
	v_fmac_f32_e32 v194, 0x3f317217, v151
	v_cndmask_b32_e32 v151, v168, v194, vcc
	global_store_dwordx4 v[170:171], v[144:147], off offset:512
	global_store_dwordx4 v[170:171], v[148:151], off offset:528
	s_nop 1
	v_add_u32_e32 v148, 0x80, v166
	v_ashrrev_i32_e32 v149, 31, v148
	v_lshlrev_b64 v[144:145], 6, v[148:149]
	v_lshl_add_u64 v[144:145], v[160:161], 0, v[144:145]
	s_nop 0
	s_waitcnt lgkmcnt(0)
; __device__ __forceinline__ float silu_f(float x) { return x * __builtin_amdgcn_rcpf(1.f + __expf(-x)); }
; __device__ __forceinline__ v4u pack8(const f32x4 a, const f32x4 b) { v4u w; w.x = cvt_pk_bf16(a[0], a[1]); w.y = cvt_pk_bf16(a[2], a[3]); w.z = cvt_pk_bf16(b[0], b[1]); w.w = cvt_pk_bf16(b[2], b[3]); return w; }
;     __device__ __forceinline__ void operator()(const f32x4 (&acc)[2][2][4][2], const pg8::Unit& u, int wr, int wc, int fr, int fq) const {
;     ...
;         if (grp == 0) { WIN_LOOP( _Pragma("unroll") for (int i = 0; i < 4; ++i) { a[i] = silu_f(a[i]); b[i] = silu_f(b[i]); } *(v4u*)(QO + (size_t)row * DM + c) = pack8(a, b); ) }
;         else if (grp == 3) { WIN_LOOP( _Pragma("unroll") for (int i = 0; i < 4; ++i) { a[i] = silu_f(a[i]); b[i] = silu_f(b[i]); } *(v4u*)(GH + (size_t)row * 512 + c) = pack8(a, b); ) }
;         else if (grp == 1) {
;             f32x4 l0[2], l1[2];
; #pragma unroll
;             for (int bj = 0; bj < 2; ++bj) { l0[bj] = *(const f32x4*)(lb + cb + bj * 128); l1[bj] = *(const f32x4*)(lb + cb + bj * 128 + 4); }
;             WIN_LOOP( _Pragma("unroll") for (int i = 0; i < 4; ++i) { const float s0 = fminf(a[i], 0.f) - __logf(1.f + __expf(-fabsf(a[i]))), s1 = fminf(b[i], 0.f) - __logf(1.f + __expf(-fabsf(b[i]))); const float la = l0[bj][i], lbv = l1[bj][i];
;                     a[i] = la > 0.f ? __logf(la + (1.f - la) * __expf(s0)) : s0; b[i] = lbv > 0.f ? __logf(lbv + (1.f - lbv) * __expf(s1)) : s1; }
;                 *(f32x4*)(LF + (size_t)row * 512 + c) = a; *(f32x4*)(LF + (size_t)row * 512 + c + 4) = b; __builtin_amdgcn_sched_barrier(0); ) }
	s_nop 3
	s_nop 0
	s_nop 1
	s_waitcnt lgkmcnt(0)
	s_nop 1
	s_waitcnt lgkmcnt(0)
	s_nop 1
	v_mov_b32_e32 v168, v254
	v_lshlrev_b64 v[144:145], 11, v[148:149]
	v_lshl_add_u64 v[170:171], s[50:51], 0, v[144:145]
	v_lshl_add_u64 v[170:171], v[170:171], 0, v[192:193]
	v_pk_mul_f32 v[148:149], v[28:29], v[168:169] op_sel_hi:[1,0]
	v_pk_mul_f32 v[144:145], v[24:25], v[168:169] op_sel_hi:[1,0]
	v_min_f32_e32 v194, 0, v148
	v_mul_f32_e64 v148, |v148|, s57
	v_exp_f32_e32 v148, v148
	v_pk_mul_f32 v[150:151], v[30:31], v[168:169] op_sel_hi:[1,0]
	v_pk_mul_f32 v[146:147], v[26:27], v[168:169] op_sel_hi:[1,0]
	v_add_f32_e32 v148, 1.0, v148
	v_log_f32_e32 v148, v148
	s_nop 0
	v_mul_f32_e32 v195, 0x3f317217, v148
	v_fma_f32 v195, v148, s52, -v195
	v_fmac_f32_e32 v195, 0x3377d1cf, v148
	v_fmac_f32_e32 v195, 0x3f317217, v148
	v_sub_f32_e32 v148, v194, v195
	v_min_f32_e32 v194, 0, v144
	v_mul_f32_e64 v144, |v144|, s57
	v_exp_f32_e32 v144, v144
	s_nop 0
	v_add_f32_e32 v144, 1.0, v144
	v_log_f32_e32 v144, v144
	s_nop 0
	v_mul_f32_e32 v195, 0x3f317217, v144
	v_fma_f32 v195, v144, s52, -v195
	v_fmac_f32_e32 v195, 0x3377d1cf, v144
	v_fmac_f32_e32 v195, 0x3f317217, v144
	v_sub_f32_e32 v194, v194, v195
	v_mul_f32_e32 v144, 0x3fb8aa3b, v148
	v_exp_f32_e32 v144, v144
	s_nop 0
	v_fma_f32 v144, v190, v144, v140
	v_log_f32_e32 v144, v144
	s_nop 0
	v_mul_f32_e32 v195, 0x3f317217, v144
	v_fma_f32 v195, v144, s52, -v195
	v_fmac_f32_e32 v195, 0x3377d1cf, v144
	v_fmac_f32_e32 v195, 0x3f317217, v144
	v_cndmask_b32_e64 v144, v148, v195, s[38:39]
	v_mul_f32_e32 v148, 0x3fb8aa3b, v194
	v_exp_f32_e32 v148, v148
	s_nop 0
	v_fma_f32 v148, v191, v148, v136
	v_log_f32_e32 v148, v148
	s_nop 0
	v_mul_f32_e32 v195, 0x3f317217, v148
	v_fma_f32 v195, v148, s52, -v195
	v_fmac_f32_e32 v195, 0x3377d1cf, v148
	v_fmac_f32_e32 v195, 0x3f317217, v148
	v_cndmask_b32_e64 v148, v194, v195, s[36:37]
	v_min_f32_e32 v194, 0, v149
	v_mul_f32_e64 v149, |v149|, s57
	v_exp_f32_e32 v149, v149
	s_nop 0
	v_add_f32_e32 v149, 1.0, v149
	v_log_f32_e32 v149, v149
	s_nop 0
	v_mul_f32_e32 v195, 0x3f317217, v149
	v_fma_f32 v195, v149, s52, -v195
	v_fmac_f32_e32 v195, 0x3377d1cf, v149
	v_fmac_f32_e32 v195, 0x3f317217, v149
	v_sub_f32_e32 v149, v194, v195
	v_min_f32_e32 v194, 0, v145
	v_mul_f32_e64 v145, |v145|, s57
	v_exp_f32_e32 v145, v145
	s_nop 0
	v_add_f32_e32 v145, 1.0, v145
	v_log_f32_e32 v145, v145
	s_nop 0
	v_mul_f32_e32 v195, 0x3f317217, v145
	v_fma_f32 v195, v145, s52, -v195
	v_fmac_f32_e32 v195, 0x3377d1cf, v145
	v_fmac_f32_e32 v195, 0x3f317217, v145
	v_sub_f32_e32 v194, v194, v195
	v_mul_f32_e32 v145, 0x3fb8aa3b, v149
	v_exp_f32_e32 v145, v145
	s_nop 0
	v_fma_f32 v145, v188, v145, v141
	v_log_f32_e32 v145, v145
	s_nop 0
	v_mul_f32_e32 v195, 0x3f317217, v145
	v_fma_f32 v195, v145, s52, -v195
	v_fmac_f32_e32 v195, 0x3377d1cf, v145
	v_fmac_f32_e32 v195, 0x3f317217, v145
	v_cndmask_b32_e64 v145, v149, v195, s[34:35]
	v_mul_f32_e32 v149, 0x3fb8aa3b, v194
	v_exp_f32_e32 v149, v149
	s_nop 0
	v_fma_f32 v149, v189, v149, v137
	v_log_f32_e32 v149, v149
	s_nop 0
	v_mul_f32_e32 v195, 0x3f317217, v149
	v_fma_f32 v195, v149, s52, -v195
	v_fmac_f32_e32 v195, 0x3377d1cf, v149
	v_fmac_f32_e32 v195, 0x3f317217, v149
	v_cndmask_b32_e64 v149, v194, v195, s[30:31]
	v_min_f32_e32 v194, 0, v150
	v_mul_f32_e64 v150, |v150|, s57
	v_exp_f32_e32 v150, v150
	s_nop 0
	v_add_f32_e32 v150, 1.0, v150
	v_log_f32_e32 v150, v150
	s_nop 0
	v_mul_f32_e32 v195, 0x3f317217, v150
	v_fma_f32 v195, v150, s52, -v195
	v_fmac_f32_e32 v195, 0x3377d1cf, v150
	v_fmac_f32_e32 v195, 0x3f317217, v150
	v_sub_f32_e32 v150, v194, v195
	v_min_f32_e32 v194, 0, v146
	v_mul_f32_e64 v146, |v146|, s57
	v_exp_f32_e32 v146, v146
	s_nop 0
	v_add_f32_e32 v146, 1.0, v146
	v_log_f32_e32 v146, v146
	s_nop 0
	v_mul_f32_e32 v195, 0x3f317217, v146
	v_fma_f32 v195, v146, s52, -v195
	v_fmac_f32_e32 v195, 0x3377d1cf, v146
	v_fmac_f32_e32 v195, 0x3f317217, v146
	v_sub_f32_e32 v194, v194, v195
	v_mul_f32_e32 v146, 0x3fb8aa3b, v150
	v_exp_f32_e32 v146, v146
	s_nop 0
	v_fma_f32 v146, v187, v146, v142
	v_log_f32_e32 v146, v146
	s_nop 0
	v_mul_f32_e32 v195, 0x3f317217, v146
	v_fma_f32 v195, v146, s52, -v195
	v_fmac_f32_e32 v195, 0x3377d1cf, v146
	v_fmac_f32_e32 v195, 0x3f317217, v146
	v_cndmask_b32_e64 v146, v150, v195, s[28:29]
	v_mul_f32_e32 v150, 0x3fb8aa3b, v194
	v_exp_f32_e32 v150, v150
	s_nop 0
	v_fma_f32 v150, v186, v150, v138
	v_log_f32_e32 v150, v150
	s_nop 0
	v_mul_f32_e32 v195, 0x3f317217, v150
	v_fma_f32 v195, v150, s52, -v195
	v_fmac_f32_e32 v195, 0x3377d1cf, v150
	v_fmac_f32_e32 v195, 0x3f317217, v150
	v_cndmask_b32_e64 v150, v194, v195, s[26:27]
	v_min_f32_e32 v194, 0, v151
	v_mul_f32_e64 v151, |v151|, s57
	v_exp_f32_e32 v151, v151
	s_nop 0
	v_add_f32_e32 v151, 1.0, v151
	v_log_f32_e32 v151, v151
	s_nop 0
	v_mul_f32_e32 v195, 0x3f317217, v151
	v_fma_f32 v195, v151, s52, -v195
	v_fmac_f32_e32 v195, 0x3377d1cf, v151
	v_fmac_f32_e32 v195, 0x3f317217, v151
	v_sub_f32_e32 v151, v194, v195
	v_min_f32_e32 v194, 0, v147
	v_mul_f32_e64 v147, |v147|, s57
	v_exp_f32_e32 v147, v147
	s_nop 0
	v_add_f32_e32 v147, 1.0, v147
	v_log_f32_e32 v147, v147
	s_nop 0
	v_mul_f32_e32 v195, 0x3f317217, v147
	v_fma_f32 v195, v147, s52, -v195
	v_fmac_f32_e32 v195, 0x3377d1cf, v147
	v_fmac_f32_e32 v195, 0x3f317217, v147
	v_sub_f32_e32 v194, v194, v195
	v_mul_f32_e32 v147, 0x3fb8aa3b, v151
	v_exp_f32_e32 v147, v147
	s_nop 0
	v_fma_f32 v147, v185, v147, v143
	v_log_f32_e32 v147, v147
	s_nop 0
	v_mul_f32_e32 v195, 0x3f317217, v147
	v_fma_f32 v195, v147, s52, -v195
	v_fmac_f32_e32 v195, 0x3377d1cf, v147
	v_fmac_f32_e32 v195, 0x3f317217, v147
	v_cndmask_b32_e64 v147, v151, v195, s[24:25]
; __device__ __forceinline__ float silu_f(float x) { return x * __builtin_amdgcn_rcpf(1.f + __expf(-x)); }
; __device__ __forceinline__ v4u pack8(const f32x4 a, const f32x4 b) { v4u w; w.x = cvt_pk_bf16(a[0], a[1]); w.y = cvt_pk_bf16(a[2], a[3]); w.z = cvt_pk_bf16(b[0], b[1]); w.w = cvt_pk_bf16(b[2], b[3]); return w; }
;     __device__ __forceinline__ void operator()(const f32x4 (&acc)[2][2][4][2], const pg8::Unit& u, int wr, int wc, int fr, int fq) const {
;     ...
;         if (grp == 0) { WIN_LOOP( _Pragma("unroll") for (int i = 0; i < 4; ++i) { a[i] = silu_f(a[i]); b[i] = silu_f(b[i]); } *(v4u*)(QO + (size_t)row * DM + c) = pack8(a, b); ) }
;         else if (grp == 3) { WIN_LOOP( _Pragma("unroll") for (int i = 0; i < 4; ++i) { a[i] = silu_f(a[i]); b[i] = silu_f(b[i]); } *(v4u*)(GH + (size_t)row * 512 + c) = pack8(a, b); ) }
;         else if (grp == 1) {
;             f32x4 l0[2], l1[2];
; #pragma unroll
;             for (int bj = 0; bj < 2; ++bj) { l0[bj] = *(const f32x4*)(lb + cb + bj * 128); l1[bj] = *(const f32x4*)(lb + cb + bj * 128 + 4); }
;             WIN_LOOP( _Pragma("unroll") for (int i = 0; i < 4; ++i) { const float s0 = fminf(a[i], 0.f) - __logf(1.f + __expf(-fabsf(a[i]))), s1 = fminf(b[i], 0.f) - __logf(1.f + __expf(-fabsf(b[i]))); const float la = l0[bj][i], lbv = l1[bj][i];
;                     a[i] = la > 0.f ? __logf(la + (1.f - la) * __expf(s0)) : s0; b[i] = lbv > 0.f ? __logf(lbv + (1.f - lbv) * __expf(s1)) : s1; }
;                 *(f32x4*)(LF + (size_t)row * 512 + c) = a; *(f32x4*)(LF + (size_t)row * 512 + c + 4) = b; __builtin_amdgcn_sched_barrier(0); ) }
	v_mul_f32_e32 v151, 0x3fb8aa3b, v194
	v_exp_f32_e32 v151, v151
	s_nop 0
	v_fma_f32 v151, v184, v151, v139
	v_log_f32_e32 v151, v151
	s_nop 0
	v_mul_f32_e32 v195, 0x3f317217, v151
	v_fma_f32 v195, v151, s52, -v195
	v_fmac_f32_e32 v195, 0x3377d1cf, v151
	v_fmac_f32_e32 v195, 0x3f317217, v151
	v_cndmask_b32_e64 v151, v194, v195, s[22:23]
	global_store_dwordx4 v[170:171], v[144:147], off
	global_store_dwordx4 v[170:171], v[148:151], off offset:16
	s_nop 1
	v_pk_mul_f32 v[148:149], v[92:93], v[168:169] op_sel_hi:[1,0]
	v_pk_mul_f32 v[150:151], v[94:95], v[168:169] op_sel_hi:[1,0]
	v_pk_mul_f32 v[146:147], v[90:91], v[168:169] op_sel_hi:[1,0]
	v_pk_mul_f32 v[144:145], v[88:89], v[168:169] op_sel_hi:[1,0]
	v_min_f32_e32 v168, 0, v148
	v_mul_f32_e64 v148, |v148|, s57
	v_exp_f32_e32 v148, v148
	s_nop 0
	v_add_f32_e32 v148, 1.0, v148
	v_log_f32_e32 v148, v148
	s_nop 0
	v_mul_f32_e32 v194, 0x3f317217, v148
	v_fma_f32 v194, v148, s52, -v194
	v_fmac_f32_e32 v194, 0x3377d1cf, v148
	v_fmac_f32_e32 v194, 0x3f317217, v148
	v_sub_f32_e32 v148, v168, v194
	v_min_f32_e32 v168, 0, v144
	v_mul_f32_e64 v144, |v144|, s57
	v_exp_f32_e32 v144, v144
	s_nop 0
	v_add_f32_e32 v144, 1.0, v144
	v_log_f32_e32 v144, v144
	s_nop 0
	v_mul_f32_e32 v194, 0x3f317217, v144
	v_fma_f32 v194, v144, s52, -v194
	v_fmac_f32_e32 v194, 0x3377d1cf, v144
	v_fmac_f32_e32 v194, 0x3f317217, v144
	v_sub_f32_e32 v168, v168, v194
	v_mul_f32_e32 v144, 0x3fb8aa3b, v148
	v_exp_f32_e32 v144, v144
	s_nop 0
	v_fma_f32 v144, v183, v144, v132
	v_log_f32_e32 v144, v144
	s_nop 0
	v_mul_f32_e32 v194, 0x3f317217, v144
	v_fma_f32 v194, v144, s52, -v194
	v_fmac_f32_e32 v194, 0x3377d1cf, v144
	v_fmac_f32_e32 v194, 0x3f317217, v144
	v_cndmask_b32_e64 v144, v148, v194, s[20:21]
	v_mul_f32_e32 v148, 0x3fb8aa3b, v168
	v_exp_f32_e32 v148, v148
	s_nop 0
	v_fma_f32 v148, v182, v148, v128
	v_log_f32_e32 v148, v148
	s_nop 0
	v_mul_f32_e32 v194, 0x3f317217, v148
	v_fma_f32 v194, v148, s52, -v194
	v_fmac_f32_e32 v194, 0x3377d1cf, v148
	v_fmac_f32_e32 v194, 0x3f317217, v148
	v_cndmask_b32_e64 v148, v168, v194, s[18:19]
	v_min_f32_e32 v168, 0, v149
	v_mul_f32_e64 v149, |v149|, s57
	v_exp_f32_e32 v149, v149
	s_nop 0
	v_add_f32_e32 v149, 1.0, v149
	v_log_f32_e32 v149, v149
	s_nop 0
	v_mul_f32_e32 v194, 0x3f317217, v149
	v_fma_f32 v194, v149, s52, -v194
	v_fmac_f32_e32 v194, 0x3377d1cf, v149
	v_fmac_f32_e32 v194, 0x3f317217, v149
	v_sub_f32_e32 v149, v168, v194
	v_min_f32_e32 v168, 0, v145
	v_mul_f32_e64 v145, |v145|, s57
	v_exp_f32_e32 v145, v145
	s_nop 0
	v_add_f32_e32 v145, 1.0, v145
	v_log_f32_e32 v145, v145
	s_nop 0
	v_mul_f32_e32 v194, 0x3f317217, v145
	v_fma_f32 v194, v145, s52, -v194
	v_fmac_f32_e32 v194, 0x3377d1cf, v145
	v_fmac_f32_e32 v194, 0x3f317217, v145
	v_sub_f32_e32 v168, v168, v194
	v_mul_f32_e32 v145, 0x3fb8aa3b, v149
	v_exp_f32_e32 v145, v145
	s_nop 0
	v_fma_f32 v145, v181, v145, v133
	v_log_f32_e32 v145, v145
	s_nop 0
	v_mul_f32_e32 v194, 0x3f317217, v145
	v_fma_f32 v194, v145, s52, -v194
	v_fmac_f32_e32 v194, 0x3377d1cf, v145
	v_fmac_f32_e32 v194, 0x3f317217, v145
	v_cndmask_b32_e64 v145, v149, v194, s[16:17]
	v_mul_f32_e32 v149, 0x3fb8aa3b, v168
	v_exp_f32_e32 v149, v149
	s_nop 0
	v_fma_f32 v149, v180, v149, v129
	v_log_f32_e32 v149, v149
	s_nop 0
	v_mul_f32_e32 v194, 0x3f317217, v149
	v_fma_f32 v194, v149, s52, -v194
	v_fmac_f32_e32 v194, 0x3377d1cf, v149
	v_fmac_f32_e32 v194, 0x3f317217, v149
	v_cndmask_b32_e64 v149, v168, v194, s[14:15]
	v_min_f32_e32 v168, 0, v150
	v_mul_f32_e64 v150, |v150|, s57
	v_exp_f32_e32 v150, v150
	s_nop 0
	v_add_f32_e32 v150, 1.0, v150
	v_log_f32_e32 v150, v150
	s_nop 0
	v_mul_f32_e32 v194, 0x3f317217, v150
	v_fma_f32 v194, v150, s52, -v194
	v_fmac_f32_e32 v194, 0x3377d1cf, v150
	v_fmac_f32_e32 v194, 0x3f317217, v150
	v_sub_f32_e32 v150, v168, v194
	v_min_f32_e32 v168, 0, v146
	v_mul_f32_e64 v146, |v146|, s57
	v_exp_f32_e32 v146, v146
	s_nop 0
	v_add_f32_e32 v146, 1.0, v146
	v_log_f32_e32 v146, v146
	s_nop 0
	v_mul_f32_e32 v194, 0x3f317217, v146
	v_fma_f32 v194, v146, s52, -v194
	v_fmac_f32_e32 v194, 0x3377d1cf, v146
	v_fmac_f32_e32 v194, 0x3f317217, v146
	v_sub_f32_e32 v168, v168, v194
	v_mul_f32_e32 v146, 0x3fb8aa3b, v150
	v_exp_f32_e32 v146, v146
	s_nop 0
	v_fma_f32 v146, v179, v146, v134
	v_log_f32_e32 v146, v146
	s_nop 0
	v_mul_f32_e32 v194, 0x3f317217, v146
	v_fma_f32 v194, v146, s52, -v194
	v_fmac_f32_e32 v194, 0x3377d1cf, v146
	v_fmac_f32_e32 v194, 0x3f317217, v146
	v_cndmask_b32_e64 v146, v150, v194, s[12:13]
	v_mul_f32_e32 v150, 0x3fb8aa3b, v168
	v_exp_f32_e32 v150, v150
	s_nop 0
	v_fma_f32 v150, v178, v150, v130
	v_log_f32_e32 v150, v150
	s_nop 0
	v_mul_f32_e32 v194, 0x3f317217, v150
	v_fma_f32 v194, v150, s52, -v194
	v_fmac_f32_e32 v194, 0x3377d1cf, v150
	v_fmac_f32_e32 v194, 0x3f317217, v150
	v_cndmask_b32_e64 v150, v168, v194, s[10:11]
	v_min_f32_e32 v168, 0, v151
	v_mul_f32_e64 v151, |v151|, s57
	v_exp_f32_e32 v151, v151
	s_nop 0
	v_add_f32_e32 v151, 1.0, v151
	v_log_f32_e32 v151, v151
	s_nop 0
	v_mul_f32_e32 v194, 0x3f317217, v151
	v_fma_f32 v194, v151, s52, -v194
	v_fmac_f32_e32 v194, 0x3377d1cf, v151
	v_fmac_f32_e32 v194, 0x3f317217, v151
	v_sub_f32_e32 v151, v168, v194
	v_min_f32_e32 v168, 0, v147
	v_mul_f32_e64 v147, |v147|, s57
	v_exp_f32_e32 v147, v147
	s_nop 0
	v_add_f32_e32 v147, 1.0, v147
	v_log_f32_e32 v147, v147
	s_nop 0
	v_mul_f32_e32 v194, 0x3f317217, v147
	v_fma_f32 v194, v147, s52, -v194
	v_fmac_f32_e32 v194, 0x3377d1cf, v147
	v_fmac_f32_e32 v194, 0x3f317217, v147
	v_sub_f32_e32 v168, v168, v194
	v_mul_f32_e32 v147, 0x3fb8aa3b, v151
	v_exp_f32_e32 v147, v147
	s_nop 0
	v_fma_f32 v147, v177, v147, v135
	v_log_f32_e32 v147, v147
	s_nop 0
	v_mul_f32_e32 v194, 0x3f317217, v147
	v_fma_f32 v194, v147, s52, -v194
	v_fmac_f32_e32 v194, 0x3377d1cf, v147
	v_fmac_f32_e32 v194, 0x3f317217, v147
	v_cndmask_b32_e64 v147, v151, v194, s[8:9]
	v_mul_f32_e32 v151, 0x3fb8aa3b, v168
	v_exp_f32_e32 v151, v151
	s_nop 0
	v_fma_f32 v151, v167, v151, v131
	v_log_f32_e32 v151, v151
	s_nop 0
	v_mul_f32_e32 v194, 0x3f317217, v151
	v_fma_f32 v194, v151, s52, -v194
	v_fmac_f32_e32 v194, 0x3377d1cf, v151
	v_fmac_f32_e32 v194, 0x3f317217, v151
	v_cndmask_b32_e32 v151, v168, v194, vcc
	global_store_dwordx4 v[170:171], v[144:147], off offset:512
	global_store_dwordx4 v[170:171], v[148:151], off offset:528
	s_nop 1
	v_add_u32_e32 v148, 0x90, v166
	v_ashrrev_i32_e32 v149, 31, v148
	v_lshlrev_b64 v[144:145], 6, v[148:149]
	v_lshl_add_u64 v[144:145], v[160:161], 0, v[144:145]
	s_nop 0
	s_waitcnt lgkmcnt(0)
; __device__ __forceinline__ float silu_f(float x) { return x * __builtin_amdgcn_rcpf(1.f + __expf(-x)); }
; __device__ __forceinline__ v4u pack8(const f32x4 a, const f32x4 b) { v4u w; w.x = cvt_pk_bf16(a[0], a[1]); w.y = cvt_pk_bf16(a[2], a[3]); w.z = cvt_pk_bf16(b[0], b[1]); w.w = cvt_pk_bf16(b[2], b[3]); return w; }
;     __device__ __forceinline__ void operator()(const f32x4 (&acc)[2][2][4][2], const pg8::Unit& u, int wr, int wc, int fr, int fq) const {
;     ...
;         if (grp == 0) { WIN_LOOP( _Pragma("unroll") for (int i = 0; i < 4; ++i) { a[i] = silu_f(a[i]); b[i] = silu_f(b[i]); } *(v4u*)(QO + (size_t)row * DM + c) = pack8(a, b); ) }
;         else if (grp == 3) { WIN_LOOP( _Pragma("unroll") for (int i = 0; i < 4; ++i) { a[i] = silu_f(a[i]); b[i] = silu_f(b[i]); } *(v4u*)(GH + (size_t)row * 512 + c) = pack8(a, b); ) }
;         else if (grp == 1) {
;             f32x4 l0[2], l1[2];
; #pragma unroll
;             for (int bj = 0; bj < 2; ++bj) { l0[bj] = *(const f32x4*)(lb + cb + bj * 128); l1[bj] = *(const f32x4*)(lb + cb + bj * 128 + 4); }
;             WIN_LOOP( _Pragma("unroll") for (int i = 0; i < 4; ++i) { const float s0 = fminf(a[i], 0.f) - __logf(1.f + __expf(-fabsf(a[i]))), s1 = fminf(b[i], 0.f) - __logf(1.f + __expf(-fabsf(b[i]))); const float la = l0[bj][i], lbv = l1[bj][i];
;                     a[i] = la > 0.f ? __logf(la + (1.f - la) * __expf(s0)) : s0; b[i] = lbv > 0.f ? __logf(lbv + (1.f - lbv) * __expf(s1)) : s1; }
;                 *(f32x4*)(LF + (size_t)row * 512 + c) = a; *(f32x4*)(LF + (size_t)row * 512 + c + 4) = b; __builtin_amdgcn_sched_barrier(0); ) }
	s_nop 3
	s_nop 0
	s_nop 1
	s_waitcnt lgkmcnt(0)
	s_nop 1
	s_waitcnt lgkmcnt(0)
	s_nop 1
	v_mov_b32_e32 v168, v240
	v_lshlrev_b64 v[144:145], 11, v[148:149]
	v_lshl_add_u64 v[170:171], s[50:51], 0, v[144:145]
	v_lshl_add_u64 v[170:171], v[170:171], 0, v[192:193]
	v_pk_mul_f32 v[148:149], v[20:21], v[168:169] op_sel_hi:[1,0]
	v_pk_mul_f32 v[144:145], v[16:17], v[168:169] op_sel_hi:[1,0]
	v_min_f32_e32 v194, 0, v148
	v_mul_f32_e64 v148, |v148|, s57
	v_exp_f32_e32 v148, v148
	v_pk_mul_f32 v[150:151], v[22:23], v[168:169] op_sel_hi:[1,0]
	v_pk_mul_f32 v[146:147], v[18:19], v[168:169] op_sel_hi:[1,0]
	v_add_f32_e32 v148, 1.0, v148
	v_log_f32_e32 v148, v148
	s_nop 0
	v_mul_f32_e32 v195, 0x3f317217, v148
	v_fma_f32 v195, v148, s52, -v195
	v_fmac_f32_e32 v195, 0x3377d1cf, v148
	v_fmac_f32_e32 v195, 0x3f317217, v148
	v_sub_f32_e32 v148, v194, v195
	v_min_f32_e32 v194, 0, v144
	v_mul_f32_e64 v144, |v144|, s57
	v_exp_f32_e32 v144, v144
	s_nop 0
	v_add_f32_e32 v144, 1.0, v144
	v_log_f32_e32 v144, v144
	s_nop 0
	v_mul_f32_e32 v195, 0x3f317217, v144
	v_fma_f32 v195, v144, s52, -v195
	v_fmac_f32_e32 v195, 0x3377d1cf, v144
	v_fmac_f32_e32 v195, 0x3f317217, v144
	v_sub_f32_e32 v194, v194, v195
	v_mul_f32_e32 v144, 0x3fb8aa3b, v148
	v_exp_f32_e32 v144, v144
	s_nop 0
	v_fma_f32 v144, v190, v144, v140
	v_log_f32_e32 v144, v144
	s_nop 0
	v_mul_f32_e32 v195, 0x3f317217, v144
	v_fma_f32 v195, v144, s52, -v195
	v_fmac_f32_e32 v195, 0x3377d1cf, v144
	v_fmac_f32_e32 v195, 0x3f317217, v144
	v_cndmask_b32_e64 v144, v148, v195, s[38:39]
	v_mul_f32_e32 v148, 0x3fb8aa3b, v194
	v_exp_f32_e32 v148, v148
	s_nop 0
	v_fma_f32 v148, v191, v148, v136
	v_log_f32_e32 v148, v148
	s_nop 0
	v_mul_f32_e32 v195, 0x3f317217, v148
	v_fma_f32 v195, v148, s52, -v195
	v_fmac_f32_e32 v195, 0x3377d1cf, v148
	v_fmac_f32_e32 v195, 0x3f317217, v148
	v_cndmask_b32_e64 v148, v194, v195, s[36:37]
	v_min_f32_e32 v194, 0, v149
	v_mul_f32_e64 v149, |v149|, s57
	v_exp_f32_e32 v149, v149
	s_nop 0
	v_add_f32_e32 v149, 1.0, v149
	v_log_f32_e32 v149, v149
	s_nop 0
	v_mul_f32_e32 v195, 0x3f317217, v149
	v_fma_f32 v195, v149, s52, -v195
	v_fmac_f32_e32 v195, 0x3377d1cf, v149
	v_fmac_f32_e32 v195, 0x3f317217, v149
	v_sub_f32_e32 v149, v194, v195
	v_min_f32_e32 v194, 0, v145
	v_mul_f32_e64 v145, |v145|, s57
	v_exp_f32_e32 v145, v145
	s_nop 0
	v_add_f32_e32 v145, 1.0, v145
	v_log_f32_e32 v145, v145
	s_nop 0
	v_mul_f32_e32 v195, 0x3f317217, v145
	v_fma_f32 v195, v145, s52, -v195
	v_fmac_f32_e32 v195, 0x3377d1cf, v145
	v_fmac_f32_e32 v195, 0x3f317217, v145
	v_sub_f32_e32 v194, v194, v195
	v_mul_f32_e32 v145, 0x3fb8aa3b, v149
	v_exp_f32_e32 v145, v145
	s_nop 0
	v_fma_f32 v145, v188, v145, v141
	v_log_f32_e32 v145, v145
	s_nop 0
	v_mul_f32_e32 v195, 0x3f317217, v145
	v_fma_f32 v195, v145, s52, -v195
	v_fmac_f32_e32 v195, 0x3377d1cf, v145
	v_fmac_f32_e32 v195, 0x3f317217, v145
	v_cndmask_b32_e64 v145, v149, v195, s[34:35]
	v_mul_f32_e32 v149, 0x3fb8aa3b, v194
	v_exp_f32_e32 v149, v149
	s_nop 0
	v_fma_f32 v149, v189, v149, v137
	v_log_f32_e32 v149, v149
	s_nop 0
	v_mul_f32_e32 v195, 0x3f317217, v149
	v_fma_f32 v195, v149, s52, -v195
	v_fmac_f32_e32 v195, 0x3377d1cf, v149
	v_fmac_f32_e32 v195, 0x3f317217, v149
	v_cndmask_b32_e64 v149, v194, v195, s[30:31]
	v_min_f32_e32 v194, 0, v150
	v_mul_f32_e64 v150, |v150|, s57
	v_exp_f32_e32 v150, v150
	s_nop 0
	v_add_f32_e32 v150, 1.0, v150
	v_log_f32_e32 v150, v150
	s_nop 0
	v_mul_f32_e32 v195, 0x3f317217, v150
	v_fma_f32 v195, v150, s52, -v195
	v_fmac_f32_e32 v195, 0x3377d1cf, v150
	v_fmac_f32_e32 v195, 0x3f317217, v150
	v_sub_f32_e32 v150, v194, v195
	v_min_f32_e32 v194, 0, v146
	v_mul_f32_e64 v146, |v146|, s57
	v_exp_f32_e32 v146, v146
	s_nop 0
	v_add_f32_e32 v146, 1.0, v146
	v_log_f32_e32 v146, v146
	s_nop 0
	v_mul_f32_e32 v195, 0x3f317217, v146
	v_fma_f32 v195, v146, s52, -v195
	v_fmac_f32_e32 v195, 0x3377d1cf, v146
	v_fmac_f32_e32 v195, 0x3f317217, v146
	v_sub_f32_e32 v194, v194, v195
	v_mul_f32_e32 v146, 0x3fb8aa3b, v150
	v_exp_f32_e32 v146, v146
	s_nop 0
	v_fma_f32 v146, v187, v146, v142
	v_log_f32_e32 v146, v146
	s_nop 0
	v_mul_f32_e32 v195, 0x3f317217, v146
	v_fma_f32 v195, v146, s52, -v195
	v_fmac_f32_e32 v195, 0x3377d1cf, v146
	v_fmac_f32_e32 v195, 0x3f317217, v146
	v_cndmask_b32_e64 v146, v150, v195, s[28:29]
	v_mul_f32_e32 v150, 0x3fb8aa3b, v194
	v_exp_f32_e32 v150, v150
	s_nop 0
	v_fma_f32 v150, v186, v150, v138
	v_log_f32_e32 v150, v150
	s_nop 0
	v_mul_f32_e32 v195, 0x3f317217, v150
	v_fma_f32 v195, v150, s52, -v195
	v_fmac_f32_e32 v195, 0x3377d1cf, v150
	v_fmac_f32_e32 v195, 0x3f317217, v150
	v_cndmask_b32_e64 v150, v194, v195, s[26:27]
	v_min_f32_e32 v194, 0, v151
	v_mul_f32_e64 v151, |v151|, s57
	v_exp_f32_e32 v151, v151
	s_nop 0
	v_add_f32_e32 v151, 1.0, v151
	v_log_f32_e32 v151, v151
	s_nop 0
	v_mul_f32_e32 v195, 0x3f317217, v151
	v_fma_f32 v195, v151, s52, -v195
	v_fmac_f32_e32 v195, 0x3377d1cf, v151
	v_fmac_f32_e32 v195, 0x3f317217, v151
	v_sub_f32_e32 v151, v194, v195
	v_min_f32_e32 v194, 0, v147
	v_mul_f32_e64 v147, |v147|, s57
	v_exp_f32_e32 v147, v147
	s_nop 0
	v_add_f32_e32 v147, 1.0, v147
	v_log_f32_e32 v147, v147
	s_nop 0
	v_mul_f32_e32 v195, 0x3f317217, v147
	v_fma_f32 v195, v147, s52, -v195
	v_fmac_f32_e32 v195, 0x3377d1cf, v147
	v_fmac_f32_e32 v195, 0x3f317217, v147
	v_sub_f32_e32 v194, v194, v195
	v_mul_f32_e32 v147, 0x3fb8aa3b, v151
	v_exp_f32_e32 v147, v147
	s_nop 0
	v_fma_f32 v147, v185, v147, v143
	v_log_f32_e32 v147, v147
	s_nop 0
	v_mul_f32_e32 v195, 0x3f317217, v147
	v_fma_f32 v195, v147, s52, -v195
	v_fmac_f32_e32 v195, 0x3377d1cf, v147
	v_fmac_f32_e32 v195, 0x3f317217, v147
	v_cndmask_b32_e64 v147, v151, v195, s[24:25]
; __device__ __forceinline__ float silu_f(float x) { return x * __builtin_amdgcn_rcpf(1.f + __expf(-x)); }
; __device__ __forceinline__ v4u pack8(const f32x4 a, const f32x4 b) { v4u w; w.x = cvt_pk_bf16(a[0], a[1]); w.y = cvt_pk_bf16(a[2], a[3]); w.z = cvt_pk_bf16(b[0], b[1]); w.w = cvt_pk_bf16(b[2], b[3]); return w; }
;     __device__ __forceinline__ void operator()(const f32x4 (&acc)[2][2][4][2], const pg8::Unit& u, int wr, int wc, int fr, int fq) const {
;     ...
;         if (grp == 0) { WIN_LOOP( _Pragma("unroll") for (int i = 0; i < 4; ++i) { a[i] = silu_f(a[i]); b[i] = silu_f(b[i]); } *(v4u*)(QO + (size_t)row * DM + c) = pack8(a, b); ) }
;         else if (grp == 3) { WIN_LOOP( _Pragma("unroll") for (int i = 0; i < 4; ++i) { a[i] = silu_f(a[i]); b[i] = silu_f(b[i]); } *(v4u*)(GH + (size_t)row * 512 + c) = pack8(a, b); ) }
;         else if (grp == 1) {
;             f32x4 l0[2], l1[2];
; #pragma unroll
;             for (int bj = 0; bj < 2; ++bj) { l0[bj] = *(const f32x4*)(lb + cb + bj * 128); l1[bj] = *(const f32x4*)(lb + cb + bj * 128 + 4); }
;             WIN_LOOP( _Pragma("unroll") for (int i = 0; i < 4; ++i) { const float s0 = fminf(a[i], 0.f) - __logf(1.f + __expf(-fabsf(a[i]))), s1 = fminf(b[i], 0.f) - __logf(1.f + __expf(-fabsf(b[i]))); const float la = l0[bj][i], lbv = l1[bj][i];
;                     a[i] = la > 0.f ? __logf(la + (1.f - la) * __expf(s0)) : s0; b[i] = lbv > 0.f ? __logf(lbv + (1.f - lbv) * __expf(s1)) : s1; }
;                 *(f32x4*)(LF + (size_t)row * 512 + c) = a; *(f32x4*)(LF + (size_t)row * 512 + c + 4) = b; __builtin_amdgcn_sched_barrier(0); ) }
	v_mul_f32_e32 v151, 0x3fb8aa3b, v194
	v_exp_f32_e32 v151, v151
	s_nop 0
	v_fma_f32 v151, v184, v151, v139
	v_log_f32_e32 v151, v151
	s_nop 0
	v_mul_f32_e32 v195, 0x3f317217, v151
	v_fma_f32 v195, v151, s52, -v195
	v_fmac_f32_e32 v195, 0x3377d1cf, v151
	v_fmac_f32_e32 v195, 0x3f317217, v151
	v_cndmask_b32_e64 v151, v194, v195, s[22:23]
	global_store_dwordx4 v[170:171], v[144:147], off
	global_store_dwordx4 v[170:171], v[148:151], off offset:16
	s_nop 1
	v_pk_mul_f32 v[148:149], v[84:85], v[168:169] op_sel_hi:[1,0]
	v_pk_mul_f32 v[150:151], v[86:87], v[168:169] op_sel_hi:[1,0]
	v_pk_mul_f32 v[146:147], v[82:83], v[168:169] op_sel_hi:[1,0]
	v_pk_mul_f32 v[144:145], v[80:81], v[168:169] op_sel_hi:[1,0]
	v_min_f32_e32 v168, 0, v148
	v_mul_f32_e64 v148, |v148|, s57
	v_exp_f32_e32 v148, v148
	s_nop 0
	v_add_f32_e32 v148, 1.0, v148
	v_log_f32_e32 v148, v148
	s_nop 0
	v_mul_f32_e32 v194, 0x3f317217, v148
	v_fma_f32 v194, v148, s52, -v194
	v_fmac_f32_e32 v194, 0x3377d1cf, v148
	v_fmac_f32_e32 v194, 0x3f317217, v148
	v_sub_f32_e32 v148, v168, v194
	v_min_f32_e32 v168, 0, v144
	v_mul_f32_e64 v144, |v144|, s57
	v_exp_f32_e32 v144, v144
	s_nop 0
	v_add_f32_e32 v144, 1.0, v144
	v_log_f32_e32 v144, v144
	s_nop 0
	v_mul_f32_e32 v194, 0x3f317217, v144
	v_fma_f32 v194, v144, s52, -v194
	v_fmac_f32_e32 v194, 0x3377d1cf, v144
	v_fmac_f32_e32 v194, 0x3f317217, v144
	v_sub_f32_e32 v168, v168, v194
	v_mul_f32_e32 v144, 0x3fb8aa3b, v148
	v_exp_f32_e32 v144, v144
	s_nop 0
	v_fma_f32 v144, v183, v144, v132
	v_log_f32_e32 v144, v144
	s_nop 0
	v_mul_f32_e32 v194, 0x3f317217, v144
	v_fma_f32 v194, v144, s52, -v194
	v_fmac_f32_e32 v194, 0x3377d1cf, v144
	v_fmac_f32_e32 v194, 0x3f317217, v144
	v_cndmask_b32_e64 v144, v148, v194, s[20:21]
	v_mul_f32_e32 v148, 0x3fb8aa3b, v168
	v_exp_f32_e32 v148, v148
	s_nop 0
	v_fma_f32 v148, v182, v148, v128
	v_log_f32_e32 v148, v148
	s_nop 0
	v_mul_f32_e32 v194, 0x3f317217, v148
	v_fma_f32 v194, v148, s52, -v194
	v_fmac_f32_e32 v194, 0x3377d1cf, v148
	v_fmac_f32_e32 v194, 0x3f317217, v148
	v_cndmask_b32_e64 v148, v168, v194, s[18:19]
	v_min_f32_e32 v168, 0, v149
	v_mul_f32_e64 v149, |v149|, s57
	v_exp_f32_e32 v149, v149
	s_nop 0
	v_add_f32_e32 v149, 1.0, v149
	v_log_f32_e32 v149, v149
	s_nop 0
	v_mul_f32_e32 v194, 0x3f317217, v149
	v_fma_f32 v194, v149, s52, -v194
	v_fmac_f32_e32 v194, 0x3377d1cf, v149
	v_fmac_f32_e32 v194, 0x3f317217, v149
	v_sub_f32_e32 v149, v168, v194
	v_min_f32_e32 v168, 0, v145
	v_mul_f32_e64 v145, |v145|, s57
	v_exp_f32_e32 v145, v145
	s_nop 0
	v_add_f32_e32 v145, 1.0, v145
	v_log_f32_e32 v145, v145
	s_nop 0
	v_mul_f32_e32 v194, 0x3f317217, v145
	v_fma_f32 v194, v145, s52, -v194
	v_fmac_f32_e32 v194, 0x3377d1cf, v145
	v_fmac_f32_e32 v194, 0x3f317217, v145
	v_sub_f32_e32 v168, v168, v194
	v_mul_f32_e32 v145, 0x3fb8aa3b, v149
	v_exp_f32_e32 v145, v145
	s_nop 0
	v_fma_f32 v145, v181, v145, v133
	v_log_f32_e32 v145, v145
	s_nop 0
	v_mul_f32_e32 v194, 0x3f317217, v145
	v_fma_f32 v194, v145, s52, -v194
	v_fmac_f32_e32 v194, 0x3377d1cf, v145
	v_fmac_f32_e32 v194, 0x3f317217, v145
	v_cndmask_b32_e64 v145, v149, v194, s[16:17]
	v_mul_f32_e32 v149, 0x3fb8aa3b, v168
	v_exp_f32_e32 v149, v149
	s_nop 0
	v_fma_f32 v149, v180, v149, v129
	v_log_f32_e32 v149, v149
	s_nop 0
	v_mul_f32_e32 v194, 0x3f317217, v149
	v_fma_f32 v194, v149, s52, -v194
	v_fmac_f32_e32 v194, 0x3377d1cf, v149
	v_fmac_f32_e32 v194, 0x3f317217, v149
	v_cndmask_b32_e64 v149, v168, v194, s[14:15]
	v_min_f32_e32 v168, 0, v150
	v_mul_f32_e64 v150, |v150|, s57
	v_exp_f32_e32 v150, v150
	s_nop 0
	v_add_f32_e32 v150, 1.0, v150
	v_log_f32_e32 v150, v150
	s_nop 0
	v_mul_f32_e32 v194, 0x3f317217, v150
	v_fma_f32 v194, v150, s52, -v194
	v_fmac_f32_e32 v194, 0x3377d1cf, v150
	v_fmac_f32_e32 v194, 0x3f317217, v150
	v_sub_f32_e32 v150, v168, v194
	v_min_f32_e32 v168, 0, v146
	v_mul_f32_e64 v146, |v146|, s57
	v_exp_f32_e32 v146, v146
	s_nop 0
	v_add_f32_e32 v146, 1.0, v146
	v_log_f32_e32 v146, v146
	s_nop 0
	v_mul_f32_e32 v194, 0x3f317217, v146
	v_fma_f32 v194, v146, s52, -v194
	v_fmac_f32_e32 v194, 0x3377d1cf, v146
	v_fmac_f32_e32 v194, 0x3f317217, v146
	v_sub_f32_e32 v168, v168, v194
	v_mul_f32_e32 v146, 0x3fb8aa3b, v150
	v_exp_f32_e32 v146, v146
	s_nop 0
	v_fma_f32 v146, v179, v146, v134
	v_log_f32_e32 v146, v146
	s_nop 0
	v_mul_f32_e32 v194, 0x3f317217, v146
	v_fma_f32 v194, v146, s52, -v194
	v_fmac_f32_e32 v194, 0x3377d1cf, v146
	v_fmac_f32_e32 v194, 0x3f317217, v146
	v_cndmask_b32_e64 v146, v150, v194, s[12:13]
	v_mul_f32_e32 v150, 0x3fb8aa3b, v168
	v_exp_f32_e32 v150, v150
	s_nop 0
	v_fma_f32 v150, v178, v150, v130
	v_log_f32_e32 v150, v150
	s_nop 0
	v_mul_f32_e32 v194, 0x3f317217, v150
	v_fma_f32 v194, v150, s52, -v194
	v_fmac_f32_e32 v194, 0x3377d1cf, v150
	v_fmac_f32_e32 v194, 0x3f317217, v150
	v_cndmask_b32_e64 v150, v168, v194, s[10:11]
	v_min_f32_e32 v168, 0, v151
	v_mul_f32_e64 v151, |v151|, s57
	v_exp_f32_e32 v151, v151
	s_nop 0
	v_add_f32_e32 v151, 1.0, v151
	v_log_f32_e32 v151, v151
	s_nop 0
	v_mul_f32_e32 v194, 0x3f317217, v151
	v_fma_f32 v194, v151, s52, -v194
	v_fmac_f32_e32 v194, 0x3377d1cf, v151
	v_fmac_f32_e32 v194, 0x3f317217, v151
	v_sub_f32_e32 v151, v168, v194
	v_min_f32_e32 v168, 0, v147
	v_mul_f32_e64 v147, |v147|, s57
	v_exp_f32_e32 v147, v147
	s_nop 0
	v_add_f32_e32 v147, 1.0, v147
	v_log_f32_e32 v147, v147
	s_nop 0
	v_mul_f32_e32 v194, 0x3f317217, v147
	v_fma_f32 v194, v147, s52, -v194
	v_fmac_f32_e32 v194, 0x3377d1cf, v147
	v_fmac_f32_e32 v194, 0x3f317217, v147
	v_sub_f32_e32 v168, v168, v194
	v_mul_f32_e32 v147, 0x3fb8aa3b, v151
	v_exp_f32_e32 v147, v147
	s_nop 0
	v_fma_f32 v147, v177, v147, v135
	v_log_f32_e32 v147, v147
	s_nop 0
	v_mul_f32_e32 v194, 0x3f317217, v147
	v_fma_f32 v194, v147, s52, -v194
	v_fmac_f32_e32 v194, 0x3377d1cf, v147
	v_fmac_f32_e32 v194, 0x3f317217, v147
	v_cndmask_b32_e64 v147, v151, v194, s[8:9]
	v_mul_f32_e32 v151, 0x3fb8aa3b, v168
	v_exp_f32_e32 v151, v151
	s_nop 0
	v_fma_f32 v151, v167, v151, v131
	v_log_f32_e32 v151, v151
	s_nop 0
	v_mul_f32_e32 v194, 0x3f317217, v151
	v_fma_f32 v194, v151, s52, -v194
	v_fmac_f32_e32 v194, 0x3377d1cf, v151
	v_fmac_f32_e32 v194, 0x3f317217, v151
	v_cndmask_b32_e32 v151, v168, v194, vcc
	global_store_dwordx4 v[170:171], v[144:147], off offset:512
	global_store_dwordx4 v[170:171], v[148:151], off offset:528
	s_nop 1
	v_add_u32_e32 v148, 0xa0, v166
	v_ashrrev_i32_e32 v149, 31, v148
	v_lshlrev_b64 v[144:145], 6, v[148:149]
	v_lshl_add_u64 v[144:145], v[160:161], 0, v[144:145]
	s_nop 0
	s_waitcnt lgkmcnt(0)
; __device__ __forceinline__ float silu_f(float x) { return x * __builtin_amdgcn_rcpf(1.f + __expf(-x)); }
; __device__ __forceinline__ v4u pack8(const f32x4 a, const f32x4 b) { v4u w; w.x = cvt_pk_bf16(a[0], a[1]); w.y = cvt_pk_bf16(a[2], a[3]); w.z = cvt_pk_bf16(b[0], b[1]); w.w = cvt_pk_bf16(b[2], b[3]); return w; }
;     __device__ __forceinline__ void operator()(const f32x4 (&acc)[2][2][4][2], const pg8::Unit& u, int wr, int wc, int fr, int fq) const {
;     ...
;         if (grp == 0) { WIN_LOOP( _Pragma("unroll") for (int i = 0; i < 4; ++i) { a[i] = silu_f(a[i]); b[i] = silu_f(b[i]); } *(v4u*)(QO + (size_t)row * DM + c) = pack8(a, b); ) }
;         else if (grp == 3) { WIN_LOOP( _Pragma("unroll") for (int i = 0; i < 4; ++i) { a[i] = silu_f(a[i]); b[i] = silu_f(b[i]); } *(v4u*)(GH + (size_t)row * 512 + c) = pack8(a, b); ) }
;         else if (grp == 1) {
;             f32x4 l0[2], l1[2];
; #pragma unroll
;             for (int bj = 0; bj < 2; ++bj) { l0[bj] = *(const f32x4*)(lb + cb + bj * 128); l1[bj] = *(const f32x4*)(lb + cb + bj * 128 + 4); }
;             WIN_LOOP( _Pragma("unroll") for (int i = 0; i < 4; ++i) { const float s0 = fminf(a[i], 0.f) - __logf(1.f + __expf(-fabsf(a[i]))), s1 = fminf(b[i], 0.f) - __logf(1.f + __expf(-fabsf(b[i]))); const float la = l0[bj][i], lbv = l1[bj][i];
;                     a[i] = la > 0.f ? __logf(la + (1.f - la) * __expf(s0)) : s0; b[i] = lbv > 0.f ? __logf(lbv + (1.f - lbv) * __expf(s1)) : s1; }
;                 *(f32x4*)(LF + (size_t)row * 512 + c) = a; *(f32x4*)(LF + (size_t)row * 512 + c + 4) = b; __builtin_amdgcn_sched_barrier(0); ) }
	s_nop 3
	s_nop 0
	s_nop 1
	s_waitcnt lgkmcnt(0)
	s_nop 1
	s_waitcnt lgkmcnt(0)
	s_nop 1
	v_mov_b32_e32 v168, v241
	v_lshlrev_b64 v[144:145], 11, v[148:149]
	v_lshl_add_u64 v[170:171], s[50:51], 0, v[144:145]
	v_lshl_add_u64 v[170:171], v[170:171], 0, v[192:193]
	v_pk_mul_f32 v[148:149], v[12:13], v[168:169] op_sel_hi:[1,0]
	v_pk_mul_f32 v[144:145], v[8:9], v[168:169] op_sel_hi:[1,0]
	v_min_f32_e32 v194, 0, v148
	v_mul_f32_e64 v148, |v148|, s57
	v_exp_f32_e32 v148, v148
	v_pk_mul_f32 v[150:151], v[14:15], v[168:169] op_sel_hi:[1,0]
	v_pk_mul_f32 v[146:147], v[10:11], v[168:169] op_sel_hi:[1,0]
	v_add_f32_e32 v148, 1.0, v148
	v_log_f32_e32 v148, v148
	s_nop 0
	v_mul_f32_e32 v195, 0x3f317217, v148
	v_fma_f32 v195, v148, s52, -v195
	v_fmac_f32_e32 v195, 0x3377d1cf, v148
	v_fmac_f32_e32 v195, 0x3f317217, v148
	v_sub_f32_e32 v148, v194, v195
	v_min_f32_e32 v194, 0, v144
	v_mul_f32_e64 v144, |v144|, s57
	v_exp_f32_e32 v144, v144
	s_nop 0
	v_add_f32_e32 v144, 1.0, v144
	v_log_f32_e32 v144, v144
	s_nop 0
	v_mul_f32_e32 v195, 0x3f317217, v144
	v_fma_f32 v195, v144, s52, -v195
	v_fmac_f32_e32 v195, 0x3377d1cf, v144
	v_fmac_f32_e32 v195, 0x3f317217, v144
	v_sub_f32_e32 v194, v194, v195
	v_mul_f32_e32 v144, 0x3fb8aa3b, v148
	v_exp_f32_e32 v144, v144
	s_nop 0
	v_fma_f32 v144, v190, v144, v140
	v_log_f32_e32 v144, v144
	s_nop 0
	v_mul_f32_e32 v195, 0x3f317217, v144
	v_fma_f32 v195, v144, s52, -v195
	v_fmac_f32_e32 v195, 0x3377d1cf, v144
	v_fmac_f32_e32 v195, 0x3f317217, v144
	v_cndmask_b32_e64 v144, v148, v195, s[38:39]
	v_mul_f32_e32 v148, 0x3fb8aa3b, v194
	v_exp_f32_e32 v148, v148
	s_nop 0
	v_fma_f32 v148, v191, v148, v136
	v_log_f32_e32 v148, v148
	s_nop 0
	v_mul_f32_e32 v195, 0x3f317217, v148
	v_fma_f32 v195, v148, s52, -v195
	v_fmac_f32_e32 v195, 0x3377d1cf, v148
	v_fmac_f32_e32 v195, 0x3f317217, v148
	v_cndmask_b32_e64 v148, v194, v195, s[36:37]
	v_min_f32_e32 v194, 0, v149
	v_mul_f32_e64 v149, |v149|, s57
	v_exp_f32_e32 v149, v149
	s_nop 0
	v_add_f32_e32 v149, 1.0, v149
	v_log_f32_e32 v149, v149
	s_nop 0
	v_mul_f32_e32 v195, 0x3f317217, v149
	v_fma_f32 v195, v149, s52, -v195
	v_fmac_f32_e32 v195, 0x3377d1cf, v149
	v_fmac_f32_e32 v195, 0x3f317217, v149
	v_sub_f32_e32 v149, v194, v195
	v_min_f32_e32 v194, 0, v145
	v_mul_f32_e64 v145, |v145|, s57
	v_exp_f32_e32 v145, v145
	s_nop 0
	v_add_f32_e32 v145, 1.0, v145
	v_log_f32_e32 v145, v145
	s_nop 0
	v_mul_f32_e32 v195, 0x3f317217, v145
	v_fma_f32 v195, v145, s52, -v195
	v_fmac_f32_e32 v195, 0x3377d1cf, v145
	v_fmac_f32_e32 v195, 0x3f317217, v145
	v_sub_f32_e32 v194, v194, v195
	v_mul_f32_e32 v145, 0x3fb8aa3b, v149
	v_exp_f32_e32 v145, v145
	s_nop 0
	v_fma_f32 v145, v188, v145, v141
	v_log_f32_e32 v145, v145
	s_nop 0
	v_mul_f32_e32 v195, 0x3f317217, v145
	v_fma_f32 v195, v145, s52, -v195
	v_fmac_f32_e32 v195, 0x3377d1cf, v145
	v_fmac_f32_e32 v195, 0x3f317217, v145
	v_cndmask_b32_e64 v145, v149, v195, s[34:35]
	v_mul_f32_e32 v149, 0x3fb8aa3b, v194
	v_exp_f32_e32 v149, v149
	s_nop 0
	v_fma_f32 v149, v189, v149, v137
	v_log_f32_e32 v149, v149
	s_nop 0
	v_mul_f32_e32 v195, 0x3f317217, v149
	v_fma_f32 v195, v149, s52, -v195
	v_fmac_f32_e32 v195, 0x3377d1cf, v149
	v_fmac_f32_e32 v195, 0x3f317217, v149
	v_cndmask_b32_e64 v149, v194, v195, s[30:31]
	v_min_f32_e32 v194, 0, v150
	v_mul_f32_e64 v150, |v150|, s57
	v_exp_f32_e32 v150, v150
	s_nop 0
	v_add_f32_e32 v150, 1.0, v150
	v_log_f32_e32 v150, v150
	s_nop 0
	v_mul_f32_e32 v195, 0x3f317217, v150
	v_fma_f32 v195, v150, s52, -v195
	v_fmac_f32_e32 v195, 0x3377d1cf, v150
	v_fmac_f32_e32 v195, 0x3f317217, v150
	v_sub_f32_e32 v150, v194, v195
	v_min_f32_e32 v194, 0, v146
	v_mul_f32_e64 v146, |v146|, s57
	v_exp_f32_e32 v146, v146
	s_nop 0
	v_add_f32_e32 v146, 1.0, v146
	v_log_f32_e32 v146, v146
	s_nop 0
	v_mul_f32_e32 v195, 0x3f317217, v146
	v_fma_f32 v195, v146, s52, -v195
	v_fmac_f32_e32 v195, 0x3377d1cf, v146
	v_fmac_f32_e32 v195, 0x3f317217, v146
	v_sub_f32_e32 v194, v194, v195
	v_mul_f32_e32 v146, 0x3fb8aa3b, v150
	v_exp_f32_e32 v146, v146
	s_nop 0
	v_fma_f32 v146, v187, v146, v142
	v_log_f32_e32 v146, v146
	s_nop 0
	v_mul_f32_e32 v195, 0x3f317217, v146
	v_fma_f32 v195, v146, s52, -v195
	v_fmac_f32_e32 v195, 0x3377d1cf, v146
	v_fmac_f32_e32 v195, 0x3f317217, v146
	v_cndmask_b32_e64 v146, v150, v195, s[28:29]
	v_mul_f32_e32 v150, 0x3fb8aa3b, v194
	v_exp_f32_e32 v150, v150
	s_nop 0
	v_fma_f32 v150, v186, v150, v138
	v_log_f32_e32 v150, v150
	s_nop 0
	v_mul_f32_e32 v195, 0x3f317217, v150
	v_fma_f32 v195, v150, s52, -v195
	v_fmac_f32_e32 v195, 0x3377d1cf, v150
	v_fmac_f32_e32 v195, 0x3f317217, v150
	v_cndmask_b32_e64 v150, v194, v195, s[26:27]
	v_min_f32_e32 v194, 0, v151
	v_mul_f32_e64 v151, |v151|, s57
	v_exp_f32_e32 v151, v151
	s_nop 0
	v_add_f32_e32 v151, 1.0, v151
	v_log_f32_e32 v151, v151
	s_nop 0
	v_mul_f32_e32 v195, 0x3f317217, v151
	v_fma_f32 v195, v151, s52, -v195
	v_fmac_f32_e32 v195, 0x3377d1cf, v151
	v_fmac_f32_e32 v195, 0x3f317217, v151
	v_sub_f32_e32 v151, v194, v195
	v_min_f32_e32 v194, 0, v147
	v_mul_f32_e64 v147, |v147|, s57
	v_exp_f32_e32 v147, v147
	s_nop 0
	v_add_f32_e32 v147, 1.0, v147
	v_log_f32_e32 v147, v147
	s_nop 0
	v_mul_f32_e32 v195, 0x3f317217, v147
	v_fma_f32 v195, v147, s52, -v195
	v_fmac_f32_e32 v195, 0x3377d1cf, v147
	v_fmac_f32_e32 v195, 0x3f317217, v147
	v_sub_f32_e32 v194, v194, v195
	v_mul_f32_e32 v147, 0x3fb8aa3b, v151
	v_exp_f32_e32 v147, v147
	s_nop 0
	v_fma_f32 v147, v185, v147, v143
	v_log_f32_e32 v147, v147
	s_nop 0
	v_mul_f32_e32 v195, 0x3f317217, v147
	v_fma_f32 v195, v147, s52, -v195
	v_fmac_f32_e32 v195, 0x3377d1cf, v147
	v_fmac_f32_e32 v195, 0x3f317217, v147
	v_cndmask_b32_e64 v147, v151, v195, s[24:25]
; __device__ __forceinline__ float silu_f(float x) { return x * __builtin_amdgcn_rcpf(1.f + __expf(-x)); }
; __device__ __forceinline__ v4u pack8(const f32x4 a, const f32x4 b) { v4u w; w.x = cvt_pk_bf16(a[0], a[1]); w.y = cvt_pk_bf16(a[2], a[3]); w.z = cvt_pk_bf16(b[0], b[1]); w.w = cvt_pk_bf16(b[2], b[3]); return w; }
;     __device__ __forceinline__ void operator()(const f32x4 (&acc)[2][2][4][2], const pg8::Unit& u, int wr, int wc, int fr, int fq) const {
;     ...
;         if (grp == 0) { WIN_LOOP( _Pragma("unroll") for (int i = 0; i < 4; ++i) { a[i] = silu_f(a[i]); b[i] = silu_f(b[i]); } *(v4u*)(QO + (size_t)row * DM + c) = pack8(a, b); ) }
;         else if (grp == 3) { WIN_LOOP( _Pragma("unroll") for (int i = 0; i < 4; ++i) { a[i] = silu_f(a[i]); b[i] = silu_f(b[i]); } *(v4u*)(GH + (size_t)row * 512 + c) = pack8(a, b); ) }
;         else if (grp == 1) {
;             f32x4 l0[2], l1[2];
; #pragma unroll
;             for (int bj = 0; bj < 2; ++bj) { l0[bj] = *(const f32x4*)(lb + cb + bj * 128); l1[bj] = *(const f32x4*)(lb + cb + bj * 128 + 4); }
;             WIN_LOOP( _Pragma("unroll") for (int i = 0; i < 4; ++i) { const float s0 = fminf(a[i], 0.f) - __logf(1.f + __expf(-fabsf(a[i]))), s1 = fminf(b[i], 0.f) - __logf(1.f + __expf(-fabsf(b[i]))); const float la = l0[bj][i], lbv = l1[bj][i];
;                     a[i] = la > 0.f ? __logf(la + (1.f - la) * __expf(s0)) : s0; b[i] = lbv > 0.f ? __logf(lbv + (1.f - lbv) * __expf(s1)) : s1; }
;                 *(f32x4*)(LF + (size_t)row * 512 + c) = a; *(f32x4*)(LF + (size_t)row * 512 + c + 4) = b; __builtin_amdgcn_sched_barrier(0); ) }
	v_mul_f32_e32 v151, 0x3fb8aa3b, v194
	v_exp_f32_e32 v151, v151
	s_nop 0
	v_fma_f32 v151, v184, v151, v139
	v_log_f32_e32 v151, v151
	s_nop 0
	v_mul_f32_e32 v195, 0x3f317217, v151
	v_fma_f32 v195, v151, s52, -v195
	v_fmac_f32_e32 v195, 0x3377d1cf, v151
	v_fmac_f32_e32 v195, 0x3f317217, v151
	v_cndmask_b32_e64 v151, v194, v195, s[22:23]
	global_store_dwordx4 v[170:171], v[144:147], off
	global_store_dwordx4 v[170:171], v[148:151], off offset:16
	s_nop 1
	v_pk_mul_f32 v[148:149], v[76:77], v[168:169] op_sel_hi:[1,0]
	v_pk_mul_f32 v[150:151], v[78:79], v[168:169] op_sel_hi:[1,0]
	v_pk_mul_f32 v[146:147], v[74:75], v[168:169] op_sel_hi:[1,0]
	v_pk_mul_f32 v[144:145], v[72:73], v[168:169] op_sel_hi:[1,0]
	v_min_f32_e32 v168, 0, v148
	v_mul_f32_e64 v148, |v148|, s57
	v_exp_f32_e32 v148, v148
	s_nop 0
	v_add_f32_e32 v148, 1.0, v148
	v_log_f32_e32 v148, v148
	s_nop 0
	v_mul_f32_e32 v194, 0x3f317217, v148
	v_fma_f32 v194, v148, s52, -v194
	v_fmac_f32_e32 v194, 0x3377d1cf, v148
	v_fmac_f32_e32 v194, 0x3f317217, v148
	v_sub_f32_e32 v148, v168, v194
	v_min_f32_e32 v168, 0, v144
	v_mul_f32_e64 v144, |v144|, s57
	v_exp_f32_e32 v144, v144
	s_nop 0
	v_add_f32_e32 v144, 1.0, v144
	v_log_f32_e32 v144, v144
	s_nop 0
	v_mul_f32_e32 v194, 0x3f317217, v144
	v_fma_f32 v194, v144, s52, -v194
	v_fmac_f32_e32 v194, 0x3377d1cf, v144
	v_fmac_f32_e32 v194, 0x3f317217, v144
	v_sub_f32_e32 v168, v168, v194
	v_mul_f32_e32 v144, 0x3fb8aa3b, v148
	v_exp_f32_e32 v144, v144
	s_nop 0
	v_fma_f32 v144, v183, v144, v132
	v_log_f32_e32 v144, v144
	s_nop 0
	v_mul_f32_e32 v194, 0x3f317217, v144
	v_fma_f32 v194, v144, s52, -v194
	v_fmac_f32_e32 v194, 0x3377d1cf, v144
	v_fmac_f32_e32 v194, 0x3f317217, v144
	v_cndmask_b32_e64 v144, v148, v194, s[20:21]
	v_mul_f32_e32 v148, 0x3fb8aa3b, v168
	v_exp_f32_e32 v148, v148
	s_nop 0
	v_fma_f32 v148, v182, v148, v128
	v_log_f32_e32 v148, v148
	s_nop 0
	v_mul_f32_e32 v194, 0x3f317217, v148
	v_fma_f32 v194, v148, s52, -v194
	v_fmac_f32_e32 v194, 0x3377d1cf, v148
	v_fmac_f32_e32 v194, 0x3f317217, v148
	v_cndmask_b32_e64 v148, v168, v194, s[18:19]
	v_min_f32_e32 v168, 0, v149
	v_mul_f32_e64 v149, |v149|, s57
	v_exp_f32_e32 v149, v149
	s_nop 0
	v_add_f32_e32 v149, 1.0, v149
	v_log_f32_e32 v149, v149
	s_nop 0
	v_mul_f32_e32 v194, 0x3f317217, v149
	v_fma_f32 v194, v149, s52, -v194
	v_fmac_f32_e32 v194, 0x3377d1cf, v149
	v_fmac_f32_e32 v194, 0x3f317217, v149
	v_sub_f32_e32 v149, v168, v194
	v_min_f32_e32 v168, 0, v145
	v_mul_f32_e64 v145, |v145|, s57
	v_exp_f32_e32 v145, v145
	s_nop 0
	v_add_f32_e32 v145, 1.0, v145
	v_log_f32_e32 v145, v145
	s_nop 0
	v_mul_f32_e32 v194, 0x3f317217, v145
	v_fma_f32 v194, v145, s52, -v194
	v_fmac_f32_e32 v194, 0x3377d1cf, v145
	v_fmac_f32_e32 v194, 0x3f317217, v145
	v_sub_f32_e32 v168, v168, v194
	v_mul_f32_e32 v145, 0x3fb8aa3b, v149
	v_exp_f32_e32 v145, v145
	s_nop 0
	v_fma_f32 v145, v181, v145, v133
	v_log_f32_e32 v145, v145
	s_nop 0
	v_mul_f32_e32 v194, 0x3f317217, v145
	v_fma_f32 v194, v145, s52, -v194
	v_fmac_f32_e32 v194, 0x3377d1cf, v145
	v_fmac_f32_e32 v194, 0x3f317217, v145
	v_cndmask_b32_e64 v145, v149, v194, s[16:17]
	v_mul_f32_e32 v149, 0x3fb8aa3b, v168
	v_exp_f32_e32 v149, v149
	s_nop 0
	v_fma_f32 v149, v180, v149, v129
	v_log_f32_e32 v149, v149
	s_nop 0
	v_mul_f32_e32 v194, 0x3f317217, v149
	v_fma_f32 v194, v149, s52, -v194
	v_fmac_f32_e32 v194, 0x3377d1cf, v149
	v_fmac_f32_e32 v194, 0x3f317217, v149
	v_cndmask_b32_e64 v149, v168, v194, s[14:15]
	v_min_f32_e32 v168, 0, v150
	v_mul_f32_e64 v150, |v150|, s57
	v_exp_f32_e32 v150, v150
	s_nop 0
	v_add_f32_e32 v150, 1.0, v150
	v_log_f32_e32 v150, v150
	s_nop 0
	v_mul_f32_e32 v194, 0x3f317217, v150
	v_fma_f32 v194, v150, s52, -v194
	v_fmac_f32_e32 v194, 0x3377d1cf, v150
	v_fmac_f32_e32 v194, 0x3f317217, v150
	v_sub_f32_e32 v150, v168, v194
	v_min_f32_e32 v168, 0, v146
	v_mul_f32_e64 v146, |v146|, s57
	v_exp_f32_e32 v146, v146
	s_nop 0
	v_add_f32_e32 v146, 1.0, v146
	v_log_f32_e32 v146, v146
	s_nop 0
	v_mul_f32_e32 v194, 0x3f317217, v146
	v_fma_f32 v194, v146, s52, -v194
	v_fmac_f32_e32 v194, 0x3377d1cf, v146
	v_fmac_f32_e32 v194, 0x3f317217, v146
	v_sub_f32_e32 v168, v168, v194
	v_mul_f32_e32 v146, 0x3fb8aa3b, v150
	v_exp_f32_e32 v146, v146
	s_nop 0
	v_fma_f32 v146, v179, v146, v134
	v_log_f32_e32 v146, v146
	s_nop 0
	v_mul_f32_e32 v194, 0x3f317217, v146
	v_fma_f32 v194, v146, s52, -v194
	v_fmac_f32_e32 v194, 0x3377d1cf, v146
	v_fmac_f32_e32 v194, 0x3f317217, v146
	v_cndmask_b32_e64 v146, v150, v194, s[12:13]
	v_mul_f32_e32 v150, 0x3fb8aa3b, v168
	v_exp_f32_e32 v150, v150
	s_nop 0
	v_fma_f32 v150, v178, v150, v130
	v_log_f32_e32 v150, v150
	s_nop 0
	v_mul_f32_e32 v194, 0x3f317217, v150
	v_fma_f32 v194, v150, s52, -v194
	v_fmac_f32_e32 v194, 0x3377d1cf, v150
	v_fmac_f32_e32 v194, 0x3f317217, v150
	v_cndmask_b32_e64 v150, v168, v194, s[10:11]
	v_min_f32_e32 v168, 0, v151
	v_mul_f32_e64 v151, |v151|, s57
	v_exp_f32_e32 v151, v151
	s_nop 0
	v_add_f32_e32 v151, 1.0, v151
	v_log_f32_e32 v151, v151
	s_nop 0
	v_mul_f32_e32 v194, 0x3f317217, v151
	v_fma_f32 v194, v151, s52, -v194
	v_fmac_f32_e32 v194, 0x3377d1cf, v151
	v_fmac_f32_e32 v194, 0x3f317217, v151
	v_sub_f32_e32 v151, v168, v194
	v_min_f32_e32 v168, 0, v147
	v_mul_f32_e64 v147, |v147|, s57
	v_exp_f32_e32 v147, v147
	s_nop 0
	v_add_f32_e32 v147, 1.0, v147
	v_log_f32_e32 v147, v147
	s_nop 0
	v_mul_f32_e32 v194, 0x3f317217, v147
	v_fma_f32 v194, v147, s52, -v194
	v_fmac_f32_e32 v194, 0x3377d1cf, v147
	v_fmac_f32_e32 v194, 0x3f317217, v147
	v_sub_f32_e32 v168, v168, v194
	v_mul_f32_e32 v147, 0x3fb8aa3b, v151
	v_exp_f32_e32 v147, v147
	s_nop 0
	v_fma_f32 v147, v177, v147, v135
	v_log_f32_e32 v147, v147
	s_nop 0
	v_mul_f32_e32 v194, 0x3f317217, v147
	v_fma_f32 v194, v147, s52, -v194
	v_fmac_f32_e32 v194, 0x3377d1cf, v147
	v_fmac_f32_e32 v194, 0x3f317217, v147
	v_cndmask_b32_e64 v147, v151, v194, s[8:9]
	v_mul_f32_e32 v151, 0x3fb8aa3b, v168
	v_exp_f32_e32 v151, v151
	s_nop 0
	v_fma_f32 v151, v167, v151, v131
	v_log_f32_e32 v151, v151
	s_nop 0
	v_mul_f32_e32 v194, 0x3f317217, v151
	v_fma_f32 v194, v151, s52, -v194
	v_fmac_f32_e32 v194, 0x3377d1cf, v151
	v_fmac_f32_e32 v194, 0x3f317217, v151
	v_cndmask_b32_e32 v151, v168, v194, vcc
	global_store_dwordx4 v[170:171], v[144:147], off offset:512
	global_store_dwordx4 v[170:171], v[148:151], off offset:528
	s_nop 1
	v_add_u32_e32 v148, 0xb0, v166
	v_ashrrev_i32_e32 v149, 31, v148
	v_lshlrev_b64 v[144:145], 6, v[148:149]
	v_lshl_add_u64 v[144:145], v[160:161], 0, v[144:145]
	s_nop 0
	s_waitcnt lgkmcnt(0)
; __device__ __forceinline__ float silu_f(float x) { return x * __builtin_amdgcn_rcpf(1.f + __expf(-x)); }
; __device__ __forceinline__ v4u pack8(const f32x4 a, const f32x4 b) { v4u w; w.x = cvt_pk_bf16(a[0], a[1]); w.y = cvt_pk_bf16(a[2], a[3]); w.z = cvt_pk_bf16(b[0], b[1]); w.w = cvt_pk_bf16(b[2], b[3]); return w; }
;     __device__ __forceinline__ void operator()(const f32x4 (&acc)[2][2][4][2], const pg8::Unit& u, int wr, int wc, int fr, int fq) const {
;     ...
;         if (grp == 0) { WIN_LOOP( _Pragma("unroll") for (int i = 0; i < 4; ++i) { a[i] = silu_f(a[i]); b[i] = silu_f(b[i]); } *(v4u*)(QO + (size_t)row * DM + c) = pack8(a, b); ) }
;         else if (grp == 3) { WIN_LOOP( _Pragma("unroll") for (int i = 0; i < 4; ++i) { a[i] = silu_f(a[i]); b[i] = silu_f(b[i]); } *(v4u*)(GH + (size_t)row * 512 + c) = pack8(a, b); ) }
;         else if (grp == 1) {
;             f32x4 l0[2], l1[2];
; #pragma unroll
;             for (int bj = 0; bj < 2; ++bj) { l0[bj] = *(const f32x4*)(lb + cb + bj * 128); l1[bj] = *(const f32x4*)(lb + cb + bj * 128 + 4); }
;             WIN_LOOP( _Pragma("unroll") for (int i = 0; i < 4; ++i) { const float s0 = fminf(a[i], 0.f) - __logf(1.f + __expf(-fabsf(a[i]))), s1 = fminf(b[i], 0.f) - __logf(1.f + __expf(-fabsf(b[i]))); const float la = l0[bj][i], lbv = l1[bj][i];
;                     a[i] = la > 0.f ? __logf(la + (1.f - la) * __expf(s0)) : s0; b[i] = lbv > 0.f ? __logf(lbv + (1.f - lbv) * __expf(s1)) : s1; }
;                 *(f32x4*)(LF + (size_t)row * 512 + c) = a; *(f32x4*)(LF + (size_t)row * 512 + c + 4) = b; __builtin_amdgcn_sched_barrier(0); ) }
	s_nop 3
	v_lshlrev_b64 v[146:147], 11, v[148:149]
	s_nop 1
	v_lshl_add_u64 v[146:147], s[50:51], 0, v[146:147]
	v_lshl_add_u64 v[146:147], v[146:147], 0, v[192:193]
	s_waitcnt lgkmcnt(0)
	s_nop 1
	s_waitcnt lgkmcnt(0)
	s_nop 1
	v_mov_b32_e32 v144, v245
	s_nop 0
	v_pk_mul_f32 v[170:171], v[4:5], v[144:145] op_sel_hi:[1,0]
	v_pk_mul_f32 v[150:151], v[6:7], v[144:145] op_sel_hi:[1,0]
	v_pk_mul_f32 v[148:149], v[2:3], v[144:145] op_sel_hi:[1,0]
	v_pk_mul_f32 v[168:169], v[0:1], v[144:145] op_sel_hi:[1,0]
	v_min_f32_e32 v145, 0, v170
	v_mul_f32_e64 v170, |v170|, s57
	v_exp_f32_e32 v170, v170
	s_nop 0
	v_add_f32_e32 v170, 1.0, v170
	v_log_f32_e32 v170, v170
	s_nop 0
	v_mul_f32_e32 v194, 0x3f317217, v170
	v_fma_f32 v194, v170, s52, -v194
	v_fmac_f32_e32 v194, 0x3377d1cf, v170
	v_fmac_f32_e32 v194, 0x3f317217, v170
	v_sub_f32_e32 v145, v145, v194
	v_min_f32_e32 v170, 0, v168
	v_mul_f32_e64 v168, |v168|, s57
	v_exp_f32_e32 v168, v168
	s_nop 0
	v_add_f32_e32 v168, 1.0, v168
	v_log_f32_e32 v168, v168
	s_nop 0
	v_mul_f32_e32 v194, 0x3f317217, v168
	v_fma_f32 v194, v168, s52, -v194
	v_fmac_f32_e32 v194, 0x3377d1cf, v168
	v_fmac_f32_e32 v194, 0x3f317217, v168
	v_sub_f32_e32 v168, v170, v194
	v_mul_f32_e32 v170, 0x3fb8aa3b, v145
	v_exp_f32_e32 v170, v170
	s_nop 0
	v_fma_f32 v140, v190, v170, v140
	v_log_f32_e32 v140, v140
	s_nop 0
	v_mul_f32_e32 v170, 0x3f317217, v140
	v_fma_f32 v170, v140, s52, -v170
	v_fmac_f32_e32 v170, 0x3377d1cf, v140
	v_fmac_f32_e32 v170, 0x3f317217, v140
	v_cndmask_b32_e64 v140, v145, v170, s[38:39]
	v_mul_f32_e32 v145, 0x3fb8aa3b, v168
	v_exp_f32_e32 v145, v145
	v_readlane_b32 s42, v255, 57
	v_readlane_b32 s43, v255, 58
	v_fma_f32 v136, v191, v145, v136
	v_log_f32_e32 v136, v136
	s_nop 0
	v_mul_f32_e32 v145, 0x3f317217, v136
	v_fma_f32 v145, v136, s52, -v145
	v_fmac_f32_e32 v145, 0x3377d1cf, v136
	v_fmac_f32_e32 v145, 0x3f317217, v136
	v_cndmask_b32_e64 v136, v168, v145, s[36:37]
	v_mul_f32_e64 v168, |v171|, s57
	v_exp_f32_e32 v168, v168
	v_min_f32_e32 v145, 0, v171
	s_mov_b32 s40, s2
	v_add_f32_e32 v168, 1.0, v168
	v_log_f32_e32 v168, v168
	s_nop 0
	v_mul_f32_e32 v170, 0x3f317217, v168
	v_fma_f32 v170, v168, s52, -v170
	v_fmac_f32_e32 v170, 0x3377d1cf, v168
	v_fmac_f32_e32 v170, 0x3f317217, v168
	v_sub_f32_e32 v145, v145, v170
	v_min_f32_e32 v168, 0, v169
	v_mul_f32_e64 v169, |v169|, s57
	v_exp_f32_e32 v169, v169
	s_nop 0
	v_add_f32_e32 v169, 1.0, v169
	v_log_f32_e32 v169, v169
	s_nop 0
	v_mul_f32_e32 v170, 0x3f317217, v169
	v_fma_f32 v170, v169, s52, -v170
	v_fmac_f32_e32 v170, 0x3377d1cf, v169
	v_fmac_f32_e32 v170, 0x3f317217, v169
	v_sub_f32_e32 v168, v168, v170
	v_mul_f32_e32 v169, 0x3fb8aa3b, v145
	v_exp_f32_e32 v169, v169
	s_nop 0
	v_fma_f32 v141, v188, v169, v141
	v_log_f32_e32 v141, v141
	s_nop 0
	v_mul_f32_e32 v169, 0x3f317217, v141
	v_fma_f32 v169, v141, s52, -v169
	v_fmac_f32_e32 v169, 0x3377d1cf, v141
	v_fmac_f32_e32 v169, 0x3f317217, v141
	v_cndmask_b32_e64 v141, v145, v169, s[34:35]
	v_mul_f32_e32 v145, 0x3fb8aa3b, v168
	v_exp_f32_e32 v145, v145
	v_readlane_b32 s38, v255, 53
	v_readlane_b32 s39, v255, 54
	v_fma_f32 v137, v189, v145, v137
	v_log_f32_e32 v137, v137
	s_nop 0
	v_mul_f32_e32 v145, 0x3f317217, v137
	v_fma_f32 v145, v137, s52, -v145
	v_fmac_f32_e32 v145, 0x3377d1cf, v137
	v_fmac_f32_e32 v145, 0x3f317217, v137
	v_mov_b32_e32 v137, v145
	v_min_f32_e32 v145, 0, v150
	v_mul_f32_e64 v150, |v150|, s57
	v_exp_f32_e32 v150, v150
	v_cndmask_b32_e64 v137, v168, v137, s[30:31]
	v_readlane_b32 s36, v255, 51
	v_readlane_b32 s37, v255, 52
	v_add_f32_e32 v150, 1.0, v150
	v_log_f32_e32 v150, v150
	s_nop 0
	v_mul_f32_e32 v168, 0x3f317217, v150
	v_fma_f32 v168, v150, s52, -v168
	v_fmac_f32_e32 v168, 0x3377d1cf, v150
	v_fmac_f32_e32 v168, 0x3f317217, v150
	v_sub_f32_e32 v145, v145, v168
	v_min_f32_e32 v150, 0, v148
	v_mul_f32_e64 v148, |v148|, s57
	v_exp_f32_e32 v148, v148
	s_nop 0
	v_add_f32_e32 v148, 1.0, v148
	v_log_f32_e32 v148, v148
	s_nop 0
	v_mul_f32_e32 v168, 0x3f317217, v148
	v_fma_f32 v168, v148, s52, -v168
	v_fmac_f32_e32 v168, 0x3377d1cf, v148
	v_fmac_f32_e32 v168, 0x3f317217, v148
	v_sub_f32_e32 v148, v150, v168
	v_mul_f32_e32 v150, 0x3fb8aa3b, v145
	v_exp_f32_e32 v150, v150
	s_nop 0
	v_fma_f32 v142, v187, v150, v142
	v_log_f32_e32 v142, v142
	s_nop 0
	v_mul_f32_e32 v150, 0x3f317217, v142
	v_fma_f32 v150, v142, s52, -v150
	v_fmac_f32_e32 v150, 0x3377d1cf, v142
	v_fmac_f32_e32 v150, 0x3f317217, v142
	v_cndmask_b32_e64 v142, v145, v150, s[28:29]
	v_mul_f32_e32 v145, 0x3fb8aa3b, v148
	v_exp_f32_e32 v145, v145
	v_readlane_b32 s34, v255, 49
	v_readlane_b32 s35, v255, 50
	v_fma_f32 v138, v186, v145, v138
	v_log_f32_e32 v138, v138
	s_nop 0
	v_mul_f32_e32 v145, 0x3f317217, v138
	v_fma_f32 v145, v138, s52, -v145
	v_fmac_f32_e32 v145, 0x3377d1cf, v138
	v_fmac_f32_e32 v145, 0x3f317217, v138
	v_cndmask_b32_e64 v138, v148, v145, s[26:27]
	v_mul_f32_e64 v148, |v151|, s57
	v_exp_f32_e32 v148, v148
	v_min_f32_e32 v145, 0, v151
	v_readlane_b32 s30, v255, 47
	v_readlane_b32 s31, v255, 48
	v_add_f32_e32 v148, 1.0, v148
	v_log_f32_e32 v148, v148
	s_nop 0
	v_mul_f32_e32 v150, 0x3f317217, v148
	v_fma_f32 v150, v148, s52, -v150
	v_fmac_f32_e32 v150, 0x3377d1cf, v148
	v_fmac_f32_e32 v150, 0x3f317217, v148
	v_sub_f32_e32 v145, v145, v150
	v_min_f32_e32 v148, 0, v149
	v_mul_f32_e64 v149, |v149|, s57
	v_exp_f32_e32 v149, v149
	s_nop 0
	v_add_f32_e32 v149, 1.0, v149
	v_log_f32_e32 v149, v149
	s_nop 0
	v_mul_f32_e32 v150, 0x3f317217, v149
	v_fma_f32 v150, v149, s52, -v150
	v_fmac_f32_e32 v150, 0x3377d1cf, v149
	v_fmac_f32_e32 v150, 0x3f317217, v149
	v_sub_f32_e32 v148, v148, v150
	v_mul_f32_e32 v149, 0x3fb8aa3b, v145
	v_exp_f32_e32 v149, v149
; __device__ __forceinline__ float silu_f(float x) { return x * __builtin_amdgcn_rcpf(1.f + __expf(-x)); }
; __device__ __forceinline__ v4u pack8(const f32x4 a, const f32x4 b) { v4u w; w.x = cvt_pk_bf16(a[0], a[1]); w.y = cvt_pk_bf16(a[2], a[3]); w.z = cvt_pk_bf16(b[0], b[1]); w.w = cvt_pk_bf16(b[2], b[3]); return w; }
;     __device__ __forceinline__ void operator()(const f32x4 (&acc)[2][2][4][2], const pg8::Unit& u, int wr, int wc, int fr, int fq) const {
;     ...
;         if (grp == 0) { WIN_LOOP( _Pragma("unroll") for (int i = 0; i < 4; ++i) { a[i] = silu_f(a[i]); b[i] = silu_f(b[i]); } *(v4u*)(QO + (size_t)row * DM + c) = pack8(a, b); ) }
;         else if (grp == 3) { WIN_LOOP( _Pragma("unroll") for (int i = 0; i < 4; ++i) { a[i] = silu_f(a[i]); b[i] = silu_f(b[i]); } *(v4u*)(GH + (size_t)row * 512 + c) = pack8(a, b); ) }
;         else if (grp == 1) {
;             f32x4 l0[2], l1[2];
; #pragma unroll
;             for (int bj = 0; bj < 2; ++bj) { l0[bj] = *(const f32x4*)(lb + cb + bj * 128); l1[bj] = *(const f32x4*)(lb + cb + bj * 128 + 4); }
;             WIN_LOOP( _Pragma("unroll") for (int i = 0; i < 4; ++i) { const float s0 = fminf(a[i], 0.f) - __logf(1.f + __expf(-fabsf(a[i]))), s1 = fminf(b[i], 0.f) - __logf(1.f + __expf(-fabsf(b[i]))); const float la = l0[bj][i], lbv = l1[bj][i];
;                     a[i] = la > 0.f ? __logf(la + (1.f - la) * __expf(s0)) : s0; b[i] = lbv > 0.f ? __logf(lbv + (1.f - lbv) * __expf(s1)) : s1; }
;                 *(f32x4*)(LF + (size_t)row * 512 + c) = a; *(f32x4*)(LF + (size_t)row * 512 + c + 4) = b; __builtin_amdgcn_sched_barrier(0); ) }
	s_nop 0
	v_fmac_f32_e32 v143, v185, v149
	v_cmp_gt_f32_e64 s[26:27], s97, v143
	s_nop 1
	v_cndmask_b32_e64 v149, 0, 32, s[26:27]
	v_ldexp_f32 v143, v143, v149
	v_log_f32_e32 v143, v143
	s_nop 0
	v_mul_f32_e32 v149, 0x3f317217, v143
	v_fma_f32 v149, v143, s52, -v149
	v_fmac_f32_e32 v149, 0x3377d1cf, v143
	v_fmac_f32_e32 v149, 0x3f317217, v143
	v_cmp_lt_f32_e64 s[28:29], |v143|, s53
	s_nop 1
	v_cndmask_b32_e64 v143, v143, v149, s[28:29]
	v_cndmask_b32_e64 v149, 0, v216, s[26:27]
	v_sub_f32_e32 v143, v143, v149
	v_cndmask_b32_e64 v143, v145, v143, s[24:25]
	v_mul_f32_e32 v145, 0x3fb8aa3b, v148
	v_exp_f32_e32 v145, v145
	s_mov_b32 s29, s91
	s_mov_b32 s28, s95
	v_fmac_f32_e32 v139, v184, v145
	v_cmp_gt_f32_e64 s[24:25], s97, v139
	s_nop 1
	v_cndmask_b32_e64 v145, 0, 32, s[24:25]
	v_ldexp_f32 v139, v139, v145
	v_log_f32_e32 v139, v139
	s_nop 0
	v_mul_f32_e32 v145, 0x3f317217, v139
	v_fma_f32 v145, v139, s52, -v145
	v_fmac_f32_e32 v145, 0x3377d1cf, v139
	v_fmac_f32_e32 v145, 0x3f317217, v139
	v_cmp_lt_f32_e64 s[26:27], |v139|, s53
	s_nop 1
	v_cndmask_b32_e64 v139, v139, v145, s[26:27]
	v_cndmask_b32_e64 v145, 0, v216, s[24:25]
	v_readlane_b32 s27, v255, 56
	v_readlane_b32 s26, v255, 31
	v_sub_f32_e32 v139, v139, v145
	v_cndmask_b32_e64 v139, v148, v139, s[22:23]
	global_store_dwordx4 v[146:147], v[140:143], off
	global_store_dwordx4 v[146:147], v[136:139], off offset:16
	s_nop 0
	v_pk_mul_f32 v[142:143], v[68:69], v[144:145] op_sel_hi:[1,0]
	v_pk_mul_f32 v[138:139], v[70:71], v[144:145] op_sel_hi:[1,0]
	v_pk_mul_f32 v[136:137], v[66:67], v[144:145] op_sel_hi:[1,0]
	v_pk_mul_f32 v[140:141], v[64:65], v[144:145] op_sel_hi:[1,0]
	v_min_f32_e32 v144, 0, v142
	v_mul_f32_e64 v142, |v142|, s57
	v_exp_f32_e32 v142, v142
	s_nop 0
	v_add_f32_e32 v142, 1.0, v142
	v_log_f32_e32 v142, v142
	s_nop 0
	v_mul_f32_e32 v145, 0x3f317217, v142
	v_fma_f32 v145, v142, s52, -v145
	v_fmac_f32_e32 v145, 0x3377d1cf, v142
	v_fmac_f32_e32 v145, 0x3f317217, v142
	v_sub_f32_e32 v142, v144, v145
	v_min_f32_e32 v144, 0, v140
	v_mul_f32_e64 v140, |v140|, s57
	v_exp_f32_e32 v140, v140
	s_nop 0
	v_add_f32_e32 v140, 1.0, v140
	v_log_f32_e32 v140, v140
	s_nop 0
	v_mul_f32_e32 v145, 0x3f317217, v140
	v_fma_f32 v145, v140, s52, -v145
	v_fmac_f32_e32 v145, 0x3377d1cf, v140
	v_fmac_f32_e32 v145, 0x3f317217, v140
	v_sub_f32_e32 v140, v144, v145
	v_mul_f32_e32 v144, 0x3fb8aa3b, v142
	v_exp_f32_e32 v144, v144
	s_nop 0
	v_fma_f32 v132, v183, v144, v132
	v_log_f32_e32 v132, v132
	s_nop 0
	v_mul_f32_e32 v144, 0x3f317217, v132
	v_fma_f32 v144, v132, s52, -v144
	v_fmac_f32_e32 v144, 0x3377d1cf, v132
	v_fmac_f32_e32 v144, 0x3f317217, v132
	v_cndmask_b32_e64 v132, v142, v144, s[20:21]
	v_mul_f32_e32 v142, 0x3fb8aa3b, v140
	v_exp_f32_e32 v142, v142
	s_nop 0
	v_fma_f32 v128, v182, v142, v128
	v_log_f32_e32 v128, v128
	s_nop 0
	v_mul_f32_e32 v142, 0x3f317217, v128
	v_fma_f32 v142, v128, s52, -v142
	v_fmac_f32_e32 v142, 0x3377d1cf, v128
	v_fmac_f32_e32 v142, 0x3f317217, v128
	v_mov_b32_e32 v128, v142
	v_mul_f32_e64 v142, |v143|, s57
	v_exp_f32_e32 v142, v142
	v_cndmask_b32_e64 v128, v140, v128, s[18:19]
	v_min_f32_e32 v140, 0, v143
	v_readlane_b32 s23, v255, 55
	v_add_f32_e32 v142, 1.0, v142
	v_log_f32_e32 v142, v142
	s_nop 0
	v_mul_f32_e32 v143, 0x3f317217, v142
	v_fma_f32 v143, v142, s52, -v143
	v_fmac_f32_e32 v143, 0x3377d1cf, v142
	v_fmac_f32_e32 v143, 0x3f317217, v142
	v_sub_f32_e32 v140, v140, v143
	v_min_f32_e32 v142, 0, v141
	v_mul_f32_e64 v141, |v141|, s57
	v_exp_f32_e32 v141, v141
	s_nop 0
	v_add_f32_e32 v141, 1.0, v141
	v_log_f32_e32 v141, v141
	s_nop 0
	v_mul_f32_e32 v143, 0x3f317217, v141
	v_fma_f32 v143, v141, s52, -v143
	v_fmac_f32_e32 v143, 0x3377d1cf, v141
	v_fmac_f32_e32 v143, 0x3f317217, v141
	v_sub_f32_e32 v141, v142, v143
	v_mul_f32_e32 v142, 0x3fb8aa3b, v140
	v_exp_f32_e32 v142, v142
	s_nop 0
	v_fma_f32 v133, v181, v142, v133
	v_log_f32_e32 v133, v133
	s_nop 0
	v_mul_f32_e32 v142, 0x3f317217, v133
; __device__ __forceinline__ float silu_f(float x) { return x * __builtin_amdgcn_rcpf(1.f + __expf(-x)); }
; __device__ __forceinline__ v4u pack8(const f32x4 a, const f32x4 b) { v4u w; w.x = cvt_pk_bf16(a[0], a[1]); w.y = cvt_pk_bf16(a[2], a[3]); w.z = cvt_pk_bf16(b[0], b[1]); w.w = cvt_pk_bf16(b[2], b[3]); return w; }
;     __device__ __forceinline__ void operator()(const f32x4 (&acc)[2][2][4][2], const pg8::Unit& u, int wr, int wc, int fr, int fq) const {
;     ...
;         if (grp == 0) { WIN_LOOP( _Pragma("unroll") for (int i = 0; i < 4; ++i) { a[i] = silu_f(a[i]); b[i] = silu_f(b[i]); } *(v4u*)(QO + (size_t)row * DM + c) = pack8(a, b); ) }
;         else if (grp == 3) { WIN_LOOP( _Pragma("unroll") for (int i = 0; i < 4; ++i) { a[i] = silu_f(a[i]); b[i] = silu_f(b[i]); } *(v4u*)(GH + (size_t)row * 512 + c) = pack8(a, b); ) }
;         else if (grp == 1) {
;             f32x4 l0[2], l1[2];
; #pragma unroll
;             for (int bj = 0; bj < 2; ++bj) { l0[bj] = *(const f32x4*)(lb + cb + bj * 128); l1[bj] = *(const f32x4*)(lb + cb + bj * 128 + 4); }
;             WIN_LOOP( _Pragma("unroll") for (int i = 0; i < 4; ++i) { const float s0 = fminf(a[i], 0.f) - __logf(1.f + __expf(-fabsf(a[i]))), s1 = fminf(b[i], 0.f) - __logf(1.f + __expf(-fabsf(b[i]))); const float la = l0[bj][i], lbv = l1[bj][i];
;                     a[i] = la > 0.f ? __logf(la + (1.f - la) * __expf(s0)) : s0; b[i] = lbv > 0.f ? __logf(lbv + (1.f - lbv) * __expf(s1)) : s1; }
;                 *(f32x4*)(LF + (size_t)row * 512 + c) = a; *(f32x4*)(LF + (size_t)row * 512 + c + 4) = b; __builtin_amdgcn_sched_barrier(0); ) }
	v_fma_f32 v142, v133, s52, -v142
	v_fmac_f32_e32 v142, 0x3377d1cf, v133
	v_fmac_f32_e32 v142, 0x3f317217, v133
	v_cndmask_b32_e64 v133, v140, v142, s[16:17]
	v_mul_f32_e32 v140, 0x3fb8aa3b, v141
	v_exp_f32_e32 v140, v140
	s_nop 0
	v_fma_f32 v129, v180, v140, v129
	v_log_f32_e32 v129, v129
	s_nop 0
	v_mul_f32_e32 v140, 0x3f317217, v129
	v_fma_f32 v140, v129, s52, -v140
	v_fmac_f32_e32 v140, 0x3377d1cf, v129
	v_fmac_f32_e32 v140, 0x3f317217, v129
	v_mov_b32_e32 v129, v140
	v_min_f32_e32 v140, 0, v138
	v_mul_f32_e64 v138, |v138|, s57
	v_exp_f32_e32 v138, v138
	v_cndmask_b32_e64 v129, v141, v129, s[14:15]
	v_add_f32_e32 v138, 1.0, v138
	v_log_f32_e32 v138, v138
	s_nop 0
	v_mul_f32_e32 v141, 0x3f317217, v138
	v_fma_f32 v141, v138, s52, -v141
	v_fmac_f32_e32 v141, 0x3377d1cf, v138
	v_fmac_f32_e32 v141, 0x3f317217, v138
	v_sub_f32_e32 v138, v140, v141
	v_min_f32_e32 v140, 0, v136
	v_mul_f32_e64 v136, |v136|, s57
	v_exp_f32_e32 v136, v136
	s_nop 0
	v_add_f32_e32 v136, 1.0, v136
	v_log_f32_e32 v136, v136
	s_nop 0
	v_mul_f32_e32 v141, 0x3f317217, v136
	v_fma_f32 v141, v136, s52, -v141
	v_fmac_f32_e32 v141, 0x3377d1cf, v136
	v_fmac_f32_e32 v141, 0x3f317217, v136
	v_sub_f32_e32 v136, v140, v141
	v_mul_f32_e32 v140, 0x3fb8aa3b, v138
	v_exp_f32_e32 v140, v140
	s_nop 0
	v_fma_f32 v134, v179, v140, v134
	v_log_f32_e32 v134, v134
	s_nop 0
	v_mul_f32_e32 v140, 0x3f317217, v134
	v_fma_f32 v140, v134, s52, -v140
	v_fmac_f32_e32 v140, 0x3377d1cf, v134
	v_fmac_f32_e32 v140, 0x3f317217, v134
	v_cndmask_b32_e64 v134, v138, v140, s[12:13]
	v_mul_f32_e32 v138, 0x3fb8aa3b, v136
	v_exp_f32_e32 v138, v138
	s_nop 0
	v_fma_f32 v130, v178, v138, v130
	v_log_f32_e32 v130, v130
	s_nop 0
	v_mul_f32_e32 v138, 0x3f317217, v130
	v_fma_f32 v138, v130, s52, -v138
	v_fmac_f32_e32 v138, 0x3377d1cf, v130
	v_fmac_f32_e32 v138, 0x3f317217, v130
	v_mov_b32_e32 v130, v138
	v_mul_f32_e64 v138, |v139|, s57
	v_exp_f32_e32 v138, v138
	v_cndmask_b32_e64 v130, v136, v130, s[10:11]
	v_min_f32_e32 v136, 0, v139
	v_add_f32_e32 v138, 1.0, v138
	v_log_f32_e32 v138, v138
	s_nop 0
	v_mul_f32_e32 v139, 0x3f317217, v138
	v_fma_f32 v139, v138, s52, -v139
	v_fmac_f32_e32 v139, 0x3377d1cf, v138
	v_fmac_f32_e32 v139, 0x3f317217, v138
	v_sub_f32_e32 v136, v136, v139
	v_min_f32_e32 v138, 0, v137
	v_mul_f32_e64 v137, |v137|, s57
	v_exp_f32_e32 v137, v137
	s_nop 0
	v_add_f32_e32 v137, 1.0, v137
	v_log_f32_e32 v137, v137
	s_nop 0
	v_mul_f32_e32 v139, 0x3f317217, v137
	v_fma_f32 v139, v137, s52, -v139
	v_fmac_f32_e32 v139, 0x3377d1cf, v137
	v_fmac_f32_e32 v139, 0x3f317217, v137
	v_sub_f32_e32 v137, v138, v139
	v_mul_f32_e32 v138, 0x3fb8aa3b, v136
	v_exp_f32_e32 v138, v138
	s_nop 0
	v_fmac_f32_e32 v135, v177, v138
	v_cmp_gt_f32_e64 s[10:11], s97, v135
	s_nop 1
	v_cndmask_b32_e64 v138, 0, 32, s[10:11]
	v_ldexp_f32 v135, v135, v138
	v_log_f32_e32 v135, v135
	s_nop 0
	v_mul_f32_e32 v138, 0x3f317217, v135
	v_fma_f32 v138, v135, s52, -v138
	v_fmac_f32_e32 v138, 0x3377d1cf, v135
	v_fmac_f32_e32 v138, 0x3f317217, v135
	v_cmp_lt_f32_e64 s[12:13], |v135|, s53
	s_nop 1
	v_cndmask_b32_e64 v135, v135, v138, s[12:13]
	v_cndmask_b32_e64 v138, 0, v216, s[10:11]
	v_sub_f32_e32 v135, v135, v138
	v_cndmask_b32_e64 v135, v136, v135, s[8:9]
	v_mul_f32_e32 v136, 0x3fb8aa3b, v137
	v_exp_f32_e32 v136, v136
	s_nop 0
	v_fmac_f32_e32 v131, v167, v136
	v_cmp_gt_f32_e64 s[8:9], s97, v131
	s_nop 1
	v_cndmask_b32_e64 v136, 0, 32, s[8:9]
	v_ldexp_f32 v131, v131, v136
	v_log_f32_e32 v131, v131
	s_nop 0
	v_mul_f32_e32 v136, 0x3f317217, v131
	v_fma_f32 v136, v131, s52, -v136
	v_fmac_f32_e32 v136, 0x3377d1cf, v131
	v_fmac_f32_e32 v136, 0x3f317217, v131
	v_cmp_lt_f32_e64 s[10:11], |v131|, s53
	s_nop 1
	v_cndmask_b32_e64 v131, v131, v136, s[10:11]
	v_cndmask_b32_e64 v136, 0, v216, s[8:9]
	v_sub_f32_e32 v131, v131, v136
	v_cndmask_b32_e32 v131, v137, v131, vcc
	global_store_dwordx4 v[146:147], v[132:135], off offset:512
	global_store_dwordx4 v[146:147], v[128:131], off offset:528
